# K-loop load phases: scalar address code + LDS-DMA issue moved ahead of the ds_read fragment reads
# speedup vs baseline: 1.0044x; 1.0044x over previous
.LBB0_169:
	v_cmp_gt_i32_e32 vcc, 1, v138
	s_cbranch_vccnz .LBB0_231
	v_lshl_add_u64 v[152:153], v[2:3], 0, s[22:23]
	v_add_u32_e32 v154, -2, v138
	s_waitcnt lgkmcnt(0)
	v_lshl_add_u64 v[150:151], v[4:5], 0, s[28:29]
	s_mov_b32 s7, 0
	s_nop 0
	v_readfirstlane_b32 s86, v152
	v_readfirstlane_b32 s87, v153
	v_readfirstlane_b32 s88, v150
	v_readfirstlane_b32 s89, v151
	v_readfirstlane_b32 s90, v146
	v_readfirstlane_b32 s91, v147
	v_readfirstlane_b32 s92, v148
	v_readfirstlane_b32 s93, v149
	v_readfirstlane_b32 s100, v154
	v_readfirstlane_b32 s101, v138
	v_add_u32_e32 v230, s76, v141
	v_add_u32_e32 v231, s77, v141
	v_add_u32_e32 v232, 0x18000, v141
	v_add_u32_e32 v233, 0x1c000, v141
	s_add_u32 s98, s86, 0xfffc0080
	s_addc_u32 s99, s87, -1
	s_cmp_eq_u32 s7, s100
	s_cselect_b64 s[94:95], s[90:91], s[98:99]
	s_cselect_b64 s[96:97], s[92:93], s[88:89]
	s_add_i32 s51, s7, 2
	s_nop 0
	s_mov_b32 m0, s78
	s_nop 0
	global_load_lds_dwordx4 v144, s[86:87]
	s_mov_b32 m0, s79
	s_nop 0
	global_load_lds_dwordx4 v142, s[86:87]
	ds_read_b128 v[164:167], v230
	ds_read_b128 v[168:171], v230 offset:1024
	ds_read_b128 v[172:175], v230 offset:2048
	ds_read_b128 v[176:179], v230 offset:3072
	ds_read_b128 v[180:183], v231
	ds_read_b128 v[184:187], v231 offset:1024
	ds_read_b128 v[188:191], v231 offset:2048
	ds_read_b128 v[192:195], v231 offset:3072
	ds_read_b128 v[196:199], v160
	ds_read_b128 v[200:203], v160 offset:1024
	ds_read_b128 v[204:207], v160 offset:2048
	ds_read_b128 v[208:211], v160 offset:3072
	ds_read_b128 v[212:215], v160 offset:4096
	ds_read_b128 v[216:219], v160 offset:5120
	ds_read_b128 v[220:223], v160 offset:6144
	ds_read_b128 v[224:227], v160 offset:7168
	s_waitcnt vmcnt(8)
	s_waitcnt lgkmcnt(0)
	s_barrier
	s_setprio 1
	s_waitcnt lgkmcnt(0)
	v_mfma_f32_16x16x32_bf16 v[122:125], v[164:167], v[196:199], 0
	v_mfma_f32_16x16x32_bf16 v[118:121], v[172:175], v[196:199], 0
	v_mfma_f32_16x16x32_bf16 v[110:113], v[164:167], v[204:207], 0
	v_mfma_f32_16x16x32_bf16 v[102:105], v[172:175], v[204:207], 0
	v_mfma_f32_16x16x32_bf16 v[94:97], v[164:167], v[212:215], 0
	v_mfma_f32_16x16x32_bf16 v[86:89], v[172:175], v[212:215], 0
	v_mfma_f32_16x16x32_bf16 v[78:81], v[164:167], v[220:223], 0
	v_mfma_f32_16x16x32_bf16 v[70:73], v[172:175], v[220:223], 0
	v_mfma_f32_16x16x32_bf16 v[122:125], v[168:171], v[200:203], v[122:125]
	v_mfma_f32_16x16x32_bf16 v[118:121], v[176:179], v[200:203], v[118:121]
	v_mfma_f32_16x16x32_bf16 v[110:113], v[168:171], v[208:211], v[110:113]
	v_mfma_f32_16x16x32_bf16 v[102:105], v[176:179], v[208:211], v[102:105]
	v_mfma_f32_16x16x32_bf16 v[94:97], v[168:171], v[216:219], v[94:97]
	v_mfma_f32_16x16x32_bf16 v[86:89], v[176:179], v[216:219], v[86:89]
	v_mfma_f32_16x16x32_bf16 v[78:81], v[168:171], v[224:227], v[78:81]
	v_mfma_f32_16x16x32_bf16 v[70:73], v[176:179], v[224:227], v[70:73]
	s_setprio 0
	s_setprio 1
	v_mfma_f32_16x16x32_bf16 v[126:129], v[180:183], v[196:199], 0
	v_mfma_f32_16x16x32_bf16 v[114:117], v[188:191], v[196:199], 0
	v_mfma_f32_16x16x32_bf16 v[106:109], v[180:183], v[204:207], 0
	v_mfma_f32_16x16x32_bf16 v[98:101], v[188:191], v[204:207], 0
	v_mfma_f32_16x16x32_bf16 v[90:93], v[180:183], v[212:215], 0
	v_mfma_f32_16x16x32_bf16 v[82:85], v[188:191], v[212:215], 0
	v_mfma_f32_16x16x32_bf16 v[74:77], v[180:183], v[220:223], 0
	v_mfma_f32_16x16x32_bf16 v[66:69], v[188:191], v[220:223], 0
	v_mfma_f32_16x16x32_bf16 v[126:129], v[184:187], v[200:203], v[126:129]
	v_mfma_f32_16x16x32_bf16 v[114:117], v[192:195], v[200:203], v[114:117]
	v_mfma_f32_16x16x32_bf16 v[106:109], v[184:187], v[208:211], v[106:109]
	v_mfma_f32_16x16x32_bf16 v[98:101], v[192:195], v[208:211], v[98:101]
	v_mfma_f32_16x16x32_bf16 v[90:93], v[184:187], v[216:219], v[90:93]
	v_mfma_f32_16x16x32_bf16 v[82:85], v[192:195], v[216:219], v[82:85]
	v_mfma_f32_16x16x32_bf16 v[74:77], v[184:187], v[224:227], v[74:77]
	v_mfma_f32_16x16x32_bf16 v[66:69], v[192:195], v[224:227], v[66:69]
	s_setprio 0
	s_barrier
	s_add_u32 s98, s96, 0x40000
	s_addc_u32 s99, s97, 0
	s_mov_b32 m0, s80
	s_nop 0
	global_load_lds_dwordx4 v132, s[96:97]
	s_mov_b32 m0, s81
	s_add_i32 s7, s77, s47
	global_load_lds_dwordx4 v136, s[96:97]
	s_mov_b32 m0, s7
	s_nop 0
	global_load_lds_dwordx4 v132, s[98:99]
	s_add_i32 m0, s7, 0x2000
	s_nop 0
	global_load_lds_dwordx4 v136, s[98:99]
	s_mov_b32 m0, s57
	s_nop 0
	global_load_lds_dwordx4 v130, s[94:95]
	s_mov_b32 m0, s62
	s_nop 0
	global_load_lds_dwordx4 v134, s[94:95]
	ds_read_b128 v[196:199], v160 offset:16384
	ds_read_b128 v[200:203], v160 offset:17408
	ds_read_b128 v[204:207], v160 offset:18432
	ds_read_b128 v[208:211], v160 offset:19456
	ds_read_b128 v[212:215], v160 offset:20480
	ds_read_b128 v[216:219], v160 offset:21504
	ds_read_b128 v[220:223], v160 offset:22528
	ds_read_b128 v[224:227], v160 offset:23552
	s_waitcnt vmcnt(8)
	s_waitcnt lgkmcnt(0)
	s_barrier
	s_setprio 1
	s_waitcnt lgkmcnt(0)
	v_mfma_f32_16x16x32_bf16 v[62:65], v[164:167], v[196:199], 0
	v_mfma_f32_16x16x32_bf16 v[54:57], v[172:175], v[196:199], 0
	v_mfma_f32_16x16x32_bf16 v[46:49], v[164:167], v[204:207], 0
	v_mfma_f32_16x16x32_bf16 v[38:41], v[172:175], v[204:207], 0
	v_mfma_f32_16x16x32_bf16 v[30:33], v[164:167], v[212:215], 0
	v_mfma_f32_16x16x32_bf16 v[22:25], v[172:175], v[212:215], 0
	v_mfma_f32_16x16x32_bf16 v[14:17], v[164:167], v[220:223], 0
	v_mfma_f32_16x16x32_bf16 v[6:9], v[172:175], v[220:223], 0
	v_mfma_f32_16x16x32_bf16 v[62:65], v[168:171], v[200:203], v[62:65]
	v_mfma_f32_16x16x32_bf16 v[54:57], v[176:179], v[200:203], v[54:57]
	v_mfma_f32_16x16x32_bf16 v[46:49], v[168:171], v[208:211], v[46:49]
	v_mfma_f32_16x16x32_bf16 v[38:41], v[176:179], v[208:211], v[38:41]
	v_mfma_f32_16x16x32_bf16 v[30:33], v[168:171], v[216:219], v[30:33]
	v_mfma_f32_16x16x32_bf16 v[22:25], v[176:179], v[216:219], v[22:25]
	v_mfma_f32_16x16x32_bf16 v[14:17], v[168:171], v[224:227], v[14:17]
	v_mfma_f32_16x16x32_bf16 v[6:9], v[176:179], v[224:227], v[6:9]
	s_setprio 0
	s_setprio 1
	v_mfma_f32_16x16x32_bf16 v[58:61], v[180:183], v[196:199], 0
	v_mfma_f32_16x16x32_bf16 v[50:53], v[188:191], v[196:199], 0
	v_mfma_f32_16x16x32_bf16 v[42:45], v[180:183], v[204:207], 0
	v_mfma_f32_16x16x32_bf16 v[34:37], v[188:191], v[204:207], 0
	v_mfma_f32_16x16x32_bf16 v[26:29], v[180:183], v[212:215], 0
	v_mfma_f32_16x16x32_bf16 v[18:21], v[188:191], v[212:215], 0
	v_mfma_f32_16x16x32_bf16 v[10:13], v[180:183], v[220:223], 0
	v_mfma_f32_16x16x32_bf16 v[2:5], v[188:191], v[220:223], 0
	v_mfma_f32_16x16x32_bf16 v[58:61], v[184:187], v[200:203], v[58:61]
	v_mfma_f32_16x16x32_bf16 v[50:53], v[192:195], v[200:203], v[50:53]
	v_mfma_f32_16x16x32_bf16 v[42:45], v[184:187], v[208:211], v[42:45]
	v_mfma_f32_16x16x32_bf16 v[34:37], v[192:195], v[208:211], v[34:37]
	v_mfma_f32_16x16x32_bf16 v[26:29], v[184:187], v[216:219], v[26:29]
	v_mfma_f32_16x16x32_bf16 v[18:21], v[192:195], v[216:219], v[18:21]
	v_mfma_f32_16x16x32_bf16 v[10:13], v[184:187], v[224:227], v[10:13]
	v_mfma_f32_16x16x32_bf16 v[2:5], v[192:195], v[224:227], v[2:5]
	s_setprio 0
	s_barrier
	s_add_u32 s98, s94, 0x40000
	s_addc_u32 s99, s95, 0
	s_add_i32 s7, 0, 0x18000
	s_add_i32 s55, 0, 0x1c000
	s_mov_b32 m0, s63
	s_nop 0
	global_load_lds_dwordx4 v130, s[98:99]
	s_mov_b32 m0, s64
	s_nop 0
	global_load_lds_dwordx4 v134, s[98:99]
	ds_read_b128 v[164:167], v232
	ds_read_b128 v[168:171], v232 offset:1024
	ds_read_b128 v[172:175], v232 offset:2048
	ds_read_b128 v[176:179], v232 offset:3072
	ds_read_b128 v[180:183], v233
	ds_read_b128 v[184:187], v233 offset:1024
	ds_read_b128 v[188:191], v233 offset:2048
	ds_read_b128 v[192:195], v233 offset:3072
	ds_read_b128 v[196:199], v160 offset:32768
	ds_read_b128 v[200:203], v160 offset:33792
	ds_read_b128 v[204:207], v160 offset:34816
	ds_read_b128 v[208:211], v160 offset:35840
	ds_read_b128 v[212:215], v160 offset:36864
	ds_read_b128 v[216:219], v160 offset:37888
	ds_read_b128 v[220:223], v160 offset:38912
	ds_read_b128 v[224:227], v160 offset:39936
	s_waitcnt vmcnt(8)
	s_waitcnt lgkmcnt(0)
	s_barrier
	s_setprio 1
	s_waitcnt lgkmcnt(0)
	v_mfma_f32_16x16x32_bf16 v[122:125], v[164:167], v[196:199], v[122:125]
	v_mfma_f32_16x16x32_bf16 v[118:121], v[172:175], v[196:199], v[118:121]
	v_mfma_f32_16x16x32_bf16 v[110:113], v[164:167], v[204:207], v[110:113]
	v_mfma_f32_16x16x32_bf16 v[102:105], v[172:175], v[204:207], v[102:105]
	v_mfma_f32_16x16x32_bf16 v[94:97], v[164:167], v[212:215], v[94:97]
	v_mfma_f32_16x16x32_bf16 v[86:89], v[172:175], v[212:215], v[86:89]
	v_mfma_f32_16x16x32_bf16 v[78:81], v[164:167], v[220:223], v[78:81]
	v_mfma_f32_16x16x32_bf16 v[70:73], v[172:175], v[220:223], v[70:73]
	v_mfma_f32_16x16x32_bf16 v[122:125], v[168:171], v[200:203], v[122:125]
	v_mfma_f32_16x16x32_bf16 v[118:121], v[176:179], v[200:203], v[118:121]
	v_mfma_f32_16x16x32_bf16 v[110:113], v[168:171], v[208:211], v[110:113]
	v_mfma_f32_16x16x32_bf16 v[102:105], v[176:179], v[208:211], v[102:105]
	v_mfma_f32_16x16x32_bf16 v[94:97], v[168:171], v[216:219], v[94:97]
	v_mfma_f32_16x16x32_bf16 v[86:89], v[176:179], v[216:219], v[86:89]
	v_mfma_f32_16x16x32_bf16 v[78:81], v[168:171], v[224:227], v[78:81]
	v_mfma_f32_16x16x32_bf16 v[70:73], v[176:179], v[224:227], v[70:73]
	s_setprio 0
	s_setprio 1
	v_mfma_f32_16x16x32_bf16 v[126:129], v[180:183], v[196:199], v[126:129]
	v_mfma_f32_16x16x32_bf16 v[114:117], v[188:191], v[196:199], v[114:117]
	v_mfma_f32_16x16x32_bf16 v[106:109], v[180:183], v[204:207], v[106:109]
	v_mfma_f32_16x16x32_bf16 v[98:101], v[188:191], v[204:207], v[98:101]
	v_mfma_f32_16x16x32_bf16 v[90:93], v[180:183], v[212:215], v[90:93]
	v_mfma_f32_16x16x32_bf16 v[82:85], v[188:191], v[212:215], v[82:85]
	v_mfma_f32_16x16x32_bf16 v[74:77], v[180:183], v[220:223], v[74:77]
	v_mfma_f32_16x16x32_bf16 v[66:69], v[188:191], v[220:223], v[66:69]
	v_mfma_f32_16x16x32_bf16 v[126:129], v[184:187], v[200:203], v[126:129]
	v_mfma_f32_16x16x32_bf16 v[114:117], v[192:195], v[200:203], v[114:117]
	v_mfma_f32_16x16x32_bf16 v[106:109], v[184:187], v[208:211], v[106:109]
	v_mfma_f32_16x16x32_bf16 v[98:101], v[192:195], v[208:211], v[98:101]
	v_mfma_f32_16x16x32_bf16 v[90:93], v[184:187], v[216:219], v[90:93]
	v_mfma_f32_16x16x32_bf16 v[82:85], v[192:195], v[216:219], v[82:85]
	v_mfma_f32_16x16x32_bf16 v[74:77], v[184:187], v[224:227], v[74:77]
	v_mfma_f32_16x16x32_bf16 v[66:69], v[192:195], v[224:227], v[66:69]
	s_setprio 0
	s_barrier
	s_add_u32 s96, s96, 0x80
	s_addc_u32 s97, s97, 0
	s_add_u32 s98, s96, 0x40000
	s_addc_u32 s99, s97, 0
	s_add_u32 s94, s94, 0x80
	s_addc_u32 s95, s95, 0
	s_add_i32 s7, s7, s47
	s_mov_b32 m0, s7
	s_nop 0
	global_load_lds_dwordx4 v132, s[96:97]
	s_add_i32 m0, s7, 0x2000
	s_add_i32 s7, s55, s47
	global_load_lds_dwordx4 v136, s[96:97]
	s_mov_b32 m0, s7
	s_nop 0
	global_load_lds_dwordx4 v132, s[98:99]
	s_add_i32 m0, s7, 0x2000
	s_nop 0
	global_load_lds_dwordx4 v136, s[98:99]
	s_mov_b32 m0, s65
	s_nop 0
	global_load_lds_dwordx4 v130, s[94:95]
	s_mov_b32 m0, s66
	s_nop 0
	global_load_lds_dwordx4 v134, s[94:95]
	ds_read_b128 v[196:199], v160 offset:49152
	ds_read_b128 v[200:203], v160 offset:50176
	ds_read_b128 v[204:207], v160 offset:51200
	ds_read_b128 v[208:211], v160 offset:52224
	ds_read_b128 v[212:215], v160 offset:53248
	ds_read_b128 v[216:219], v160 offset:54272
	ds_read_b128 v[220:223], v160 offset:55296
	ds_read_b128 v[224:227], v160 offset:56320
	s_waitcnt vmcnt(8)
	s_waitcnt lgkmcnt(0)
	s_barrier
	s_setprio 1
	s_waitcnt lgkmcnt(0)
	v_mfma_f32_16x16x32_bf16 v[62:65], v[164:167], v[196:199], v[62:65]
	v_mfma_f32_16x16x32_bf16 v[54:57], v[172:175], v[196:199], v[54:57]
	v_mfma_f32_16x16x32_bf16 v[46:49], v[164:167], v[204:207], v[46:49]
	v_mfma_f32_16x16x32_bf16 v[38:41], v[172:175], v[204:207], v[38:41]
	v_mfma_f32_16x16x32_bf16 v[30:33], v[164:167], v[212:215], v[30:33]
	v_mfma_f32_16x16x32_bf16 v[22:25], v[172:175], v[212:215], v[22:25]
	v_mfma_f32_16x16x32_bf16 v[14:17], v[164:167], v[220:223], v[14:17]
	v_mfma_f32_16x16x32_bf16 v[6:9], v[172:175], v[220:223], v[6:9]
	v_mfma_f32_16x16x32_bf16 v[62:65], v[168:171], v[200:203], v[62:65]
	v_mfma_f32_16x16x32_bf16 v[54:57], v[176:179], v[200:203], v[54:57]
	v_mfma_f32_16x16x32_bf16 v[46:49], v[168:171], v[208:211], v[46:49]
	v_mfma_f32_16x16x32_bf16 v[38:41], v[176:179], v[208:211], v[38:41]
	v_mfma_f32_16x16x32_bf16 v[30:33], v[168:171], v[216:219], v[30:33]
	v_mfma_f32_16x16x32_bf16 v[22:25], v[176:179], v[216:219], v[22:25]
	v_mfma_f32_16x16x32_bf16 v[14:17], v[168:171], v[224:227], v[14:17]
	v_mfma_f32_16x16x32_bf16 v[6:9], v[176:179], v[224:227], v[6:9]
	s_setprio 0
	s_setprio 1
	v_mfma_f32_16x16x32_bf16 v[58:61], v[180:183], v[196:199], v[58:61]
	v_mfma_f32_16x16x32_bf16 v[50:53], v[188:191], v[196:199], v[50:53]
	v_mfma_f32_16x16x32_bf16 v[42:45], v[180:183], v[204:207], v[42:45]
	v_mfma_f32_16x16x32_bf16 v[34:37], v[188:191], v[204:207], v[34:37]
	v_mfma_f32_16x16x32_bf16 v[26:29], v[180:183], v[212:215], v[26:29]
	v_mfma_f32_16x16x32_bf16 v[18:21], v[188:191], v[212:215], v[18:21]
	v_mfma_f32_16x16x32_bf16 v[10:13], v[180:183], v[220:223], v[10:13]
	v_mfma_f32_16x16x32_bf16 v[2:5], v[188:191], v[220:223], v[2:5]
	v_mfma_f32_16x16x32_bf16 v[58:61], v[184:187], v[200:203], v[58:61]
	v_mfma_f32_16x16x32_bf16 v[50:53], v[192:195], v[200:203], v[50:53]
	v_mfma_f32_16x16x32_bf16 v[42:45], v[184:187], v[208:211], v[42:45]
	v_mfma_f32_16x16x32_bf16 v[34:37], v[192:195], v[208:211], v[34:37]
	v_mfma_f32_16x16x32_bf16 v[26:29], v[184:187], v[216:219], v[26:29]
	v_mfma_f32_16x16x32_bf16 v[18:21], v[192:195], v[216:219], v[18:21]
	v_mfma_f32_16x16x32_bf16 v[10:13], v[184:187], v[224:227], v[10:13]
	v_mfma_f32_16x16x32_bf16 v[2:5], v[192:195], v[224:227], v[2:5]
	s_setprio 0
	s_barrier
	s_mov_b32 s7, s51
	s_add_u32 s88, s88, 0x100
	s_addc_u32 s89, s89, 0
	s_add_u32 s86, s86, 0x100
	s_addc_u32 s87, s87, 0
	s_cmp_ge_i32 s51, s101
	s_cbranch_scc1 .Lmy_kexit_0
.LBB0_171:
	s_add_u32 s98, s86, 0xfffc0080
	s_addc_u32 s99, s87, -1
	s_cmp_eq_u32 s7, s100
	s_cselect_b64 s[94:95], s[90:91], s[98:99]
	s_cselect_b64 s[96:97], s[92:93], s[88:89]
	s_add_i32 s51, s7, 2
	s_nop 0
	s_mov_b32 m0, s78
	s_nop 0
	global_load_lds_dwordx4 v144, s[86:87]
	s_mov_b32 m0, s79
	s_nop 0
	global_load_lds_dwordx4 v142, s[86:87]
	ds_read_b128 v[164:167], v230
	ds_read_b128 v[168:171], v230 offset:1024
	ds_read_b128 v[172:175], v230 offset:2048
	ds_read_b128 v[176:179], v230 offset:3072
	ds_read_b128 v[180:183], v231
	ds_read_b128 v[184:187], v231 offset:1024
	ds_read_b128 v[188:191], v231 offset:2048
	ds_read_b128 v[192:195], v231 offset:3072
	ds_read_b128 v[196:199], v160
	ds_read_b128 v[200:203], v160 offset:1024
	ds_read_b128 v[204:207], v160 offset:2048
	ds_read_b128 v[208:211], v160 offset:3072
	ds_read_b128 v[212:215], v160 offset:4096
	ds_read_b128 v[216:219], v160 offset:5120
	ds_read_b128 v[220:223], v160 offset:6144
	ds_read_b128 v[224:227], v160 offset:7168
	s_waitcnt vmcnt(8)
	s_waitcnt lgkmcnt(0)
	s_barrier
	s_setprio 1
	s_waitcnt lgkmcnt(0)
	v_mfma_f32_16x16x32_bf16 v[122:125], v[164:167], v[196:199], v[122:125]
	v_mfma_f32_16x16x32_bf16 v[118:121], v[172:175], v[196:199], v[118:121]
	v_mfma_f32_16x16x32_bf16 v[110:113], v[164:167], v[204:207], v[110:113]
	v_mfma_f32_16x16x32_bf16 v[102:105], v[172:175], v[204:207], v[102:105]
	v_mfma_f32_16x16x32_bf16 v[94:97], v[164:167], v[212:215], v[94:97]
	v_mfma_f32_16x16x32_bf16 v[86:89], v[172:175], v[212:215], v[86:89]
	v_mfma_f32_16x16x32_bf16 v[78:81], v[164:167], v[220:223], v[78:81]
	v_mfma_f32_16x16x32_bf16 v[70:73], v[172:175], v[220:223], v[70:73]
	v_mfma_f32_16x16x32_bf16 v[122:125], v[168:171], v[200:203], v[122:125]
	v_mfma_f32_16x16x32_bf16 v[118:121], v[176:179], v[200:203], v[118:121]
	v_mfma_f32_16x16x32_bf16 v[110:113], v[168:171], v[208:211], v[110:113]
	v_mfma_f32_16x16x32_bf16 v[102:105], v[176:179], v[208:211], v[102:105]
	v_mfma_f32_16x16x32_bf16 v[94:97], v[168:171], v[216:219], v[94:97]
	v_mfma_f32_16x16x32_bf16 v[86:89], v[176:179], v[216:219], v[86:89]
	v_mfma_f32_16x16x32_bf16 v[78:81], v[168:171], v[224:227], v[78:81]
	v_mfma_f32_16x16x32_bf16 v[70:73], v[176:179], v[224:227], v[70:73]
	s_setprio 0
	s_setprio 1
	v_mfma_f32_16x16x32_bf16 v[126:129], v[180:183], v[196:199], v[126:129]
	v_mfma_f32_16x16x32_bf16 v[114:117], v[188:191], v[196:199], v[114:117]
	v_mfma_f32_16x16x32_bf16 v[106:109], v[180:183], v[204:207], v[106:109]
	v_mfma_f32_16x16x32_bf16 v[98:101], v[188:191], v[204:207], v[98:101]
	v_mfma_f32_16x16x32_bf16 v[90:93], v[180:183], v[212:215], v[90:93]
	v_mfma_f32_16x16x32_bf16 v[82:85], v[188:191], v[212:215], v[82:85]
	v_mfma_f32_16x16x32_bf16 v[74:77], v[180:183], v[220:223], v[74:77]
	v_mfma_f32_16x16x32_bf16 v[66:69], v[188:191], v[220:223], v[66:69]
	v_mfma_f32_16x16x32_bf16 v[126:129], v[184:187], v[200:203], v[126:129]
	v_mfma_f32_16x16x32_bf16 v[114:117], v[192:195], v[200:203], v[114:117]
	v_mfma_f32_16x16x32_bf16 v[106:109], v[184:187], v[208:211], v[106:109]
	v_mfma_f32_16x16x32_bf16 v[98:101], v[192:195], v[208:211], v[98:101]
	v_mfma_f32_16x16x32_bf16 v[90:93], v[184:187], v[216:219], v[90:93]
	v_mfma_f32_16x16x32_bf16 v[82:85], v[192:195], v[216:219], v[82:85]
	v_mfma_f32_16x16x32_bf16 v[74:77], v[184:187], v[224:227], v[74:77]
	v_mfma_f32_16x16x32_bf16 v[66:69], v[192:195], v[224:227], v[66:69]
	s_setprio 0
	s_barrier
	s_add_u32 s98, s96, 0x40000
	s_addc_u32 s99, s97, 0
	s_mov_b32 m0, s80
	s_nop 0
	global_load_lds_dwordx4 v132, s[96:97]
	s_mov_b32 m0, s81
	s_add_i32 s7, s77, s47
	global_load_lds_dwordx4 v136, s[96:97]
	s_mov_b32 m0, s7
	s_nop 0
	global_load_lds_dwordx4 v132, s[98:99]
	s_add_i32 m0, s7, 0x2000
	s_nop 0
	global_load_lds_dwordx4 v136, s[98:99]
	s_mov_b32 m0, s57
	s_nop 0
	global_load_lds_dwordx4 v130, s[94:95]
	s_mov_b32 m0, s62
	s_nop 0
	global_load_lds_dwordx4 v134, s[94:95]
	ds_read_b128 v[196:199], v160 offset:16384
	ds_read_b128 v[200:203], v160 offset:17408
	ds_read_b128 v[204:207], v160 offset:18432
	ds_read_b128 v[208:211], v160 offset:19456
	ds_read_b128 v[212:215], v160 offset:20480
	ds_read_b128 v[216:219], v160 offset:21504
	ds_read_b128 v[220:223], v160 offset:22528
	ds_read_b128 v[224:227], v160 offset:23552
	s_waitcnt vmcnt(8)
	s_waitcnt lgkmcnt(0)
	s_barrier
	s_setprio 1
	s_waitcnt lgkmcnt(0)
	v_mfma_f32_16x16x32_bf16 v[62:65], v[164:167], v[196:199], v[62:65]
	v_mfma_f32_16x16x32_bf16 v[54:57], v[172:175], v[196:199], v[54:57]
	v_mfma_f32_16x16x32_bf16 v[46:49], v[164:167], v[204:207], v[46:49]
	v_mfma_f32_16x16x32_bf16 v[38:41], v[172:175], v[204:207], v[38:41]
	v_mfma_f32_16x16x32_bf16 v[30:33], v[164:167], v[212:215], v[30:33]
	v_mfma_f32_16x16x32_bf16 v[22:25], v[172:175], v[212:215], v[22:25]
	v_mfma_f32_16x16x32_bf16 v[14:17], v[164:167], v[220:223], v[14:17]
	v_mfma_f32_16x16x32_bf16 v[6:9], v[172:175], v[220:223], v[6:9]
	v_mfma_f32_16x16x32_bf16 v[62:65], v[168:171], v[200:203], v[62:65]
	v_mfma_f32_16x16x32_bf16 v[54:57], v[176:179], v[200:203], v[54:57]
	v_mfma_f32_16x16x32_bf16 v[46:49], v[168:171], v[208:211], v[46:49]
	v_mfma_f32_16x16x32_bf16 v[38:41], v[176:179], v[208:211], v[38:41]
	v_mfma_f32_16x16x32_bf16 v[30:33], v[168:171], v[216:219], v[30:33]
	v_mfma_f32_16x16x32_bf16 v[22:25], v[176:179], v[216:219], v[22:25]
	v_mfma_f32_16x16x32_bf16 v[14:17], v[168:171], v[224:227], v[14:17]
	v_mfma_f32_16x16x32_bf16 v[6:9], v[176:179], v[224:227], v[6:9]
	s_setprio 0
	s_setprio 1
	v_mfma_f32_16x16x32_bf16 v[58:61], v[180:183], v[196:199], v[58:61]
	v_mfma_f32_16x16x32_bf16 v[50:53], v[188:191], v[196:199], v[50:53]
	v_mfma_f32_16x16x32_bf16 v[42:45], v[180:183], v[204:207], v[42:45]
	v_mfma_f32_16x16x32_bf16 v[34:37], v[188:191], v[204:207], v[34:37]
	v_mfma_f32_16x16x32_bf16 v[26:29], v[180:183], v[212:215], v[26:29]
	v_mfma_f32_16x16x32_bf16 v[18:21], v[188:191], v[212:215], v[18:21]
	v_mfma_f32_16x16x32_bf16 v[10:13], v[180:183], v[220:223], v[10:13]
	v_mfma_f32_16x16x32_bf16 v[2:5], v[188:191], v[220:223], v[2:5]
	v_mfma_f32_16x16x32_bf16 v[58:61], v[184:187], v[200:203], v[58:61]
	v_mfma_f32_16x16x32_bf16 v[50:53], v[192:195], v[200:203], v[50:53]
	v_mfma_f32_16x16x32_bf16 v[42:45], v[184:187], v[208:211], v[42:45]
	v_mfma_f32_16x16x32_bf16 v[34:37], v[192:195], v[208:211], v[34:37]
	v_mfma_f32_16x16x32_bf16 v[26:29], v[184:187], v[216:219], v[26:29]
	v_mfma_f32_16x16x32_bf16 v[18:21], v[192:195], v[216:219], v[18:21]
	v_mfma_f32_16x16x32_bf16 v[10:13], v[184:187], v[224:227], v[10:13]
	v_mfma_f32_16x16x32_bf16 v[2:5], v[192:195], v[224:227], v[2:5]
	s_setprio 0
	s_barrier
	s_add_u32 s98, s94, 0x40000
	s_addc_u32 s99, s95, 0
	s_add_i32 s7, 0, 0x18000
	s_add_i32 s55, 0, 0x1c000
	s_mov_b32 m0, s63
	s_nop 0
	global_load_lds_dwordx4 v130, s[98:99]
	s_mov_b32 m0, s64
	s_nop 0
	global_load_lds_dwordx4 v134, s[98:99]
	ds_read_b128 v[164:167], v232
	ds_read_b128 v[168:171], v232 offset:1024
	ds_read_b128 v[172:175], v232 offset:2048
	ds_read_b128 v[176:179], v232 offset:3072
	ds_read_b128 v[180:183], v233
	ds_read_b128 v[184:187], v233 offset:1024
	ds_read_b128 v[188:191], v233 offset:2048
	ds_read_b128 v[192:195], v233 offset:3072
	ds_read_b128 v[196:199], v160 offset:32768
	ds_read_b128 v[200:203], v160 offset:33792
	ds_read_b128 v[204:207], v160 offset:34816
	ds_read_b128 v[208:211], v160 offset:35840
	ds_read_b128 v[212:215], v160 offset:36864
	ds_read_b128 v[216:219], v160 offset:37888
	ds_read_b128 v[220:223], v160 offset:38912
	ds_read_b128 v[224:227], v160 offset:39936
	s_waitcnt vmcnt(8)
	s_waitcnt lgkmcnt(0)
	s_barrier
	s_setprio 1
	s_waitcnt lgkmcnt(0)
	v_mfma_f32_16x16x32_bf16 v[122:125], v[164:167], v[196:199], v[122:125]
	v_mfma_f32_16x16x32_bf16 v[118:121], v[172:175], v[196:199], v[118:121]
	v_mfma_f32_16x16x32_bf16 v[110:113], v[164:167], v[204:207], v[110:113]
	v_mfma_f32_16x16x32_bf16 v[102:105], v[172:175], v[204:207], v[102:105]
	v_mfma_f32_16x16x32_bf16 v[94:97], v[164:167], v[212:215], v[94:97]
	v_mfma_f32_16x16x32_bf16 v[86:89], v[172:175], v[212:215], v[86:89]
	v_mfma_f32_16x16x32_bf16 v[78:81], v[164:167], v[220:223], v[78:81]
	v_mfma_f32_16x16x32_bf16 v[70:73], v[172:175], v[220:223], v[70:73]
	v_mfma_f32_16x16x32_bf16 v[122:125], v[168:171], v[200:203], v[122:125]
	v_mfma_f32_16x16x32_bf16 v[118:121], v[176:179], v[200:203], v[118:121]
	v_mfma_f32_16x16x32_bf16 v[110:113], v[168:171], v[208:211], v[110:113]
	v_mfma_f32_16x16x32_bf16 v[102:105], v[176:179], v[208:211], v[102:105]
	v_mfma_f32_16x16x32_bf16 v[94:97], v[168:171], v[216:219], v[94:97]
	v_mfma_f32_16x16x32_bf16 v[86:89], v[176:179], v[216:219], v[86:89]
	v_mfma_f32_16x16x32_bf16 v[78:81], v[168:171], v[224:227], v[78:81]
	v_mfma_f32_16x16x32_bf16 v[70:73], v[176:179], v[224:227], v[70:73]
	s_setprio 0
	s_setprio 1
	v_mfma_f32_16x16x32_bf16 v[126:129], v[180:183], v[196:199], v[126:129]
	v_mfma_f32_16x16x32_bf16 v[114:117], v[188:191], v[196:199], v[114:117]
	v_mfma_f32_16x16x32_bf16 v[106:109], v[180:183], v[204:207], v[106:109]
	v_mfma_f32_16x16x32_bf16 v[98:101], v[188:191], v[204:207], v[98:101]
	v_mfma_f32_16x16x32_bf16 v[90:93], v[180:183], v[212:215], v[90:93]
	v_mfma_f32_16x16x32_bf16 v[82:85], v[188:191], v[212:215], v[82:85]
	v_mfma_f32_16x16x32_bf16 v[74:77], v[180:183], v[220:223], v[74:77]
	v_mfma_f32_16x16x32_bf16 v[66:69], v[188:191], v[220:223], v[66:69]
	v_mfma_f32_16x16x32_bf16 v[126:129], v[184:187], v[200:203], v[126:129]
	v_mfma_f32_16x16x32_bf16 v[114:117], v[192:195], v[200:203], v[114:117]
	v_mfma_f32_16x16x32_bf16 v[106:109], v[184:187], v[208:211], v[106:109]
	v_mfma_f32_16x16x32_bf16 v[98:101], v[192:195], v[208:211], v[98:101]
	v_mfma_f32_16x16x32_bf16 v[90:93], v[184:187], v[216:219], v[90:93]
	v_mfma_f32_16x16x32_bf16 v[82:85], v[192:195], v[216:219], v[82:85]
	v_mfma_f32_16x16x32_bf16 v[74:77], v[184:187], v[224:227], v[74:77]
	v_mfma_f32_16x16x32_bf16 v[66:69], v[192:195], v[224:227], v[66:69]
	s_setprio 0
	s_barrier
	s_add_u32 s96, s96, 0x80
	s_addc_u32 s97, s97, 0
	s_add_u32 s98, s96, 0x40000
	s_addc_u32 s99, s97, 0
	s_add_u32 s94, s94, 0x80
	s_addc_u32 s95, s95, 0
	s_add_i32 s7, s7, s47
	s_mov_b32 m0, s7
	s_nop 0
	global_load_lds_dwordx4 v132, s[96:97]
	s_add_i32 m0, s7, 0x2000
	s_add_i32 s7, s55, s47
	global_load_lds_dwordx4 v136, s[96:97]
	s_mov_b32 m0, s7
	s_nop 0
	global_load_lds_dwordx4 v132, s[98:99]
	s_add_i32 m0, s7, 0x2000
	s_nop 0
	global_load_lds_dwordx4 v136, s[98:99]
	s_mov_b32 m0, s65
	s_nop 0
	global_load_lds_dwordx4 v130, s[94:95]
	s_mov_b32 m0, s66
	s_nop 0
	global_load_lds_dwordx4 v134, s[94:95]
	ds_read_b128 v[196:199], v160 offset:49152
	ds_read_b128 v[200:203], v160 offset:50176
	ds_read_b128 v[204:207], v160 offset:51200
	ds_read_b128 v[208:211], v160 offset:52224
	ds_read_b128 v[212:215], v160 offset:53248
	ds_read_b128 v[216:219], v160 offset:54272
	ds_read_b128 v[220:223], v160 offset:55296
	ds_read_b128 v[224:227], v160 offset:56320
	s_waitcnt vmcnt(8)
	s_waitcnt lgkmcnt(0)
	s_barrier
	s_setprio 1
	s_waitcnt lgkmcnt(0)
	v_mfma_f32_16x16x32_bf16 v[62:65], v[164:167], v[196:199], v[62:65]
	v_mfma_f32_16x16x32_bf16 v[54:57], v[172:175], v[196:199], v[54:57]
	v_mfma_f32_16x16x32_bf16 v[46:49], v[164:167], v[204:207], v[46:49]
	v_mfma_f32_16x16x32_bf16 v[38:41], v[172:175], v[204:207], v[38:41]
	v_mfma_f32_16x16x32_bf16 v[30:33], v[164:167], v[212:215], v[30:33]
	v_mfma_f32_16x16x32_bf16 v[22:25], v[172:175], v[212:215], v[22:25]
	v_mfma_f32_16x16x32_bf16 v[14:17], v[164:167], v[220:223], v[14:17]
	v_mfma_f32_16x16x32_bf16 v[6:9], v[172:175], v[220:223], v[6:9]
	v_mfma_f32_16x16x32_bf16 v[62:65], v[168:171], v[200:203], v[62:65]
	v_mfma_f32_16x16x32_bf16 v[54:57], v[176:179], v[200:203], v[54:57]
	v_mfma_f32_16x16x32_bf16 v[46:49], v[168:171], v[208:211], v[46:49]
	v_mfma_f32_16x16x32_bf16 v[38:41], v[176:179], v[208:211], v[38:41]
	v_mfma_f32_16x16x32_bf16 v[30:33], v[168:171], v[216:219], v[30:33]
	v_mfma_f32_16x16x32_bf16 v[22:25], v[176:179], v[216:219], v[22:25]
	v_mfma_f32_16x16x32_bf16 v[14:17], v[168:171], v[224:227], v[14:17]
	v_mfma_f32_16x16x32_bf16 v[6:9], v[176:179], v[224:227], v[6:9]
	s_setprio 0
	s_setprio 1
	v_mfma_f32_16x16x32_bf16 v[58:61], v[180:183], v[196:199], v[58:61]
	v_mfma_f32_16x16x32_bf16 v[50:53], v[188:191], v[196:199], v[50:53]
	v_mfma_f32_16x16x32_bf16 v[42:45], v[180:183], v[204:207], v[42:45]
	v_mfma_f32_16x16x32_bf16 v[34:37], v[188:191], v[204:207], v[34:37]
	v_mfma_f32_16x16x32_bf16 v[26:29], v[180:183], v[212:215], v[26:29]
	v_mfma_f32_16x16x32_bf16 v[18:21], v[188:191], v[212:215], v[18:21]
	v_mfma_f32_16x16x32_bf16 v[10:13], v[180:183], v[220:223], v[10:13]
	v_mfma_f32_16x16x32_bf16 v[2:5], v[188:191], v[220:223], v[2:5]
	v_mfma_f32_16x16x32_bf16 v[58:61], v[184:187], v[200:203], v[58:61]
	v_mfma_f32_16x16x32_bf16 v[50:53], v[192:195], v[200:203], v[50:53]
	v_mfma_f32_16x16x32_bf16 v[42:45], v[184:187], v[208:211], v[42:45]
	v_mfma_f32_16x16x32_bf16 v[34:37], v[192:195], v[208:211], v[34:37]
	v_mfma_f32_16x16x32_bf16 v[26:29], v[184:187], v[216:219], v[26:29]
	v_mfma_f32_16x16x32_bf16 v[18:21], v[192:195], v[216:219], v[18:21]
	v_mfma_f32_16x16x32_bf16 v[10:13], v[184:187], v[224:227], v[10:13]
	v_mfma_f32_16x16x32_bf16 v[2:5], v[192:195], v[224:227], v[2:5]
	s_setprio 0
	s_barrier
	s_mov_b32 s7, s51
	s_add_u32 s88, s88, 0x100
	s_addc_u32 s89, s89, 0
	s_add_u32 s86, s86, 0x100
	s_addc_u32 s87, s87, 0
	s_cmp_ge_i32 s51, s101
	s_cbranch_scc0 .LBB0_171

.LBB0_308:
	v_cmp_gt_i32_e32 vcc, 1, v141
	s_cbranch_vccnz .LBB0_370
	v_lshl_add_u64 v[154:155], v[2:3], 0, s[28:29]
	v_add_u32_e32 v138, -2, v141
	s_mov_b32 s8, 0
	s_nop 0
	v_readfirstlane_b32 s86, v152
	v_readfirstlane_b32 s87, v153
	v_readfirstlane_b32 s88, v154
	v_readfirstlane_b32 s89, v155
	v_readfirstlane_b32 s90, v148
	v_readfirstlane_b32 s91, v149
	v_readfirstlane_b32 s92, v150
	v_readfirstlane_b32 s93, v151
	v_readfirstlane_b32 s100, v138
	v_readfirstlane_b32 s101, v141
	v_add_u32_e32 v230, s69, v160
	v_add_u32_e32 v231, s72, v160
	v_add_u32_e32 v232, 0x18000, v160
	v_add_u32_e32 v233, 0x1c000, v160
	s_add_u32 s98, s86, 0x100
	s_addc_u32 s99, s87, 0
	s_cmp_eq_u32 s8, s100
	s_cselect_b64 s[94:95], s[90:91], s[98:99]
	s_cselect_b64 s[96:97], s[92:93], s[88:89]
	s_add_i32 s9, s8, 2
	s_nop 0
	s_add_i32 m0, s55, 0xc000
	s_nop 0
	global_load_lds_dwordx4 v144, s[86:87]
	s_add_i32 m0, s55, 0xe000
	s_nop 0
	global_load_lds_dwordx4 v142, s[86:87]
	ds_read_b128 v[166:169], v230
	ds_read_b128 v[170:173], v230 offset:1024
	ds_read_b128 v[174:177], v230 offset:2048
	ds_read_b128 v[178:181], v230 offset:3072
	ds_read_b128 v[182:185], v231
	ds_read_b128 v[186:189], v231 offset:1024
	ds_read_b128 v[190:193], v231 offset:2048
	ds_read_b128 v[194:197], v231 offset:3072
	ds_read_b128 v[198:201], v163
	ds_read_b128 v[202:205], v163 offset:1024
	ds_read_b128 v[206:209], v163 offset:2048
	ds_read_b128 v[210:213], v163 offset:3072
	ds_read_b128 v[214:217], v163 offset:4096
	ds_read_b128 v[218:221], v163 offset:5120
	ds_read_b128 v[222:225], v163 offset:6144
	ds_read_b128 v[226:229], v163 offset:7168
	s_waitcnt vmcnt(8)
	s_waitcnt lgkmcnt(0)
	s_barrier
	s_setprio 1
	s_waitcnt lgkmcnt(0)
	v_mfma_f32_16x16x32_bf16 v[122:125], v[166:169], v[198:201], 0
	v_mfma_f32_16x16x32_bf16 v[118:121], v[174:177], v[198:201], 0
	v_mfma_f32_16x16x32_bf16 v[110:113], v[166:169], v[206:209], 0
	v_mfma_f32_16x16x32_bf16 v[102:105], v[174:177], v[206:209], 0
	v_mfma_f32_16x16x32_bf16 v[94:97], v[166:169], v[214:217], 0
	v_mfma_f32_16x16x32_bf16 v[86:89], v[174:177], v[214:217], 0
	v_mfma_f32_16x16x32_bf16 v[78:81], v[166:169], v[222:225], 0
	v_mfma_f32_16x16x32_bf16 v[70:73], v[174:177], v[222:225], 0
	v_mfma_f32_16x16x32_bf16 v[122:125], v[170:173], v[202:205], v[122:125]
	v_mfma_f32_16x16x32_bf16 v[118:121], v[178:181], v[202:205], v[118:121]
	v_mfma_f32_16x16x32_bf16 v[110:113], v[170:173], v[210:213], v[110:113]
	v_mfma_f32_16x16x32_bf16 v[102:105], v[178:181], v[210:213], v[102:105]
	v_mfma_f32_16x16x32_bf16 v[94:97], v[170:173], v[218:221], v[94:97]
	v_mfma_f32_16x16x32_bf16 v[86:89], v[178:181], v[218:221], v[86:89]
	v_mfma_f32_16x16x32_bf16 v[78:81], v[170:173], v[226:229], v[78:81]
	v_mfma_f32_16x16x32_bf16 v[70:73], v[178:181], v[226:229], v[70:73]
	s_setprio 0
	s_setprio 1
	v_mfma_f32_16x16x32_bf16 v[126:129], v[182:185], v[198:201], 0
	v_mfma_f32_16x16x32_bf16 v[114:117], v[190:193], v[198:201], 0
	v_mfma_f32_16x16x32_bf16 v[106:109], v[182:185], v[206:209], 0
	v_mfma_f32_16x16x32_bf16 v[98:101], v[190:193], v[206:209], 0
	v_mfma_f32_16x16x32_bf16 v[90:93], v[182:185], v[214:217], 0
	v_mfma_f32_16x16x32_bf16 v[82:85], v[190:193], v[214:217], 0
	v_mfma_f32_16x16x32_bf16 v[74:77], v[182:185], v[222:225], 0
	v_mfma_f32_16x16x32_bf16 v[66:69], v[190:193], v[222:225], 0
	v_mfma_f32_16x16x32_bf16 v[126:129], v[186:189], v[202:205], v[126:129]
	v_mfma_f32_16x16x32_bf16 v[114:117], v[194:197], v[202:205], v[114:117]
	v_mfma_f32_16x16x32_bf16 v[106:109], v[186:189], v[210:213], v[106:109]
	v_mfma_f32_16x16x32_bf16 v[98:101], v[194:197], v[210:213], v[98:101]
	v_mfma_f32_16x16x32_bf16 v[90:93], v[186:189], v[218:221], v[90:93]
	v_mfma_f32_16x16x32_bf16 v[82:85], v[194:197], v[218:221], v[82:85]
	v_mfma_f32_16x16x32_bf16 v[74:77], v[186:189], v[226:229], v[74:77]
	v_mfma_f32_16x16x32_bf16 v[66:69], v[194:197], v[226:229], v[66:69]
	s_setprio 0
	s_barrier
	s_add_u32 s98, s96, 0xb0000
	s_addc_u32 s99, s97, 0
	s_add_i32 s8, s69, s54
	s_mov_b32 m0, s8
	s_nop 0
	global_load_lds_dwordx4 v132, s[96:97]
	s_add_i32 m0, s8, 0x2000
	s_add_i32 s8, s72, s54
	global_load_lds_dwordx4 v136, s[96:97]
	s_mov_b32 m0, s8
	s_nop 0
	global_load_lds_dwordx4 v132, s[98:99]
	s_add_i32 m0, s8, 0x2000
	s_nop 0
	global_load_lds_dwordx4 v136, s[98:99]
	s_mov_b32 m0, s55
	s_nop 0
	global_load_lds_dwordx4 v130, s[94:95]
	s_mov_b32 m0, s56
	s_nop 0
	global_load_lds_dwordx4 v134, s[94:95]
	ds_read_b128 v[198:201], v163 offset:16384
	ds_read_b128 v[202:205], v163 offset:17408
	ds_read_b128 v[206:209], v163 offset:18432
	ds_read_b128 v[210:213], v163 offset:19456
	ds_read_b128 v[214:217], v163 offset:20480
	ds_read_b128 v[218:221], v163 offset:21504
	ds_read_b128 v[222:225], v163 offset:22528
	ds_read_b128 v[226:229], v163 offset:23552
	s_waitcnt vmcnt(8)
	s_waitcnt lgkmcnt(0)
	s_barrier
	s_setprio 1
	s_waitcnt lgkmcnt(0)
	v_mfma_f32_16x16x32_bf16 v[62:65], v[166:169], v[198:201], 0
	v_mfma_f32_16x16x32_bf16 v[54:57], v[174:177], v[198:201], 0
	v_mfma_f32_16x16x32_bf16 v[46:49], v[166:169], v[206:209], 0
	v_mfma_f32_16x16x32_bf16 v[38:41], v[174:177], v[206:209], 0
	v_mfma_f32_16x16x32_bf16 v[30:33], v[166:169], v[214:217], 0
	v_mfma_f32_16x16x32_bf16 v[22:25], v[174:177], v[214:217], 0
	v_mfma_f32_16x16x32_bf16 v[14:17], v[166:169], v[222:225], 0
	v_mfma_f32_16x16x32_bf16 v[6:9], v[174:177], v[222:225], 0
	v_mfma_f32_16x16x32_bf16 v[62:65], v[170:173], v[202:205], v[62:65]
	v_mfma_f32_16x16x32_bf16 v[54:57], v[178:181], v[202:205], v[54:57]
	v_mfma_f32_16x16x32_bf16 v[46:49], v[170:173], v[210:213], v[46:49]
	v_mfma_f32_16x16x32_bf16 v[38:41], v[178:181], v[210:213], v[38:41]
	v_mfma_f32_16x16x32_bf16 v[30:33], v[170:173], v[218:221], v[30:33]
	v_mfma_f32_16x16x32_bf16 v[22:25], v[178:181], v[218:221], v[22:25]
	v_mfma_f32_16x16x32_bf16 v[14:17], v[170:173], v[226:229], v[14:17]
	v_mfma_f32_16x16x32_bf16 v[6:9], v[178:181], v[226:229], v[6:9]
	s_setprio 0
	s_setprio 1
	v_mfma_f32_16x16x32_bf16 v[58:61], v[182:185], v[198:201], 0
	v_mfma_f32_16x16x32_bf16 v[50:53], v[190:193], v[198:201], 0
	v_mfma_f32_16x16x32_bf16 v[42:45], v[182:185], v[206:209], 0
	v_mfma_f32_16x16x32_bf16 v[34:37], v[190:193], v[206:209], 0
	v_mfma_f32_16x16x32_bf16 v[26:29], v[182:185], v[214:217], 0
	v_mfma_f32_16x16x32_bf16 v[18:21], v[190:193], v[214:217], 0
	v_mfma_f32_16x16x32_bf16 v[10:13], v[182:185], v[222:225], 0
	v_mfma_f32_16x16x32_bf16 v[2:5], v[190:193], v[222:225], 0
	v_mfma_f32_16x16x32_bf16 v[58:61], v[186:189], v[202:205], v[58:61]
	v_mfma_f32_16x16x32_bf16 v[50:53], v[194:197], v[202:205], v[50:53]
	v_mfma_f32_16x16x32_bf16 v[42:45], v[186:189], v[210:213], v[42:45]
	v_mfma_f32_16x16x32_bf16 v[34:37], v[194:197], v[210:213], v[34:37]
	v_mfma_f32_16x16x32_bf16 v[26:29], v[186:189], v[218:221], v[26:29]
	v_mfma_f32_16x16x32_bf16 v[18:21], v[194:197], v[218:221], v[18:21]
	v_mfma_f32_16x16x32_bf16 v[10:13], v[186:189], v[226:229], v[10:13]
	v_mfma_f32_16x16x32_bf16 v[2:5], v[194:197], v[226:229], v[2:5]
	s_setprio 0
	s_barrier
	s_add_u32 s98, s94, 0xb0000
	s_addc_u32 s99, s95, 0
	s_add_i32 s8, 0, 0x18000
	s_add_i32 s50, 0, 0x1c000
	s_mov_b32 m0, s57
	s_nop 0
	global_load_lds_dwordx4 v130, s[98:99]
	s_mov_b32 m0, s58
	s_nop 0
	global_load_lds_dwordx4 v134, s[98:99]
	ds_read_b128 v[166:169], v232
	ds_read_b128 v[170:173], v232 offset:1024
	ds_read_b128 v[174:177], v232 offset:2048
	ds_read_b128 v[178:181], v232 offset:3072
	ds_read_b128 v[182:185], v233
	ds_read_b128 v[186:189], v233 offset:1024
	ds_read_b128 v[190:193], v233 offset:2048
	ds_read_b128 v[194:197], v233 offset:3072
	ds_read_b128 v[198:201], v163 offset:32768
	ds_read_b128 v[202:205], v163 offset:33792
	ds_read_b128 v[206:209], v163 offset:34816
	ds_read_b128 v[210:213], v163 offset:35840
	ds_read_b128 v[214:217], v163 offset:36864
	ds_read_b128 v[218:221], v163 offset:37888
	ds_read_b128 v[222:225], v163 offset:38912
	ds_read_b128 v[226:229], v163 offset:39936
	s_waitcnt vmcnt(8)
	s_waitcnt lgkmcnt(0)
	s_barrier
	s_setprio 1
	s_waitcnt lgkmcnt(0)
	v_mfma_f32_16x16x32_bf16 v[122:125], v[166:169], v[198:201], v[122:125]
	v_mfma_f32_16x16x32_bf16 v[118:121], v[174:177], v[198:201], v[118:121]
	v_mfma_f32_16x16x32_bf16 v[110:113], v[166:169], v[206:209], v[110:113]
	v_mfma_f32_16x16x32_bf16 v[102:105], v[174:177], v[206:209], v[102:105]
	v_mfma_f32_16x16x32_bf16 v[94:97], v[166:169], v[214:217], v[94:97]
	v_mfma_f32_16x16x32_bf16 v[86:89], v[174:177], v[214:217], v[86:89]
	v_mfma_f32_16x16x32_bf16 v[78:81], v[166:169], v[222:225], v[78:81]
	v_mfma_f32_16x16x32_bf16 v[70:73], v[174:177], v[222:225], v[70:73]
	v_mfma_f32_16x16x32_bf16 v[122:125], v[170:173], v[202:205], v[122:125]
	v_mfma_f32_16x16x32_bf16 v[118:121], v[178:181], v[202:205], v[118:121]
	v_mfma_f32_16x16x32_bf16 v[110:113], v[170:173], v[210:213], v[110:113]
	v_mfma_f32_16x16x32_bf16 v[102:105], v[178:181], v[210:213], v[102:105]
	v_mfma_f32_16x16x32_bf16 v[94:97], v[170:173], v[218:221], v[94:97]
	v_mfma_f32_16x16x32_bf16 v[86:89], v[178:181], v[218:221], v[86:89]
	v_mfma_f32_16x16x32_bf16 v[78:81], v[170:173], v[226:229], v[78:81]
	v_mfma_f32_16x16x32_bf16 v[70:73], v[178:181], v[226:229], v[70:73]
	s_setprio 0
	s_setprio 1
	v_mfma_f32_16x16x32_bf16 v[126:129], v[182:185], v[198:201], v[126:129]
	v_mfma_f32_16x16x32_bf16 v[114:117], v[190:193], v[198:201], v[114:117]
	v_mfma_f32_16x16x32_bf16 v[106:109], v[182:185], v[206:209], v[106:109]
	v_mfma_f32_16x16x32_bf16 v[98:101], v[190:193], v[206:209], v[98:101]
	v_mfma_f32_16x16x32_bf16 v[90:93], v[182:185], v[214:217], v[90:93]
	v_mfma_f32_16x16x32_bf16 v[82:85], v[190:193], v[214:217], v[82:85]
	v_mfma_f32_16x16x32_bf16 v[74:77], v[182:185], v[222:225], v[74:77]
	v_mfma_f32_16x16x32_bf16 v[66:69], v[190:193], v[222:225], v[66:69]
	v_mfma_f32_16x16x32_bf16 v[126:129], v[186:189], v[202:205], v[126:129]
	v_mfma_f32_16x16x32_bf16 v[114:117], v[194:197], v[202:205], v[114:117]
	v_mfma_f32_16x16x32_bf16 v[106:109], v[186:189], v[210:213], v[106:109]
	v_mfma_f32_16x16x32_bf16 v[98:101], v[194:197], v[210:213], v[98:101]
	v_mfma_f32_16x16x32_bf16 v[90:93], v[186:189], v[218:221], v[90:93]
	v_mfma_f32_16x16x32_bf16 v[82:85], v[194:197], v[218:221], v[82:85]
	v_mfma_f32_16x16x32_bf16 v[74:77], v[186:189], v[226:229], v[74:77]
	v_mfma_f32_16x16x32_bf16 v[66:69], v[194:197], v[226:229], v[66:69]
	s_setprio 0
	s_barrier
	s_add_u32 s96, s96, 0x80
	s_addc_u32 s97, s97, 0
	s_add_u32 s98, s96, 0xb0000
	s_addc_u32 s99, s97, 0
	s_add_u32 s94, s94, 0x80
	s_addc_u32 s95, s95, 0
	s_add_i32 s8, s8, s54
	s_mov_b32 m0, s8
	s_nop 0
	global_load_lds_dwordx4 v132, s[96:97]
	s_add_i32 m0, s8, 0x2000
	s_add_i32 s8, s50, s54
	global_load_lds_dwordx4 v136, s[96:97]
	s_mov_b32 m0, s8
	s_nop 0
	global_load_lds_dwordx4 v132, s[98:99]
	s_add_i32 m0, s8, 0x2000
	s_nop 0
	global_load_lds_dwordx4 v136, s[98:99]
	s_mov_b32 m0, s64
	s_nop 0
	global_load_lds_dwordx4 v130, s[94:95]
	s_mov_b32 m0, s65
	s_nop 0
	global_load_lds_dwordx4 v134, s[94:95]
	ds_read_b128 v[198:201], v163 offset:49152
	ds_read_b128 v[202:205], v163 offset:50176
	ds_read_b128 v[206:209], v163 offset:51200
	ds_read_b128 v[210:213], v163 offset:52224
	ds_read_b128 v[214:217], v163 offset:53248
	ds_read_b128 v[218:221], v163 offset:54272
	ds_read_b128 v[222:225], v163 offset:55296
	ds_read_b128 v[226:229], v163 offset:56320
	s_waitcnt vmcnt(8)
	s_waitcnt lgkmcnt(0)
	s_barrier
	s_setprio 1
	s_waitcnt lgkmcnt(0)
	v_mfma_f32_16x16x32_bf16 v[62:65], v[166:169], v[198:201], v[62:65]
	v_mfma_f32_16x16x32_bf16 v[54:57], v[174:177], v[198:201], v[54:57]
	v_mfma_f32_16x16x32_bf16 v[46:49], v[166:169], v[206:209], v[46:49]
	v_mfma_f32_16x16x32_bf16 v[38:41], v[174:177], v[206:209], v[38:41]
	v_mfma_f32_16x16x32_bf16 v[30:33], v[166:169], v[214:217], v[30:33]
	v_mfma_f32_16x16x32_bf16 v[22:25], v[174:177], v[214:217], v[22:25]
	v_mfma_f32_16x16x32_bf16 v[14:17], v[166:169], v[222:225], v[14:17]
	v_mfma_f32_16x16x32_bf16 v[6:9], v[174:177], v[222:225], v[6:9]
	v_mfma_f32_16x16x32_bf16 v[62:65], v[170:173], v[202:205], v[62:65]
	v_mfma_f32_16x16x32_bf16 v[54:57], v[178:181], v[202:205], v[54:57]
	v_mfma_f32_16x16x32_bf16 v[46:49], v[170:173], v[210:213], v[46:49]
	v_mfma_f32_16x16x32_bf16 v[38:41], v[178:181], v[210:213], v[38:41]
	v_mfma_f32_16x16x32_bf16 v[30:33], v[170:173], v[218:221], v[30:33]
	v_mfma_f32_16x16x32_bf16 v[22:25], v[178:181], v[218:221], v[22:25]
	v_mfma_f32_16x16x32_bf16 v[14:17], v[170:173], v[226:229], v[14:17]
	v_mfma_f32_16x16x32_bf16 v[6:9], v[178:181], v[226:229], v[6:9]
	s_setprio 0
	s_setprio 1
	v_mfma_f32_16x16x32_bf16 v[58:61], v[182:185], v[198:201], v[58:61]
	v_mfma_f32_16x16x32_bf16 v[50:53], v[190:193], v[198:201], v[50:53]
	v_mfma_f32_16x16x32_bf16 v[42:45], v[182:185], v[206:209], v[42:45]
	v_mfma_f32_16x16x32_bf16 v[34:37], v[190:193], v[206:209], v[34:37]
	v_mfma_f32_16x16x32_bf16 v[26:29], v[182:185], v[214:217], v[26:29]
	v_mfma_f32_16x16x32_bf16 v[18:21], v[190:193], v[214:217], v[18:21]
	v_mfma_f32_16x16x32_bf16 v[10:13], v[182:185], v[222:225], v[10:13]
	v_mfma_f32_16x16x32_bf16 v[2:5], v[190:193], v[222:225], v[2:5]
	v_mfma_f32_16x16x32_bf16 v[58:61], v[186:189], v[202:205], v[58:61]
	v_mfma_f32_16x16x32_bf16 v[50:53], v[194:197], v[202:205], v[50:53]
	v_mfma_f32_16x16x32_bf16 v[42:45], v[186:189], v[210:213], v[42:45]
	v_mfma_f32_16x16x32_bf16 v[34:37], v[194:197], v[210:213], v[34:37]
	v_mfma_f32_16x16x32_bf16 v[26:29], v[186:189], v[218:221], v[26:29]
	v_mfma_f32_16x16x32_bf16 v[18:21], v[194:197], v[218:221], v[18:21]
	v_mfma_f32_16x16x32_bf16 v[10:13], v[186:189], v[226:229], v[10:13]
	v_mfma_f32_16x16x32_bf16 v[2:5], v[194:197], v[226:229], v[2:5]
	s_setprio 0
	s_barrier
	s_mov_b32 s8, s9
	s_add_u32 s88, s88, 0x100
	s_addc_u32 s89, s89, 0
	s_add_u32 s86, s86, 0x100
	s_addc_u32 s87, s87, 0
	s_cmp_ge_i32 s9, s101
	s_cbranch_scc1 .Lmy_kexit_1
.LBB0_310:
	s_add_u32 s98, s86, 0x100
	s_addc_u32 s99, s87, 0
	s_cmp_eq_u32 s8, s100
	s_cselect_b64 s[94:95], s[90:91], s[98:99]
	s_cselect_b64 s[96:97], s[92:93], s[88:89]
	s_add_i32 s9, s8, 2
	s_nop 0
	s_add_i32 m0, s55, 0xc000
	s_nop 0
	global_load_lds_dwordx4 v144, s[86:87]
	s_add_i32 m0, s55, 0xe000
	s_nop 0
	global_load_lds_dwordx4 v142, s[86:87]
	ds_read_b128 v[166:169], v230
	ds_read_b128 v[170:173], v230 offset:1024
	ds_read_b128 v[174:177], v230 offset:2048
	ds_read_b128 v[178:181], v230 offset:3072
	ds_read_b128 v[182:185], v231
	ds_read_b128 v[186:189], v231 offset:1024
	ds_read_b128 v[190:193], v231 offset:2048
	ds_read_b128 v[194:197], v231 offset:3072
	ds_read_b128 v[198:201], v163
	ds_read_b128 v[202:205], v163 offset:1024
	ds_read_b128 v[206:209], v163 offset:2048
	ds_read_b128 v[210:213], v163 offset:3072
	ds_read_b128 v[214:217], v163 offset:4096
	ds_read_b128 v[218:221], v163 offset:5120
	ds_read_b128 v[222:225], v163 offset:6144
	ds_read_b128 v[226:229], v163 offset:7168
	s_waitcnt vmcnt(8)
	s_waitcnt lgkmcnt(0)
	s_barrier
	s_setprio 1
	s_waitcnt lgkmcnt(0)
	v_mfma_f32_16x16x32_bf16 v[122:125], v[166:169], v[198:201], v[122:125]
	v_mfma_f32_16x16x32_bf16 v[118:121], v[174:177], v[198:201], v[118:121]
	v_mfma_f32_16x16x32_bf16 v[110:113], v[166:169], v[206:209], v[110:113]
	v_mfma_f32_16x16x32_bf16 v[102:105], v[174:177], v[206:209], v[102:105]
	v_mfma_f32_16x16x32_bf16 v[94:97], v[166:169], v[214:217], v[94:97]
	v_mfma_f32_16x16x32_bf16 v[86:89], v[174:177], v[214:217], v[86:89]
	v_mfma_f32_16x16x32_bf16 v[78:81], v[166:169], v[222:225], v[78:81]
	v_mfma_f32_16x16x32_bf16 v[70:73], v[174:177], v[222:225], v[70:73]
	v_mfma_f32_16x16x32_bf16 v[122:125], v[170:173], v[202:205], v[122:125]
	v_mfma_f32_16x16x32_bf16 v[118:121], v[178:181], v[202:205], v[118:121]
	v_mfma_f32_16x16x32_bf16 v[110:113], v[170:173], v[210:213], v[110:113]
	v_mfma_f32_16x16x32_bf16 v[102:105], v[178:181], v[210:213], v[102:105]
	v_mfma_f32_16x16x32_bf16 v[94:97], v[170:173], v[218:221], v[94:97]
	v_mfma_f32_16x16x32_bf16 v[86:89], v[178:181], v[218:221], v[86:89]
	v_mfma_f32_16x16x32_bf16 v[78:81], v[170:173], v[226:229], v[78:81]
	v_mfma_f32_16x16x32_bf16 v[70:73], v[178:181], v[226:229], v[70:73]
	s_setprio 0
	s_setprio 1
	v_mfma_f32_16x16x32_bf16 v[126:129], v[182:185], v[198:201], v[126:129]
	v_mfma_f32_16x16x32_bf16 v[114:117], v[190:193], v[198:201], v[114:117]
	v_mfma_f32_16x16x32_bf16 v[106:109], v[182:185], v[206:209], v[106:109]
	v_mfma_f32_16x16x32_bf16 v[98:101], v[190:193], v[206:209], v[98:101]
	v_mfma_f32_16x16x32_bf16 v[90:93], v[182:185], v[214:217], v[90:93]
	v_mfma_f32_16x16x32_bf16 v[82:85], v[190:193], v[214:217], v[82:85]
	v_mfma_f32_16x16x32_bf16 v[74:77], v[182:185], v[222:225], v[74:77]
	v_mfma_f32_16x16x32_bf16 v[66:69], v[190:193], v[222:225], v[66:69]
	v_mfma_f32_16x16x32_bf16 v[126:129], v[186:189], v[202:205], v[126:129]
	v_mfma_f32_16x16x32_bf16 v[114:117], v[194:197], v[202:205], v[114:117]
	v_mfma_f32_16x16x32_bf16 v[106:109], v[186:189], v[210:213], v[106:109]
	v_mfma_f32_16x16x32_bf16 v[98:101], v[194:197], v[210:213], v[98:101]
	v_mfma_f32_16x16x32_bf16 v[90:93], v[186:189], v[218:221], v[90:93]
	v_mfma_f32_16x16x32_bf16 v[82:85], v[194:197], v[218:221], v[82:85]
	v_mfma_f32_16x16x32_bf16 v[74:77], v[186:189], v[226:229], v[74:77]
	v_mfma_f32_16x16x32_bf16 v[66:69], v[194:197], v[226:229], v[66:69]
	s_setprio 0
	s_barrier
	s_add_u32 s98, s96, 0xb0000
	s_addc_u32 s99, s97, 0
	s_add_i32 s8, s69, s54
	s_mov_b32 m0, s8
	s_nop 0
	global_load_lds_dwordx4 v132, s[96:97]
	s_add_i32 m0, s8, 0x2000
	s_add_i32 s8, s72, s54
	global_load_lds_dwordx4 v136, s[96:97]
	s_mov_b32 m0, s8
	s_nop 0
	global_load_lds_dwordx4 v132, s[98:99]
	s_add_i32 m0, s8, 0x2000
	s_nop 0
	global_load_lds_dwordx4 v136, s[98:99]
	s_mov_b32 m0, s55
	s_nop 0
	global_load_lds_dwordx4 v130, s[94:95]
	s_mov_b32 m0, s56
	s_nop 0
	global_load_lds_dwordx4 v134, s[94:95]
	ds_read_b128 v[198:201], v163 offset:16384
	ds_read_b128 v[202:205], v163 offset:17408
	ds_read_b128 v[206:209], v163 offset:18432
	ds_read_b128 v[210:213], v163 offset:19456
	ds_read_b128 v[214:217], v163 offset:20480
	ds_read_b128 v[218:221], v163 offset:21504
	ds_read_b128 v[222:225], v163 offset:22528
	ds_read_b128 v[226:229], v163 offset:23552
	s_waitcnt vmcnt(8)
	s_waitcnt lgkmcnt(0)
	s_barrier
	s_setprio 1
	s_waitcnt lgkmcnt(0)
	v_mfma_f32_16x16x32_bf16 v[62:65], v[166:169], v[198:201], v[62:65]
	v_mfma_f32_16x16x32_bf16 v[54:57], v[174:177], v[198:201], v[54:57]
	v_mfma_f32_16x16x32_bf16 v[46:49], v[166:169], v[206:209], v[46:49]
	v_mfma_f32_16x16x32_bf16 v[38:41], v[174:177], v[206:209], v[38:41]
	v_mfma_f32_16x16x32_bf16 v[30:33], v[166:169], v[214:217], v[30:33]
	v_mfma_f32_16x16x32_bf16 v[22:25], v[174:177], v[214:217], v[22:25]
	v_mfma_f32_16x16x32_bf16 v[14:17], v[166:169], v[222:225], v[14:17]
	v_mfma_f32_16x16x32_bf16 v[6:9], v[174:177], v[222:225], v[6:9]
	v_mfma_f32_16x16x32_bf16 v[62:65], v[170:173], v[202:205], v[62:65]
	v_mfma_f32_16x16x32_bf16 v[54:57], v[178:181], v[202:205], v[54:57]
	v_mfma_f32_16x16x32_bf16 v[46:49], v[170:173], v[210:213], v[46:49]
	v_mfma_f32_16x16x32_bf16 v[38:41], v[178:181], v[210:213], v[38:41]
	v_mfma_f32_16x16x32_bf16 v[30:33], v[170:173], v[218:221], v[30:33]
	v_mfma_f32_16x16x32_bf16 v[22:25], v[178:181], v[218:221], v[22:25]
	v_mfma_f32_16x16x32_bf16 v[14:17], v[170:173], v[226:229], v[14:17]
	v_mfma_f32_16x16x32_bf16 v[6:9], v[178:181], v[226:229], v[6:9]
	s_setprio 0
	s_setprio 1
	v_mfma_f32_16x16x32_bf16 v[58:61], v[182:185], v[198:201], v[58:61]
	v_mfma_f32_16x16x32_bf16 v[50:53], v[190:193], v[198:201], v[50:53]
	v_mfma_f32_16x16x32_bf16 v[42:45], v[182:185], v[206:209], v[42:45]
	v_mfma_f32_16x16x32_bf16 v[34:37], v[190:193], v[206:209], v[34:37]
	v_mfma_f32_16x16x32_bf16 v[26:29], v[182:185], v[214:217], v[26:29]
	v_mfma_f32_16x16x32_bf16 v[18:21], v[190:193], v[214:217], v[18:21]
	v_mfma_f32_16x16x32_bf16 v[10:13], v[182:185], v[222:225], v[10:13]
	v_mfma_f32_16x16x32_bf16 v[2:5], v[190:193], v[222:225], v[2:5]
	v_mfma_f32_16x16x32_bf16 v[58:61], v[186:189], v[202:205], v[58:61]
	v_mfma_f32_16x16x32_bf16 v[50:53], v[194:197], v[202:205], v[50:53]
	v_mfma_f32_16x16x32_bf16 v[42:45], v[186:189], v[210:213], v[42:45]
	v_mfma_f32_16x16x32_bf16 v[34:37], v[194:197], v[210:213], v[34:37]
	v_mfma_f32_16x16x32_bf16 v[26:29], v[186:189], v[218:221], v[26:29]
	v_mfma_f32_16x16x32_bf16 v[18:21], v[194:197], v[218:221], v[18:21]
	v_mfma_f32_16x16x32_bf16 v[10:13], v[186:189], v[226:229], v[10:13]
	v_mfma_f32_16x16x32_bf16 v[2:5], v[194:197], v[226:229], v[2:5]
	s_setprio 0
	s_barrier
	s_add_u32 s98, s94, 0xb0000
	s_addc_u32 s99, s95, 0
	s_add_i32 s8, 0, 0x18000
	s_add_i32 s50, 0, 0x1c000
	s_mov_b32 m0, s57
	s_nop 0
	global_load_lds_dwordx4 v130, s[98:99]
	s_mov_b32 m0, s58
	s_nop 0
	global_load_lds_dwordx4 v134, s[98:99]
	ds_read_b128 v[166:169], v232
	ds_read_b128 v[170:173], v232 offset:1024
	ds_read_b128 v[174:177], v232 offset:2048
	ds_read_b128 v[178:181], v232 offset:3072
	ds_read_b128 v[182:185], v233
	ds_read_b128 v[186:189], v233 offset:1024
	ds_read_b128 v[190:193], v233 offset:2048
	ds_read_b128 v[194:197], v233 offset:3072
	ds_read_b128 v[198:201], v163 offset:32768
	ds_read_b128 v[202:205], v163 offset:33792
	ds_read_b128 v[206:209], v163 offset:34816
	ds_read_b128 v[210:213], v163 offset:35840
	ds_read_b128 v[214:217], v163 offset:36864
	ds_read_b128 v[218:221], v163 offset:37888
	ds_read_b128 v[222:225], v163 offset:38912
	ds_read_b128 v[226:229], v163 offset:39936
	s_waitcnt vmcnt(8)
	s_waitcnt lgkmcnt(0)
	s_barrier
	s_setprio 1
	s_waitcnt lgkmcnt(0)
	v_mfma_f32_16x16x32_bf16 v[122:125], v[166:169], v[198:201], v[122:125]
	v_mfma_f32_16x16x32_bf16 v[118:121], v[174:177], v[198:201], v[118:121]
	v_mfma_f32_16x16x32_bf16 v[110:113], v[166:169], v[206:209], v[110:113]
	v_mfma_f32_16x16x32_bf16 v[102:105], v[174:177], v[206:209], v[102:105]
	v_mfma_f32_16x16x32_bf16 v[94:97], v[166:169], v[214:217], v[94:97]
	v_mfma_f32_16x16x32_bf16 v[86:89], v[174:177], v[214:217], v[86:89]
	v_mfma_f32_16x16x32_bf16 v[78:81], v[166:169], v[222:225], v[78:81]
	v_mfma_f32_16x16x32_bf16 v[70:73], v[174:177], v[222:225], v[70:73]
	v_mfma_f32_16x16x32_bf16 v[122:125], v[170:173], v[202:205], v[122:125]
	v_mfma_f32_16x16x32_bf16 v[118:121], v[178:181], v[202:205], v[118:121]
	v_mfma_f32_16x16x32_bf16 v[110:113], v[170:173], v[210:213], v[110:113]
	v_mfma_f32_16x16x32_bf16 v[102:105], v[178:181], v[210:213], v[102:105]
	v_mfma_f32_16x16x32_bf16 v[94:97], v[170:173], v[218:221], v[94:97]
	v_mfma_f32_16x16x32_bf16 v[86:89], v[178:181], v[218:221], v[86:89]
	v_mfma_f32_16x16x32_bf16 v[78:81], v[170:173], v[226:229], v[78:81]
	v_mfma_f32_16x16x32_bf16 v[70:73], v[178:181], v[226:229], v[70:73]
	s_setprio 0
	s_setprio 1
	v_mfma_f32_16x16x32_bf16 v[126:129], v[182:185], v[198:201], v[126:129]
	v_mfma_f32_16x16x32_bf16 v[114:117], v[190:193], v[198:201], v[114:117]
	v_mfma_f32_16x16x32_bf16 v[106:109], v[182:185], v[206:209], v[106:109]
	v_mfma_f32_16x16x32_bf16 v[98:101], v[190:193], v[206:209], v[98:101]
	v_mfma_f32_16x16x32_bf16 v[90:93], v[182:185], v[214:217], v[90:93]
	v_mfma_f32_16x16x32_bf16 v[82:85], v[190:193], v[214:217], v[82:85]
	v_mfma_f32_16x16x32_bf16 v[74:77], v[182:185], v[222:225], v[74:77]
	v_mfma_f32_16x16x32_bf16 v[66:69], v[190:193], v[222:225], v[66:69]
	v_mfma_f32_16x16x32_bf16 v[126:129], v[186:189], v[202:205], v[126:129]
	v_mfma_f32_16x16x32_bf16 v[114:117], v[194:197], v[202:205], v[114:117]
	v_mfma_f32_16x16x32_bf16 v[106:109], v[186:189], v[210:213], v[106:109]
	v_mfma_f32_16x16x32_bf16 v[98:101], v[194:197], v[210:213], v[98:101]
	v_mfma_f32_16x16x32_bf16 v[90:93], v[186:189], v[218:221], v[90:93]
	v_mfma_f32_16x16x32_bf16 v[82:85], v[194:197], v[218:221], v[82:85]
	v_mfma_f32_16x16x32_bf16 v[74:77], v[186:189], v[226:229], v[74:77]
	v_mfma_f32_16x16x32_bf16 v[66:69], v[194:197], v[226:229], v[66:69]
	s_setprio 0
	s_barrier
	s_add_u32 s96, s96, 0x80
	s_addc_u32 s97, s97, 0
	s_add_u32 s98, s96, 0xb0000
	s_addc_u32 s99, s97, 0
	s_add_u32 s94, s94, 0x80
	s_addc_u32 s95, s95, 0
	s_add_i32 s8, s8, s54
	s_mov_b32 m0, s8
	s_nop 0
	global_load_lds_dwordx4 v132, s[96:97]
	s_add_i32 m0, s8, 0x2000
	s_add_i32 s8, s50, s54
	global_load_lds_dwordx4 v136, s[96:97]
	s_mov_b32 m0, s8
	s_nop 0
	global_load_lds_dwordx4 v132, s[98:99]
	s_add_i32 m0, s8, 0x2000
	s_nop 0
	global_load_lds_dwordx4 v136, s[98:99]
	s_mov_b32 m0, s64
	s_nop 0
	global_load_lds_dwordx4 v130, s[94:95]
	s_mov_b32 m0, s65
	s_nop 0
	global_load_lds_dwordx4 v134, s[94:95]
	ds_read_b128 v[198:201], v163 offset:49152
	ds_read_b128 v[202:205], v163 offset:50176
	ds_read_b128 v[206:209], v163 offset:51200
	ds_read_b128 v[210:213], v163 offset:52224
	ds_read_b128 v[214:217], v163 offset:53248
	ds_read_b128 v[218:221], v163 offset:54272
	ds_read_b128 v[222:225], v163 offset:55296
	ds_read_b128 v[226:229], v163 offset:56320
	s_waitcnt vmcnt(8)
	s_waitcnt lgkmcnt(0)
	s_barrier
	s_setprio 1
	s_waitcnt lgkmcnt(0)
	v_mfma_f32_16x16x32_bf16 v[62:65], v[166:169], v[198:201], v[62:65]
	v_mfma_f32_16x16x32_bf16 v[54:57], v[174:177], v[198:201], v[54:57]
	v_mfma_f32_16x16x32_bf16 v[46:49], v[166:169], v[206:209], v[46:49]
	v_mfma_f32_16x16x32_bf16 v[38:41], v[174:177], v[206:209], v[38:41]
	v_mfma_f32_16x16x32_bf16 v[30:33], v[166:169], v[214:217], v[30:33]
	v_mfma_f32_16x16x32_bf16 v[22:25], v[174:177], v[214:217], v[22:25]
	v_mfma_f32_16x16x32_bf16 v[14:17], v[166:169], v[222:225], v[14:17]
	v_mfma_f32_16x16x32_bf16 v[6:9], v[174:177], v[222:225], v[6:9]
	v_mfma_f32_16x16x32_bf16 v[62:65], v[170:173], v[202:205], v[62:65]
	v_mfma_f32_16x16x32_bf16 v[54:57], v[178:181], v[202:205], v[54:57]
	v_mfma_f32_16x16x32_bf16 v[46:49], v[170:173], v[210:213], v[46:49]
	v_mfma_f32_16x16x32_bf16 v[38:41], v[178:181], v[210:213], v[38:41]
	v_mfma_f32_16x16x32_bf16 v[30:33], v[170:173], v[218:221], v[30:33]
	v_mfma_f32_16x16x32_bf16 v[22:25], v[178:181], v[218:221], v[22:25]
	v_mfma_f32_16x16x32_bf16 v[14:17], v[170:173], v[226:229], v[14:17]
	v_mfma_f32_16x16x32_bf16 v[6:9], v[178:181], v[226:229], v[6:9]
	s_setprio 0
	s_setprio 1
	v_mfma_f32_16x16x32_bf16 v[58:61], v[182:185], v[198:201], v[58:61]
	v_mfma_f32_16x16x32_bf16 v[50:53], v[190:193], v[198:201], v[50:53]
	v_mfma_f32_16x16x32_bf16 v[42:45], v[182:185], v[206:209], v[42:45]
	v_mfma_f32_16x16x32_bf16 v[34:37], v[190:193], v[206:209], v[34:37]
	v_mfma_f32_16x16x32_bf16 v[26:29], v[182:185], v[214:217], v[26:29]
	v_mfma_f32_16x16x32_bf16 v[18:21], v[190:193], v[214:217], v[18:21]
	v_mfma_f32_16x16x32_bf16 v[10:13], v[182:185], v[222:225], v[10:13]
	v_mfma_f32_16x16x32_bf16 v[2:5], v[190:193], v[222:225], v[2:5]
	v_mfma_f32_16x16x32_bf16 v[58:61], v[186:189], v[202:205], v[58:61]
	v_mfma_f32_16x16x32_bf16 v[50:53], v[194:197], v[202:205], v[50:53]
	v_mfma_f32_16x16x32_bf16 v[42:45], v[186:189], v[210:213], v[42:45]
	v_mfma_f32_16x16x32_bf16 v[34:37], v[194:197], v[210:213], v[34:37]
	v_mfma_f32_16x16x32_bf16 v[26:29], v[186:189], v[218:221], v[26:29]
	v_mfma_f32_16x16x32_bf16 v[18:21], v[194:197], v[218:221], v[18:21]
	v_mfma_f32_16x16x32_bf16 v[10:13], v[186:189], v[226:229], v[10:13]
	v_mfma_f32_16x16x32_bf16 v[2:5], v[194:197], v[226:229], v[2:5]
	s_setprio 0
	s_barrier
	s_mov_b32 s8, s9
	s_add_u32 s88, s88, 0x100
	s_addc_u32 s89, s89, 0
	s_add_u32 s86, s86, 0x100
	s_addc_u32 s87, s87, 0
	s_cmp_ge_i32 s9, s101
	s_cbranch_scc0 .LBB0_310

.LBB0_497:
	v_cmp_gt_i32_e32 vcc, 1, v141
	s_cbranch_vccnz .LBB0_559
	v_lshl_add_u64 v[154:155], v[2:3], 0, s[16:17]
	v_add_u32_e32 v138, -2, v141
	v_lshl_add_u64 v[152:153], v[4:5], 0, s[20:21]
	s_mov_b32 s7, 0
	s_nop 0
	v_readfirstlane_b32 s86, v154
	v_readfirstlane_b32 s87, v155
	v_readfirstlane_b32 s88, v152
	v_readfirstlane_b32 s89, v153
	v_readfirstlane_b32 s90, v148
	v_readfirstlane_b32 s91, v149
	v_readfirstlane_b32 s92, v150
	v_readfirstlane_b32 s93, v151
	v_readfirstlane_b32 s100, v138
	v_readfirstlane_b32 s101, v141
	v_add_u32_e32 v230, s77, v160
	v_add_u32_e32 v231, s78, v160
	v_add_u32_e32 v232, 0x18000, v160
	v_add_u32_e32 v233, 0x1c000, v160
	s_add_u32 s98, s86, 0xfffc0080
	s_addc_u32 s99, s87, -1
	s_cmp_eq_u32 s7, s100
	s_cselect_b64 s[94:95], s[90:91], s[98:99]
	s_cselect_b64 s[96:97], s[92:93], s[88:89]
	s_add_i32 s45, s7, 2
	s_nop 0
	s_add_i32 m0, s49, 0xc000
	s_nop 0
	global_load_lds_dwordx4 v144, s[86:87]
	s_add_i32 m0, s49, 0xe000
	s_nop 0
	global_load_lds_dwordx4 v142, s[86:87]
	ds_read_b128 v[156:159], v230
	ds_read_b128 v[166:169], v230 offset:1024
	ds_read_b128 v[170:173], v230 offset:2048
	ds_read_b128 v[174:177], v230 offset:3072
	ds_read_b128 v[178:181], v231
	ds_read_b128 v[182:185], v231 offset:1024
	ds_read_b128 v[186:189], v231 offset:2048
	ds_read_b128 v[190:193], v231 offset:3072
	ds_read_b128 v[194:197], v163
	ds_read_b128 v[198:201], v163 offset:1024
	ds_read_b128 v[202:205], v163 offset:2048
	ds_read_b128 v[206:209], v163 offset:3072
	ds_read_b128 v[210:213], v163 offset:4096
	ds_read_b128 v[214:217], v163 offset:5120
	ds_read_b128 v[218:221], v163 offset:6144
	ds_read_b128 v[222:225], v163 offset:7168
	s_waitcnt vmcnt(8)
	s_waitcnt lgkmcnt(0)
	s_barrier
	s_setprio 1
	s_waitcnt lgkmcnt(0)
	v_mfma_f32_16x16x32_bf16 v[122:125], v[156:159], v[194:197], 0
	v_mfma_f32_16x16x32_bf16 v[118:121], v[170:173], v[194:197], 0
	v_mfma_f32_16x16x32_bf16 v[110:113], v[156:159], v[202:205], 0
	v_mfma_f32_16x16x32_bf16 v[102:105], v[170:173], v[202:205], 0
	v_mfma_f32_16x16x32_bf16 v[94:97], v[156:159], v[210:213], 0
	v_mfma_f32_16x16x32_bf16 v[86:89], v[170:173], v[210:213], 0
	v_mfma_f32_16x16x32_bf16 v[78:81], v[156:159], v[218:221], 0
	v_mfma_f32_16x16x32_bf16 v[70:73], v[170:173], v[218:221], 0
	v_mfma_f32_16x16x32_bf16 v[122:125], v[166:169], v[198:201], v[122:125]
	v_mfma_f32_16x16x32_bf16 v[118:121], v[174:177], v[198:201], v[118:121]
	v_mfma_f32_16x16x32_bf16 v[110:113], v[166:169], v[206:209], v[110:113]
	v_mfma_f32_16x16x32_bf16 v[102:105], v[174:177], v[206:209], v[102:105]
	v_mfma_f32_16x16x32_bf16 v[94:97], v[166:169], v[214:217], v[94:97]
	v_mfma_f32_16x16x32_bf16 v[86:89], v[174:177], v[214:217], v[86:89]
	v_mfma_f32_16x16x32_bf16 v[78:81], v[166:169], v[222:225], v[78:81]
	v_mfma_f32_16x16x32_bf16 v[70:73], v[174:177], v[222:225], v[70:73]
	s_setprio 0
	s_setprio 1
	v_mfma_f32_16x16x32_bf16 v[126:129], v[178:181], v[194:197], 0
	v_mfma_f32_16x16x32_bf16 v[114:117], v[186:189], v[194:197], 0
	v_mfma_f32_16x16x32_bf16 v[106:109], v[178:181], v[202:205], 0
	v_mfma_f32_16x16x32_bf16 v[98:101], v[186:189], v[202:205], 0
	v_mfma_f32_16x16x32_bf16 v[90:93], v[178:181], v[210:213], 0
	v_mfma_f32_16x16x32_bf16 v[82:85], v[186:189], v[210:213], 0
	v_mfma_f32_16x16x32_bf16 v[74:77], v[178:181], v[218:221], 0
	v_mfma_f32_16x16x32_bf16 v[66:69], v[186:189], v[218:221], 0
	v_mfma_f32_16x16x32_bf16 v[126:129], v[182:185], v[198:201], v[126:129]
	v_mfma_f32_16x16x32_bf16 v[114:117], v[190:193], v[198:201], v[114:117]
	v_mfma_f32_16x16x32_bf16 v[106:109], v[182:185], v[206:209], v[106:109]
	v_mfma_f32_16x16x32_bf16 v[98:101], v[190:193], v[206:209], v[98:101]
	v_mfma_f32_16x16x32_bf16 v[90:93], v[182:185], v[214:217], v[90:93]
	v_mfma_f32_16x16x32_bf16 v[82:85], v[190:193], v[214:217], v[82:85]
	v_mfma_f32_16x16x32_bf16 v[74:77], v[182:185], v[222:225], v[74:77]
	v_mfma_f32_16x16x32_bf16 v[66:69], v[190:193], v[222:225], v[66:69]
	s_setprio 0
	s_barrier
	s_add_u32 s98, s96, 0x40000
	s_addc_u32 s99, s97, 0
	s_add_i32 s7, s77, s25
	s_mov_b32 m0, s7
	s_nop 0
	global_load_lds_dwordx4 v132, s[96:97]
	s_add_i32 m0, s7, 0x2000
	s_add_i32 s7, s78, s25
	global_load_lds_dwordx4 v136, s[96:97]
	s_mov_b32 m0, s7
	s_nop 0
	global_load_lds_dwordx4 v132, s[98:99]
	s_add_i32 m0, s7, 0x2000
	s_nop 0
	global_load_lds_dwordx4 v136, s[98:99]
	s_mov_b32 m0, s49
	s_nop 0
	global_load_lds_dwordx4 v130, s[94:95]
	s_mov_b32 m0, s58
	s_nop 0
	global_load_lds_dwordx4 v134, s[94:95]
	ds_read_b128 v[194:197], v163 offset:16384
	ds_read_b128 v[198:201], v163 offset:17408
	ds_read_b128 v[202:205], v163 offset:18432
	ds_read_b128 v[206:209], v163 offset:19456
	ds_read_b128 v[210:213], v163 offset:20480
	ds_read_b128 v[214:217], v163 offset:21504
	ds_read_b128 v[218:221], v163 offset:22528
	ds_read_b128 v[222:225], v163 offset:23552
	s_waitcnt vmcnt(8)
	s_waitcnt lgkmcnt(0)
	s_barrier
	s_setprio 1
	s_waitcnt lgkmcnt(0)
	v_mfma_f32_16x16x32_bf16 v[62:65], v[156:159], v[194:197], 0
	v_mfma_f32_16x16x32_bf16 v[54:57], v[170:173], v[194:197], 0
	v_mfma_f32_16x16x32_bf16 v[46:49], v[156:159], v[202:205], 0
	v_mfma_f32_16x16x32_bf16 v[38:41], v[170:173], v[202:205], 0
	v_mfma_f32_16x16x32_bf16 v[30:33], v[156:159], v[210:213], 0
	v_mfma_f32_16x16x32_bf16 v[22:25], v[170:173], v[210:213], 0
	v_mfma_f32_16x16x32_bf16 v[14:17], v[156:159], v[218:221], 0
	v_mfma_f32_16x16x32_bf16 v[6:9], v[170:173], v[218:221], 0
	v_mfma_f32_16x16x32_bf16 v[62:65], v[166:169], v[198:201], v[62:65]
	v_mfma_f32_16x16x32_bf16 v[54:57], v[174:177], v[198:201], v[54:57]
	v_mfma_f32_16x16x32_bf16 v[46:49], v[166:169], v[206:209], v[46:49]
	v_mfma_f32_16x16x32_bf16 v[38:41], v[174:177], v[206:209], v[38:41]
	v_mfma_f32_16x16x32_bf16 v[30:33], v[166:169], v[214:217], v[30:33]
	v_mfma_f32_16x16x32_bf16 v[22:25], v[174:177], v[214:217], v[22:25]
	v_mfma_f32_16x16x32_bf16 v[14:17], v[166:169], v[222:225], v[14:17]
	v_mfma_f32_16x16x32_bf16 v[6:9], v[174:177], v[222:225], v[6:9]
	s_setprio 0
	s_setprio 1
	v_mfma_f32_16x16x32_bf16 v[58:61], v[178:181], v[194:197], 0
	v_mfma_f32_16x16x32_bf16 v[50:53], v[186:189], v[194:197], 0
	v_mfma_f32_16x16x32_bf16 v[42:45], v[178:181], v[202:205], 0
	v_mfma_f32_16x16x32_bf16 v[34:37], v[186:189], v[202:205], 0
	v_mfma_f32_16x16x32_bf16 v[26:29], v[178:181], v[210:213], 0
	v_mfma_f32_16x16x32_bf16 v[18:21], v[186:189], v[210:213], 0
	v_mfma_f32_16x16x32_bf16 v[10:13], v[178:181], v[218:221], 0
	v_mfma_f32_16x16x32_bf16 v[2:5], v[186:189], v[218:221], 0
	v_mfma_f32_16x16x32_bf16 v[58:61], v[182:185], v[198:201], v[58:61]
	v_mfma_f32_16x16x32_bf16 v[50:53], v[190:193], v[198:201], v[50:53]
	v_mfma_f32_16x16x32_bf16 v[42:45], v[182:185], v[206:209], v[42:45]
	v_mfma_f32_16x16x32_bf16 v[34:37], v[190:193], v[206:209], v[34:37]
	v_mfma_f32_16x16x32_bf16 v[26:29], v[182:185], v[214:217], v[26:29]
	v_mfma_f32_16x16x32_bf16 v[18:21], v[190:193], v[214:217], v[18:21]
	v_mfma_f32_16x16x32_bf16 v[10:13], v[182:185], v[222:225], v[10:13]
	v_mfma_f32_16x16x32_bf16 v[2:5], v[190:193], v[222:225], v[2:5]
	s_setprio 0
	s_barrier
	s_add_u32 s98, s94, 0x40000
	s_addc_u32 s99, s95, 0
	s_add_i32 s7, 0, 0x18000
	s_add_i32 s47, 0, 0x1c000
	s_mov_b32 m0, s59
	s_nop 0
	global_load_lds_dwordx4 v130, s[98:99]
	s_mov_b32 m0, s60
	s_nop 0
	global_load_lds_dwordx4 v134, s[98:99]
	ds_read_b128 v[156:159], v232
	ds_read_b128 v[166:169], v232 offset:1024
	ds_read_b128 v[170:173], v232 offset:2048
	ds_read_b128 v[174:177], v232 offset:3072
	ds_read_b128 v[178:181], v233
	ds_read_b128 v[182:185], v233 offset:1024
	ds_read_b128 v[186:189], v233 offset:2048
	ds_read_b128 v[190:193], v233 offset:3072
	ds_read_b128 v[194:197], v163 offset:32768
	ds_read_b128 v[198:201], v163 offset:33792
	ds_read_b128 v[202:205], v163 offset:34816
	ds_read_b128 v[206:209], v163 offset:35840
	ds_read_b128 v[210:213], v163 offset:36864
	ds_read_b128 v[214:217], v163 offset:37888
	ds_read_b128 v[218:221], v163 offset:38912
	ds_read_b128 v[222:225], v163 offset:39936
	s_waitcnt vmcnt(8)
	s_waitcnt lgkmcnt(0)
	s_barrier
	s_setprio 1
	s_waitcnt lgkmcnt(0)
	v_mfma_f32_16x16x32_bf16 v[122:125], v[156:159], v[194:197], v[122:125]
	v_mfma_f32_16x16x32_bf16 v[118:121], v[170:173], v[194:197], v[118:121]
	v_mfma_f32_16x16x32_bf16 v[110:113], v[156:159], v[202:205], v[110:113]
	v_mfma_f32_16x16x32_bf16 v[102:105], v[170:173], v[202:205], v[102:105]
	v_mfma_f32_16x16x32_bf16 v[94:97], v[156:159], v[210:213], v[94:97]
	v_mfma_f32_16x16x32_bf16 v[86:89], v[170:173], v[210:213], v[86:89]
	v_mfma_f32_16x16x32_bf16 v[78:81], v[156:159], v[218:221], v[78:81]
	v_mfma_f32_16x16x32_bf16 v[70:73], v[170:173], v[218:221], v[70:73]
	v_mfma_f32_16x16x32_bf16 v[122:125], v[166:169], v[198:201], v[122:125]
	v_mfma_f32_16x16x32_bf16 v[118:121], v[174:177], v[198:201], v[118:121]
	v_mfma_f32_16x16x32_bf16 v[110:113], v[166:169], v[206:209], v[110:113]
	v_mfma_f32_16x16x32_bf16 v[102:105], v[174:177], v[206:209], v[102:105]
	v_mfma_f32_16x16x32_bf16 v[94:97], v[166:169], v[214:217], v[94:97]
	v_mfma_f32_16x16x32_bf16 v[86:89], v[174:177], v[214:217], v[86:89]
	v_mfma_f32_16x16x32_bf16 v[78:81], v[166:169], v[222:225], v[78:81]
	v_mfma_f32_16x16x32_bf16 v[70:73], v[174:177], v[222:225], v[70:73]
	s_setprio 0
	s_setprio 1
	v_mfma_f32_16x16x32_bf16 v[126:129], v[178:181], v[194:197], v[126:129]
	v_mfma_f32_16x16x32_bf16 v[114:117], v[186:189], v[194:197], v[114:117]
	v_mfma_f32_16x16x32_bf16 v[106:109], v[178:181], v[202:205], v[106:109]
	v_mfma_f32_16x16x32_bf16 v[98:101], v[186:189], v[202:205], v[98:101]
	v_mfma_f32_16x16x32_bf16 v[90:93], v[178:181], v[210:213], v[90:93]
	v_mfma_f32_16x16x32_bf16 v[82:85], v[186:189], v[210:213], v[82:85]
	v_mfma_f32_16x16x32_bf16 v[74:77], v[178:181], v[218:221], v[74:77]
	v_mfma_f32_16x16x32_bf16 v[66:69], v[186:189], v[218:221], v[66:69]
	v_mfma_f32_16x16x32_bf16 v[126:129], v[182:185], v[198:201], v[126:129]
	v_mfma_f32_16x16x32_bf16 v[114:117], v[190:193], v[198:201], v[114:117]
	v_mfma_f32_16x16x32_bf16 v[106:109], v[182:185], v[206:209], v[106:109]
	v_mfma_f32_16x16x32_bf16 v[98:101], v[190:193], v[206:209], v[98:101]
	v_mfma_f32_16x16x32_bf16 v[90:93], v[182:185], v[214:217], v[90:93]
	v_mfma_f32_16x16x32_bf16 v[82:85], v[190:193], v[214:217], v[82:85]
	v_mfma_f32_16x16x32_bf16 v[74:77], v[182:185], v[222:225], v[74:77]
	v_mfma_f32_16x16x32_bf16 v[66:69], v[190:193], v[222:225], v[66:69]
	s_setprio 0
	s_barrier
	s_add_u32 s96, s96, 0x80
	s_addc_u32 s97, s97, 0
	s_add_u32 s98, s96, 0x40000
	s_addc_u32 s99, s97, 0
	s_add_u32 s94, s94, 0x80
	s_addc_u32 s95, s95, 0
	s_add_i32 s7, s7, s25
	s_mov_b32 m0, s7
	s_nop 0
	global_load_lds_dwordx4 v132, s[96:97]
	s_add_i32 m0, s7, 0x2000
	s_add_i32 s7, s47, s25
	global_load_lds_dwordx4 v136, s[96:97]
	s_mov_b32 m0, s7
	s_nop 0
	global_load_lds_dwordx4 v132, s[98:99]
	s_add_i32 m0, s7, 0x2000
	s_nop 0
	global_load_lds_dwordx4 v136, s[98:99]
	s_mov_b32 m0, s66
	s_nop 0
	global_load_lds_dwordx4 v130, s[94:95]
	s_mov_b32 m0, s67
	s_nop 0
	global_load_lds_dwordx4 v134, s[94:95]
	ds_read_b128 v[194:197], v163 offset:49152
	ds_read_b128 v[198:201], v163 offset:50176
	ds_read_b128 v[202:205], v163 offset:51200
	ds_read_b128 v[206:209], v163 offset:52224
	ds_read_b128 v[210:213], v163 offset:53248
	ds_read_b128 v[214:217], v163 offset:54272
	ds_read_b128 v[218:221], v163 offset:55296
	ds_read_b128 v[222:225], v163 offset:56320
	s_waitcnt vmcnt(8)
	s_waitcnt lgkmcnt(0)
	s_barrier
	s_setprio 1
	s_waitcnt lgkmcnt(0)
	v_mfma_f32_16x16x32_bf16 v[62:65], v[156:159], v[194:197], v[62:65]
	v_mfma_f32_16x16x32_bf16 v[54:57], v[170:173], v[194:197], v[54:57]
	v_mfma_f32_16x16x32_bf16 v[46:49], v[156:159], v[202:205], v[46:49]
	v_mfma_f32_16x16x32_bf16 v[38:41], v[170:173], v[202:205], v[38:41]
	v_mfma_f32_16x16x32_bf16 v[30:33], v[156:159], v[210:213], v[30:33]
	v_mfma_f32_16x16x32_bf16 v[22:25], v[170:173], v[210:213], v[22:25]
	v_mfma_f32_16x16x32_bf16 v[14:17], v[156:159], v[218:221], v[14:17]
	v_mfma_f32_16x16x32_bf16 v[6:9], v[170:173], v[218:221], v[6:9]
	v_mfma_f32_16x16x32_bf16 v[62:65], v[166:169], v[198:201], v[62:65]
	v_mfma_f32_16x16x32_bf16 v[54:57], v[174:177], v[198:201], v[54:57]
	v_mfma_f32_16x16x32_bf16 v[46:49], v[166:169], v[206:209], v[46:49]
	v_mfma_f32_16x16x32_bf16 v[38:41], v[174:177], v[206:209], v[38:41]
	v_mfma_f32_16x16x32_bf16 v[30:33], v[166:169], v[214:217], v[30:33]
	v_mfma_f32_16x16x32_bf16 v[22:25], v[174:177], v[214:217], v[22:25]
	v_mfma_f32_16x16x32_bf16 v[14:17], v[166:169], v[222:225], v[14:17]
	v_mfma_f32_16x16x32_bf16 v[6:9], v[174:177], v[222:225], v[6:9]
	s_setprio 0
	s_setprio 1
	v_mfma_f32_16x16x32_bf16 v[58:61], v[178:181], v[194:197], v[58:61]
	v_mfma_f32_16x16x32_bf16 v[50:53], v[186:189], v[194:197], v[50:53]
	v_mfma_f32_16x16x32_bf16 v[42:45], v[178:181], v[202:205], v[42:45]
	v_mfma_f32_16x16x32_bf16 v[34:37], v[186:189], v[202:205], v[34:37]
	v_mfma_f32_16x16x32_bf16 v[26:29], v[178:181], v[210:213], v[26:29]
	v_mfma_f32_16x16x32_bf16 v[18:21], v[186:189], v[210:213], v[18:21]
	v_mfma_f32_16x16x32_bf16 v[10:13], v[178:181], v[218:221], v[10:13]
	v_mfma_f32_16x16x32_bf16 v[2:5], v[186:189], v[218:221], v[2:5]
	v_mfma_f32_16x16x32_bf16 v[58:61], v[182:185], v[198:201], v[58:61]
	v_mfma_f32_16x16x32_bf16 v[50:53], v[190:193], v[198:201], v[50:53]
	v_mfma_f32_16x16x32_bf16 v[42:45], v[182:185], v[206:209], v[42:45]
	v_mfma_f32_16x16x32_bf16 v[34:37], v[190:193], v[206:209], v[34:37]
	v_mfma_f32_16x16x32_bf16 v[26:29], v[182:185], v[214:217], v[26:29]
	v_mfma_f32_16x16x32_bf16 v[18:21], v[190:193], v[214:217], v[18:21]
	v_mfma_f32_16x16x32_bf16 v[10:13], v[182:185], v[222:225], v[10:13]
	v_mfma_f32_16x16x32_bf16 v[2:5], v[190:193], v[222:225], v[2:5]
	s_setprio 0
	s_barrier
	s_mov_b32 s7, s45
	s_add_u32 s88, s88, 0x100
	s_addc_u32 s89, s89, 0
	s_add_u32 s86, s86, 0x100
	s_addc_u32 s87, s87, 0
	s_cmp_ge_i32 s45, s101
	s_cbranch_scc1 .Lmy_kexit_2
.LBB0_499:
	s_add_u32 s98, s86, 0xfffc0080
	s_addc_u32 s99, s87, -1
	s_cmp_eq_u32 s7, s100
	s_cselect_b64 s[94:95], s[90:91], s[98:99]
	s_cselect_b64 s[96:97], s[92:93], s[88:89]
	s_add_i32 s45, s7, 2
	s_nop 0
	s_add_i32 m0, s49, 0xc000
	s_nop 0
	global_load_lds_dwordx4 v144, s[86:87]
	s_add_i32 m0, s49, 0xe000
	s_nop 0
	global_load_lds_dwordx4 v142, s[86:87]
	ds_read_b128 v[156:159], v230
	ds_read_b128 v[166:169], v230 offset:1024
	ds_read_b128 v[170:173], v230 offset:2048
	ds_read_b128 v[174:177], v230 offset:3072
	ds_read_b128 v[178:181], v231
	ds_read_b128 v[182:185], v231 offset:1024
	ds_read_b128 v[186:189], v231 offset:2048
	ds_read_b128 v[190:193], v231 offset:3072
	ds_read_b128 v[194:197], v163
	ds_read_b128 v[198:201], v163 offset:1024
	ds_read_b128 v[202:205], v163 offset:2048
	ds_read_b128 v[206:209], v163 offset:3072
	ds_read_b128 v[210:213], v163 offset:4096
	ds_read_b128 v[214:217], v163 offset:5120
	ds_read_b128 v[218:221], v163 offset:6144
	ds_read_b128 v[222:225], v163 offset:7168
	s_waitcnt vmcnt(8)
	s_waitcnt lgkmcnt(0)
	s_barrier
	s_setprio 1
	s_waitcnt lgkmcnt(0)
	v_mfma_f32_16x16x32_bf16 v[122:125], v[156:159], v[194:197], v[122:125]
	v_mfma_f32_16x16x32_bf16 v[118:121], v[170:173], v[194:197], v[118:121]
	v_mfma_f32_16x16x32_bf16 v[110:113], v[156:159], v[202:205], v[110:113]
	v_mfma_f32_16x16x32_bf16 v[102:105], v[170:173], v[202:205], v[102:105]
	v_mfma_f32_16x16x32_bf16 v[94:97], v[156:159], v[210:213], v[94:97]
	v_mfma_f32_16x16x32_bf16 v[86:89], v[170:173], v[210:213], v[86:89]
	v_mfma_f32_16x16x32_bf16 v[78:81], v[156:159], v[218:221], v[78:81]
	v_mfma_f32_16x16x32_bf16 v[70:73], v[170:173], v[218:221], v[70:73]
	v_mfma_f32_16x16x32_bf16 v[122:125], v[166:169], v[198:201], v[122:125]
	v_mfma_f32_16x16x32_bf16 v[118:121], v[174:177], v[198:201], v[118:121]
	v_mfma_f32_16x16x32_bf16 v[110:113], v[166:169], v[206:209], v[110:113]
	v_mfma_f32_16x16x32_bf16 v[102:105], v[174:177], v[206:209], v[102:105]
	v_mfma_f32_16x16x32_bf16 v[94:97], v[166:169], v[214:217], v[94:97]
	v_mfma_f32_16x16x32_bf16 v[86:89], v[174:177], v[214:217], v[86:89]
	v_mfma_f32_16x16x32_bf16 v[78:81], v[166:169], v[222:225], v[78:81]
	v_mfma_f32_16x16x32_bf16 v[70:73], v[174:177], v[222:225], v[70:73]
	s_setprio 0
	s_setprio 1
	v_mfma_f32_16x16x32_bf16 v[126:129], v[178:181], v[194:197], v[126:129]
	v_mfma_f32_16x16x32_bf16 v[114:117], v[186:189], v[194:197], v[114:117]
	v_mfma_f32_16x16x32_bf16 v[106:109], v[178:181], v[202:205], v[106:109]
	v_mfma_f32_16x16x32_bf16 v[98:101], v[186:189], v[202:205], v[98:101]
	v_mfma_f32_16x16x32_bf16 v[90:93], v[178:181], v[210:213], v[90:93]
	v_mfma_f32_16x16x32_bf16 v[82:85], v[186:189], v[210:213], v[82:85]
	v_mfma_f32_16x16x32_bf16 v[74:77], v[178:181], v[218:221], v[74:77]
	v_mfma_f32_16x16x32_bf16 v[66:69], v[186:189], v[218:221], v[66:69]
	v_mfma_f32_16x16x32_bf16 v[126:129], v[182:185], v[198:201], v[126:129]
	v_mfma_f32_16x16x32_bf16 v[114:117], v[190:193], v[198:201], v[114:117]
	v_mfma_f32_16x16x32_bf16 v[106:109], v[182:185], v[206:209], v[106:109]
	v_mfma_f32_16x16x32_bf16 v[98:101], v[190:193], v[206:209], v[98:101]
	v_mfma_f32_16x16x32_bf16 v[90:93], v[182:185], v[214:217], v[90:93]
	v_mfma_f32_16x16x32_bf16 v[82:85], v[190:193], v[214:217], v[82:85]
	v_mfma_f32_16x16x32_bf16 v[74:77], v[182:185], v[222:225], v[74:77]
	v_mfma_f32_16x16x32_bf16 v[66:69], v[190:193], v[222:225], v[66:69]
	s_setprio 0
	s_barrier
	s_add_u32 s98, s96, 0x40000
	s_addc_u32 s99, s97, 0
	s_add_i32 s7, s77, s25
	s_mov_b32 m0, s7
	s_nop 0
	global_load_lds_dwordx4 v132, s[96:97]
	s_add_i32 m0, s7, 0x2000
	s_add_i32 s7, s78, s25
	global_load_lds_dwordx4 v136, s[96:97]
	s_mov_b32 m0, s7
	s_nop 0
	global_load_lds_dwordx4 v132, s[98:99]
	s_add_i32 m0, s7, 0x2000
	s_nop 0
	global_load_lds_dwordx4 v136, s[98:99]
	s_mov_b32 m0, s49
	s_nop 0
	global_load_lds_dwordx4 v130, s[94:95]
	s_mov_b32 m0, s58
	s_nop 0
	global_load_lds_dwordx4 v134, s[94:95]
	ds_read_b128 v[194:197], v163 offset:16384
	ds_read_b128 v[198:201], v163 offset:17408
	ds_read_b128 v[202:205], v163 offset:18432
	ds_read_b128 v[206:209], v163 offset:19456
	ds_read_b128 v[210:213], v163 offset:20480
	ds_read_b128 v[214:217], v163 offset:21504
	ds_read_b128 v[218:221], v163 offset:22528
	ds_read_b128 v[222:225], v163 offset:23552
	s_waitcnt vmcnt(8)
	s_waitcnt lgkmcnt(0)
	s_barrier
	s_setprio 1
	s_waitcnt lgkmcnt(0)
	v_mfma_f32_16x16x32_bf16 v[62:65], v[156:159], v[194:197], v[62:65]
	v_mfma_f32_16x16x32_bf16 v[54:57], v[170:173], v[194:197], v[54:57]
	v_mfma_f32_16x16x32_bf16 v[46:49], v[156:159], v[202:205], v[46:49]
	v_mfma_f32_16x16x32_bf16 v[38:41], v[170:173], v[202:205], v[38:41]
	v_mfma_f32_16x16x32_bf16 v[30:33], v[156:159], v[210:213], v[30:33]
	v_mfma_f32_16x16x32_bf16 v[22:25], v[170:173], v[210:213], v[22:25]
	v_mfma_f32_16x16x32_bf16 v[14:17], v[156:159], v[218:221], v[14:17]
	v_mfma_f32_16x16x32_bf16 v[6:9], v[170:173], v[218:221], v[6:9]
	v_mfma_f32_16x16x32_bf16 v[62:65], v[166:169], v[198:201], v[62:65]
	v_mfma_f32_16x16x32_bf16 v[54:57], v[174:177], v[198:201], v[54:57]
	v_mfma_f32_16x16x32_bf16 v[46:49], v[166:169], v[206:209], v[46:49]
	v_mfma_f32_16x16x32_bf16 v[38:41], v[174:177], v[206:209], v[38:41]
	v_mfma_f32_16x16x32_bf16 v[30:33], v[166:169], v[214:217], v[30:33]
	v_mfma_f32_16x16x32_bf16 v[22:25], v[174:177], v[214:217], v[22:25]
	v_mfma_f32_16x16x32_bf16 v[14:17], v[166:169], v[222:225], v[14:17]
	v_mfma_f32_16x16x32_bf16 v[6:9], v[174:177], v[222:225], v[6:9]
	s_setprio 0
	s_setprio 1
	v_mfma_f32_16x16x32_bf16 v[58:61], v[178:181], v[194:197], v[58:61]
	v_mfma_f32_16x16x32_bf16 v[50:53], v[186:189], v[194:197], v[50:53]
	v_mfma_f32_16x16x32_bf16 v[42:45], v[178:181], v[202:205], v[42:45]
	v_mfma_f32_16x16x32_bf16 v[34:37], v[186:189], v[202:205], v[34:37]
	v_mfma_f32_16x16x32_bf16 v[26:29], v[178:181], v[210:213], v[26:29]
	v_mfma_f32_16x16x32_bf16 v[18:21], v[186:189], v[210:213], v[18:21]
	v_mfma_f32_16x16x32_bf16 v[10:13], v[178:181], v[218:221], v[10:13]
	v_mfma_f32_16x16x32_bf16 v[2:5], v[186:189], v[218:221], v[2:5]
	v_mfma_f32_16x16x32_bf16 v[58:61], v[182:185], v[198:201], v[58:61]
	v_mfma_f32_16x16x32_bf16 v[50:53], v[190:193], v[198:201], v[50:53]
	v_mfma_f32_16x16x32_bf16 v[42:45], v[182:185], v[206:209], v[42:45]
	v_mfma_f32_16x16x32_bf16 v[34:37], v[190:193], v[206:209], v[34:37]
	v_mfma_f32_16x16x32_bf16 v[26:29], v[182:185], v[214:217], v[26:29]
	v_mfma_f32_16x16x32_bf16 v[18:21], v[190:193], v[214:217], v[18:21]
	v_mfma_f32_16x16x32_bf16 v[10:13], v[182:185], v[222:225], v[10:13]
	v_mfma_f32_16x16x32_bf16 v[2:5], v[190:193], v[222:225], v[2:5]
	s_setprio 0
	s_barrier
	s_add_u32 s98, s94, 0x40000
	s_addc_u32 s99, s95, 0
	s_add_i32 s7, 0, 0x18000
	s_add_i32 s47, 0, 0x1c000
	s_mov_b32 m0, s59
	s_nop 0
	global_load_lds_dwordx4 v130, s[98:99]
	s_mov_b32 m0, s60
	s_nop 0
	global_load_lds_dwordx4 v134, s[98:99]
	ds_read_b128 v[156:159], v232
	ds_read_b128 v[166:169], v232 offset:1024
	ds_read_b128 v[170:173], v232 offset:2048
	ds_read_b128 v[174:177], v232 offset:3072
	ds_read_b128 v[178:181], v233
	ds_read_b128 v[182:185], v233 offset:1024
	ds_read_b128 v[186:189], v233 offset:2048
	ds_read_b128 v[190:193], v233 offset:3072
	ds_read_b128 v[194:197], v163 offset:32768
	ds_read_b128 v[198:201], v163 offset:33792
	ds_read_b128 v[202:205], v163 offset:34816
	ds_read_b128 v[206:209], v163 offset:35840
	ds_read_b128 v[210:213], v163 offset:36864
	ds_read_b128 v[214:217], v163 offset:37888
	ds_read_b128 v[218:221], v163 offset:38912
	ds_read_b128 v[222:225], v163 offset:39936
	s_waitcnt vmcnt(8)
	s_waitcnt lgkmcnt(0)
	s_barrier
	s_setprio 1
	s_waitcnt lgkmcnt(0)
	v_mfma_f32_16x16x32_bf16 v[122:125], v[156:159], v[194:197], v[122:125]
	v_mfma_f32_16x16x32_bf16 v[118:121], v[170:173], v[194:197], v[118:121]
	v_mfma_f32_16x16x32_bf16 v[110:113], v[156:159], v[202:205], v[110:113]
	v_mfma_f32_16x16x32_bf16 v[102:105], v[170:173], v[202:205], v[102:105]
	v_mfma_f32_16x16x32_bf16 v[94:97], v[156:159], v[210:213], v[94:97]
	v_mfma_f32_16x16x32_bf16 v[86:89], v[170:173], v[210:213], v[86:89]
	v_mfma_f32_16x16x32_bf16 v[78:81], v[156:159], v[218:221], v[78:81]
	v_mfma_f32_16x16x32_bf16 v[70:73], v[170:173], v[218:221], v[70:73]
	v_mfma_f32_16x16x32_bf16 v[122:125], v[166:169], v[198:201], v[122:125]
	v_mfma_f32_16x16x32_bf16 v[118:121], v[174:177], v[198:201], v[118:121]
	v_mfma_f32_16x16x32_bf16 v[110:113], v[166:169], v[206:209], v[110:113]
	v_mfma_f32_16x16x32_bf16 v[102:105], v[174:177], v[206:209], v[102:105]
	v_mfma_f32_16x16x32_bf16 v[94:97], v[166:169], v[214:217], v[94:97]
	v_mfma_f32_16x16x32_bf16 v[86:89], v[174:177], v[214:217], v[86:89]
	v_mfma_f32_16x16x32_bf16 v[78:81], v[166:169], v[222:225], v[78:81]
	v_mfma_f32_16x16x32_bf16 v[70:73], v[174:177], v[222:225], v[70:73]
	s_setprio 0
	s_setprio 1
	v_mfma_f32_16x16x32_bf16 v[126:129], v[178:181], v[194:197], v[126:129]
	v_mfma_f32_16x16x32_bf16 v[114:117], v[186:189], v[194:197], v[114:117]
	v_mfma_f32_16x16x32_bf16 v[106:109], v[178:181], v[202:205], v[106:109]
	v_mfma_f32_16x16x32_bf16 v[98:101], v[186:189], v[202:205], v[98:101]
	v_mfma_f32_16x16x32_bf16 v[90:93], v[178:181], v[210:213], v[90:93]
	v_mfma_f32_16x16x32_bf16 v[82:85], v[186:189], v[210:213], v[82:85]
	v_mfma_f32_16x16x32_bf16 v[74:77], v[178:181], v[218:221], v[74:77]
	v_mfma_f32_16x16x32_bf16 v[66:69], v[186:189], v[218:221], v[66:69]
	v_mfma_f32_16x16x32_bf16 v[126:129], v[182:185], v[198:201], v[126:129]
	v_mfma_f32_16x16x32_bf16 v[114:117], v[190:193], v[198:201], v[114:117]
	v_mfma_f32_16x16x32_bf16 v[106:109], v[182:185], v[206:209], v[106:109]
	v_mfma_f32_16x16x32_bf16 v[98:101], v[190:193], v[206:209], v[98:101]
	v_mfma_f32_16x16x32_bf16 v[90:93], v[182:185], v[214:217], v[90:93]
	v_mfma_f32_16x16x32_bf16 v[82:85], v[190:193], v[214:217], v[82:85]
	v_mfma_f32_16x16x32_bf16 v[74:77], v[182:185], v[222:225], v[74:77]
	v_mfma_f32_16x16x32_bf16 v[66:69], v[190:193], v[222:225], v[66:69]
	s_setprio 0
	s_barrier
	s_add_u32 s96, s96, 0x80
	s_addc_u32 s97, s97, 0
	s_add_u32 s98, s96, 0x40000
	s_addc_u32 s99, s97, 0
	s_add_u32 s94, s94, 0x80
	s_addc_u32 s95, s95, 0
	s_add_i32 s7, s7, s25
	s_mov_b32 m0, s7
	s_nop 0
	global_load_lds_dwordx4 v132, s[96:97]
	s_add_i32 m0, s7, 0x2000
	s_add_i32 s7, s47, s25
	global_load_lds_dwordx4 v136, s[96:97]
	s_mov_b32 m0, s7
	s_nop 0
	global_load_lds_dwordx4 v132, s[98:99]
	s_add_i32 m0, s7, 0x2000
	s_nop 0
	global_load_lds_dwordx4 v136, s[98:99]
	s_mov_b32 m0, s66
	s_nop 0
	global_load_lds_dwordx4 v130, s[94:95]
	s_mov_b32 m0, s67
	s_nop 0
	global_load_lds_dwordx4 v134, s[94:95]
	ds_read_b128 v[194:197], v163 offset:49152
	ds_read_b128 v[198:201], v163 offset:50176
	ds_read_b128 v[202:205], v163 offset:51200
	ds_read_b128 v[206:209], v163 offset:52224
	ds_read_b128 v[210:213], v163 offset:53248
	ds_read_b128 v[214:217], v163 offset:54272
	ds_read_b128 v[218:221], v163 offset:55296
	ds_read_b128 v[222:225], v163 offset:56320
	s_waitcnt vmcnt(8)
	s_waitcnt lgkmcnt(0)
	s_barrier
	s_setprio 1
	s_waitcnt lgkmcnt(0)
	v_mfma_f32_16x16x32_bf16 v[62:65], v[156:159], v[194:197], v[62:65]
	v_mfma_f32_16x16x32_bf16 v[54:57], v[170:173], v[194:197], v[54:57]
	v_mfma_f32_16x16x32_bf16 v[46:49], v[156:159], v[202:205], v[46:49]
	v_mfma_f32_16x16x32_bf16 v[38:41], v[170:173], v[202:205], v[38:41]
	v_mfma_f32_16x16x32_bf16 v[30:33], v[156:159], v[210:213], v[30:33]
	v_mfma_f32_16x16x32_bf16 v[22:25], v[170:173], v[210:213], v[22:25]
	v_mfma_f32_16x16x32_bf16 v[14:17], v[156:159], v[218:221], v[14:17]
	v_mfma_f32_16x16x32_bf16 v[6:9], v[170:173], v[218:221], v[6:9]
	v_mfma_f32_16x16x32_bf16 v[62:65], v[166:169], v[198:201], v[62:65]
	v_mfma_f32_16x16x32_bf16 v[54:57], v[174:177], v[198:201], v[54:57]
	v_mfma_f32_16x16x32_bf16 v[46:49], v[166:169], v[206:209], v[46:49]
	v_mfma_f32_16x16x32_bf16 v[38:41], v[174:177], v[206:209], v[38:41]
	v_mfma_f32_16x16x32_bf16 v[30:33], v[166:169], v[214:217], v[30:33]
	v_mfma_f32_16x16x32_bf16 v[22:25], v[174:177], v[214:217], v[22:25]
	v_mfma_f32_16x16x32_bf16 v[14:17], v[166:169], v[222:225], v[14:17]
	v_mfma_f32_16x16x32_bf16 v[6:9], v[174:177], v[222:225], v[6:9]
	s_setprio 0
	s_setprio 1
	v_mfma_f32_16x16x32_bf16 v[58:61], v[178:181], v[194:197], v[58:61]
	v_mfma_f32_16x16x32_bf16 v[50:53], v[186:189], v[194:197], v[50:53]
	v_mfma_f32_16x16x32_bf16 v[42:45], v[178:181], v[202:205], v[42:45]
	v_mfma_f32_16x16x32_bf16 v[34:37], v[186:189], v[202:205], v[34:37]
	v_mfma_f32_16x16x32_bf16 v[26:29], v[178:181], v[210:213], v[26:29]
	v_mfma_f32_16x16x32_bf16 v[18:21], v[186:189], v[210:213], v[18:21]
	v_mfma_f32_16x16x32_bf16 v[10:13], v[178:181], v[218:221], v[10:13]
	v_mfma_f32_16x16x32_bf16 v[2:5], v[186:189], v[218:221], v[2:5]
	v_mfma_f32_16x16x32_bf16 v[58:61], v[182:185], v[198:201], v[58:61]
	v_mfma_f32_16x16x32_bf16 v[50:53], v[190:193], v[198:201], v[50:53]
	v_mfma_f32_16x16x32_bf16 v[42:45], v[182:185], v[206:209], v[42:45]
	v_mfma_f32_16x16x32_bf16 v[34:37], v[190:193], v[206:209], v[34:37]
	v_mfma_f32_16x16x32_bf16 v[26:29], v[182:185], v[214:217], v[26:29]
	v_mfma_f32_16x16x32_bf16 v[18:21], v[190:193], v[214:217], v[18:21]
	v_mfma_f32_16x16x32_bf16 v[10:13], v[182:185], v[222:225], v[10:13]
	v_mfma_f32_16x16x32_bf16 v[2:5], v[190:193], v[222:225], v[2:5]
	s_setprio 0
	s_barrier
	s_mov_b32 s7, s45
	s_add_u32 s88, s88, 0x100
	s_addc_u32 s89, s89, 0
	s_add_u32 s86, s86, 0x100
	s_addc_u32 s87, s87, 0
	s_cmp_ge_i32 s45, s101
	s_cbranch_scc0 .LBB0_499

.LBB0_766:
	v_cmp_gt_i32_e32 vcc, 1, v138
	s_cbranch_vccnz .LBB0_828
	v_lshl_add_u64 v[152:153], v[2:3], 0, s[16:17]
	v_add_u32_e32 v154, -2, v138
	s_waitcnt lgkmcnt(0)
	v_lshl_add_u64 v[150:151], v[4:5], 0, s[20:21]
	s_mov_b32 s7, 0
	s_nop 0
	v_readfirstlane_b32 s86, v152
	v_readfirstlane_b32 s87, v153
	v_readfirstlane_b32 s88, v150
	v_readfirstlane_b32 s89, v151
	v_readfirstlane_b32 s90, v146
	v_readfirstlane_b32 s91, v147
	v_readfirstlane_b32 s92, v148
	v_readfirstlane_b32 s93, v149
	v_readfirstlane_b32 s100, v154
	v_readfirstlane_b32 s101, v138
	v_add_u32_e32 v230, s76, v141
	v_add_u32_e32 v231, s77, v141
	v_add_u32_e32 v232, 0x18000, v141
	v_add_u32_e32 v233, 0x1c000, v141
	s_add_u32 s98, s86, 0xfffc0080
	s_addc_u32 s99, s87, -1
	s_cmp_eq_u32 s7, s100
	s_cselect_b64 s[94:95], s[90:91], s[98:99]
	s_cselect_b64 s[96:97], s[92:93], s[88:89]
	s_add_i32 s45, s7, 2
	s_nop 0
	s_add_i32 m0, s49, 0xc000
	s_nop 0
	global_load_lds_dwordx4 v144, s[86:87]
	s_add_i32 m0, s49, 0xe000
	s_nop 0
	global_load_lds_dwordx4 v142, s[86:87]
	ds_read_b128 v[164:167], v230
	ds_read_b128 v[168:171], v230 offset:1024
	ds_read_b128 v[172:175], v230 offset:2048
	ds_read_b128 v[176:179], v230 offset:3072
	ds_read_b128 v[180:183], v231
	ds_read_b128 v[184:187], v231 offset:1024
	ds_read_b128 v[188:191], v231 offset:2048
	ds_read_b128 v[192:195], v231 offset:3072
	ds_read_b128 v[196:199], v160
	ds_read_b128 v[200:203], v160 offset:1024
	ds_read_b128 v[204:207], v160 offset:2048
	ds_read_b128 v[208:211], v160 offset:3072
	ds_read_b128 v[212:215], v160 offset:4096
	ds_read_b128 v[216:219], v160 offset:5120
	ds_read_b128 v[220:223], v160 offset:6144
	ds_read_b128 v[224:227], v160 offset:7168
	s_waitcnt vmcnt(8)
	s_waitcnt lgkmcnt(0)
	s_barrier
	s_setprio 1
	s_waitcnt lgkmcnt(0)
	v_mfma_f32_16x16x32_bf16 v[122:125], v[164:167], v[196:199], 0
	v_mfma_f32_16x16x32_bf16 v[118:121], v[172:175], v[196:199], 0
	v_mfma_f32_16x16x32_bf16 v[110:113], v[164:167], v[204:207], 0
	v_mfma_f32_16x16x32_bf16 v[102:105], v[172:175], v[204:207], 0
	v_mfma_f32_16x16x32_bf16 v[94:97], v[164:167], v[212:215], 0
	v_mfma_f32_16x16x32_bf16 v[86:89], v[172:175], v[212:215], 0
	v_mfma_f32_16x16x32_bf16 v[78:81], v[164:167], v[220:223], 0
	v_mfma_f32_16x16x32_bf16 v[70:73], v[172:175], v[220:223], 0
	v_mfma_f32_16x16x32_bf16 v[122:125], v[168:171], v[200:203], v[122:125]
	v_mfma_f32_16x16x32_bf16 v[118:121], v[176:179], v[200:203], v[118:121]
	v_mfma_f32_16x16x32_bf16 v[110:113], v[168:171], v[208:211], v[110:113]
	v_mfma_f32_16x16x32_bf16 v[102:105], v[176:179], v[208:211], v[102:105]
	v_mfma_f32_16x16x32_bf16 v[94:97], v[168:171], v[216:219], v[94:97]
	v_mfma_f32_16x16x32_bf16 v[86:89], v[176:179], v[216:219], v[86:89]
	v_mfma_f32_16x16x32_bf16 v[78:81], v[168:171], v[224:227], v[78:81]
	v_mfma_f32_16x16x32_bf16 v[70:73], v[176:179], v[224:227], v[70:73]
	s_setprio 0
	s_setprio 1
	v_mfma_f32_16x16x32_bf16 v[126:129], v[180:183], v[196:199], 0
	v_mfma_f32_16x16x32_bf16 v[114:117], v[188:191], v[196:199], 0
	v_mfma_f32_16x16x32_bf16 v[106:109], v[180:183], v[204:207], 0
	v_mfma_f32_16x16x32_bf16 v[98:101], v[188:191], v[204:207], 0
	v_mfma_f32_16x16x32_bf16 v[90:93], v[180:183], v[212:215], 0
	v_mfma_f32_16x16x32_bf16 v[82:85], v[188:191], v[212:215], 0
	v_mfma_f32_16x16x32_bf16 v[74:77], v[180:183], v[220:223], 0
	v_mfma_f32_16x16x32_bf16 v[66:69], v[188:191], v[220:223], 0
	v_mfma_f32_16x16x32_bf16 v[126:129], v[184:187], v[200:203], v[126:129]
	v_mfma_f32_16x16x32_bf16 v[114:117], v[192:195], v[200:203], v[114:117]
	v_mfma_f32_16x16x32_bf16 v[106:109], v[184:187], v[208:211], v[106:109]
	v_mfma_f32_16x16x32_bf16 v[98:101], v[192:195], v[208:211], v[98:101]
	v_mfma_f32_16x16x32_bf16 v[90:93], v[184:187], v[216:219], v[90:93]
	v_mfma_f32_16x16x32_bf16 v[82:85], v[192:195], v[216:219], v[82:85]
	v_mfma_f32_16x16x32_bf16 v[74:77], v[184:187], v[224:227], v[74:77]
	v_mfma_f32_16x16x32_bf16 v[66:69], v[192:195], v[224:227], v[66:69]
	s_setprio 0
	s_barrier
	s_add_u32 s98, s96, 0x40000
	s_addc_u32 s99, s97, 0
	s_add_i32 s7, s76, s25
	s_mov_b32 m0, s7
	s_nop 0
	global_load_lds_dwordx4 v132, s[96:97]
	s_add_i32 m0, s7, 0x2000
	s_add_i32 s7, s77, s25
	global_load_lds_dwordx4 v136, s[96:97]
	s_mov_b32 m0, s7
	s_nop 0
	global_load_lds_dwordx4 v132, s[98:99]
	s_add_i32 m0, s7, 0x2000
	s_nop 0
	global_load_lds_dwordx4 v136, s[98:99]
	s_mov_b32 m0, s49
	s_nop 0
	global_load_lds_dwordx4 v130, s[94:95]
	s_mov_b32 m0, s58
	s_nop 0
	global_load_lds_dwordx4 v134, s[94:95]
	ds_read_b128 v[196:199], v160 offset:16384
	ds_read_b128 v[200:203], v160 offset:17408
	ds_read_b128 v[204:207], v160 offset:18432
	ds_read_b128 v[208:211], v160 offset:19456
	ds_read_b128 v[212:215], v160 offset:20480
	ds_read_b128 v[216:219], v160 offset:21504
	ds_read_b128 v[220:223], v160 offset:22528
	ds_read_b128 v[224:227], v160 offset:23552
	s_waitcnt vmcnt(8)
	s_waitcnt lgkmcnt(0)
	s_barrier
	s_setprio 1
	s_waitcnt lgkmcnt(0)
	v_mfma_f32_16x16x32_bf16 v[62:65], v[164:167], v[196:199], 0
	v_mfma_f32_16x16x32_bf16 v[54:57], v[172:175], v[196:199], 0
	v_mfma_f32_16x16x32_bf16 v[46:49], v[164:167], v[204:207], 0
	v_mfma_f32_16x16x32_bf16 v[38:41], v[172:175], v[204:207], 0
	v_mfma_f32_16x16x32_bf16 v[30:33], v[164:167], v[212:215], 0
	v_mfma_f32_16x16x32_bf16 v[22:25], v[172:175], v[212:215], 0
	v_mfma_f32_16x16x32_bf16 v[14:17], v[164:167], v[220:223], 0
	v_mfma_f32_16x16x32_bf16 v[6:9], v[172:175], v[220:223], 0
	v_mfma_f32_16x16x32_bf16 v[62:65], v[168:171], v[200:203], v[62:65]
	v_mfma_f32_16x16x32_bf16 v[54:57], v[176:179], v[200:203], v[54:57]
	v_mfma_f32_16x16x32_bf16 v[46:49], v[168:171], v[208:211], v[46:49]
	v_mfma_f32_16x16x32_bf16 v[38:41], v[176:179], v[208:211], v[38:41]
	v_mfma_f32_16x16x32_bf16 v[30:33], v[168:171], v[216:219], v[30:33]
	v_mfma_f32_16x16x32_bf16 v[22:25], v[176:179], v[216:219], v[22:25]
	v_mfma_f32_16x16x32_bf16 v[14:17], v[168:171], v[224:227], v[14:17]
	v_mfma_f32_16x16x32_bf16 v[6:9], v[176:179], v[224:227], v[6:9]
	s_setprio 0
	s_setprio 1
	v_mfma_f32_16x16x32_bf16 v[58:61], v[180:183], v[196:199], 0
	v_mfma_f32_16x16x32_bf16 v[50:53], v[188:191], v[196:199], 0
	v_mfma_f32_16x16x32_bf16 v[42:45], v[180:183], v[204:207], 0
	v_mfma_f32_16x16x32_bf16 v[34:37], v[188:191], v[204:207], 0
	v_mfma_f32_16x16x32_bf16 v[26:29], v[180:183], v[212:215], 0
	v_mfma_f32_16x16x32_bf16 v[18:21], v[188:191], v[212:215], 0
	v_mfma_f32_16x16x32_bf16 v[10:13], v[180:183], v[220:223], 0
	v_mfma_f32_16x16x32_bf16 v[2:5], v[188:191], v[220:223], 0
	v_mfma_f32_16x16x32_bf16 v[58:61], v[184:187], v[200:203], v[58:61]
	v_mfma_f32_16x16x32_bf16 v[50:53], v[192:195], v[200:203], v[50:53]
	v_mfma_f32_16x16x32_bf16 v[42:45], v[184:187], v[208:211], v[42:45]
	v_mfma_f32_16x16x32_bf16 v[34:37], v[192:195], v[208:211], v[34:37]
	v_mfma_f32_16x16x32_bf16 v[26:29], v[184:187], v[216:219], v[26:29]
	v_mfma_f32_16x16x32_bf16 v[18:21], v[192:195], v[216:219], v[18:21]
	v_mfma_f32_16x16x32_bf16 v[10:13], v[184:187], v[224:227], v[10:13]
	v_mfma_f32_16x16x32_bf16 v[2:5], v[192:195], v[224:227], v[2:5]
	s_setprio 0
	s_barrier
	s_add_u32 s98, s94, 0x40000
	s_addc_u32 s99, s95, 0
	s_add_i32 s7, 0, 0x18000
	s_add_i32 s47, 0, 0x1c000
	s_mov_b32 m0, s59
	s_nop 0
	global_load_lds_dwordx4 v130, s[98:99]
	s_mov_b32 m0, s60
	s_nop 0
	global_load_lds_dwordx4 v134, s[98:99]
	ds_read_b128 v[164:167], v232
	ds_read_b128 v[168:171], v232 offset:1024
	ds_read_b128 v[172:175], v232 offset:2048
	ds_read_b128 v[176:179], v232 offset:3072
	ds_read_b128 v[180:183], v233
	ds_read_b128 v[184:187], v233 offset:1024
	ds_read_b128 v[188:191], v233 offset:2048
	ds_read_b128 v[192:195], v233 offset:3072
	ds_read_b128 v[196:199], v160 offset:32768
	ds_read_b128 v[200:203], v160 offset:33792
	ds_read_b128 v[204:207], v160 offset:34816
	ds_read_b128 v[208:211], v160 offset:35840
	ds_read_b128 v[212:215], v160 offset:36864
	ds_read_b128 v[216:219], v160 offset:37888
	ds_read_b128 v[220:223], v160 offset:38912
	ds_read_b128 v[224:227], v160 offset:39936
	s_waitcnt vmcnt(8)
	s_waitcnt lgkmcnt(0)
	s_barrier
	s_setprio 1
	s_waitcnt lgkmcnt(0)
	v_mfma_f32_16x16x32_bf16 v[122:125], v[164:167], v[196:199], v[122:125]
	v_mfma_f32_16x16x32_bf16 v[118:121], v[172:175], v[196:199], v[118:121]
	v_mfma_f32_16x16x32_bf16 v[110:113], v[164:167], v[204:207], v[110:113]
	v_mfma_f32_16x16x32_bf16 v[102:105], v[172:175], v[204:207], v[102:105]
	v_mfma_f32_16x16x32_bf16 v[94:97], v[164:167], v[212:215], v[94:97]
	v_mfma_f32_16x16x32_bf16 v[86:89], v[172:175], v[212:215], v[86:89]
	v_mfma_f32_16x16x32_bf16 v[78:81], v[164:167], v[220:223], v[78:81]
	v_mfma_f32_16x16x32_bf16 v[70:73], v[172:175], v[220:223], v[70:73]
	v_mfma_f32_16x16x32_bf16 v[122:125], v[168:171], v[200:203], v[122:125]
	v_mfma_f32_16x16x32_bf16 v[118:121], v[176:179], v[200:203], v[118:121]
	v_mfma_f32_16x16x32_bf16 v[110:113], v[168:171], v[208:211], v[110:113]
	v_mfma_f32_16x16x32_bf16 v[102:105], v[176:179], v[208:211], v[102:105]
	v_mfma_f32_16x16x32_bf16 v[94:97], v[168:171], v[216:219], v[94:97]
	v_mfma_f32_16x16x32_bf16 v[86:89], v[176:179], v[216:219], v[86:89]
	v_mfma_f32_16x16x32_bf16 v[78:81], v[168:171], v[224:227], v[78:81]
	v_mfma_f32_16x16x32_bf16 v[70:73], v[176:179], v[224:227], v[70:73]
	s_setprio 0
	s_setprio 1
	v_mfma_f32_16x16x32_bf16 v[126:129], v[180:183], v[196:199], v[126:129]
	v_mfma_f32_16x16x32_bf16 v[114:117], v[188:191], v[196:199], v[114:117]
	v_mfma_f32_16x16x32_bf16 v[106:109], v[180:183], v[204:207], v[106:109]
	v_mfma_f32_16x16x32_bf16 v[98:101], v[188:191], v[204:207], v[98:101]
	v_mfma_f32_16x16x32_bf16 v[90:93], v[180:183], v[212:215], v[90:93]
	v_mfma_f32_16x16x32_bf16 v[82:85], v[188:191], v[212:215], v[82:85]
	v_mfma_f32_16x16x32_bf16 v[74:77], v[180:183], v[220:223], v[74:77]
	v_mfma_f32_16x16x32_bf16 v[66:69], v[188:191], v[220:223], v[66:69]
	v_mfma_f32_16x16x32_bf16 v[126:129], v[184:187], v[200:203], v[126:129]
	v_mfma_f32_16x16x32_bf16 v[114:117], v[192:195], v[200:203], v[114:117]
	v_mfma_f32_16x16x32_bf16 v[106:109], v[184:187], v[208:211], v[106:109]
	v_mfma_f32_16x16x32_bf16 v[98:101], v[192:195], v[208:211], v[98:101]
	v_mfma_f32_16x16x32_bf16 v[90:93], v[184:187], v[216:219], v[90:93]
	v_mfma_f32_16x16x32_bf16 v[82:85], v[192:195], v[216:219], v[82:85]
	v_mfma_f32_16x16x32_bf16 v[74:77], v[184:187], v[224:227], v[74:77]
	v_mfma_f32_16x16x32_bf16 v[66:69], v[192:195], v[224:227], v[66:69]
	s_setprio 0
	s_barrier
	s_add_u32 s96, s96, 0x80
	s_addc_u32 s97, s97, 0
	s_add_u32 s98, s96, 0x40000
	s_addc_u32 s99, s97, 0
	s_add_u32 s94, s94, 0x80
	s_addc_u32 s95, s95, 0
	s_add_i32 s7, s7, s25
	s_mov_b32 m0, s7
	s_nop 0
	global_load_lds_dwordx4 v132, s[96:97]
	s_add_i32 m0, s7, 0x2000
	s_add_i32 s7, s47, s25
	global_load_lds_dwordx4 v136, s[96:97]
	s_mov_b32 m0, s7
	s_nop 0
	global_load_lds_dwordx4 v132, s[98:99]
	s_add_i32 m0, s7, 0x2000
	s_nop 0
	global_load_lds_dwordx4 v136, s[98:99]
	s_mov_b32 m0, s66
	s_nop 0
	global_load_lds_dwordx4 v130, s[94:95]
	s_mov_b32 m0, s67
	s_nop 0
	global_load_lds_dwordx4 v134, s[94:95]
	ds_read_b128 v[196:199], v160 offset:49152
	ds_read_b128 v[200:203], v160 offset:50176
	ds_read_b128 v[204:207], v160 offset:51200
	ds_read_b128 v[208:211], v160 offset:52224
	ds_read_b128 v[212:215], v160 offset:53248
	ds_read_b128 v[216:219], v160 offset:54272
	ds_read_b128 v[220:223], v160 offset:55296
	ds_read_b128 v[224:227], v160 offset:56320
	s_waitcnt vmcnt(8)
	s_waitcnt lgkmcnt(0)
	s_barrier
	s_setprio 1
	s_waitcnt lgkmcnt(0)
	v_mfma_f32_16x16x32_bf16 v[62:65], v[164:167], v[196:199], v[62:65]
	v_mfma_f32_16x16x32_bf16 v[54:57], v[172:175], v[196:199], v[54:57]
	v_mfma_f32_16x16x32_bf16 v[46:49], v[164:167], v[204:207], v[46:49]
	v_mfma_f32_16x16x32_bf16 v[38:41], v[172:175], v[204:207], v[38:41]
	v_mfma_f32_16x16x32_bf16 v[30:33], v[164:167], v[212:215], v[30:33]
	v_mfma_f32_16x16x32_bf16 v[22:25], v[172:175], v[212:215], v[22:25]
	v_mfma_f32_16x16x32_bf16 v[14:17], v[164:167], v[220:223], v[14:17]
	v_mfma_f32_16x16x32_bf16 v[6:9], v[172:175], v[220:223], v[6:9]
	v_mfma_f32_16x16x32_bf16 v[62:65], v[168:171], v[200:203], v[62:65]
	v_mfma_f32_16x16x32_bf16 v[54:57], v[176:179], v[200:203], v[54:57]
	v_mfma_f32_16x16x32_bf16 v[46:49], v[168:171], v[208:211], v[46:49]
	v_mfma_f32_16x16x32_bf16 v[38:41], v[176:179], v[208:211], v[38:41]
	v_mfma_f32_16x16x32_bf16 v[30:33], v[168:171], v[216:219], v[30:33]
	v_mfma_f32_16x16x32_bf16 v[22:25], v[176:179], v[216:219], v[22:25]
	v_mfma_f32_16x16x32_bf16 v[14:17], v[168:171], v[224:227], v[14:17]
	v_mfma_f32_16x16x32_bf16 v[6:9], v[176:179], v[224:227], v[6:9]
	s_setprio 0
	s_setprio 1
	v_mfma_f32_16x16x32_bf16 v[58:61], v[180:183], v[196:199], v[58:61]
	v_mfma_f32_16x16x32_bf16 v[50:53], v[188:191], v[196:199], v[50:53]
	v_mfma_f32_16x16x32_bf16 v[42:45], v[180:183], v[204:207], v[42:45]
	v_mfma_f32_16x16x32_bf16 v[34:37], v[188:191], v[204:207], v[34:37]
	v_mfma_f32_16x16x32_bf16 v[26:29], v[180:183], v[212:215], v[26:29]
	v_mfma_f32_16x16x32_bf16 v[18:21], v[188:191], v[212:215], v[18:21]
	v_mfma_f32_16x16x32_bf16 v[10:13], v[180:183], v[220:223], v[10:13]
	v_mfma_f32_16x16x32_bf16 v[2:5], v[188:191], v[220:223], v[2:5]
	v_mfma_f32_16x16x32_bf16 v[58:61], v[184:187], v[200:203], v[58:61]
	v_mfma_f32_16x16x32_bf16 v[50:53], v[192:195], v[200:203], v[50:53]
	v_mfma_f32_16x16x32_bf16 v[42:45], v[184:187], v[208:211], v[42:45]
	v_mfma_f32_16x16x32_bf16 v[34:37], v[192:195], v[208:211], v[34:37]
	v_mfma_f32_16x16x32_bf16 v[26:29], v[184:187], v[216:219], v[26:29]
	v_mfma_f32_16x16x32_bf16 v[18:21], v[192:195], v[216:219], v[18:21]
	v_mfma_f32_16x16x32_bf16 v[10:13], v[184:187], v[224:227], v[10:13]
	v_mfma_f32_16x16x32_bf16 v[2:5], v[192:195], v[224:227], v[2:5]
	s_setprio 0
	s_barrier
	s_mov_b32 s7, s45
	s_add_u32 s88, s88, 0x100
	s_addc_u32 s89, s89, 0
	s_add_u32 s86, s86, 0x100
	s_addc_u32 s87, s87, 0
	s_cmp_ge_i32 s45, s101
	s_cbranch_scc1 .Lmy_kexit_3
.LBB0_768:
	s_add_u32 s98, s86, 0xfffc0080
	s_addc_u32 s99, s87, -1
	s_cmp_eq_u32 s7, s100
	s_cselect_b64 s[94:95], s[90:91], s[98:99]
	s_cselect_b64 s[96:97], s[92:93], s[88:89]
	s_add_i32 s45, s7, 2
	s_nop 0
	s_add_i32 m0, s49, 0xc000
	s_nop 0
	global_load_lds_dwordx4 v144, s[86:87]
	s_add_i32 m0, s49, 0xe000
	s_nop 0
	global_load_lds_dwordx4 v142, s[86:87]
	ds_read_b128 v[164:167], v230
	ds_read_b128 v[168:171], v230 offset:1024
	ds_read_b128 v[172:175], v230 offset:2048
	ds_read_b128 v[176:179], v230 offset:3072
	ds_read_b128 v[180:183], v231
	ds_read_b128 v[184:187], v231 offset:1024
	ds_read_b128 v[188:191], v231 offset:2048
	ds_read_b128 v[192:195], v231 offset:3072
	ds_read_b128 v[196:199], v160
	ds_read_b128 v[200:203], v160 offset:1024
	ds_read_b128 v[204:207], v160 offset:2048
	ds_read_b128 v[208:211], v160 offset:3072
	ds_read_b128 v[212:215], v160 offset:4096
	ds_read_b128 v[216:219], v160 offset:5120
	ds_read_b128 v[220:223], v160 offset:6144
	ds_read_b128 v[224:227], v160 offset:7168
	s_waitcnt vmcnt(8)
	s_waitcnt lgkmcnt(0)
	s_barrier
	s_setprio 1
	s_waitcnt lgkmcnt(0)
	v_mfma_f32_16x16x32_bf16 v[122:125], v[164:167], v[196:199], v[122:125]
	v_mfma_f32_16x16x32_bf16 v[118:121], v[172:175], v[196:199], v[118:121]
	v_mfma_f32_16x16x32_bf16 v[110:113], v[164:167], v[204:207], v[110:113]
	v_mfma_f32_16x16x32_bf16 v[102:105], v[172:175], v[204:207], v[102:105]
	v_mfma_f32_16x16x32_bf16 v[94:97], v[164:167], v[212:215], v[94:97]
	v_mfma_f32_16x16x32_bf16 v[86:89], v[172:175], v[212:215], v[86:89]
	v_mfma_f32_16x16x32_bf16 v[78:81], v[164:167], v[220:223], v[78:81]
	v_mfma_f32_16x16x32_bf16 v[70:73], v[172:175], v[220:223], v[70:73]
	v_mfma_f32_16x16x32_bf16 v[122:125], v[168:171], v[200:203], v[122:125]
	v_mfma_f32_16x16x32_bf16 v[118:121], v[176:179], v[200:203], v[118:121]
	v_mfma_f32_16x16x32_bf16 v[110:113], v[168:171], v[208:211], v[110:113]
	v_mfma_f32_16x16x32_bf16 v[102:105], v[176:179], v[208:211], v[102:105]
	v_mfma_f32_16x16x32_bf16 v[94:97], v[168:171], v[216:219], v[94:97]
	v_mfma_f32_16x16x32_bf16 v[86:89], v[176:179], v[216:219], v[86:89]
	v_mfma_f32_16x16x32_bf16 v[78:81], v[168:171], v[224:227], v[78:81]
	v_mfma_f32_16x16x32_bf16 v[70:73], v[176:179], v[224:227], v[70:73]
	s_setprio 0
	s_setprio 1
	v_mfma_f32_16x16x32_bf16 v[126:129], v[180:183], v[196:199], v[126:129]
	v_mfma_f32_16x16x32_bf16 v[114:117], v[188:191], v[196:199], v[114:117]
	v_mfma_f32_16x16x32_bf16 v[106:109], v[180:183], v[204:207], v[106:109]
	v_mfma_f32_16x16x32_bf16 v[98:101], v[188:191], v[204:207], v[98:101]
	v_mfma_f32_16x16x32_bf16 v[90:93], v[180:183], v[212:215], v[90:93]
	v_mfma_f32_16x16x32_bf16 v[82:85], v[188:191], v[212:215], v[82:85]
	v_mfma_f32_16x16x32_bf16 v[74:77], v[180:183], v[220:223], v[74:77]
	v_mfma_f32_16x16x32_bf16 v[66:69], v[188:191], v[220:223], v[66:69]
	v_mfma_f32_16x16x32_bf16 v[126:129], v[184:187], v[200:203], v[126:129]
	v_mfma_f32_16x16x32_bf16 v[114:117], v[192:195], v[200:203], v[114:117]
	v_mfma_f32_16x16x32_bf16 v[106:109], v[184:187], v[208:211], v[106:109]
	v_mfma_f32_16x16x32_bf16 v[98:101], v[192:195], v[208:211], v[98:101]
	v_mfma_f32_16x16x32_bf16 v[90:93], v[184:187], v[216:219], v[90:93]
	v_mfma_f32_16x16x32_bf16 v[82:85], v[192:195], v[216:219], v[82:85]
	v_mfma_f32_16x16x32_bf16 v[74:77], v[184:187], v[224:227], v[74:77]
	v_mfma_f32_16x16x32_bf16 v[66:69], v[192:195], v[224:227], v[66:69]
	s_setprio 0
	s_barrier
	s_add_u32 s98, s96, 0x40000
	s_addc_u32 s99, s97, 0
	s_add_i32 s7, s76, s25
	s_mov_b32 m0, s7
	s_nop 0
	global_load_lds_dwordx4 v132, s[96:97]
	s_add_i32 m0, s7, 0x2000
	s_add_i32 s7, s77, s25
	global_load_lds_dwordx4 v136, s[96:97]
	s_mov_b32 m0, s7
	s_nop 0
	global_load_lds_dwordx4 v132, s[98:99]
	s_add_i32 m0, s7, 0x2000
	s_nop 0
	global_load_lds_dwordx4 v136, s[98:99]
	s_mov_b32 m0, s49
	s_nop 0
	global_load_lds_dwordx4 v130, s[94:95]
	s_mov_b32 m0, s58
	s_nop 0
	global_load_lds_dwordx4 v134, s[94:95]
	ds_read_b128 v[196:199], v160 offset:16384
	ds_read_b128 v[200:203], v160 offset:17408
	ds_read_b128 v[204:207], v160 offset:18432
	ds_read_b128 v[208:211], v160 offset:19456
	ds_read_b128 v[212:215], v160 offset:20480
	ds_read_b128 v[216:219], v160 offset:21504
	ds_read_b128 v[220:223], v160 offset:22528
	ds_read_b128 v[224:227], v160 offset:23552
	s_waitcnt vmcnt(8)
	s_waitcnt lgkmcnt(0)
	s_barrier
	s_setprio 1
	s_waitcnt lgkmcnt(0)
	v_mfma_f32_16x16x32_bf16 v[62:65], v[164:167], v[196:199], v[62:65]
	v_mfma_f32_16x16x32_bf16 v[54:57], v[172:175], v[196:199], v[54:57]
	v_mfma_f32_16x16x32_bf16 v[46:49], v[164:167], v[204:207], v[46:49]
	v_mfma_f32_16x16x32_bf16 v[38:41], v[172:175], v[204:207], v[38:41]
	v_mfma_f32_16x16x32_bf16 v[30:33], v[164:167], v[212:215], v[30:33]
	v_mfma_f32_16x16x32_bf16 v[22:25], v[172:175], v[212:215], v[22:25]
	v_mfma_f32_16x16x32_bf16 v[14:17], v[164:167], v[220:223], v[14:17]
	v_mfma_f32_16x16x32_bf16 v[6:9], v[172:175], v[220:223], v[6:9]
	v_mfma_f32_16x16x32_bf16 v[62:65], v[168:171], v[200:203], v[62:65]
	v_mfma_f32_16x16x32_bf16 v[54:57], v[176:179], v[200:203], v[54:57]
	v_mfma_f32_16x16x32_bf16 v[46:49], v[168:171], v[208:211], v[46:49]
	v_mfma_f32_16x16x32_bf16 v[38:41], v[176:179], v[208:211], v[38:41]
	v_mfma_f32_16x16x32_bf16 v[30:33], v[168:171], v[216:219], v[30:33]
	v_mfma_f32_16x16x32_bf16 v[22:25], v[176:179], v[216:219], v[22:25]
	v_mfma_f32_16x16x32_bf16 v[14:17], v[168:171], v[224:227], v[14:17]
	v_mfma_f32_16x16x32_bf16 v[6:9], v[176:179], v[224:227], v[6:9]
	s_setprio 0
	s_setprio 1
	v_mfma_f32_16x16x32_bf16 v[58:61], v[180:183], v[196:199], v[58:61]
	v_mfma_f32_16x16x32_bf16 v[50:53], v[188:191], v[196:199], v[50:53]
	v_mfma_f32_16x16x32_bf16 v[42:45], v[180:183], v[204:207], v[42:45]
	v_mfma_f32_16x16x32_bf16 v[34:37], v[188:191], v[204:207], v[34:37]
	v_mfma_f32_16x16x32_bf16 v[26:29], v[180:183], v[212:215], v[26:29]
	v_mfma_f32_16x16x32_bf16 v[18:21], v[188:191], v[212:215], v[18:21]
	v_mfma_f32_16x16x32_bf16 v[10:13], v[180:183], v[220:223], v[10:13]
	v_mfma_f32_16x16x32_bf16 v[2:5], v[188:191], v[220:223], v[2:5]
	v_mfma_f32_16x16x32_bf16 v[58:61], v[184:187], v[200:203], v[58:61]
	v_mfma_f32_16x16x32_bf16 v[50:53], v[192:195], v[200:203], v[50:53]
	v_mfma_f32_16x16x32_bf16 v[42:45], v[184:187], v[208:211], v[42:45]
	v_mfma_f32_16x16x32_bf16 v[34:37], v[192:195], v[208:211], v[34:37]
	v_mfma_f32_16x16x32_bf16 v[26:29], v[184:187], v[216:219], v[26:29]
	v_mfma_f32_16x16x32_bf16 v[18:21], v[192:195], v[216:219], v[18:21]
	v_mfma_f32_16x16x32_bf16 v[10:13], v[184:187], v[224:227], v[10:13]
	v_mfma_f32_16x16x32_bf16 v[2:5], v[192:195], v[224:227], v[2:5]
	s_setprio 0
	s_barrier
	s_add_u32 s98, s94, 0x40000
	s_addc_u32 s99, s95, 0
	s_add_i32 s7, 0, 0x18000
	s_add_i32 s47, 0, 0x1c000
	s_mov_b32 m0, s59
	s_nop 0
	global_load_lds_dwordx4 v130, s[98:99]
	s_mov_b32 m0, s60
	s_nop 0
	global_load_lds_dwordx4 v134, s[98:99]
	ds_read_b128 v[164:167], v232
	ds_read_b128 v[168:171], v232 offset:1024
	ds_read_b128 v[172:175], v232 offset:2048
	ds_read_b128 v[176:179], v232 offset:3072
	ds_read_b128 v[180:183], v233
	ds_read_b128 v[184:187], v233 offset:1024
	ds_read_b128 v[188:191], v233 offset:2048
	ds_read_b128 v[192:195], v233 offset:3072
	ds_read_b128 v[196:199], v160 offset:32768
	ds_read_b128 v[200:203], v160 offset:33792
	ds_read_b128 v[204:207], v160 offset:34816
	ds_read_b128 v[208:211], v160 offset:35840
	ds_read_b128 v[212:215], v160 offset:36864
	ds_read_b128 v[216:219], v160 offset:37888
	ds_read_b128 v[220:223], v160 offset:38912
	ds_read_b128 v[224:227], v160 offset:39936
	s_waitcnt vmcnt(8)
	s_waitcnt lgkmcnt(0)
	s_barrier
	s_setprio 1
	s_waitcnt lgkmcnt(0)
	v_mfma_f32_16x16x32_bf16 v[122:125], v[164:167], v[196:199], v[122:125]
	v_mfma_f32_16x16x32_bf16 v[118:121], v[172:175], v[196:199], v[118:121]
	v_mfma_f32_16x16x32_bf16 v[110:113], v[164:167], v[204:207], v[110:113]
	v_mfma_f32_16x16x32_bf16 v[102:105], v[172:175], v[204:207], v[102:105]
	v_mfma_f32_16x16x32_bf16 v[94:97], v[164:167], v[212:215], v[94:97]
	v_mfma_f32_16x16x32_bf16 v[86:89], v[172:175], v[212:215], v[86:89]
	v_mfma_f32_16x16x32_bf16 v[78:81], v[164:167], v[220:223], v[78:81]
	v_mfma_f32_16x16x32_bf16 v[70:73], v[172:175], v[220:223], v[70:73]
	v_mfma_f32_16x16x32_bf16 v[122:125], v[168:171], v[200:203], v[122:125]
	v_mfma_f32_16x16x32_bf16 v[118:121], v[176:179], v[200:203], v[118:121]
	v_mfma_f32_16x16x32_bf16 v[110:113], v[168:171], v[208:211], v[110:113]
	v_mfma_f32_16x16x32_bf16 v[102:105], v[176:179], v[208:211], v[102:105]
	v_mfma_f32_16x16x32_bf16 v[94:97], v[168:171], v[216:219], v[94:97]
	v_mfma_f32_16x16x32_bf16 v[86:89], v[176:179], v[216:219], v[86:89]
	v_mfma_f32_16x16x32_bf16 v[78:81], v[168:171], v[224:227], v[78:81]
	v_mfma_f32_16x16x32_bf16 v[70:73], v[176:179], v[224:227], v[70:73]
	s_setprio 0
	s_setprio 1
	v_mfma_f32_16x16x32_bf16 v[126:129], v[180:183], v[196:199], v[126:129]
	v_mfma_f32_16x16x32_bf16 v[114:117], v[188:191], v[196:199], v[114:117]
	v_mfma_f32_16x16x32_bf16 v[106:109], v[180:183], v[204:207], v[106:109]
	v_mfma_f32_16x16x32_bf16 v[98:101], v[188:191], v[204:207], v[98:101]
	v_mfma_f32_16x16x32_bf16 v[90:93], v[180:183], v[212:215], v[90:93]
	v_mfma_f32_16x16x32_bf16 v[82:85], v[188:191], v[212:215], v[82:85]
	v_mfma_f32_16x16x32_bf16 v[74:77], v[180:183], v[220:223], v[74:77]
	v_mfma_f32_16x16x32_bf16 v[66:69], v[188:191], v[220:223], v[66:69]
	v_mfma_f32_16x16x32_bf16 v[126:129], v[184:187], v[200:203], v[126:129]
	v_mfma_f32_16x16x32_bf16 v[114:117], v[192:195], v[200:203], v[114:117]
	v_mfma_f32_16x16x32_bf16 v[106:109], v[184:187], v[208:211], v[106:109]
	v_mfma_f32_16x16x32_bf16 v[98:101], v[192:195], v[208:211], v[98:101]
	v_mfma_f32_16x16x32_bf16 v[90:93], v[184:187], v[216:219], v[90:93]
	v_mfma_f32_16x16x32_bf16 v[82:85], v[192:195], v[216:219], v[82:85]
	v_mfma_f32_16x16x32_bf16 v[74:77], v[184:187], v[224:227], v[74:77]
	v_mfma_f32_16x16x32_bf16 v[66:69], v[192:195], v[224:227], v[66:69]
	s_setprio 0
	s_barrier
	s_add_u32 s96, s96, 0x80
	s_addc_u32 s97, s97, 0
	s_add_u32 s98, s96, 0x40000
	s_addc_u32 s99, s97, 0
	s_add_u32 s94, s94, 0x80
	s_addc_u32 s95, s95, 0
	s_add_i32 s7, s7, s25
	s_mov_b32 m0, s7
	s_nop 0
	global_load_lds_dwordx4 v132, s[96:97]
	s_add_i32 m0, s7, 0x2000
	s_add_i32 s7, s47, s25
	global_load_lds_dwordx4 v136, s[96:97]
	s_mov_b32 m0, s7
	s_nop 0
	global_load_lds_dwordx4 v132, s[98:99]
	s_add_i32 m0, s7, 0x2000
	s_nop 0
	global_load_lds_dwordx4 v136, s[98:99]
	s_mov_b32 m0, s66
	s_nop 0
	global_load_lds_dwordx4 v130, s[94:95]
	s_mov_b32 m0, s67
	s_nop 0
	global_load_lds_dwordx4 v134, s[94:95]
	ds_read_b128 v[196:199], v160 offset:49152
	ds_read_b128 v[200:203], v160 offset:50176
	ds_read_b128 v[204:207], v160 offset:51200
	ds_read_b128 v[208:211], v160 offset:52224
	ds_read_b128 v[212:215], v160 offset:53248
	ds_read_b128 v[216:219], v160 offset:54272
	ds_read_b128 v[220:223], v160 offset:55296
	ds_read_b128 v[224:227], v160 offset:56320
	s_waitcnt vmcnt(8)
	s_waitcnt lgkmcnt(0)
	s_barrier
	s_setprio 1
	s_waitcnt lgkmcnt(0)
	v_mfma_f32_16x16x32_bf16 v[62:65], v[164:167], v[196:199], v[62:65]
	v_mfma_f32_16x16x32_bf16 v[54:57], v[172:175], v[196:199], v[54:57]
	v_mfma_f32_16x16x32_bf16 v[46:49], v[164:167], v[204:207], v[46:49]
	v_mfma_f32_16x16x32_bf16 v[38:41], v[172:175], v[204:207], v[38:41]
	v_mfma_f32_16x16x32_bf16 v[30:33], v[164:167], v[212:215], v[30:33]
	v_mfma_f32_16x16x32_bf16 v[22:25], v[172:175], v[212:215], v[22:25]
	v_mfma_f32_16x16x32_bf16 v[14:17], v[164:167], v[220:223], v[14:17]
	v_mfma_f32_16x16x32_bf16 v[6:9], v[172:175], v[220:223], v[6:9]
	v_mfma_f32_16x16x32_bf16 v[62:65], v[168:171], v[200:203], v[62:65]
	v_mfma_f32_16x16x32_bf16 v[54:57], v[176:179], v[200:203], v[54:57]
	v_mfma_f32_16x16x32_bf16 v[46:49], v[168:171], v[208:211], v[46:49]
	v_mfma_f32_16x16x32_bf16 v[38:41], v[176:179], v[208:211], v[38:41]
	v_mfma_f32_16x16x32_bf16 v[30:33], v[168:171], v[216:219], v[30:33]
	v_mfma_f32_16x16x32_bf16 v[22:25], v[176:179], v[216:219], v[22:25]
	v_mfma_f32_16x16x32_bf16 v[14:17], v[168:171], v[224:227], v[14:17]
	v_mfma_f32_16x16x32_bf16 v[6:9], v[176:179], v[224:227], v[6:9]
	s_setprio 0
	s_setprio 1
	v_mfma_f32_16x16x32_bf16 v[58:61], v[180:183], v[196:199], v[58:61]
	v_mfma_f32_16x16x32_bf16 v[50:53], v[188:191], v[196:199], v[50:53]
	v_mfma_f32_16x16x32_bf16 v[42:45], v[180:183], v[204:207], v[42:45]
	v_mfma_f32_16x16x32_bf16 v[34:37], v[188:191], v[204:207], v[34:37]
	v_mfma_f32_16x16x32_bf16 v[26:29], v[180:183], v[212:215], v[26:29]
	v_mfma_f32_16x16x32_bf16 v[18:21], v[188:191], v[212:215], v[18:21]
	v_mfma_f32_16x16x32_bf16 v[10:13], v[180:183], v[220:223], v[10:13]
	v_mfma_f32_16x16x32_bf16 v[2:5], v[188:191], v[220:223], v[2:5]
	v_mfma_f32_16x16x32_bf16 v[58:61], v[184:187], v[200:203], v[58:61]
	v_mfma_f32_16x16x32_bf16 v[50:53], v[192:195], v[200:203], v[50:53]
	v_mfma_f32_16x16x32_bf16 v[42:45], v[184:187], v[208:211], v[42:45]
	v_mfma_f32_16x16x32_bf16 v[34:37], v[192:195], v[208:211], v[34:37]
	v_mfma_f32_16x16x32_bf16 v[26:29], v[184:187], v[216:219], v[26:29]
	v_mfma_f32_16x16x32_bf16 v[18:21], v[192:195], v[216:219], v[18:21]
	v_mfma_f32_16x16x32_bf16 v[10:13], v[184:187], v[224:227], v[10:13]
	v_mfma_f32_16x16x32_bf16 v[2:5], v[192:195], v[224:227], v[2:5]
	s_setprio 0
	s_barrier
	s_mov_b32 s7, s45
	s_add_u32 s88, s88, 0x100
	s_addc_u32 s89, s89, 0
	s_add_u32 s86, s86, 0x100
	s_addc_u32 s87, s87, 0
	s_cmp_ge_i32 s45, s101
	s_cbranch_scc0 .LBB0_768

.LBB0_947:
	v_cmp_gt_i32_e32 vcc, 1, v138
	s_cbranch_vccnz .LBB0_1009
	v_lshl_add_u64 v[152:153], v[2:3], 0, s[18:19]
	v_add_u32_e32 v154, -2, v138
	s_waitcnt lgkmcnt(0)
	v_lshl_add_u64 v[150:151], v[4:5], 0, s[22:23]
	s_mov_b32 s7, 0
	s_nop 0
	v_readfirstlane_b32 s86, v152
	v_readfirstlane_b32 s87, v153
	v_readfirstlane_b32 s88, v150
	v_readfirstlane_b32 s89, v151
	v_readfirstlane_b32 s90, v146
	v_readfirstlane_b32 s91, v147
	v_readfirstlane_b32 s92, v148
	v_readfirstlane_b32 s93, v149
	v_readfirstlane_b32 s100, v154
	v_readfirstlane_b32 s101, v138
	v_add_u32_e32 v230, s74, v141
	v_add_u32_e32 v231, s75, v141
	v_add_u32_e32 v232, 0x18000, v141
	v_add_u32_e32 v233, 0x1c000, v141
	s_add_u32 s98, s86, 0xfffc0080
	s_addc_u32 s99, s87, -1
	s_cmp_eq_u32 s7, s100
	s_cselect_b64 s[94:95], s[90:91], s[98:99]
	s_cselect_b64 s[96:97], s[92:93], s[88:89]
	s_add_i32 s47, s7, 2
	s_nop 0
	s_mov_b32 m0, s76
	s_nop 0
	global_load_lds_dwordx4 v144, s[86:87]
	s_mov_b32 m0, s77
	s_nop 0
	global_load_lds_dwordx4 v142, s[86:87]
	ds_read_b128 v[164:167], v230
	ds_read_b128 v[168:171], v230 offset:1024
	ds_read_b128 v[172:175], v230 offset:2048
	ds_read_b128 v[176:179], v230 offset:3072
	ds_read_b128 v[180:183], v231
	ds_read_b128 v[184:187], v231 offset:1024
	ds_read_b128 v[188:191], v231 offset:2048
	ds_read_b128 v[192:195], v231 offset:3072
	ds_read_b128 v[196:199], v160
	ds_read_b128 v[200:203], v160 offset:1024
	ds_read_b128 v[204:207], v160 offset:2048
	ds_read_b128 v[208:211], v160 offset:3072
	ds_read_b128 v[212:215], v160 offset:4096
	ds_read_b128 v[216:219], v160 offset:5120
	ds_read_b128 v[220:223], v160 offset:6144
	ds_read_b128 v[224:227], v160 offset:7168
	s_waitcnt vmcnt(8)
	s_waitcnt lgkmcnt(0)
	s_barrier
	s_setprio 1
	s_waitcnt lgkmcnt(0)
	v_mfma_f32_16x16x32_bf16 v[122:125], v[164:167], v[196:199], 0
	v_mfma_f32_16x16x32_bf16 v[118:121], v[172:175], v[196:199], 0
	v_mfma_f32_16x16x32_bf16 v[110:113], v[164:167], v[204:207], 0
	v_mfma_f32_16x16x32_bf16 v[102:105], v[172:175], v[204:207], 0
	v_mfma_f32_16x16x32_bf16 v[94:97], v[164:167], v[212:215], 0
	v_mfma_f32_16x16x32_bf16 v[86:89], v[172:175], v[212:215], 0
	v_mfma_f32_16x16x32_bf16 v[78:81], v[164:167], v[220:223], 0
	v_mfma_f32_16x16x32_bf16 v[70:73], v[172:175], v[220:223], 0
	v_mfma_f32_16x16x32_bf16 v[122:125], v[168:171], v[200:203], v[122:125]
	v_mfma_f32_16x16x32_bf16 v[118:121], v[176:179], v[200:203], v[118:121]
	v_mfma_f32_16x16x32_bf16 v[110:113], v[168:171], v[208:211], v[110:113]
	v_mfma_f32_16x16x32_bf16 v[102:105], v[176:179], v[208:211], v[102:105]
	v_mfma_f32_16x16x32_bf16 v[94:97], v[168:171], v[216:219], v[94:97]
	v_mfma_f32_16x16x32_bf16 v[86:89], v[176:179], v[216:219], v[86:89]
	v_mfma_f32_16x16x32_bf16 v[78:81], v[168:171], v[224:227], v[78:81]
	v_mfma_f32_16x16x32_bf16 v[70:73], v[176:179], v[224:227], v[70:73]
	s_setprio 0
	s_setprio 1
	v_mfma_f32_16x16x32_bf16 v[126:129], v[180:183], v[196:199], 0
	v_mfma_f32_16x16x32_bf16 v[114:117], v[188:191], v[196:199], 0
	v_mfma_f32_16x16x32_bf16 v[106:109], v[180:183], v[204:207], 0
	v_mfma_f32_16x16x32_bf16 v[98:101], v[188:191], v[204:207], 0
	v_mfma_f32_16x16x32_bf16 v[90:93], v[180:183], v[212:215], 0
	v_mfma_f32_16x16x32_bf16 v[82:85], v[188:191], v[212:215], 0
	v_mfma_f32_16x16x32_bf16 v[74:77], v[180:183], v[220:223], 0
	v_mfma_f32_16x16x32_bf16 v[66:69], v[188:191], v[220:223], 0
	v_mfma_f32_16x16x32_bf16 v[126:129], v[184:187], v[200:203], v[126:129]
	v_mfma_f32_16x16x32_bf16 v[114:117], v[192:195], v[200:203], v[114:117]
	v_mfma_f32_16x16x32_bf16 v[106:109], v[184:187], v[208:211], v[106:109]
	v_mfma_f32_16x16x32_bf16 v[98:101], v[192:195], v[208:211], v[98:101]
	v_mfma_f32_16x16x32_bf16 v[90:93], v[184:187], v[216:219], v[90:93]
	v_mfma_f32_16x16x32_bf16 v[82:85], v[192:195], v[216:219], v[82:85]
	v_mfma_f32_16x16x32_bf16 v[74:77], v[184:187], v[224:227], v[74:77]
	v_mfma_f32_16x16x32_bf16 v[66:69], v[192:195], v[224:227], v[66:69]
	s_setprio 0
	s_barrier
	s_add_u32 s98, s96, 0x40000
	s_addc_u32 s99, s97, 0
	s_mov_b32 m0, s78
	s_nop 0
	global_load_lds_dwordx4 v132, s[96:97]
	s_mov_b32 m0, s79
	s_add_i32 s7, s75, s29
	global_load_lds_dwordx4 v136, s[96:97]
	s_mov_b32 m0, s7
	s_nop 0
	global_load_lds_dwordx4 v132, s[98:99]
	s_add_i32 m0, s7, 0x2000
	s_nop 0
	global_load_lds_dwordx4 v136, s[98:99]
	s_mov_b32 m0, s51
	s_nop 0
	global_load_lds_dwordx4 v130, s[94:95]
	s_mov_b32 m0, s60
	s_nop 0
	global_load_lds_dwordx4 v134, s[94:95]
	ds_read_b128 v[196:199], v160 offset:16384
	ds_read_b128 v[200:203], v160 offset:17408
	ds_read_b128 v[204:207], v160 offset:18432
	ds_read_b128 v[208:211], v160 offset:19456
	ds_read_b128 v[212:215], v160 offset:20480
	ds_read_b128 v[216:219], v160 offset:21504
	ds_read_b128 v[220:223], v160 offset:22528
	ds_read_b128 v[224:227], v160 offset:23552
	s_waitcnt vmcnt(8)
	s_waitcnt lgkmcnt(0)
	s_barrier
	s_setprio 1
	s_waitcnt lgkmcnt(0)
	v_mfma_f32_16x16x32_bf16 v[62:65], v[164:167], v[196:199], 0
	v_mfma_f32_16x16x32_bf16 v[54:57], v[172:175], v[196:199], 0
	v_mfma_f32_16x16x32_bf16 v[46:49], v[164:167], v[204:207], 0
	v_mfma_f32_16x16x32_bf16 v[38:41], v[172:175], v[204:207], 0
	v_mfma_f32_16x16x32_bf16 v[30:33], v[164:167], v[212:215], 0
	v_mfma_f32_16x16x32_bf16 v[22:25], v[172:175], v[212:215], 0
	v_mfma_f32_16x16x32_bf16 v[14:17], v[164:167], v[220:223], 0
	v_mfma_f32_16x16x32_bf16 v[6:9], v[172:175], v[220:223], 0
	v_mfma_f32_16x16x32_bf16 v[62:65], v[168:171], v[200:203], v[62:65]
	v_mfma_f32_16x16x32_bf16 v[54:57], v[176:179], v[200:203], v[54:57]
	v_mfma_f32_16x16x32_bf16 v[46:49], v[168:171], v[208:211], v[46:49]
	v_mfma_f32_16x16x32_bf16 v[38:41], v[176:179], v[208:211], v[38:41]
	v_mfma_f32_16x16x32_bf16 v[30:33], v[168:171], v[216:219], v[30:33]
	v_mfma_f32_16x16x32_bf16 v[22:25], v[176:179], v[216:219], v[22:25]
	v_mfma_f32_16x16x32_bf16 v[14:17], v[168:171], v[224:227], v[14:17]
	v_mfma_f32_16x16x32_bf16 v[6:9], v[176:179], v[224:227], v[6:9]
	s_setprio 0
	s_setprio 1
	v_mfma_f32_16x16x32_bf16 v[58:61], v[180:183], v[196:199], 0
	v_mfma_f32_16x16x32_bf16 v[50:53], v[188:191], v[196:199], 0
	v_mfma_f32_16x16x32_bf16 v[42:45], v[180:183], v[204:207], 0
	v_mfma_f32_16x16x32_bf16 v[34:37], v[188:191], v[204:207], 0
	v_mfma_f32_16x16x32_bf16 v[26:29], v[180:183], v[212:215], 0
	v_mfma_f32_16x16x32_bf16 v[18:21], v[188:191], v[212:215], 0
	v_mfma_f32_16x16x32_bf16 v[10:13], v[180:183], v[220:223], 0
	v_mfma_f32_16x16x32_bf16 v[2:5], v[188:191], v[220:223], 0
	v_mfma_f32_16x16x32_bf16 v[58:61], v[184:187], v[200:203], v[58:61]
	v_mfma_f32_16x16x32_bf16 v[50:53], v[192:195], v[200:203], v[50:53]
	v_mfma_f32_16x16x32_bf16 v[42:45], v[184:187], v[208:211], v[42:45]
	v_mfma_f32_16x16x32_bf16 v[34:37], v[192:195], v[208:211], v[34:37]
	v_mfma_f32_16x16x32_bf16 v[26:29], v[184:187], v[216:219], v[26:29]
	v_mfma_f32_16x16x32_bf16 v[18:21], v[192:195], v[216:219], v[18:21]
	v_mfma_f32_16x16x32_bf16 v[10:13], v[184:187], v[224:227], v[10:13]
	v_mfma_f32_16x16x32_bf16 v[2:5], v[192:195], v[224:227], v[2:5]
	s_setprio 0
	s_barrier
	s_add_u32 s98, s94, 0x40000
	s_addc_u32 s99, s95, 0
	s_add_i32 s7, 0, 0x18000
	s_add_i32 s49, 0, 0x1c000
	s_mov_b32 m0, s61
	s_nop 0
	global_load_lds_dwordx4 v130, s[98:99]
	s_mov_b32 m0, s62
	s_nop 0
	global_load_lds_dwordx4 v134, s[98:99]
	ds_read_b128 v[164:167], v232
	ds_read_b128 v[168:171], v232 offset:1024
	ds_read_b128 v[172:175], v232 offset:2048
	ds_read_b128 v[176:179], v232 offset:3072
	ds_read_b128 v[180:183], v233
	ds_read_b128 v[184:187], v233 offset:1024
	ds_read_b128 v[188:191], v233 offset:2048
	ds_read_b128 v[192:195], v233 offset:3072
	ds_read_b128 v[196:199], v160 offset:32768
	ds_read_b128 v[200:203], v160 offset:33792
	ds_read_b128 v[204:207], v160 offset:34816
	ds_read_b128 v[208:211], v160 offset:35840
	ds_read_b128 v[212:215], v160 offset:36864
	ds_read_b128 v[216:219], v160 offset:37888
	ds_read_b128 v[220:223], v160 offset:38912
	ds_read_b128 v[224:227], v160 offset:39936
	s_waitcnt vmcnt(8)
	s_waitcnt lgkmcnt(0)
	s_barrier
	s_setprio 1
	s_waitcnt lgkmcnt(0)
	v_mfma_f32_16x16x32_bf16 v[122:125], v[164:167], v[196:199], v[122:125]
	v_mfma_f32_16x16x32_bf16 v[118:121], v[172:175], v[196:199], v[118:121]
	v_mfma_f32_16x16x32_bf16 v[110:113], v[164:167], v[204:207], v[110:113]
	v_mfma_f32_16x16x32_bf16 v[102:105], v[172:175], v[204:207], v[102:105]
	v_mfma_f32_16x16x32_bf16 v[94:97], v[164:167], v[212:215], v[94:97]
	v_mfma_f32_16x16x32_bf16 v[86:89], v[172:175], v[212:215], v[86:89]
	v_mfma_f32_16x16x32_bf16 v[78:81], v[164:167], v[220:223], v[78:81]
	v_mfma_f32_16x16x32_bf16 v[70:73], v[172:175], v[220:223], v[70:73]
	v_mfma_f32_16x16x32_bf16 v[122:125], v[168:171], v[200:203], v[122:125]
	v_mfma_f32_16x16x32_bf16 v[118:121], v[176:179], v[200:203], v[118:121]
	v_mfma_f32_16x16x32_bf16 v[110:113], v[168:171], v[208:211], v[110:113]
	v_mfma_f32_16x16x32_bf16 v[102:105], v[176:179], v[208:211], v[102:105]
	v_mfma_f32_16x16x32_bf16 v[94:97], v[168:171], v[216:219], v[94:97]
	v_mfma_f32_16x16x32_bf16 v[86:89], v[176:179], v[216:219], v[86:89]
	v_mfma_f32_16x16x32_bf16 v[78:81], v[168:171], v[224:227], v[78:81]
	v_mfma_f32_16x16x32_bf16 v[70:73], v[176:179], v[224:227], v[70:73]
	s_setprio 0
	s_setprio 1
	v_mfma_f32_16x16x32_bf16 v[126:129], v[180:183], v[196:199], v[126:129]
	v_mfma_f32_16x16x32_bf16 v[114:117], v[188:191], v[196:199], v[114:117]
	v_mfma_f32_16x16x32_bf16 v[106:109], v[180:183], v[204:207], v[106:109]
	v_mfma_f32_16x16x32_bf16 v[98:101], v[188:191], v[204:207], v[98:101]
	v_mfma_f32_16x16x32_bf16 v[90:93], v[180:183], v[212:215], v[90:93]
	v_mfma_f32_16x16x32_bf16 v[82:85], v[188:191], v[212:215], v[82:85]
	v_mfma_f32_16x16x32_bf16 v[74:77], v[180:183], v[220:223], v[74:77]
	v_mfma_f32_16x16x32_bf16 v[66:69], v[188:191], v[220:223], v[66:69]
	v_mfma_f32_16x16x32_bf16 v[126:129], v[184:187], v[200:203], v[126:129]
	v_mfma_f32_16x16x32_bf16 v[114:117], v[192:195], v[200:203], v[114:117]
	v_mfma_f32_16x16x32_bf16 v[106:109], v[184:187], v[208:211], v[106:109]
	v_mfma_f32_16x16x32_bf16 v[98:101], v[192:195], v[208:211], v[98:101]
	v_mfma_f32_16x16x32_bf16 v[90:93], v[184:187], v[216:219], v[90:93]
	v_mfma_f32_16x16x32_bf16 v[82:85], v[192:195], v[216:219], v[82:85]
	v_mfma_f32_16x16x32_bf16 v[74:77], v[184:187], v[224:227], v[74:77]
	v_mfma_f32_16x16x32_bf16 v[66:69], v[192:195], v[224:227], v[66:69]
	s_setprio 0
	s_barrier
	s_add_u32 s96, s96, 0x80
	s_addc_u32 s97, s97, 0
	s_add_u32 s98, s96, 0x40000
	s_addc_u32 s99, s97, 0
	s_add_u32 s94, s94, 0x80
	s_addc_u32 s95, s95, 0
	s_add_i32 s7, s7, s29
	s_mov_b32 m0, s7
	s_nop 0
	global_load_lds_dwordx4 v132, s[96:97]
	s_add_i32 m0, s7, 0x2000
	s_add_i32 s7, s49, s29
	global_load_lds_dwordx4 v136, s[96:97]
	s_mov_b32 m0, s7
	s_nop 0
	global_load_lds_dwordx4 v132, s[98:99]
	s_add_i32 m0, s7, 0x2000
	s_nop 0
	global_load_lds_dwordx4 v136, s[98:99]
	s_mov_b32 m0, s63
	s_nop 0
	global_load_lds_dwordx4 v130, s[94:95]
	s_mov_b32 m0, s64
	s_nop 0
	global_load_lds_dwordx4 v134, s[94:95]
	ds_read_b128 v[196:199], v160 offset:49152
	ds_read_b128 v[200:203], v160 offset:50176
	ds_read_b128 v[204:207], v160 offset:51200
	ds_read_b128 v[208:211], v160 offset:52224
	ds_read_b128 v[212:215], v160 offset:53248
	ds_read_b128 v[216:219], v160 offset:54272
	ds_read_b128 v[220:223], v160 offset:55296
	ds_read_b128 v[224:227], v160 offset:56320
	s_waitcnt vmcnt(8)
	s_waitcnt lgkmcnt(0)
	s_barrier
	s_setprio 1
	s_waitcnt lgkmcnt(0)
	v_mfma_f32_16x16x32_bf16 v[62:65], v[164:167], v[196:199], v[62:65]
	v_mfma_f32_16x16x32_bf16 v[54:57], v[172:175], v[196:199], v[54:57]
	v_mfma_f32_16x16x32_bf16 v[46:49], v[164:167], v[204:207], v[46:49]
	v_mfma_f32_16x16x32_bf16 v[38:41], v[172:175], v[204:207], v[38:41]
	v_mfma_f32_16x16x32_bf16 v[30:33], v[164:167], v[212:215], v[30:33]
	v_mfma_f32_16x16x32_bf16 v[22:25], v[172:175], v[212:215], v[22:25]
	v_mfma_f32_16x16x32_bf16 v[14:17], v[164:167], v[220:223], v[14:17]
	v_mfma_f32_16x16x32_bf16 v[6:9], v[172:175], v[220:223], v[6:9]
	v_mfma_f32_16x16x32_bf16 v[62:65], v[168:171], v[200:203], v[62:65]
	v_mfma_f32_16x16x32_bf16 v[54:57], v[176:179], v[200:203], v[54:57]
	v_mfma_f32_16x16x32_bf16 v[46:49], v[168:171], v[208:211], v[46:49]
	v_mfma_f32_16x16x32_bf16 v[38:41], v[176:179], v[208:211], v[38:41]
	v_mfma_f32_16x16x32_bf16 v[30:33], v[168:171], v[216:219], v[30:33]
	v_mfma_f32_16x16x32_bf16 v[22:25], v[176:179], v[216:219], v[22:25]
	v_mfma_f32_16x16x32_bf16 v[14:17], v[168:171], v[224:227], v[14:17]
	v_mfma_f32_16x16x32_bf16 v[6:9], v[176:179], v[224:227], v[6:9]
	s_setprio 0
	s_setprio 1
	v_mfma_f32_16x16x32_bf16 v[58:61], v[180:183], v[196:199], v[58:61]
	v_mfma_f32_16x16x32_bf16 v[50:53], v[188:191], v[196:199], v[50:53]
	v_mfma_f32_16x16x32_bf16 v[42:45], v[180:183], v[204:207], v[42:45]
	v_mfma_f32_16x16x32_bf16 v[34:37], v[188:191], v[204:207], v[34:37]
	v_mfma_f32_16x16x32_bf16 v[26:29], v[180:183], v[212:215], v[26:29]
	v_mfma_f32_16x16x32_bf16 v[18:21], v[188:191], v[212:215], v[18:21]
	v_mfma_f32_16x16x32_bf16 v[10:13], v[180:183], v[220:223], v[10:13]
	v_mfma_f32_16x16x32_bf16 v[2:5], v[188:191], v[220:223], v[2:5]
	v_mfma_f32_16x16x32_bf16 v[58:61], v[184:187], v[200:203], v[58:61]
	v_mfma_f32_16x16x32_bf16 v[50:53], v[192:195], v[200:203], v[50:53]
	v_mfma_f32_16x16x32_bf16 v[42:45], v[184:187], v[208:211], v[42:45]
	v_mfma_f32_16x16x32_bf16 v[34:37], v[192:195], v[208:211], v[34:37]
	v_mfma_f32_16x16x32_bf16 v[26:29], v[184:187], v[216:219], v[26:29]
	v_mfma_f32_16x16x32_bf16 v[18:21], v[192:195], v[216:219], v[18:21]
	v_mfma_f32_16x16x32_bf16 v[10:13], v[184:187], v[224:227], v[10:13]
	v_mfma_f32_16x16x32_bf16 v[2:5], v[192:195], v[224:227], v[2:5]
	s_setprio 0
	s_barrier
	s_mov_b32 s7, s47
	s_add_u32 s88, s88, 0x100
	s_addc_u32 s89, s89, 0
	s_add_u32 s86, s86, 0x100
	s_addc_u32 s87, s87, 0
	s_cmp_ge_i32 s47, s101
	s_cbranch_scc1 .Lmy_kexit_4
.LBB0_949:
	s_add_u32 s98, s86, 0xfffc0080
	s_addc_u32 s99, s87, -1
	s_cmp_eq_u32 s7, s100
	s_cselect_b64 s[94:95], s[90:91], s[98:99]
	s_cselect_b64 s[96:97], s[92:93], s[88:89]
	s_add_i32 s47, s7, 2
	s_nop 0
	s_mov_b32 m0, s76
	s_nop 0
	global_load_lds_dwordx4 v144, s[86:87]
	s_mov_b32 m0, s77
	s_nop 0
	global_load_lds_dwordx4 v142, s[86:87]
	ds_read_b128 v[164:167], v230
	ds_read_b128 v[168:171], v230 offset:1024
	ds_read_b128 v[172:175], v230 offset:2048
	ds_read_b128 v[176:179], v230 offset:3072
	ds_read_b128 v[180:183], v231
	ds_read_b128 v[184:187], v231 offset:1024
	ds_read_b128 v[188:191], v231 offset:2048
	ds_read_b128 v[192:195], v231 offset:3072
	ds_read_b128 v[196:199], v160
	ds_read_b128 v[200:203], v160 offset:1024
	ds_read_b128 v[204:207], v160 offset:2048
	ds_read_b128 v[208:211], v160 offset:3072
	ds_read_b128 v[212:215], v160 offset:4096
	ds_read_b128 v[216:219], v160 offset:5120
	ds_read_b128 v[220:223], v160 offset:6144
	ds_read_b128 v[224:227], v160 offset:7168
	s_waitcnt vmcnt(8)
	s_waitcnt lgkmcnt(0)
	s_barrier
	s_setprio 1
	s_waitcnt lgkmcnt(0)
	v_mfma_f32_16x16x32_bf16 v[122:125], v[164:167], v[196:199], v[122:125]
	v_mfma_f32_16x16x32_bf16 v[118:121], v[172:175], v[196:199], v[118:121]
	v_mfma_f32_16x16x32_bf16 v[110:113], v[164:167], v[204:207], v[110:113]
	v_mfma_f32_16x16x32_bf16 v[102:105], v[172:175], v[204:207], v[102:105]
	v_mfma_f32_16x16x32_bf16 v[94:97], v[164:167], v[212:215], v[94:97]
	v_mfma_f32_16x16x32_bf16 v[86:89], v[172:175], v[212:215], v[86:89]
	v_mfma_f32_16x16x32_bf16 v[78:81], v[164:167], v[220:223], v[78:81]
	v_mfma_f32_16x16x32_bf16 v[70:73], v[172:175], v[220:223], v[70:73]
	v_mfma_f32_16x16x32_bf16 v[122:125], v[168:171], v[200:203], v[122:125]
	v_mfma_f32_16x16x32_bf16 v[118:121], v[176:179], v[200:203], v[118:121]
	v_mfma_f32_16x16x32_bf16 v[110:113], v[168:171], v[208:211], v[110:113]
	v_mfma_f32_16x16x32_bf16 v[102:105], v[176:179], v[208:211], v[102:105]
	v_mfma_f32_16x16x32_bf16 v[94:97], v[168:171], v[216:219], v[94:97]
	v_mfma_f32_16x16x32_bf16 v[86:89], v[176:179], v[216:219], v[86:89]
	v_mfma_f32_16x16x32_bf16 v[78:81], v[168:171], v[224:227], v[78:81]
	v_mfma_f32_16x16x32_bf16 v[70:73], v[176:179], v[224:227], v[70:73]
	s_setprio 0
	s_setprio 1
	v_mfma_f32_16x16x32_bf16 v[126:129], v[180:183], v[196:199], v[126:129]
	v_mfma_f32_16x16x32_bf16 v[114:117], v[188:191], v[196:199], v[114:117]
	v_mfma_f32_16x16x32_bf16 v[106:109], v[180:183], v[204:207], v[106:109]
	v_mfma_f32_16x16x32_bf16 v[98:101], v[188:191], v[204:207], v[98:101]
	v_mfma_f32_16x16x32_bf16 v[90:93], v[180:183], v[212:215], v[90:93]
	v_mfma_f32_16x16x32_bf16 v[82:85], v[188:191], v[212:215], v[82:85]
	v_mfma_f32_16x16x32_bf16 v[74:77], v[180:183], v[220:223], v[74:77]
	v_mfma_f32_16x16x32_bf16 v[66:69], v[188:191], v[220:223], v[66:69]
	v_mfma_f32_16x16x32_bf16 v[126:129], v[184:187], v[200:203], v[126:129]
	v_mfma_f32_16x16x32_bf16 v[114:117], v[192:195], v[200:203], v[114:117]
	v_mfma_f32_16x16x32_bf16 v[106:109], v[184:187], v[208:211], v[106:109]
	v_mfma_f32_16x16x32_bf16 v[98:101], v[192:195], v[208:211], v[98:101]
	v_mfma_f32_16x16x32_bf16 v[90:93], v[184:187], v[216:219], v[90:93]
	v_mfma_f32_16x16x32_bf16 v[82:85], v[192:195], v[216:219], v[82:85]
	v_mfma_f32_16x16x32_bf16 v[74:77], v[184:187], v[224:227], v[74:77]
	v_mfma_f32_16x16x32_bf16 v[66:69], v[192:195], v[224:227], v[66:69]
	s_setprio 0
	s_barrier
	s_add_u32 s98, s96, 0x40000
	s_addc_u32 s99, s97, 0
	s_mov_b32 m0, s78
	s_nop 0
	global_load_lds_dwordx4 v132, s[96:97]
	s_mov_b32 m0, s79
	s_add_i32 s7, s75, s29
	global_load_lds_dwordx4 v136, s[96:97]
	s_mov_b32 m0, s7
	s_nop 0
	global_load_lds_dwordx4 v132, s[98:99]
	s_add_i32 m0, s7, 0x2000
	s_nop 0
	global_load_lds_dwordx4 v136, s[98:99]
	s_mov_b32 m0, s51
	s_nop 0
	global_load_lds_dwordx4 v130, s[94:95]
	s_mov_b32 m0, s60
	s_nop 0
	global_load_lds_dwordx4 v134, s[94:95]
	ds_read_b128 v[196:199], v160 offset:16384
	ds_read_b128 v[200:203], v160 offset:17408
	ds_read_b128 v[204:207], v160 offset:18432
	ds_read_b128 v[208:211], v160 offset:19456
	ds_read_b128 v[212:215], v160 offset:20480
	ds_read_b128 v[216:219], v160 offset:21504
	ds_read_b128 v[220:223], v160 offset:22528
	ds_read_b128 v[224:227], v160 offset:23552
	s_waitcnt vmcnt(8)
	s_waitcnt lgkmcnt(0)
	s_barrier
	s_setprio 1
	s_waitcnt lgkmcnt(0)
	v_mfma_f32_16x16x32_bf16 v[62:65], v[164:167], v[196:199], v[62:65]
	v_mfma_f32_16x16x32_bf16 v[54:57], v[172:175], v[196:199], v[54:57]
	v_mfma_f32_16x16x32_bf16 v[46:49], v[164:167], v[204:207], v[46:49]
	v_mfma_f32_16x16x32_bf16 v[38:41], v[172:175], v[204:207], v[38:41]
	v_mfma_f32_16x16x32_bf16 v[30:33], v[164:167], v[212:215], v[30:33]
	v_mfma_f32_16x16x32_bf16 v[22:25], v[172:175], v[212:215], v[22:25]
	v_mfma_f32_16x16x32_bf16 v[14:17], v[164:167], v[220:223], v[14:17]
	v_mfma_f32_16x16x32_bf16 v[6:9], v[172:175], v[220:223], v[6:9]
	v_mfma_f32_16x16x32_bf16 v[62:65], v[168:171], v[200:203], v[62:65]
	v_mfma_f32_16x16x32_bf16 v[54:57], v[176:179], v[200:203], v[54:57]
	v_mfma_f32_16x16x32_bf16 v[46:49], v[168:171], v[208:211], v[46:49]
	v_mfma_f32_16x16x32_bf16 v[38:41], v[176:179], v[208:211], v[38:41]
	v_mfma_f32_16x16x32_bf16 v[30:33], v[168:171], v[216:219], v[30:33]
	v_mfma_f32_16x16x32_bf16 v[22:25], v[176:179], v[216:219], v[22:25]
	v_mfma_f32_16x16x32_bf16 v[14:17], v[168:171], v[224:227], v[14:17]
	v_mfma_f32_16x16x32_bf16 v[6:9], v[176:179], v[224:227], v[6:9]
	s_setprio 0
	s_setprio 1
	v_mfma_f32_16x16x32_bf16 v[58:61], v[180:183], v[196:199], v[58:61]
	v_mfma_f32_16x16x32_bf16 v[50:53], v[188:191], v[196:199], v[50:53]
	v_mfma_f32_16x16x32_bf16 v[42:45], v[180:183], v[204:207], v[42:45]
	v_mfma_f32_16x16x32_bf16 v[34:37], v[188:191], v[204:207], v[34:37]
	v_mfma_f32_16x16x32_bf16 v[26:29], v[180:183], v[212:215], v[26:29]
	v_mfma_f32_16x16x32_bf16 v[18:21], v[188:191], v[212:215], v[18:21]
	v_mfma_f32_16x16x32_bf16 v[10:13], v[180:183], v[220:223], v[10:13]
	v_mfma_f32_16x16x32_bf16 v[2:5], v[188:191], v[220:223], v[2:5]
	v_mfma_f32_16x16x32_bf16 v[58:61], v[184:187], v[200:203], v[58:61]
	v_mfma_f32_16x16x32_bf16 v[50:53], v[192:195], v[200:203], v[50:53]
	v_mfma_f32_16x16x32_bf16 v[42:45], v[184:187], v[208:211], v[42:45]
	v_mfma_f32_16x16x32_bf16 v[34:37], v[192:195], v[208:211], v[34:37]
	v_mfma_f32_16x16x32_bf16 v[26:29], v[184:187], v[216:219], v[26:29]
	v_mfma_f32_16x16x32_bf16 v[18:21], v[192:195], v[216:219], v[18:21]
	v_mfma_f32_16x16x32_bf16 v[10:13], v[184:187], v[224:227], v[10:13]
	v_mfma_f32_16x16x32_bf16 v[2:5], v[192:195], v[224:227], v[2:5]
	s_setprio 0
	s_barrier
	s_add_u32 s98, s94, 0x40000
	s_addc_u32 s99, s95, 0
	s_add_i32 s7, 0, 0x18000
	s_add_i32 s49, 0, 0x1c000
	s_mov_b32 m0, s61
	s_nop 0
	global_load_lds_dwordx4 v130, s[98:99]
	s_mov_b32 m0, s62
	s_nop 0
	global_load_lds_dwordx4 v134, s[98:99]
	ds_read_b128 v[164:167], v232
	ds_read_b128 v[168:171], v232 offset:1024
	ds_read_b128 v[172:175], v232 offset:2048
	ds_read_b128 v[176:179], v232 offset:3072
	ds_read_b128 v[180:183], v233
	ds_read_b128 v[184:187], v233 offset:1024
	ds_read_b128 v[188:191], v233 offset:2048
	ds_read_b128 v[192:195], v233 offset:3072
	ds_read_b128 v[196:199], v160 offset:32768
	ds_read_b128 v[200:203], v160 offset:33792
	ds_read_b128 v[204:207], v160 offset:34816
	ds_read_b128 v[208:211], v160 offset:35840
	ds_read_b128 v[212:215], v160 offset:36864
	ds_read_b128 v[216:219], v160 offset:37888
	ds_read_b128 v[220:223], v160 offset:38912
	ds_read_b128 v[224:227], v160 offset:39936
	s_waitcnt vmcnt(8)
	s_waitcnt lgkmcnt(0)
	s_barrier
	s_setprio 1
	s_waitcnt lgkmcnt(0)
	v_mfma_f32_16x16x32_bf16 v[122:125], v[164:167], v[196:199], v[122:125]
	v_mfma_f32_16x16x32_bf16 v[118:121], v[172:175], v[196:199], v[118:121]
	v_mfma_f32_16x16x32_bf16 v[110:113], v[164:167], v[204:207], v[110:113]
	v_mfma_f32_16x16x32_bf16 v[102:105], v[172:175], v[204:207], v[102:105]
	v_mfma_f32_16x16x32_bf16 v[94:97], v[164:167], v[212:215], v[94:97]
	v_mfma_f32_16x16x32_bf16 v[86:89], v[172:175], v[212:215], v[86:89]
	v_mfma_f32_16x16x32_bf16 v[78:81], v[164:167], v[220:223], v[78:81]
	v_mfma_f32_16x16x32_bf16 v[70:73], v[172:175], v[220:223], v[70:73]
	v_mfma_f32_16x16x32_bf16 v[122:125], v[168:171], v[200:203], v[122:125]
	v_mfma_f32_16x16x32_bf16 v[118:121], v[176:179], v[200:203], v[118:121]
	v_mfma_f32_16x16x32_bf16 v[110:113], v[168:171], v[208:211], v[110:113]
	v_mfma_f32_16x16x32_bf16 v[102:105], v[176:179], v[208:211], v[102:105]
	v_mfma_f32_16x16x32_bf16 v[94:97], v[168:171], v[216:219], v[94:97]
	v_mfma_f32_16x16x32_bf16 v[86:89], v[176:179], v[216:219], v[86:89]
	v_mfma_f32_16x16x32_bf16 v[78:81], v[168:171], v[224:227], v[78:81]
	v_mfma_f32_16x16x32_bf16 v[70:73], v[176:179], v[224:227], v[70:73]
	s_setprio 0
	s_setprio 1
	v_mfma_f32_16x16x32_bf16 v[126:129], v[180:183], v[196:199], v[126:129]
	v_mfma_f32_16x16x32_bf16 v[114:117], v[188:191], v[196:199], v[114:117]
	v_mfma_f32_16x16x32_bf16 v[106:109], v[180:183], v[204:207], v[106:109]
	v_mfma_f32_16x16x32_bf16 v[98:101], v[188:191], v[204:207], v[98:101]
	v_mfma_f32_16x16x32_bf16 v[90:93], v[180:183], v[212:215], v[90:93]
	v_mfma_f32_16x16x32_bf16 v[82:85], v[188:191], v[212:215], v[82:85]
	v_mfma_f32_16x16x32_bf16 v[74:77], v[180:183], v[220:223], v[74:77]
	v_mfma_f32_16x16x32_bf16 v[66:69], v[188:191], v[220:223], v[66:69]
	v_mfma_f32_16x16x32_bf16 v[126:129], v[184:187], v[200:203], v[126:129]
	v_mfma_f32_16x16x32_bf16 v[114:117], v[192:195], v[200:203], v[114:117]
	v_mfma_f32_16x16x32_bf16 v[106:109], v[184:187], v[208:211], v[106:109]
	v_mfma_f32_16x16x32_bf16 v[98:101], v[192:195], v[208:211], v[98:101]
	v_mfma_f32_16x16x32_bf16 v[90:93], v[184:187], v[216:219], v[90:93]
	v_mfma_f32_16x16x32_bf16 v[82:85], v[192:195], v[216:219], v[82:85]
	v_mfma_f32_16x16x32_bf16 v[74:77], v[184:187], v[224:227], v[74:77]
	v_mfma_f32_16x16x32_bf16 v[66:69], v[192:195], v[224:227], v[66:69]
	s_setprio 0
	s_barrier
	s_add_u32 s96, s96, 0x80
	s_addc_u32 s97, s97, 0
	s_add_u32 s98, s96, 0x40000
	s_addc_u32 s99, s97, 0
	s_add_u32 s94, s94, 0x80
	s_addc_u32 s95, s95, 0
	s_add_i32 s7, s7, s29
	s_mov_b32 m0, s7
	s_nop 0
	global_load_lds_dwordx4 v132, s[96:97]
	s_add_i32 m0, s7, 0x2000
	s_add_i32 s7, s49, s29
	global_load_lds_dwordx4 v136, s[96:97]
	s_mov_b32 m0, s7
	s_nop 0
	global_load_lds_dwordx4 v132, s[98:99]
	s_add_i32 m0, s7, 0x2000
	s_nop 0
	global_load_lds_dwordx4 v136, s[98:99]
	s_mov_b32 m0, s63
	s_nop 0
	global_load_lds_dwordx4 v130, s[94:95]
	s_mov_b32 m0, s64
	s_nop 0
	global_load_lds_dwordx4 v134, s[94:95]
	ds_read_b128 v[196:199], v160 offset:49152
	ds_read_b128 v[200:203], v160 offset:50176
	ds_read_b128 v[204:207], v160 offset:51200
	ds_read_b128 v[208:211], v160 offset:52224
	ds_read_b128 v[212:215], v160 offset:53248
	ds_read_b128 v[216:219], v160 offset:54272
	ds_read_b128 v[220:223], v160 offset:55296
	ds_read_b128 v[224:227], v160 offset:56320
	s_waitcnt vmcnt(8)
	s_waitcnt lgkmcnt(0)
	s_barrier
	s_setprio 1
	s_waitcnt lgkmcnt(0)
	v_mfma_f32_16x16x32_bf16 v[62:65], v[164:167], v[196:199], v[62:65]
	v_mfma_f32_16x16x32_bf16 v[54:57], v[172:175], v[196:199], v[54:57]
	v_mfma_f32_16x16x32_bf16 v[46:49], v[164:167], v[204:207], v[46:49]
	v_mfma_f32_16x16x32_bf16 v[38:41], v[172:175], v[204:207], v[38:41]
	v_mfma_f32_16x16x32_bf16 v[30:33], v[164:167], v[212:215], v[30:33]
	v_mfma_f32_16x16x32_bf16 v[22:25], v[172:175], v[212:215], v[22:25]
	v_mfma_f32_16x16x32_bf16 v[14:17], v[164:167], v[220:223], v[14:17]
	v_mfma_f32_16x16x32_bf16 v[6:9], v[172:175], v[220:223], v[6:9]
	v_mfma_f32_16x16x32_bf16 v[62:65], v[168:171], v[200:203], v[62:65]
	v_mfma_f32_16x16x32_bf16 v[54:57], v[176:179], v[200:203], v[54:57]
	v_mfma_f32_16x16x32_bf16 v[46:49], v[168:171], v[208:211], v[46:49]
	v_mfma_f32_16x16x32_bf16 v[38:41], v[176:179], v[208:211], v[38:41]
	v_mfma_f32_16x16x32_bf16 v[30:33], v[168:171], v[216:219], v[30:33]
	v_mfma_f32_16x16x32_bf16 v[22:25], v[176:179], v[216:219], v[22:25]
	v_mfma_f32_16x16x32_bf16 v[14:17], v[168:171], v[224:227], v[14:17]
	v_mfma_f32_16x16x32_bf16 v[6:9], v[176:179], v[224:227], v[6:9]
	s_setprio 0
	s_setprio 1
	v_mfma_f32_16x16x32_bf16 v[58:61], v[180:183], v[196:199], v[58:61]
	v_mfma_f32_16x16x32_bf16 v[50:53], v[188:191], v[196:199], v[50:53]
	v_mfma_f32_16x16x32_bf16 v[42:45], v[180:183], v[204:207], v[42:45]
	v_mfma_f32_16x16x32_bf16 v[34:37], v[188:191], v[204:207], v[34:37]
	v_mfma_f32_16x16x32_bf16 v[26:29], v[180:183], v[212:215], v[26:29]
	v_mfma_f32_16x16x32_bf16 v[18:21], v[188:191], v[212:215], v[18:21]
	v_mfma_f32_16x16x32_bf16 v[10:13], v[180:183], v[220:223], v[10:13]
	v_mfma_f32_16x16x32_bf16 v[2:5], v[188:191], v[220:223], v[2:5]
	v_mfma_f32_16x16x32_bf16 v[58:61], v[184:187], v[200:203], v[58:61]
	v_mfma_f32_16x16x32_bf16 v[50:53], v[192:195], v[200:203], v[50:53]
	v_mfma_f32_16x16x32_bf16 v[42:45], v[184:187], v[208:211], v[42:45]
	v_mfma_f32_16x16x32_bf16 v[34:37], v[192:195], v[208:211], v[34:37]
	v_mfma_f32_16x16x32_bf16 v[26:29], v[184:187], v[216:219], v[26:29]
	v_mfma_f32_16x16x32_bf16 v[18:21], v[192:195], v[216:219], v[18:21]
	v_mfma_f32_16x16x32_bf16 v[10:13], v[184:187], v[224:227], v[10:13]
	v_mfma_f32_16x16x32_bf16 v[2:5], v[192:195], v[224:227], v[2:5]
	s_setprio 0
	s_barrier
	s_mov_b32 s7, s47
	s_add_u32 s88, s88, 0x100
	s_addc_u32 s89, s89, 0
	s_add_u32 s86, s86, 0x100
	s_addc_u32 s87, s87, 0
	s_cmp_ge_i32 s47, s101
	s_cbranch_scc0 .LBB0_949

.LBB0_1078:
	v_cmp_gt_i32_e32 vcc, 1, v156
	s_cbranch_vccnz .LBB0_1140
	v_lshl_add_u64 v[152:153], v[2:3], 0, s[20:21]
	v_add_u32_e32 v138, -2, v156
	s_mov_b32 s6, 0
	s_nop 0
	v_readfirstlane_b32 s86, v150
	v_readfirstlane_b32 s87, v151
	v_readfirstlane_b32 s88, v152
	v_readfirstlane_b32 s89, v153
	v_readfirstlane_b32 s90, v146
	v_readfirstlane_b32 s91, v147
	v_readfirstlane_b32 s92, v148
	v_readfirstlane_b32 s93, v149
	v_readfirstlane_b32 s100, v138
	v_readfirstlane_b32 s101, v156
	v_add_u32_e32 v230, s67, v141
	v_add_u32_e32 v231, s68, v141
	v_add_u32_e32 v232, 0x18000, v141
	v_add_u32_e32 v233, 0x1c000, v141
	s_add_u32 s98, s86, 0x100
	s_addc_u32 s99, s87, 0
	s_cmp_eq_u32 s6, s100
	s_cselect_b64 s[94:95], s[90:91], s[98:99]
	s_cselect_b64 s[96:97], s[92:93], s[88:89]
	s_add_i32 s7, s6, 2
	s_nop 0
	s_add_i32 m0, s46, 0xc000
	s_nop 0
	global_load_lds_dwordx4 v144, s[86:87]
	s_add_i32 m0, s46, 0xe000
	s_nop 0
	global_load_lds_dwordx4 v142, s[86:87]
	ds_read_b128 v[164:167], v230
	ds_read_b128 v[168:171], v230 offset:1024
	ds_read_b128 v[172:175], v230 offset:2048
	ds_read_b128 v[176:179], v230 offset:3072
	ds_read_b128 v[180:183], v231
	ds_read_b128 v[184:187], v231 offset:1024
	ds_read_b128 v[188:191], v231 offset:2048
	ds_read_b128 v[192:195], v231 offset:3072
	ds_read_b128 v[196:199], v160
	ds_read_b128 v[200:203], v160 offset:1024
	ds_read_b128 v[204:207], v160 offset:2048
	ds_read_b128 v[208:211], v160 offset:3072
	ds_read_b128 v[212:215], v160 offset:4096
	ds_read_b128 v[216:219], v160 offset:5120
	ds_read_b128 v[220:223], v160 offset:6144
	ds_read_b128 v[224:227], v160 offset:7168
	s_waitcnt vmcnt(8)
	s_waitcnt lgkmcnt(0)
	s_barrier
	s_setprio 1
	s_waitcnt lgkmcnt(0)
	v_mfma_f32_16x16x32_bf16 v[122:125], v[164:167], v[196:199], 0
	v_mfma_f32_16x16x32_bf16 v[118:121], v[172:175], v[196:199], 0
	v_mfma_f32_16x16x32_bf16 v[110:113], v[164:167], v[204:207], 0
	v_mfma_f32_16x16x32_bf16 v[102:105], v[172:175], v[204:207], 0
	v_mfma_f32_16x16x32_bf16 v[94:97], v[164:167], v[212:215], 0
	v_mfma_f32_16x16x32_bf16 v[86:89], v[172:175], v[212:215], 0
	v_mfma_f32_16x16x32_bf16 v[78:81], v[164:167], v[220:223], 0
	v_mfma_f32_16x16x32_bf16 v[70:73], v[172:175], v[220:223], 0
	v_mfma_f32_16x16x32_bf16 v[122:125], v[168:171], v[200:203], v[122:125]
	v_mfma_f32_16x16x32_bf16 v[118:121], v[176:179], v[200:203], v[118:121]
	v_mfma_f32_16x16x32_bf16 v[110:113], v[168:171], v[208:211], v[110:113]
	v_mfma_f32_16x16x32_bf16 v[102:105], v[176:179], v[208:211], v[102:105]
	v_mfma_f32_16x16x32_bf16 v[94:97], v[168:171], v[216:219], v[94:97]
	v_mfma_f32_16x16x32_bf16 v[86:89], v[176:179], v[216:219], v[86:89]
	v_mfma_f32_16x16x32_bf16 v[78:81], v[168:171], v[224:227], v[78:81]
	v_mfma_f32_16x16x32_bf16 v[70:73], v[176:179], v[224:227], v[70:73]
	s_setprio 0
	s_setprio 1
	v_mfma_f32_16x16x32_bf16 v[126:129], v[180:183], v[196:199], 0
	v_mfma_f32_16x16x32_bf16 v[114:117], v[188:191], v[196:199], 0
	v_mfma_f32_16x16x32_bf16 v[106:109], v[180:183], v[204:207], 0
	v_mfma_f32_16x16x32_bf16 v[98:101], v[188:191], v[204:207], 0
	v_mfma_f32_16x16x32_bf16 v[90:93], v[180:183], v[212:215], 0
	v_mfma_f32_16x16x32_bf16 v[82:85], v[188:191], v[212:215], 0
	v_mfma_f32_16x16x32_bf16 v[74:77], v[180:183], v[220:223], 0
	v_mfma_f32_16x16x32_bf16 v[66:69], v[188:191], v[220:223], 0
	v_mfma_f32_16x16x32_bf16 v[126:129], v[184:187], v[200:203], v[126:129]
	v_mfma_f32_16x16x32_bf16 v[114:117], v[192:195], v[200:203], v[114:117]
	v_mfma_f32_16x16x32_bf16 v[106:109], v[184:187], v[208:211], v[106:109]
	v_mfma_f32_16x16x32_bf16 v[98:101], v[192:195], v[208:211], v[98:101]
	v_mfma_f32_16x16x32_bf16 v[90:93], v[184:187], v[216:219], v[90:93]
	v_mfma_f32_16x16x32_bf16 v[82:85], v[192:195], v[216:219], v[82:85]
	v_mfma_f32_16x16x32_bf16 v[74:77], v[184:187], v[224:227], v[74:77]
	v_mfma_f32_16x16x32_bf16 v[66:69], v[192:195], v[224:227], v[66:69]
	s_setprio 0
	s_barrier
	s_add_u32 s98, s96, 0xb0000
	s_addc_u32 s99, s97, 0
	s_add_i32 s6, s67, s23
	s_mov_b32 m0, s6
	s_nop 0
	global_load_lds_dwordx4 v132, s[96:97]
	s_add_i32 m0, s6, 0x2000
	s_add_i32 s6, s68, s23
	global_load_lds_dwordx4 v136, s[96:97]
	s_mov_b32 m0, s6
	s_nop 0
	global_load_lds_dwordx4 v132, s[98:99]
	s_add_i32 m0, s6, 0x2000
	s_nop 0
	global_load_lds_dwordx4 v136, s[98:99]
	s_mov_b32 m0, s46
	s_nop 0
	global_load_lds_dwordx4 v130, s[94:95]
	s_mov_b32 m0, s47
	s_nop 0
	global_load_lds_dwordx4 v134, s[94:95]
	ds_read_b128 v[196:199], v160 offset:16384
	ds_read_b128 v[200:203], v160 offset:17408
	ds_read_b128 v[204:207], v160 offset:18432
	ds_read_b128 v[208:211], v160 offset:19456
	ds_read_b128 v[212:215], v160 offset:20480
	ds_read_b128 v[216:219], v160 offset:21504
	ds_read_b128 v[220:223], v160 offset:22528
	ds_read_b128 v[224:227], v160 offset:23552
	s_waitcnt vmcnt(8)
	s_waitcnt lgkmcnt(0)
	s_barrier
	s_setprio 1
	s_waitcnt lgkmcnt(0)
	v_mfma_f32_16x16x32_bf16 v[62:65], v[164:167], v[196:199], 0
	v_mfma_f32_16x16x32_bf16 v[54:57], v[172:175], v[196:199], 0
	v_mfma_f32_16x16x32_bf16 v[46:49], v[164:167], v[204:207], 0
	v_mfma_f32_16x16x32_bf16 v[38:41], v[172:175], v[204:207], 0
	v_mfma_f32_16x16x32_bf16 v[30:33], v[164:167], v[212:215], 0
	v_mfma_f32_16x16x32_bf16 v[22:25], v[172:175], v[212:215], 0
	v_mfma_f32_16x16x32_bf16 v[14:17], v[164:167], v[220:223], 0
	v_mfma_f32_16x16x32_bf16 v[6:9], v[172:175], v[220:223], 0
	v_mfma_f32_16x16x32_bf16 v[62:65], v[168:171], v[200:203], v[62:65]
	v_mfma_f32_16x16x32_bf16 v[54:57], v[176:179], v[200:203], v[54:57]
	v_mfma_f32_16x16x32_bf16 v[46:49], v[168:171], v[208:211], v[46:49]
	v_mfma_f32_16x16x32_bf16 v[38:41], v[176:179], v[208:211], v[38:41]
	v_mfma_f32_16x16x32_bf16 v[30:33], v[168:171], v[216:219], v[30:33]
	v_mfma_f32_16x16x32_bf16 v[22:25], v[176:179], v[216:219], v[22:25]
	v_mfma_f32_16x16x32_bf16 v[14:17], v[168:171], v[224:227], v[14:17]
	v_mfma_f32_16x16x32_bf16 v[6:9], v[176:179], v[224:227], v[6:9]
	s_setprio 0
	s_setprio 1
	v_mfma_f32_16x16x32_bf16 v[58:61], v[180:183], v[196:199], 0
	v_mfma_f32_16x16x32_bf16 v[50:53], v[188:191], v[196:199], 0
	v_mfma_f32_16x16x32_bf16 v[42:45], v[180:183], v[204:207], 0
	v_mfma_f32_16x16x32_bf16 v[34:37], v[188:191], v[204:207], 0
	v_mfma_f32_16x16x32_bf16 v[26:29], v[180:183], v[212:215], 0
	v_mfma_f32_16x16x32_bf16 v[18:21], v[188:191], v[212:215], 0
	v_mfma_f32_16x16x32_bf16 v[10:13], v[180:183], v[220:223], 0
	v_mfma_f32_16x16x32_bf16 v[2:5], v[188:191], v[220:223], 0
	v_mfma_f32_16x16x32_bf16 v[58:61], v[184:187], v[200:203], v[58:61]
	v_mfma_f32_16x16x32_bf16 v[50:53], v[192:195], v[200:203], v[50:53]
	v_mfma_f32_16x16x32_bf16 v[42:45], v[184:187], v[208:211], v[42:45]
	v_mfma_f32_16x16x32_bf16 v[34:37], v[192:195], v[208:211], v[34:37]
	v_mfma_f32_16x16x32_bf16 v[26:29], v[184:187], v[216:219], v[26:29]
	v_mfma_f32_16x16x32_bf16 v[18:21], v[192:195], v[216:219], v[18:21]
	v_mfma_f32_16x16x32_bf16 v[10:13], v[184:187], v[224:227], v[10:13]
	v_mfma_f32_16x16x32_bf16 v[2:5], v[192:195], v[224:227], v[2:5]
	s_setprio 0
	s_barrier
	s_add_u32 s98, s94, 0xb0000
	s_addc_u32 s99, s95, 0
	s_add_i32 s6, 0, 0x18000
	s_add_i32 s29, 0, 0x1c000
	s_mov_b32 m0, s48
	s_nop 0
	global_load_lds_dwordx4 v130, s[98:99]
	s_mov_b32 m0, s49
	s_nop 0
	global_load_lds_dwordx4 v134, s[98:99]
	ds_read_b128 v[164:167], v232
	ds_read_b128 v[168:171], v232 offset:1024
	ds_read_b128 v[172:175], v232 offset:2048
	ds_read_b128 v[176:179], v232 offset:3072
	ds_read_b128 v[180:183], v233
	ds_read_b128 v[184:187], v233 offset:1024
	ds_read_b128 v[188:191], v233 offset:2048
	ds_read_b128 v[192:195], v233 offset:3072
	ds_read_b128 v[196:199], v160 offset:32768
	ds_read_b128 v[200:203], v160 offset:33792
	ds_read_b128 v[204:207], v160 offset:34816
	ds_read_b128 v[208:211], v160 offset:35840
	ds_read_b128 v[212:215], v160 offset:36864
	ds_read_b128 v[216:219], v160 offset:37888
	ds_read_b128 v[220:223], v160 offset:38912
	ds_read_b128 v[224:227], v160 offset:39936
	s_waitcnt vmcnt(8)
	s_waitcnt lgkmcnt(0)
	s_barrier
	s_setprio 1
	s_waitcnt lgkmcnt(0)
	v_mfma_f32_16x16x32_bf16 v[122:125], v[164:167], v[196:199], v[122:125]
	v_mfma_f32_16x16x32_bf16 v[118:121], v[172:175], v[196:199], v[118:121]
	v_mfma_f32_16x16x32_bf16 v[110:113], v[164:167], v[204:207], v[110:113]
	v_mfma_f32_16x16x32_bf16 v[102:105], v[172:175], v[204:207], v[102:105]
	v_mfma_f32_16x16x32_bf16 v[94:97], v[164:167], v[212:215], v[94:97]
	v_mfma_f32_16x16x32_bf16 v[86:89], v[172:175], v[212:215], v[86:89]
	v_mfma_f32_16x16x32_bf16 v[78:81], v[164:167], v[220:223], v[78:81]
	v_mfma_f32_16x16x32_bf16 v[70:73], v[172:175], v[220:223], v[70:73]
	v_mfma_f32_16x16x32_bf16 v[122:125], v[168:171], v[200:203], v[122:125]
	v_mfma_f32_16x16x32_bf16 v[118:121], v[176:179], v[200:203], v[118:121]
	v_mfma_f32_16x16x32_bf16 v[110:113], v[168:171], v[208:211], v[110:113]
	v_mfma_f32_16x16x32_bf16 v[102:105], v[176:179], v[208:211], v[102:105]
	v_mfma_f32_16x16x32_bf16 v[94:97], v[168:171], v[216:219], v[94:97]
	v_mfma_f32_16x16x32_bf16 v[86:89], v[176:179], v[216:219], v[86:89]
	v_mfma_f32_16x16x32_bf16 v[78:81], v[168:171], v[224:227], v[78:81]
	v_mfma_f32_16x16x32_bf16 v[70:73], v[176:179], v[224:227], v[70:73]
	s_setprio 0
	s_setprio 1
	v_mfma_f32_16x16x32_bf16 v[126:129], v[180:183], v[196:199], v[126:129]
	v_mfma_f32_16x16x32_bf16 v[114:117], v[188:191], v[196:199], v[114:117]
	v_mfma_f32_16x16x32_bf16 v[106:109], v[180:183], v[204:207], v[106:109]
	v_mfma_f32_16x16x32_bf16 v[98:101], v[188:191], v[204:207], v[98:101]
	v_mfma_f32_16x16x32_bf16 v[90:93], v[180:183], v[212:215], v[90:93]
	v_mfma_f32_16x16x32_bf16 v[82:85], v[188:191], v[212:215], v[82:85]
	v_mfma_f32_16x16x32_bf16 v[74:77], v[180:183], v[220:223], v[74:77]
	v_mfma_f32_16x16x32_bf16 v[66:69], v[188:191], v[220:223], v[66:69]
	v_mfma_f32_16x16x32_bf16 v[126:129], v[184:187], v[200:203], v[126:129]
	v_mfma_f32_16x16x32_bf16 v[114:117], v[192:195], v[200:203], v[114:117]
	v_mfma_f32_16x16x32_bf16 v[106:109], v[184:187], v[208:211], v[106:109]
	v_mfma_f32_16x16x32_bf16 v[98:101], v[192:195], v[208:211], v[98:101]
	v_mfma_f32_16x16x32_bf16 v[90:93], v[184:187], v[216:219], v[90:93]
	v_mfma_f32_16x16x32_bf16 v[82:85], v[192:195], v[216:219], v[82:85]
	v_mfma_f32_16x16x32_bf16 v[74:77], v[184:187], v[224:227], v[74:77]
	v_mfma_f32_16x16x32_bf16 v[66:69], v[192:195], v[224:227], v[66:69]
	s_setprio 0
	s_barrier
	s_add_u32 s96, s96, 0x80
	s_addc_u32 s97, s97, 0
	s_add_u32 s98, s96, 0xb0000
	s_addc_u32 s99, s97, 0
	s_add_u32 s94, s94, 0x80
	s_addc_u32 s95, s95, 0
	s_add_i32 s6, s6, s23
	s_mov_b32 m0, s6
	s_nop 0
	global_load_lds_dwordx4 v132, s[96:97]
	s_add_i32 m0, s6, 0x2000
	s_add_i32 s6, s29, s23
	global_load_lds_dwordx4 v136, s[96:97]
	s_mov_b32 m0, s6
	s_nop 0
	global_load_lds_dwordx4 v132, s[98:99]
	s_add_i32 m0, s6, 0x2000
	s_nop 0
	global_load_lds_dwordx4 v136, s[98:99]
	s_mov_b32 m0, s59
	s_nop 0
	global_load_lds_dwordx4 v130, s[94:95]
	s_mov_b32 m0, s60
	s_nop 0
	global_load_lds_dwordx4 v134, s[94:95]
	ds_read_b128 v[196:199], v160 offset:49152
	ds_read_b128 v[200:203], v160 offset:50176
	ds_read_b128 v[204:207], v160 offset:51200
	ds_read_b128 v[208:211], v160 offset:52224
	ds_read_b128 v[212:215], v160 offset:53248
	ds_read_b128 v[216:219], v160 offset:54272
	ds_read_b128 v[220:223], v160 offset:55296
	ds_read_b128 v[224:227], v160 offset:56320
	s_waitcnt vmcnt(8)
	s_waitcnt lgkmcnt(0)
	s_barrier
	s_setprio 1
	s_waitcnt lgkmcnt(0)
	v_mfma_f32_16x16x32_bf16 v[62:65], v[164:167], v[196:199], v[62:65]
	v_mfma_f32_16x16x32_bf16 v[54:57], v[172:175], v[196:199], v[54:57]
	v_mfma_f32_16x16x32_bf16 v[46:49], v[164:167], v[204:207], v[46:49]
	v_mfma_f32_16x16x32_bf16 v[38:41], v[172:175], v[204:207], v[38:41]
	v_mfma_f32_16x16x32_bf16 v[30:33], v[164:167], v[212:215], v[30:33]
	v_mfma_f32_16x16x32_bf16 v[22:25], v[172:175], v[212:215], v[22:25]
	v_mfma_f32_16x16x32_bf16 v[14:17], v[164:167], v[220:223], v[14:17]
	v_mfma_f32_16x16x32_bf16 v[6:9], v[172:175], v[220:223], v[6:9]
	v_mfma_f32_16x16x32_bf16 v[62:65], v[168:171], v[200:203], v[62:65]
	v_mfma_f32_16x16x32_bf16 v[54:57], v[176:179], v[200:203], v[54:57]
	v_mfma_f32_16x16x32_bf16 v[46:49], v[168:171], v[208:211], v[46:49]
	v_mfma_f32_16x16x32_bf16 v[38:41], v[176:179], v[208:211], v[38:41]
	v_mfma_f32_16x16x32_bf16 v[30:33], v[168:171], v[216:219], v[30:33]
	v_mfma_f32_16x16x32_bf16 v[22:25], v[176:179], v[216:219], v[22:25]
	v_mfma_f32_16x16x32_bf16 v[14:17], v[168:171], v[224:227], v[14:17]
	v_mfma_f32_16x16x32_bf16 v[6:9], v[176:179], v[224:227], v[6:9]
	s_setprio 0
	s_setprio 1
	v_mfma_f32_16x16x32_bf16 v[58:61], v[180:183], v[196:199], v[58:61]
	v_mfma_f32_16x16x32_bf16 v[50:53], v[188:191], v[196:199], v[50:53]
	v_mfma_f32_16x16x32_bf16 v[42:45], v[180:183], v[204:207], v[42:45]
	v_mfma_f32_16x16x32_bf16 v[34:37], v[188:191], v[204:207], v[34:37]
	v_mfma_f32_16x16x32_bf16 v[26:29], v[180:183], v[212:215], v[26:29]
	v_mfma_f32_16x16x32_bf16 v[18:21], v[188:191], v[212:215], v[18:21]
	v_mfma_f32_16x16x32_bf16 v[10:13], v[180:183], v[220:223], v[10:13]
	v_mfma_f32_16x16x32_bf16 v[2:5], v[188:191], v[220:223], v[2:5]
	v_mfma_f32_16x16x32_bf16 v[58:61], v[184:187], v[200:203], v[58:61]
	v_mfma_f32_16x16x32_bf16 v[50:53], v[192:195], v[200:203], v[50:53]
	v_mfma_f32_16x16x32_bf16 v[42:45], v[184:187], v[208:211], v[42:45]
	v_mfma_f32_16x16x32_bf16 v[34:37], v[192:195], v[208:211], v[34:37]
	v_mfma_f32_16x16x32_bf16 v[26:29], v[184:187], v[216:219], v[26:29]
	v_mfma_f32_16x16x32_bf16 v[18:21], v[192:195], v[216:219], v[18:21]
	v_mfma_f32_16x16x32_bf16 v[10:13], v[184:187], v[224:227], v[10:13]
	v_mfma_f32_16x16x32_bf16 v[2:5], v[192:195], v[224:227], v[2:5]
	s_setprio 0
	s_barrier
	s_mov_b32 s6, s7
	s_add_u32 s88, s88, 0x100
	s_addc_u32 s89, s89, 0
	s_add_u32 s86, s86, 0x100
	s_addc_u32 s87, s87, 0
	s_cmp_ge_i32 s7, s101
	s_cbranch_scc1 .Lmy_kexit_5
.LBB0_1080:
	s_add_u32 s98, s86, 0x100
	s_addc_u32 s99, s87, 0
	s_cmp_eq_u32 s6, s100
	s_cselect_b64 s[94:95], s[90:91], s[98:99]
	s_cselect_b64 s[96:97], s[92:93], s[88:89]
	s_add_i32 s7, s6, 2
	s_nop 0
	s_add_i32 m0, s46, 0xc000
	s_nop 0
	global_load_lds_dwordx4 v144, s[86:87]
	s_add_i32 m0, s46, 0xe000
	s_nop 0
	global_load_lds_dwordx4 v142, s[86:87]
	ds_read_b128 v[164:167], v230
	ds_read_b128 v[168:171], v230 offset:1024
	ds_read_b128 v[172:175], v230 offset:2048
	ds_read_b128 v[176:179], v230 offset:3072
	ds_read_b128 v[180:183], v231
	ds_read_b128 v[184:187], v231 offset:1024
	ds_read_b128 v[188:191], v231 offset:2048
	ds_read_b128 v[192:195], v231 offset:3072
	ds_read_b128 v[196:199], v160
	ds_read_b128 v[200:203], v160 offset:1024
	ds_read_b128 v[204:207], v160 offset:2048
	ds_read_b128 v[208:211], v160 offset:3072
	ds_read_b128 v[212:215], v160 offset:4096
	ds_read_b128 v[216:219], v160 offset:5120
	ds_read_b128 v[220:223], v160 offset:6144
	ds_read_b128 v[224:227], v160 offset:7168
	s_waitcnt vmcnt(8)
	s_waitcnt lgkmcnt(0)
	s_barrier
	s_setprio 1
	s_waitcnt lgkmcnt(0)
	v_mfma_f32_16x16x32_bf16 v[122:125], v[164:167], v[196:199], v[122:125]
	v_mfma_f32_16x16x32_bf16 v[118:121], v[172:175], v[196:199], v[118:121]
	v_mfma_f32_16x16x32_bf16 v[110:113], v[164:167], v[204:207], v[110:113]
	v_mfma_f32_16x16x32_bf16 v[102:105], v[172:175], v[204:207], v[102:105]
	v_mfma_f32_16x16x32_bf16 v[94:97], v[164:167], v[212:215], v[94:97]
	v_mfma_f32_16x16x32_bf16 v[86:89], v[172:175], v[212:215], v[86:89]
	v_mfma_f32_16x16x32_bf16 v[78:81], v[164:167], v[220:223], v[78:81]
	v_mfma_f32_16x16x32_bf16 v[70:73], v[172:175], v[220:223], v[70:73]
	v_mfma_f32_16x16x32_bf16 v[122:125], v[168:171], v[200:203], v[122:125]
	v_mfma_f32_16x16x32_bf16 v[118:121], v[176:179], v[200:203], v[118:121]
	v_mfma_f32_16x16x32_bf16 v[110:113], v[168:171], v[208:211], v[110:113]
	v_mfma_f32_16x16x32_bf16 v[102:105], v[176:179], v[208:211], v[102:105]
	v_mfma_f32_16x16x32_bf16 v[94:97], v[168:171], v[216:219], v[94:97]
	v_mfma_f32_16x16x32_bf16 v[86:89], v[176:179], v[216:219], v[86:89]
	v_mfma_f32_16x16x32_bf16 v[78:81], v[168:171], v[224:227], v[78:81]
	v_mfma_f32_16x16x32_bf16 v[70:73], v[176:179], v[224:227], v[70:73]
	s_setprio 0
	s_setprio 1
	v_mfma_f32_16x16x32_bf16 v[126:129], v[180:183], v[196:199], v[126:129]
	v_mfma_f32_16x16x32_bf16 v[114:117], v[188:191], v[196:199], v[114:117]
	v_mfma_f32_16x16x32_bf16 v[106:109], v[180:183], v[204:207], v[106:109]
	v_mfma_f32_16x16x32_bf16 v[98:101], v[188:191], v[204:207], v[98:101]
	v_mfma_f32_16x16x32_bf16 v[90:93], v[180:183], v[212:215], v[90:93]
	v_mfma_f32_16x16x32_bf16 v[82:85], v[188:191], v[212:215], v[82:85]
	v_mfma_f32_16x16x32_bf16 v[74:77], v[180:183], v[220:223], v[74:77]
	v_mfma_f32_16x16x32_bf16 v[66:69], v[188:191], v[220:223], v[66:69]
	v_mfma_f32_16x16x32_bf16 v[126:129], v[184:187], v[200:203], v[126:129]
	v_mfma_f32_16x16x32_bf16 v[114:117], v[192:195], v[200:203], v[114:117]
	v_mfma_f32_16x16x32_bf16 v[106:109], v[184:187], v[208:211], v[106:109]
	v_mfma_f32_16x16x32_bf16 v[98:101], v[192:195], v[208:211], v[98:101]
	v_mfma_f32_16x16x32_bf16 v[90:93], v[184:187], v[216:219], v[90:93]
	v_mfma_f32_16x16x32_bf16 v[82:85], v[192:195], v[216:219], v[82:85]
	v_mfma_f32_16x16x32_bf16 v[74:77], v[184:187], v[224:227], v[74:77]
	v_mfma_f32_16x16x32_bf16 v[66:69], v[192:195], v[224:227], v[66:69]
	s_setprio 0
	s_barrier
	s_add_u32 s98, s96, 0xb0000
	s_addc_u32 s99, s97, 0
	s_add_i32 s6, s67, s23
	s_mov_b32 m0, s6
	s_nop 0
	global_load_lds_dwordx4 v132, s[96:97]
	s_add_i32 m0, s6, 0x2000
	s_add_i32 s6, s68, s23
	global_load_lds_dwordx4 v136, s[96:97]
	s_mov_b32 m0, s6
	s_nop 0
	global_load_lds_dwordx4 v132, s[98:99]
	s_add_i32 m0, s6, 0x2000
	s_nop 0
	global_load_lds_dwordx4 v136, s[98:99]
	s_mov_b32 m0, s46
	s_nop 0
	global_load_lds_dwordx4 v130, s[94:95]
	s_mov_b32 m0, s47
	s_nop 0
	global_load_lds_dwordx4 v134, s[94:95]
	ds_read_b128 v[196:199], v160 offset:16384
	ds_read_b128 v[200:203], v160 offset:17408
	ds_read_b128 v[204:207], v160 offset:18432
	ds_read_b128 v[208:211], v160 offset:19456
	ds_read_b128 v[212:215], v160 offset:20480
	ds_read_b128 v[216:219], v160 offset:21504
	ds_read_b128 v[220:223], v160 offset:22528
	ds_read_b128 v[224:227], v160 offset:23552
	s_waitcnt vmcnt(8)
	s_waitcnt lgkmcnt(0)
	s_barrier
	s_setprio 1
	s_waitcnt lgkmcnt(0)
	v_mfma_f32_16x16x32_bf16 v[62:65], v[164:167], v[196:199], v[62:65]
	v_mfma_f32_16x16x32_bf16 v[54:57], v[172:175], v[196:199], v[54:57]
	v_mfma_f32_16x16x32_bf16 v[46:49], v[164:167], v[204:207], v[46:49]
	v_mfma_f32_16x16x32_bf16 v[38:41], v[172:175], v[204:207], v[38:41]
	v_mfma_f32_16x16x32_bf16 v[30:33], v[164:167], v[212:215], v[30:33]
	v_mfma_f32_16x16x32_bf16 v[22:25], v[172:175], v[212:215], v[22:25]
	v_mfma_f32_16x16x32_bf16 v[14:17], v[164:167], v[220:223], v[14:17]
	v_mfma_f32_16x16x32_bf16 v[6:9], v[172:175], v[220:223], v[6:9]
	v_mfma_f32_16x16x32_bf16 v[62:65], v[168:171], v[200:203], v[62:65]
	v_mfma_f32_16x16x32_bf16 v[54:57], v[176:179], v[200:203], v[54:57]
	v_mfma_f32_16x16x32_bf16 v[46:49], v[168:171], v[208:211], v[46:49]
	v_mfma_f32_16x16x32_bf16 v[38:41], v[176:179], v[208:211], v[38:41]
	v_mfma_f32_16x16x32_bf16 v[30:33], v[168:171], v[216:219], v[30:33]
	v_mfma_f32_16x16x32_bf16 v[22:25], v[176:179], v[216:219], v[22:25]
	v_mfma_f32_16x16x32_bf16 v[14:17], v[168:171], v[224:227], v[14:17]
	v_mfma_f32_16x16x32_bf16 v[6:9], v[176:179], v[224:227], v[6:9]
	s_setprio 0
	s_setprio 1
	v_mfma_f32_16x16x32_bf16 v[58:61], v[180:183], v[196:199], v[58:61]
	v_mfma_f32_16x16x32_bf16 v[50:53], v[188:191], v[196:199], v[50:53]
	v_mfma_f32_16x16x32_bf16 v[42:45], v[180:183], v[204:207], v[42:45]
	v_mfma_f32_16x16x32_bf16 v[34:37], v[188:191], v[204:207], v[34:37]
	v_mfma_f32_16x16x32_bf16 v[26:29], v[180:183], v[212:215], v[26:29]
	v_mfma_f32_16x16x32_bf16 v[18:21], v[188:191], v[212:215], v[18:21]
	v_mfma_f32_16x16x32_bf16 v[10:13], v[180:183], v[220:223], v[10:13]
	v_mfma_f32_16x16x32_bf16 v[2:5], v[188:191], v[220:223], v[2:5]
	v_mfma_f32_16x16x32_bf16 v[58:61], v[184:187], v[200:203], v[58:61]
	v_mfma_f32_16x16x32_bf16 v[50:53], v[192:195], v[200:203], v[50:53]
	v_mfma_f32_16x16x32_bf16 v[42:45], v[184:187], v[208:211], v[42:45]
	v_mfma_f32_16x16x32_bf16 v[34:37], v[192:195], v[208:211], v[34:37]
	v_mfma_f32_16x16x32_bf16 v[26:29], v[184:187], v[216:219], v[26:29]
	v_mfma_f32_16x16x32_bf16 v[18:21], v[192:195], v[216:219], v[18:21]
	v_mfma_f32_16x16x32_bf16 v[10:13], v[184:187], v[224:227], v[10:13]
	v_mfma_f32_16x16x32_bf16 v[2:5], v[192:195], v[224:227], v[2:5]
	s_setprio 0
	s_barrier
	s_add_u32 s98, s94, 0xb0000
	s_addc_u32 s99, s95, 0
	s_add_i32 s6, 0, 0x18000
	s_add_i32 s29, 0, 0x1c000
	s_mov_b32 m0, s48
	s_nop 0
	global_load_lds_dwordx4 v130, s[98:99]
	s_mov_b32 m0, s49
	s_nop 0
	global_load_lds_dwordx4 v134, s[98:99]
	ds_read_b128 v[164:167], v232
	ds_read_b128 v[168:171], v232 offset:1024
	ds_read_b128 v[172:175], v232 offset:2048
	ds_read_b128 v[176:179], v232 offset:3072
	ds_read_b128 v[180:183], v233
	ds_read_b128 v[184:187], v233 offset:1024
	ds_read_b128 v[188:191], v233 offset:2048
	ds_read_b128 v[192:195], v233 offset:3072
	ds_read_b128 v[196:199], v160 offset:32768
	ds_read_b128 v[200:203], v160 offset:33792
	ds_read_b128 v[204:207], v160 offset:34816
	ds_read_b128 v[208:211], v160 offset:35840
	ds_read_b128 v[212:215], v160 offset:36864
	ds_read_b128 v[216:219], v160 offset:37888
	ds_read_b128 v[220:223], v160 offset:38912
	ds_read_b128 v[224:227], v160 offset:39936
	s_waitcnt vmcnt(8)
	s_waitcnt lgkmcnt(0)
	s_barrier
	s_setprio 1
	s_waitcnt lgkmcnt(0)
	v_mfma_f32_16x16x32_bf16 v[122:125], v[164:167], v[196:199], v[122:125]
	v_mfma_f32_16x16x32_bf16 v[118:121], v[172:175], v[196:199], v[118:121]
	v_mfma_f32_16x16x32_bf16 v[110:113], v[164:167], v[204:207], v[110:113]
	v_mfma_f32_16x16x32_bf16 v[102:105], v[172:175], v[204:207], v[102:105]
	v_mfma_f32_16x16x32_bf16 v[94:97], v[164:167], v[212:215], v[94:97]
	v_mfma_f32_16x16x32_bf16 v[86:89], v[172:175], v[212:215], v[86:89]
	v_mfma_f32_16x16x32_bf16 v[78:81], v[164:167], v[220:223], v[78:81]
	v_mfma_f32_16x16x32_bf16 v[70:73], v[172:175], v[220:223], v[70:73]
	v_mfma_f32_16x16x32_bf16 v[122:125], v[168:171], v[200:203], v[122:125]
	v_mfma_f32_16x16x32_bf16 v[118:121], v[176:179], v[200:203], v[118:121]
	v_mfma_f32_16x16x32_bf16 v[110:113], v[168:171], v[208:211], v[110:113]
	v_mfma_f32_16x16x32_bf16 v[102:105], v[176:179], v[208:211], v[102:105]
	v_mfma_f32_16x16x32_bf16 v[94:97], v[168:171], v[216:219], v[94:97]
	v_mfma_f32_16x16x32_bf16 v[86:89], v[176:179], v[216:219], v[86:89]
	v_mfma_f32_16x16x32_bf16 v[78:81], v[168:171], v[224:227], v[78:81]
	v_mfma_f32_16x16x32_bf16 v[70:73], v[176:179], v[224:227], v[70:73]
	s_setprio 0
	s_setprio 1
	v_mfma_f32_16x16x32_bf16 v[126:129], v[180:183], v[196:199], v[126:129]
	v_mfma_f32_16x16x32_bf16 v[114:117], v[188:191], v[196:199], v[114:117]
	v_mfma_f32_16x16x32_bf16 v[106:109], v[180:183], v[204:207], v[106:109]
	v_mfma_f32_16x16x32_bf16 v[98:101], v[188:191], v[204:207], v[98:101]
	v_mfma_f32_16x16x32_bf16 v[90:93], v[180:183], v[212:215], v[90:93]
	v_mfma_f32_16x16x32_bf16 v[82:85], v[188:191], v[212:215], v[82:85]
	v_mfma_f32_16x16x32_bf16 v[74:77], v[180:183], v[220:223], v[74:77]
	v_mfma_f32_16x16x32_bf16 v[66:69], v[188:191], v[220:223], v[66:69]
	v_mfma_f32_16x16x32_bf16 v[126:129], v[184:187], v[200:203], v[126:129]
	v_mfma_f32_16x16x32_bf16 v[114:117], v[192:195], v[200:203], v[114:117]
	v_mfma_f32_16x16x32_bf16 v[106:109], v[184:187], v[208:211], v[106:109]
	v_mfma_f32_16x16x32_bf16 v[98:101], v[192:195], v[208:211], v[98:101]
	v_mfma_f32_16x16x32_bf16 v[90:93], v[184:187], v[216:219], v[90:93]
	v_mfma_f32_16x16x32_bf16 v[82:85], v[192:195], v[216:219], v[82:85]
	v_mfma_f32_16x16x32_bf16 v[74:77], v[184:187], v[224:227], v[74:77]
	v_mfma_f32_16x16x32_bf16 v[66:69], v[192:195], v[224:227], v[66:69]
	s_setprio 0
	s_barrier
	s_add_u32 s96, s96, 0x80
	s_addc_u32 s97, s97, 0
	s_add_u32 s98, s96, 0xb0000
	s_addc_u32 s99, s97, 0
	s_add_u32 s94, s94, 0x80
	s_addc_u32 s95, s95, 0
	s_add_i32 s6, s6, s23
	s_mov_b32 m0, s6
	s_nop 0
	global_load_lds_dwordx4 v132, s[96:97]
	s_add_i32 m0, s6, 0x2000
	s_add_i32 s6, s29, s23
	global_load_lds_dwordx4 v136, s[96:97]
	s_mov_b32 m0, s6
	s_nop 0
	global_load_lds_dwordx4 v132, s[98:99]
	s_add_i32 m0, s6, 0x2000
	s_nop 0
	global_load_lds_dwordx4 v136, s[98:99]
	s_mov_b32 m0, s59
	s_nop 0
	global_load_lds_dwordx4 v130, s[94:95]
	s_mov_b32 m0, s60
	s_nop 0
	global_load_lds_dwordx4 v134, s[94:95]
	ds_read_b128 v[196:199], v160 offset:49152
	ds_read_b128 v[200:203], v160 offset:50176
	ds_read_b128 v[204:207], v160 offset:51200
	ds_read_b128 v[208:211], v160 offset:52224
	ds_read_b128 v[212:215], v160 offset:53248
	ds_read_b128 v[216:219], v160 offset:54272
	ds_read_b128 v[220:223], v160 offset:55296
	ds_read_b128 v[224:227], v160 offset:56320
	s_waitcnt vmcnt(8)
	s_waitcnt lgkmcnt(0)
	s_barrier
	s_setprio 1
	s_waitcnt lgkmcnt(0)
	v_mfma_f32_16x16x32_bf16 v[62:65], v[164:167], v[196:199], v[62:65]
	v_mfma_f32_16x16x32_bf16 v[54:57], v[172:175], v[196:199], v[54:57]
	v_mfma_f32_16x16x32_bf16 v[46:49], v[164:167], v[204:207], v[46:49]
	v_mfma_f32_16x16x32_bf16 v[38:41], v[172:175], v[204:207], v[38:41]
	v_mfma_f32_16x16x32_bf16 v[30:33], v[164:167], v[212:215], v[30:33]
	v_mfma_f32_16x16x32_bf16 v[22:25], v[172:175], v[212:215], v[22:25]
	v_mfma_f32_16x16x32_bf16 v[14:17], v[164:167], v[220:223], v[14:17]
	v_mfma_f32_16x16x32_bf16 v[6:9], v[172:175], v[220:223], v[6:9]
	v_mfma_f32_16x16x32_bf16 v[62:65], v[168:171], v[200:203], v[62:65]
	v_mfma_f32_16x16x32_bf16 v[54:57], v[176:179], v[200:203], v[54:57]
	v_mfma_f32_16x16x32_bf16 v[46:49], v[168:171], v[208:211], v[46:49]
	v_mfma_f32_16x16x32_bf16 v[38:41], v[176:179], v[208:211], v[38:41]
	v_mfma_f32_16x16x32_bf16 v[30:33], v[168:171], v[216:219], v[30:33]
	v_mfma_f32_16x16x32_bf16 v[22:25], v[176:179], v[216:219], v[22:25]
	v_mfma_f32_16x16x32_bf16 v[14:17], v[168:171], v[224:227], v[14:17]
	v_mfma_f32_16x16x32_bf16 v[6:9], v[176:179], v[224:227], v[6:9]
	s_setprio 0
	s_setprio 1
	v_mfma_f32_16x16x32_bf16 v[58:61], v[180:183], v[196:199], v[58:61]
	v_mfma_f32_16x16x32_bf16 v[50:53], v[188:191], v[196:199], v[50:53]
	v_mfma_f32_16x16x32_bf16 v[42:45], v[180:183], v[204:207], v[42:45]
	v_mfma_f32_16x16x32_bf16 v[34:37], v[188:191], v[204:207], v[34:37]
	v_mfma_f32_16x16x32_bf16 v[26:29], v[180:183], v[212:215], v[26:29]
	v_mfma_f32_16x16x32_bf16 v[18:21], v[188:191], v[212:215], v[18:21]
	v_mfma_f32_16x16x32_bf16 v[10:13], v[180:183], v[220:223], v[10:13]
	v_mfma_f32_16x16x32_bf16 v[2:5], v[188:191], v[220:223], v[2:5]
	v_mfma_f32_16x16x32_bf16 v[58:61], v[184:187], v[200:203], v[58:61]
	v_mfma_f32_16x16x32_bf16 v[50:53], v[192:195], v[200:203], v[50:53]
	v_mfma_f32_16x16x32_bf16 v[42:45], v[184:187], v[208:211], v[42:45]
	v_mfma_f32_16x16x32_bf16 v[34:37], v[192:195], v[208:211], v[34:37]
	v_mfma_f32_16x16x32_bf16 v[26:29], v[184:187], v[216:219], v[26:29]
	v_mfma_f32_16x16x32_bf16 v[18:21], v[192:195], v[216:219], v[18:21]
	v_mfma_f32_16x16x32_bf16 v[10:13], v[184:187], v[224:227], v[10:13]
	v_mfma_f32_16x16x32_bf16 v[2:5], v[192:195], v[224:227], v[2:5]
	s_setprio 0
	s_barrier
	s_mov_b32 s6, s7
	s_add_u32 s88, s88, 0x100
	s_addc_u32 s89, s89, 0
	s_add_u32 s86, s86, 0x100
	s_addc_u32 s87, s87, 0
	s_cmp_ge_i32 s7, s101
	s_cbranch_scc0 .LBB0_1080

.LBB0_1390:
	v_cmp_gt_i32_e32 vcc, 1, v156
	s_cbranch_vccnz .LBB0_1452
	v_lshl_add_u64 v[152:153], v[2:3], 0, s[20:21]
	v_add_u32_e32 v138, -2, v156
	s_mov_b32 s6, 0
	s_nop 0
	v_readfirstlane_b32 s86, v150
	v_readfirstlane_b32 s87, v151
	v_readfirstlane_b32 s88, v152
	v_readfirstlane_b32 s89, v153
	v_readfirstlane_b32 s90, v146
	v_readfirstlane_b32 s91, v147
	v_readfirstlane_b32 s92, v148
	v_readfirstlane_b32 s93, v149
	v_readfirstlane_b32 s100, v138
	v_readfirstlane_b32 s101, v156
	v_add_u32_e32 v230, s67, v141
	v_add_u32_e32 v231, s70, v141
	v_add_u32_e32 v232, 0x18000, v141
	v_add_u32_e32 v233, 0x1c000, v141
	s_add_u32 s98, s86, 0x100
	s_addc_u32 s99, s87, 0
	s_cmp_eq_u32 s6, s100
	s_cselect_b64 s[94:95], s[90:91], s[98:99]
	s_cselect_b64 s[96:97], s[92:93], s[88:89]
	s_add_i32 s7, s6, 2
	s_nop 0
	s_add_i32 m0, s46, 0xc000
	s_nop 0
	global_load_lds_dwordx4 v144, s[86:87]
	s_add_i32 m0, s46, 0xe000
	s_nop 0
	global_load_lds_dwordx4 v142, s[86:87]
	ds_read_b128 v[164:167], v230
	ds_read_b128 v[168:171], v230 offset:1024
	ds_read_b128 v[172:175], v230 offset:2048
	ds_read_b128 v[176:179], v230 offset:3072
	ds_read_b128 v[180:183], v231
	ds_read_b128 v[184:187], v231 offset:1024
	ds_read_b128 v[188:191], v231 offset:2048
	ds_read_b128 v[192:195], v231 offset:3072
	ds_read_b128 v[196:199], v160
	ds_read_b128 v[200:203], v160 offset:1024
	ds_read_b128 v[204:207], v160 offset:2048
	ds_read_b128 v[208:211], v160 offset:3072
	ds_read_b128 v[212:215], v160 offset:4096
	ds_read_b128 v[216:219], v160 offset:5120
	ds_read_b128 v[220:223], v160 offset:6144
	ds_read_b128 v[224:227], v160 offset:7168
	s_waitcnt vmcnt(8)
	s_waitcnt lgkmcnt(0)
	s_barrier
	s_setprio 1
	s_waitcnt lgkmcnt(0)
	v_mfma_f32_16x16x32_bf16 v[122:125], v[164:167], v[196:199], 0
	v_mfma_f32_16x16x32_bf16 v[118:121], v[172:175], v[196:199], 0
	v_mfma_f32_16x16x32_bf16 v[110:113], v[164:167], v[204:207], 0
	v_mfma_f32_16x16x32_bf16 v[102:105], v[172:175], v[204:207], 0
	v_mfma_f32_16x16x32_bf16 v[94:97], v[164:167], v[212:215], 0
	v_mfma_f32_16x16x32_bf16 v[86:89], v[172:175], v[212:215], 0
	v_mfma_f32_16x16x32_bf16 v[78:81], v[164:167], v[220:223], 0
	v_mfma_f32_16x16x32_bf16 v[70:73], v[172:175], v[220:223], 0
	v_mfma_f32_16x16x32_bf16 v[122:125], v[168:171], v[200:203], v[122:125]
	v_mfma_f32_16x16x32_bf16 v[118:121], v[176:179], v[200:203], v[118:121]
	v_mfma_f32_16x16x32_bf16 v[110:113], v[168:171], v[208:211], v[110:113]
	v_mfma_f32_16x16x32_bf16 v[102:105], v[176:179], v[208:211], v[102:105]
	v_mfma_f32_16x16x32_bf16 v[94:97], v[168:171], v[216:219], v[94:97]
	v_mfma_f32_16x16x32_bf16 v[86:89], v[176:179], v[216:219], v[86:89]
	v_mfma_f32_16x16x32_bf16 v[78:81], v[168:171], v[224:227], v[78:81]
	v_mfma_f32_16x16x32_bf16 v[70:73], v[176:179], v[224:227], v[70:73]
	s_setprio 0
	s_setprio 1
	v_mfma_f32_16x16x32_bf16 v[126:129], v[180:183], v[196:199], 0
	v_mfma_f32_16x16x32_bf16 v[114:117], v[188:191], v[196:199], 0
	v_mfma_f32_16x16x32_bf16 v[106:109], v[180:183], v[204:207], 0
	v_mfma_f32_16x16x32_bf16 v[98:101], v[188:191], v[204:207], 0
	v_mfma_f32_16x16x32_bf16 v[90:93], v[180:183], v[212:215], 0
	v_mfma_f32_16x16x32_bf16 v[82:85], v[188:191], v[212:215], 0
	v_mfma_f32_16x16x32_bf16 v[74:77], v[180:183], v[220:223], 0
	v_mfma_f32_16x16x32_bf16 v[66:69], v[188:191], v[220:223], 0
	v_mfma_f32_16x16x32_bf16 v[126:129], v[184:187], v[200:203], v[126:129]
	v_mfma_f32_16x16x32_bf16 v[114:117], v[192:195], v[200:203], v[114:117]
	v_mfma_f32_16x16x32_bf16 v[106:109], v[184:187], v[208:211], v[106:109]
	v_mfma_f32_16x16x32_bf16 v[98:101], v[192:195], v[208:211], v[98:101]
	v_mfma_f32_16x16x32_bf16 v[90:93], v[184:187], v[216:219], v[90:93]
	v_mfma_f32_16x16x32_bf16 v[82:85], v[192:195], v[216:219], v[82:85]
	v_mfma_f32_16x16x32_bf16 v[74:77], v[184:187], v[224:227], v[74:77]
	v_mfma_f32_16x16x32_bf16 v[66:69], v[192:195], v[224:227], v[66:69]
	s_setprio 0
	s_barrier
	s_add_u32 s98, s96, 0xb0000
	s_addc_u32 s99, s97, 0
	s_add_i32 s6, s67, s23
	s_mov_b32 m0, s6
	s_nop 0
	global_load_lds_dwordx4 v132, s[96:97]
	s_add_i32 m0, s6, 0x2000
	s_add_i32 s6, s70, s23
	global_load_lds_dwordx4 v136, s[96:97]
	s_mov_b32 m0, s6
	s_nop 0
	global_load_lds_dwordx4 v132, s[98:99]
	s_add_i32 m0, s6, 0x2000
	s_nop 0
	global_load_lds_dwordx4 v136, s[98:99]
	s_mov_b32 m0, s46
	s_nop 0
	global_load_lds_dwordx4 v130, s[94:95]
	s_mov_b32 m0, s47
	s_nop 0
	global_load_lds_dwordx4 v134, s[94:95]
	ds_read_b128 v[196:199], v160 offset:16384
	ds_read_b128 v[200:203], v160 offset:17408
	ds_read_b128 v[204:207], v160 offset:18432
	ds_read_b128 v[208:211], v160 offset:19456
	ds_read_b128 v[212:215], v160 offset:20480
	ds_read_b128 v[216:219], v160 offset:21504
	ds_read_b128 v[220:223], v160 offset:22528
	ds_read_b128 v[224:227], v160 offset:23552
	s_waitcnt vmcnt(8)
	s_waitcnt lgkmcnt(0)
	s_barrier
	s_setprio 1
	s_waitcnt lgkmcnt(0)
	v_mfma_f32_16x16x32_bf16 v[62:65], v[164:167], v[196:199], 0
	v_mfma_f32_16x16x32_bf16 v[54:57], v[172:175], v[196:199], 0
	v_mfma_f32_16x16x32_bf16 v[46:49], v[164:167], v[204:207], 0
	v_mfma_f32_16x16x32_bf16 v[38:41], v[172:175], v[204:207], 0
	v_mfma_f32_16x16x32_bf16 v[30:33], v[164:167], v[212:215], 0
	v_mfma_f32_16x16x32_bf16 v[22:25], v[172:175], v[212:215], 0
	v_mfma_f32_16x16x32_bf16 v[14:17], v[164:167], v[220:223], 0
	v_mfma_f32_16x16x32_bf16 v[6:9], v[172:175], v[220:223], 0
	v_mfma_f32_16x16x32_bf16 v[62:65], v[168:171], v[200:203], v[62:65]
	v_mfma_f32_16x16x32_bf16 v[54:57], v[176:179], v[200:203], v[54:57]
	v_mfma_f32_16x16x32_bf16 v[46:49], v[168:171], v[208:211], v[46:49]
	v_mfma_f32_16x16x32_bf16 v[38:41], v[176:179], v[208:211], v[38:41]
	v_mfma_f32_16x16x32_bf16 v[30:33], v[168:171], v[216:219], v[30:33]
	v_mfma_f32_16x16x32_bf16 v[22:25], v[176:179], v[216:219], v[22:25]
	v_mfma_f32_16x16x32_bf16 v[14:17], v[168:171], v[224:227], v[14:17]
	v_mfma_f32_16x16x32_bf16 v[6:9], v[176:179], v[224:227], v[6:9]
	s_setprio 0
	s_setprio 1
	v_mfma_f32_16x16x32_bf16 v[58:61], v[180:183], v[196:199], 0
	v_mfma_f32_16x16x32_bf16 v[50:53], v[188:191], v[196:199], 0
	v_mfma_f32_16x16x32_bf16 v[42:45], v[180:183], v[204:207], 0
	v_mfma_f32_16x16x32_bf16 v[34:37], v[188:191], v[204:207], 0
	v_mfma_f32_16x16x32_bf16 v[26:29], v[180:183], v[212:215], 0
	v_mfma_f32_16x16x32_bf16 v[18:21], v[188:191], v[212:215], 0
	v_mfma_f32_16x16x32_bf16 v[10:13], v[180:183], v[220:223], 0
	v_mfma_f32_16x16x32_bf16 v[2:5], v[188:191], v[220:223], 0
	v_mfma_f32_16x16x32_bf16 v[58:61], v[184:187], v[200:203], v[58:61]
	v_mfma_f32_16x16x32_bf16 v[50:53], v[192:195], v[200:203], v[50:53]
	v_mfma_f32_16x16x32_bf16 v[42:45], v[184:187], v[208:211], v[42:45]
	v_mfma_f32_16x16x32_bf16 v[34:37], v[192:195], v[208:211], v[34:37]
	v_mfma_f32_16x16x32_bf16 v[26:29], v[184:187], v[216:219], v[26:29]
	v_mfma_f32_16x16x32_bf16 v[18:21], v[192:195], v[216:219], v[18:21]
	v_mfma_f32_16x16x32_bf16 v[10:13], v[184:187], v[224:227], v[10:13]
	v_mfma_f32_16x16x32_bf16 v[2:5], v[192:195], v[224:227], v[2:5]
	s_setprio 0
	s_barrier
	s_add_u32 s98, s94, 0xb0000
	s_addc_u32 s99, s95, 0
	s_add_i32 s6, 0, 0x18000
	s_add_i32 s29, 0, 0x1c000
	s_mov_b32 m0, s48
	s_nop 0
	global_load_lds_dwordx4 v130, s[98:99]
	s_mov_b32 m0, s49
	s_nop 0
	global_load_lds_dwordx4 v134, s[98:99]
	ds_read_b128 v[164:167], v232
	ds_read_b128 v[168:171], v232 offset:1024
	ds_read_b128 v[172:175], v232 offset:2048
	ds_read_b128 v[176:179], v232 offset:3072
	ds_read_b128 v[180:183], v233
	ds_read_b128 v[184:187], v233 offset:1024
	ds_read_b128 v[188:191], v233 offset:2048
	ds_read_b128 v[192:195], v233 offset:3072
	ds_read_b128 v[196:199], v160 offset:32768
	ds_read_b128 v[200:203], v160 offset:33792
	ds_read_b128 v[204:207], v160 offset:34816
	ds_read_b128 v[208:211], v160 offset:35840
	ds_read_b128 v[212:215], v160 offset:36864
	ds_read_b128 v[216:219], v160 offset:37888
	ds_read_b128 v[220:223], v160 offset:38912
	ds_read_b128 v[224:227], v160 offset:39936
	s_waitcnt vmcnt(8)
	s_waitcnt lgkmcnt(0)
	s_barrier
	s_setprio 1
	s_waitcnt lgkmcnt(0)
	v_mfma_f32_16x16x32_bf16 v[122:125], v[164:167], v[196:199], v[122:125]
	v_mfma_f32_16x16x32_bf16 v[118:121], v[172:175], v[196:199], v[118:121]
	v_mfma_f32_16x16x32_bf16 v[110:113], v[164:167], v[204:207], v[110:113]
	v_mfma_f32_16x16x32_bf16 v[102:105], v[172:175], v[204:207], v[102:105]
	v_mfma_f32_16x16x32_bf16 v[94:97], v[164:167], v[212:215], v[94:97]
	v_mfma_f32_16x16x32_bf16 v[86:89], v[172:175], v[212:215], v[86:89]
	v_mfma_f32_16x16x32_bf16 v[78:81], v[164:167], v[220:223], v[78:81]
	v_mfma_f32_16x16x32_bf16 v[70:73], v[172:175], v[220:223], v[70:73]
	v_mfma_f32_16x16x32_bf16 v[122:125], v[168:171], v[200:203], v[122:125]
	v_mfma_f32_16x16x32_bf16 v[118:121], v[176:179], v[200:203], v[118:121]
	v_mfma_f32_16x16x32_bf16 v[110:113], v[168:171], v[208:211], v[110:113]
	v_mfma_f32_16x16x32_bf16 v[102:105], v[176:179], v[208:211], v[102:105]
	v_mfma_f32_16x16x32_bf16 v[94:97], v[168:171], v[216:219], v[94:97]
	v_mfma_f32_16x16x32_bf16 v[86:89], v[176:179], v[216:219], v[86:89]
	v_mfma_f32_16x16x32_bf16 v[78:81], v[168:171], v[224:227], v[78:81]
	v_mfma_f32_16x16x32_bf16 v[70:73], v[176:179], v[224:227], v[70:73]
	s_setprio 0
	s_setprio 1
	v_mfma_f32_16x16x32_bf16 v[126:129], v[180:183], v[196:199], v[126:129]
	v_mfma_f32_16x16x32_bf16 v[114:117], v[188:191], v[196:199], v[114:117]
	v_mfma_f32_16x16x32_bf16 v[106:109], v[180:183], v[204:207], v[106:109]
	v_mfma_f32_16x16x32_bf16 v[98:101], v[188:191], v[204:207], v[98:101]
	v_mfma_f32_16x16x32_bf16 v[90:93], v[180:183], v[212:215], v[90:93]
	v_mfma_f32_16x16x32_bf16 v[82:85], v[188:191], v[212:215], v[82:85]
	v_mfma_f32_16x16x32_bf16 v[74:77], v[180:183], v[220:223], v[74:77]
	v_mfma_f32_16x16x32_bf16 v[66:69], v[188:191], v[220:223], v[66:69]
	v_mfma_f32_16x16x32_bf16 v[126:129], v[184:187], v[200:203], v[126:129]
	v_mfma_f32_16x16x32_bf16 v[114:117], v[192:195], v[200:203], v[114:117]
	v_mfma_f32_16x16x32_bf16 v[106:109], v[184:187], v[208:211], v[106:109]
	v_mfma_f32_16x16x32_bf16 v[98:101], v[192:195], v[208:211], v[98:101]
	v_mfma_f32_16x16x32_bf16 v[90:93], v[184:187], v[216:219], v[90:93]
	v_mfma_f32_16x16x32_bf16 v[82:85], v[192:195], v[216:219], v[82:85]
	v_mfma_f32_16x16x32_bf16 v[74:77], v[184:187], v[224:227], v[74:77]
	v_mfma_f32_16x16x32_bf16 v[66:69], v[192:195], v[224:227], v[66:69]
	s_setprio 0
	s_barrier
	s_add_u32 s96, s96, 0x80
	s_addc_u32 s97, s97, 0
	s_add_u32 s98, s96, 0xb0000
	s_addc_u32 s99, s97, 0
	s_add_u32 s94, s94, 0x80
	s_addc_u32 s95, s95, 0
	s_add_i32 s6, s6, s23
	s_mov_b32 m0, s6
	s_nop 0
	global_load_lds_dwordx4 v132, s[96:97]
	s_add_i32 m0, s6, 0x2000
	s_add_i32 s6, s29, s23
	global_load_lds_dwordx4 v136, s[96:97]
	s_mov_b32 m0, s6
	s_nop 0
	global_load_lds_dwordx4 v132, s[98:99]
	s_add_i32 m0, s6, 0x2000
	s_nop 0
	global_load_lds_dwordx4 v136, s[98:99]
	s_mov_b32 m0, s59
	s_nop 0
	global_load_lds_dwordx4 v130, s[94:95]
	s_mov_b32 m0, s60
	s_nop 0
	global_load_lds_dwordx4 v134, s[94:95]
	ds_read_b128 v[196:199], v160 offset:49152
	ds_read_b128 v[200:203], v160 offset:50176
	ds_read_b128 v[204:207], v160 offset:51200
	ds_read_b128 v[208:211], v160 offset:52224
	ds_read_b128 v[212:215], v160 offset:53248
	ds_read_b128 v[216:219], v160 offset:54272
	ds_read_b128 v[220:223], v160 offset:55296
	ds_read_b128 v[224:227], v160 offset:56320
	s_waitcnt vmcnt(8)
	s_waitcnt lgkmcnt(0)
	s_barrier
	s_setprio 1
	s_waitcnt lgkmcnt(0)
	v_mfma_f32_16x16x32_bf16 v[62:65], v[164:167], v[196:199], v[62:65]
	v_mfma_f32_16x16x32_bf16 v[54:57], v[172:175], v[196:199], v[54:57]
	v_mfma_f32_16x16x32_bf16 v[46:49], v[164:167], v[204:207], v[46:49]
	v_mfma_f32_16x16x32_bf16 v[38:41], v[172:175], v[204:207], v[38:41]
	v_mfma_f32_16x16x32_bf16 v[30:33], v[164:167], v[212:215], v[30:33]
	v_mfma_f32_16x16x32_bf16 v[22:25], v[172:175], v[212:215], v[22:25]
	v_mfma_f32_16x16x32_bf16 v[14:17], v[164:167], v[220:223], v[14:17]
	v_mfma_f32_16x16x32_bf16 v[6:9], v[172:175], v[220:223], v[6:9]
	v_mfma_f32_16x16x32_bf16 v[62:65], v[168:171], v[200:203], v[62:65]
	v_mfma_f32_16x16x32_bf16 v[54:57], v[176:179], v[200:203], v[54:57]
	v_mfma_f32_16x16x32_bf16 v[46:49], v[168:171], v[208:211], v[46:49]
	v_mfma_f32_16x16x32_bf16 v[38:41], v[176:179], v[208:211], v[38:41]
	v_mfma_f32_16x16x32_bf16 v[30:33], v[168:171], v[216:219], v[30:33]
	v_mfma_f32_16x16x32_bf16 v[22:25], v[176:179], v[216:219], v[22:25]
	v_mfma_f32_16x16x32_bf16 v[14:17], v[168:171], v[224:227], v[14:17]
	v_mfma_f32_16x16x32_bf16 v[6:9], v[176:179], v[224:227], v[6:9]
	s_setprio 0
	s_setprio 1
	v_mfma_f32_16x16x32_bf16 v[58:61], v[180:183], v[196:199], v[58:61]
	v_mfma_f32_16x16x32_bf16 v[50:53], v[188:191], v[196:199], v[50:53]
	v_mfma_f32_16x16x32_bf16 v[42:45], v[180:183], v[204:207], v[42:45]
	v_mfma_f32_16x16x32_bf16 v[34:37], v[188:191], v[204:207], v[34:37]
	v_mfma_f32_16x16x32_bf16 v[26:29], v[180:183], v[212:215], v[26:29]
	v_mfma_f32_16x16x32_bf16 v[18:21], v[188:191], v[212:215], v[18:21]
	v_mfma_f32_16x16x32_bf16 v[10:13], v[180:183], v[220:223], v[10:13]
	v_mfma_f32_16x16x32_bf16 v[2:5], v[188:191], v[220:223], v[2:5]
	v_mfma_f32_16x16x32_bf16 v[58:61], v[184:187], v[200:203], v[58:61]
	v_mfma_f32_16x16x32_bf16 v[50:53], v[192:195], v[200:203], v[50:53]
	v_mfma_f32_16x16x32_bf16 v[42:45], v[184:187], v[208:211], v[42:45]
	v_mfma_f32_16x16x32_bf16 v[34:37], v[192:195], v[208:211], v[34:37]
	v_mfma_f32_16x16x32_bf16 v[26:29], v[184:187], v[216:219], v[26:29]
	v_mfma_f32_16x16x32_bf16 v[18:21], v[192:195], v[216:219], v[18:21]
	v_mfma_f32_16x16x32_bf16 v[10:13], v[184:187], v[224:227], v[10:13]
	v_mfma_f32_16x16x32_bf16 v[2:5], v[192:195], v[224:227], v[2:5]
	s_setprio 0
	s_barrier
	s_mov_b32 s6, s7
	s_add_u32 s88, s88, 0x100
	s_addc_u32 s89, s89, 0
	s_add_u32 s86, s86, 0x100
	s_addc_u32 s87, s87, 0
	s_cmp_ge_i32 s7, s101
	s_cbranch_scc1 .Lmy_kexit_7
.LBB0_1392:
	s_add_u32 s98, s86, 0x100
	s_addc_u32 s99, s87, 0
	s_cmp_eq_u32 s6, s100
	s_cselect_b64 s[94:95], s[90:91], s[98:99]
	s_cselect_b64 s[96:97], s[92:93], s[88:89]
	s_add_i32 s7, s6, 2
	s_nop 0
	s_add_i32 m0, s46, 0xc000
	s_nop 0
	global_load_lds_dwordx4 v144, s[86:87]
	s_add_i32 m0, s46, 0xe000
	s_nop 0
	global_load_lds_dwordx4 v142, s[86:87]
	ds_read_b128 v[164:167], v230
	ds_read_b128 v[168:171], v230 offset:1024
	ds_read_b128 v[172:175], v230 offset:2048
	ds_read_b128 v[176:179], v230 offset:3072
	ds_read_b128 v[180:183], v231
	ds_read_b128 v[184:187], v231 offset:1024
	ds_read_b128 v[188:191], v231 offset:2048
	ds_read_b128 v[192:195], v231 offset:3072
	ds_read_b128 v[196:199], v160
	ds_read_b128 v[200:203], v160 offset:1024
	ds_read_b128 v[204:207], v160 offset:2048
	ds_read_b128 v[208:211], v160 offset:3072
	ds_read_b128 v[212:215], v160 offset:4096
	ds_read_b128 v[216:219], v160 offset:5120
	ds_read_b128 v[220:223], v160 offset:6144
	ds_read_b128 v[224:227], v160 offset:7168
	s_waitcnt vmcnt(8)
	s_waitcnt lgkmcnt(0)
	s_barrier
	s_setprio 1
	s_waitcnt lgkmcnt(0)
	v_mfma_f32_16x16x32_bf16 v[122:125], v[164:167], v[196:199], v[122:125]
	v_mfma_f32_16x16x32_bf16 v[118:121], v[172:175], v[196:199], v[118:121]
	v_mfma_f32_16x16x32_bf16 v[110:113], v[164:167], v[204:207], v[110:113]
	v_mfma_f32_16x16x32_bf16 v[102:105], v[172:175], v[204:207], v[102:105]
	v_mfma_f32_16x16x32_bf16 v[94:97], v[164:167], v[212:215], v[94:97]
	v_mfma_f32_16x16x32_bf16 v[86:89], v[172:175], v[212:215], v[86:89]
	v_mfma_f32_16x16x32_bf16 v[78:81], v[164:167], v[220:223], v[78:81]
	v_mfma_f32_16x16x32_bf16 v[70:73], v[172:175], v[220:223], v[70:73]
	v_mfma_f32_16x16x32_bf16 v[122:125], v[168:171], v[200:203], v[122:125]
	v_mfma_f32_16x16x32_bf16 v[118:121], v[176:179], v[200:203], v[118:121]
	v_mfma_f32_16x16x32_bf16 v[110:113], v[168:171], v[208:211], v[110:113]
	v_mfma_f32_16x16x32_bf16 v[102:105], v[176:179], v[208:211], v[102:105]
	v_mfma_f32_16x16x32_bf16 v[94:97], v[168:171], v[216:219], v[94:97]
	v_mfma_f32_16x16x32_bf16 v[86:89], v[176:179], v[216:219], v[86:89]
	v_mfma_f32_16x16x32_bf16 v[78:81], v[168:171], v[224:227], v[78:81]
	v_mfma_f32_16x16x32_bf16 v[70:73], v[176:179], v[224:227], v[70:73]
	s_setprio 0
	s_setprio 1
	v_mfma_f32_16x16x32_bf16 v[126:129], v[180:183], v[196:199], v[126:129]
	v_mfma_f32_16x16x32_bf16 v[114:117], v[188:191], v[196:199], v[114:117]
	v_mfma_f32_16x16x32_bf16 v[106:109], v[180:183], v[204:207], v[106:109]
	v_mfma_f32_16x16x32_bf16 v[98:101], v[188:191], v[204:207], v[98:101]
	v_mfma_f32_16x16x32_bf16 v[90:93], v[180:183], v[212:215], v[90:93]
	v_mfma_f32_16x16x32_bf16 v[82:85], v[188:191], v[212:215], v[82:85]
	v_mfma_f32_16x16x32_bf16 v[74:77], v[180:183], v[220:223], v[74:77]
	v_mfma_f32_16x16x32_bf16 v[66:69], v[188:191], v[220:223], v[66:69]
	v_mfma_f32_16x16x32_bf16 v[126:129], v[184:187], v[200:203], v[126:129]
	v_mfma_f32_16x16x32_bf16 v[114:117], v[192:195], v[200:203], v[114:117]
	v_mfma_f32_16x16x32_bf16 v[106:109], v[184:187], v[208:211], v[106:109]
	v_mfma_f32_16x16x32_bf16 v[98:101], v[192:195], v[208:211], v[98:101]
	v_mfma_f32_16x16x32_bf16 v[90:93], v[184:187], v[216:219], v[90:93]
	v_mfma_f32_16x16x32_bf16 v[82:85], v[192:195], v[216:219], v[82:85]
	v_mfma_f32_16x16x32_bf16 v[74:77], v[184:187], v[224:227], v[74:77]
	v_mfma_f32_16x16x32_bf16 v[66:69], v[192:195], v[224:227], v[66:69]
	s_setprio 0
	s_barrier
	s_add_u32 s98, s96, 0xb0000
	s_addc_u32 s99, s97, 0
	s_add_i32 s6, s67, s23
	s_mov_b32 m0, s6
	s_nop 0
	global_load_lds_dwordx4 v132, s[96:97]
	s_add_i32 m0, s6, 0x2000
	s_add_i32 s6, s70, s23
	global_load_lds_dwordx4 v136, s[96:97]
	s_mov_b32 m0, s6
	s_nop 0
	global_load_lds_dwordx4 v132, s[98:99]
	s_add_i32 m0, s6, 0x2000
	s_nop 0
	global_load_lds_dwordx4 v136, s[98:99]
	s_mov_b32 m0, s46
	s_nop 0
	global_load_lds_dwordx4 v130, s[94:95]
	s_mov_b32 m0, s47
	s_nop 0
	global_load_lds_dwordx4 v134, s[94:95]
	ds_read_b128 v[196:199], v160 offset:16384
	ds_read_b128 v[200:203], v160 offset:17408
	ds_read_b128 v[204:207], v160 offset:18432
	ds_read_b128 v[208:211], v160 offset:19456
	ds_read_b128 v[212:215], v160 offset:20480
	ds_read_b128 v[216:219], v160 offset:21504
	ds_read_b128 v[220:223], v160 offset:22528
	ds_read_b128 v[224:227], v160 offset:23552
	s_waitcnt vmcnt(8)
	s_waitcnt lgkmcnt(0)
	s_barrier
	s_setprio 1
	s_waitcnt lgkmcnt(0)
	v_mfma_f32_16x16x32_bf16 v[62:65], v[164:167], v[196:199], v[62:65]
	v_mfma_f32_16x16x32_bf16 v[54:57], v[172:175], v[196:199], v[54:57]
	v_mfma_f32_16x16x32_bf16 v[46:49], v[164:167], v[204:207], v[46:49]
	v_mfma_f32_16x16x32_bf16 v[38:41], v[172:175], v[204:207], v[38:41]
	v_mfma_f32_16x16x32_bf16 v[30:33], v[164:167], v[212:215], v[30:33]
	v_mfma_f32_16x16x32_bf16 v[22:25], v[172:175], v[212:215], v[22:25]
	v_mfma_f32_16x16x32_bf16 v[14:17], v[164:167], v[220:223], v[14:17]
	v_mfma_f32_16x16x32_bf16 v[6:9], v[172:175], v[220:223], v[6:9]
	v_mfma_f32_16x16x32_bf16 v[62:65], v[168:171], v[200:203], v[62:65]
	v_mfma_f32_16x16x32_bf16 v[54:57], v[176:179], v[200:203], v[54:57]
	v_mfma_f32_16x16x32_bf16 v[46:49], v[168:171], v[208:211], v[46:49]
	v_mfma_f32_16x16x32_bf16 v[38:41], v[176:179], v[208:211], v[38:41]
	v_mfma_f32_16x16x32_bf16 v[30:33], v[168:171], v[216:219], v[30:33]
	v_mfma_f32_16x16x32_bf16 v[22:25], v[176:179], v[216:219], v[22:25]
	v_mfma_f32_16x16x32_bf16 v[14:17], v[168:171], v[224:227], v[14:17]
	v_mfma_f32_16x16x32_bf16 v[6:9], v[176:179], v[224:227], v[6:9]
	s_setprio 0
	s_setprio 1
	v_mfma_f32_16x16x32_bf16 v[58:61], v[180:183], v[196:199], v[58:61]
	v_mfma_f32_16x16x32_bf16 v[50:53], v[188:191], v[196:199], v[50:53]
	v_mfma_f32_16x16x32_bf16 v[42:45], v[180:183], v[204:207], v[42:45]
	v_mfma_f32_16x16x32_bf16 v[34:37], v[188:191], v[204:207], v[34:37]
	v_mfma_f32_16x16x32_bf16 v[26:29], v[180:183], v[212:215], v[26:29]
	v_mfma_f32_16x16x32_bf16 v[18:21], v[188:191], v[212:215], v[18:21]
	v_mfma_f32_16x16x32_bf16 v[10:13], v[180:183], v[220:223], v[10:13]
	v_mfma_f32_16x16x32_bf16 v[2:5], v[188:191], v[220:223], v[2:5]
	v_mfma_f32_16x16x32_bf16 v[58:61], v[184:187], v[200:203], v[58:61]
	v_mfma_f32_16x16x32_bf16 v[50:53], v[192:195], v[200:203], v[50:53]
	v_mfma_f32_16x16x32_bf16 v[42:45], v[184:187], v[208:211], v[42:45]
	v_mfma_f32_16x16x32_bf16 v[34:37], v[192:195], v[208:211], v[34:37]
	v_mfma_f32_16x16x32_bf16 v[26:29], v[184:187], v[216:219], v[26:29]
	v_mfma_f32_16x16x32_bf16 v[18:21], v[192:195], v[216:219], v[18:21]
	v_mfma_f32_16x16x32_bf16 v[10:13], v[184:187], v[224:227], v[10:13]
	v_mfma_f32_16x16x32_bf16 v[2:5], v[192:195], v[224:227], v[2:5]
	s_setprio 0
	s_barrier
	s_add_u32 s98, s94, 0xb0000
	s_addc_u32 s99, s95, 0
	s_add_i32 s6, 0, 0x18000
	s_add_i32 s29, 0, 0x1c000
	s_mov_b32 m0, s48
	s_nop 0
	global_load_lds_dwordx4 v130, s[98:99]
	s_mov_b32 m0, s49
	s_nop 0
	global_load_lds_dwordx4 v134, s[98:99]
	ds_read_b128 v[164:167], v232
	ds_read_b128 v[168:171], v232 offset:1024
	ds_read_b128 v[172:175], v232 offset:2048
	ds_read_b128 v[176:179], v232 offset:3072
	ds_read_b128 v[180:183], v233
	ds_read_b128 v[184:187], v233 offset:1024
	ds_read_b128 v[188:191], v233 offset:2048
	ds_read_b128 v[192:195], v233 offset:3072
	ds_read_b128 v[196:199], v160 offset:32768
	ds_read_b128 v[200:203], v160 offset:33792
	ds_read_b128 v[204:207], v160 offset:34816
	ds_read_b128 v[208:211], v160 offset:35840
	ds_read_b128 v[212:215], v160 offset:36864
	ds_read_b128 v[216:219], v160 offset:37888
	ds_read_b128 v[220:223], v160 offset:38912
	ds_read_b128 v[224:227], v160 offset:39936
	s_waitcnt vmcnt(8)
	s_waitcnt lgkmcnt(0)
	s_barrier
	s_setprio 1
	s_waitcnt lgkmcnt(0)
	v_mfma_f32_16x16x32_bf16 v[122:125], v[164:167], v[196:199], v[122:125]
	v_mfma_f32_16x16x32_bf16 v[118:121], v[172:175], v[196:199], v[118:121]
	v_mfma_f32_16x16x32_bf16 v[110:113], v[164:167], v[204:207], v[110:113]
	v_mfma_f32_16x16x32_bf16 v[102:105], v[172:175], v[204:207], v[102:105]
	v_mfma_f32_16x16x32_bf16 v[94:97], v[164:167], v[212:215], v[94:97]
	v_mfma_f32_16x16x32_bf16 v[86:89], v[172:175], v[212:215], v[86:89]
	v_mfma_f32_16x16x32_bf16 v[78:81], v[164:167], v[220:223], v[78:81]
	v_mfma_f32_16x16x32_bf16 v[70:73], v[172:175], v[220:223], v[70:73]
	v_mfma_f32_16x16x32_bf16 v[122:125], v[168:171], v[200:203], v[122:125]
	v_mfma_f32_16x16x32_bf16 v[118:121], v[176:179], v[200:203], v[118:121]
	v_mfma_f32_16x16x32_bf16 v[110:113], v[168:171], v[208:211], v[110:113]
	v_mfma_f32_16x16x32_bf16 v[102:105], v[176:179], v[208:211], v[102:105]
	v_mfma_f32_16x16x32_bf16 v[94:97], v[168:171], v[216:219], v[94:97]
	v_mfma_f32_16x16x32_bf16 v[86:89], v[176:179], v[216:219], v[86:89]
	v_mfma_f32_16x16x32_bf16 v[78:81], v[168:171], v[224:227], v[78:81]
	v_mfma_f32_16x16x32_bf16 v[70:73], v[176:179], v[224:227], v[70:73]
	s_setprio 0
	s_setprio 1
	v_mfma_f32_16x16x32_bf16 v[126:129], v[180:183], v[196:199], v[126:129]
	v_mfma_f32_16x16x32_bf16 v[114:117], v[188:191], v[196:199], v[114:117]
	v_mfma_f32_16x16x32_bf16 v[106:109], v[180:183], v[204:207], v[106:109]
	v_mfma_f32_16x16x32_bf16 v[98:101], v[188:191], v[204:207], v[98:101]
	v_mfma_f32_16x16x32_bf16 v[90:93], v[180:183], v[212:215], v[90:93]
	v_mfma_f32_16x16x32_bf16 v[82:85], v[188:191], v[212:215], v[82:85]
	v_mfma_f32_16x16x32_bf16 v[74:77], v[180:183], v[220:223], v[74:77]
	v_mfma_f32_16x16x32_bf16 v[66:69], v[188:191], v[220:223], v[66:69]
	v_mfma_f32_16x16x32_bf16 v[126:129], v[184:187], v[200:203], v[126:129]
	v_mfma_f32_16x16x32_bf16 v[114:117], v[192:195], v[200:203], v[114:117]
	v_mfma_f32_16x16x32_bf16 v[106:109], v[184:187], v[208:211], v[106:109]
	v_mfma_f32_16x16x32_bf16 v[98:101], v[192:195], v[208:211], v[98:101]
	v_mfma_f32_16x16x32_bf16 v[90:93], v[184:187], v[216:219], v[90:93]
	v_mfma_f32_16x16x32_bf16 v[82:85], v[192:195], v[216:219], v[82:85]
	v_mfma_f32_16x16x32_bf16 v[74:77], v[184:187], v[224:227], v[74:77]
	v_mfma_f32_16x16x32_bf16 v[66:69], v[192:195], v[224:227], v[66:69]
	s_setprio 0
	s_barrier
	s_add_u32 s96, s96, 0x80
	s_addc_u32 s97, s97, 0
	s_add_u32 s98, s96, 0xb0000
	s_addc_u32 s99, s97, 0
	s_add_u32 s94, s94, 0x80
	s_addc_u32 s95, s95, 0
	s_add_i32 s6, s6, s23
	s_mov_b32 m0, s6
	s_nop 0
	global_load_lds_dwordx4 v132, s[96:97]
	s_add_i32 m0, s6, 0x2000
	s_add_i32 s6, s29, s23
	global_load_lds_dwordx4 v136, s[96:97]
	s_mov_b32 m0, s6
	s_nop 0
	global_load_lds_dwordx4 v132, s[98:99]
	s_add_i32 m0, s6, 0x2000
	s_nop 0
	global_load_lds_dwordx4 v136, s[98:99]
	s_mov_b32 m0, s59
	s_nop 0
	global_load_lds_dwordx4 v130, s[94:95]
	s_mov_b32 m0, s60
	s_nop 0
	global_load_lds_dwordx4 v134, s[94:95]
	ds_read_b128 v[196:199], v160 offset:49152
	ds_read_b128 v[200:203], v160 offset:50176
	ds_read_b128 v[204:207], v160 offset:51200
	ds_read_b128 v[208:211], v160 offset:52224
	ds_read_b128 v[212:215], v160 offset:53248
	ds_read_b128 v[216:219], v160 offset:54272
	ds_read_b128 v[220:223], v160 offset:55296
	ds_read_b128 v[224:227], v160 offset:56320
	s_waitcnt vmcnt(8)
	s_waitcnt lgkmcnt(0)
	s_barrier
	s_setprio 1
	s_waitcnt lgkmcnt(0)
	v_mfma_f32_16x16x32_bf16 v[62:65], v[164:167], v[196:199], v[62:65]
	v_mfma_f32_16x16x32_bf16 v[54:57], v[172:175], v[196:199], v[54:57]
	v_mfma_f32_16x16x32_bf16 v[46:49], v[164:167], v[204:207], v[46:49]
	v_mfma_f32_16x16x32_bf16 v[38:41], v[172:175], v[204:207], v[38:41]
	v_mfma_f32_16x16x32_bf16 v[30:33], v[164:167], v[212:215], v[30:33]
	v_mfma_f32_16x16x32_bf16 v[22:25], v[172:175], v[212:215], v[22:25]
	v_mfma_f32_16x16x32_bf16 v[14:17], v[164:167], v[220:223], v[14:17]
	v_mfma_f32_16x16x32_bf16 v[6:9], v[172:175], v[220:223], v[6:9]
	v_mfma_f32_16x16x32_bf16 v[62:65], v[168:171], v[200:203], v[62:65]
	v_mfma_f32_16x16x32_bf16 v[54:57], v[176:179], v[200:203], v[54:57]
	v_mfma_f32_16x16x32_bf16 v[46:49], v[168:171], v[208:211], v[46:49]
	v_mfma_f32_16x16x32_bf16 v[38:41], v[176:179], v[208:211], v[38:41]
	v_mfma_f32_16x16x32_bf16 v[30:33], v[168:171], v[216:219], v[30:33]
	v_mfma_f32_16x16x32_bf16 v[22:25], v[176:179], v[216:219], v[22:25]
	v_mfma_f32_16x16x32_bf16 v[14:17], v[168:171], v[224:227], v[14:17]
	v_mfma_f32_16x16x32_bf16 v[6:9], v[176:179], v[224:227], v[6:9]
	s_setprio 0
	s_setprio 1
	v_mfma_f32_16x16x32_bf16 v[58:61], v[180:183], v[196:199], v[58:61]
	v_mfma_f32_16x16x32_bf16 v[50:53], v[188:191], v[196:199], v[50:53]
	v_mfma_f32_16x16x32_bf16 v[42:45], v[180:183], v[204:207], v[42:45]
	v_mfma_f32_16x16x32_bf16 v[34:37], v[188:191], v[204:207], v[34:37]
	v_mfma_f32_16x16x32_bf16 v[26:29], v[180:183], v[212:215], v[26:29]
	v_mfma_f32_16x16x32_bf16 v[18:21], v[188:191], v[212:215], v[18:21]
	v_mfma_f32_16x16x32_bf16 v[10:13], v[180:183], v[220:223], v[10:13]
	v_mfma_f32_16x16x32_bf16 v[2:5], v[188:191], v[220:223], v[2:5]
	v_mfma_f32_16x16x32_bf16 v[58:61], v[184:187], v[200:203], v[58:61]
	v_mfma_f32_16x16x32_bf16 v[50:53], v[192:195], v[200:203], v[50:53]
	v_mfma_f32_16x16x32_bf16 v[42:45], v[184:187], v[208:211], v[42:45]
	v_mfma_f32_16x16x32_bf16 v[34:37], v[192:195], v[208:211], v[34:37]
	v_mfma_f32_16x16x32_bf16 v[26:29], v[184:187], v[216:219], v[26:29]
	v_mfma_f32_16x16x32_bf16 v[18:21], v[192:195], v[216:219], v[18:21]
	v_mfma_f32_16x16x32_bf16 v[10:13], v[184:187], v[224:227], v[10:13]
	v_mfma_f32_16x16x32_bf16 v[2:5], v[192:195], v[224:227], v[2:5]
	s_setprio 0
	s_barrier
	s_mov_b32 s6, s7
	s_add_u32 s88, s88, 0x100
	s_addc_u32 s89, s89, 0
	s_add_u32 s86, s86, 0x100
	s_addc_u32 s87, s87, 0
	s_cmp_ge_i32 s7, s101
	s_cbranch_scc0 .LBB0_1392

.LBB0_1571:
	v_cmp_gt_i32_e32 vcc, 1, v141
	s_cbranch_vccnz .LBB0_1633
	v_lshl_add_u64 v[154:155], v[2:3], 0, s[18:19]
	v_add_u32_e32 v138, -2, v141
	v_lshl_add_u64 v[152:153], v[4:5], 0, s[22:23]
	s_mov_b32 s7, 0
	s_nop 0
	v_readfirstlane_b32 s86, v154
	v_readfirstlane_b32 s87, v155
	v_readfirstlane_b32 s88, v152
	v_readfirstlane_b32 s89, v153
	v_readfirstlane_b32 s90, v148
	v_readfirstlane_b32 s91, v149
	v_readfirstlane_b32 s92, v150
	v_readfirstlane_b32 s93, v151
	v_readfirstlane_b32 s100, v138
	v_readfirstlane_b32 s101, v141
	v_add_u32_e32 v230, s71, v160
	v_add_u32_e32 v231, s72, v160
	v_add_u32_e32 v232, 0x18000, v160
	v_add_u32_e32 v233, 0x1c000, v160
	s_add_u32 s98, s86, 0xfffc0080
	s_addc_u32 s99, s87, -1
	s_cmp_eq_u32 s7, s100
	s_cselect_b64 s[94:95], s[90:91], s[98:99]
	s_cselect_b64 s[96:97], s[92:93], s[88:89]
	s_add_i32 s47, s7, 2
	s_nop 0
	s_mov_b32 m0, s74
	s_nop 0
	global_load_lds_dwordx4 v144, s[86:87]
	s_mov_b32 m0, s75
	s_nop 0
	global_load_lds_dwordx4 v142, s[86:87]
	ds_read_b128 v[156:159], v230
	ds_read_b128 v[166:169], v230 offset:1024
	ds_read_b128 v[170:173], v230 offset:2048
	ds_read_b128 v[174:177], v230 offset:3072
	ds_read_b128 v[178:181], v231
	ds_read_b128 v[182:185], v231 offset:1024
	ds_read_b128 v[186:189], v231 offset:2048
	ds_read_b128 v[190:193], v231 offset:3072
	ds_read_b128 v[194:197], v163
	ds_read_b128 v[198:201], v163 offset:1024
	ds_read_b128 v[202:205], v163 offset:2048
	ds_read_b128 v[206:209], v163 offset:3072
	ds_read_b128 v[210:213], v163 offset:4096
	ds_read_b128 v[214:217], v163 offset:5120
	ds_read_b128 v[218:221], v163 offset:6144
	ds_read_b128 v[222:225], v163 offset:7168
	s_waitcnt vmcnt(8)
	s_waitcnt lgkmcnt(0)
	s_barrier
	s_setprio 1
	s_waitcnt lgkmcnt(0)
	v_mfma_f32_16x16x32_bf16 v[122:125], v[156:159], v[194:197], 0
	v_mfma_f32_16x16x32_bf16 v[118:121], v[170:173], v[194:197], 0
	v_mfma_f32_16x16x32_bf16 v[110:113], v[156:159], v[202:205], 0
	v_mfma_f32_16x16x32_bf16 v[102:105], v[170:173], v[202:205], 0
	v_mfma_f32_16x16x32_bf16 v[94:97], v[156:159], v[210:213], 0
	v_mfma_f32_16x16x32_bf16 v[86:89], v[170:173], v[210:213], 0
	v_mfma_f32_16x16x32_bf16 v[78:81], v[156:159], v[218:221], 0
	v_mfma_f32_16x16x32_bf16 v[70:73], v[170:173], v[218:221], 0
	v_mfma_f32_16x16x32_bf16 v[122:125], v[166:169], v[198:201], v[122:125]
	v_mfma_f32_16x16x32_bf16 v[118:121], v[174:177], v[198:201], v[118:121]
	v_mfma_f32_16x16x32_bf16 v[110:113], v[166:169], v[206:209], v[110:113]
	v_mfma_f32_16x16x32_bf16 v[102:105], v[174:177], v[206:209], v[102:105]
	v_mfma_f32_16x16x32_bf16 v[94:97], v[166:169], v[214:217], v[94:97]
	v_mfma_f32_16x16x32_bf16 v[86:89], v[174:177], v[214:217], v[86:89]
	v_mfma_f32_16x16x32_bf16 v[78:81], v[166:169], v[222:225], v[78:81]
	v_mfma_f32_16x16x32_bf16 v[70:73], v[174:177], v[222:225], v[70:73]
	s_setprio 0
	s_setprio 1
	v_mfma_f32_16x16x32_bf16 v[126:129], v[178:181], v[194:197], 0
	v_mfma_f32_16x16x32_bf16 v[114:117], v[186:189], v[194:197], 0
	v_mfma_f32_16x16x32_bf16 v[106:109], v[178:181], v[202:205], 0
	v_mfma_f32_16x16x32_bf16 v[98:101], v[186:189], v[202:205], 0
	v_mfma_f32_16x16x32_bf16 v[90:93], v[178:181], v[210:213], 0
	v_mfma_f32_16x16x32_bf16 v[82:85], v[186:189], v[210:213], 0
	v_mfma_f32_16x16x32_bf16 v[74:77], v[178:181], v[218:221], 0
	v_mfma_f32_16x16x32_bf16 v[66:69], v[186:189], v[218:221], 0
	v_mfma_f32_16x16x32_bf16 v[126:129], v[182:185], v[198:201], v[126:129]
	v_mfma_f32_16x16x32_bf16 v[114:117], v[190:193], v[198:201], v[114:117]
	v_mfma_f32_16x16x32_bf16 v[106:109], v[182:185], v[206:209], v[106:109]
	v_mfma_f32_16x16x32_bf16 v[98:101], v[190:193], v[206:209], v[98:101]
	v_mfma_f32_16x16x32_bf16 v[90:93], v[182:185], v[214:217], v[90:93]
	v_mfma_f32_16x16x32_bf16 v[82:85], v[190:193], v[214:217], v[82:85]
	v_mfma_f32_16x16x32_bf16 v[74:77], v[182:185], v[222:225], v[74:77]
	v_mfma_f32_16x16x32_bf16 v[66:69], v[190:193], v[222:225], v[66:69]
	s_setprio 0
	s_barrier
	s_add_u32 s98, s96, 0x40000
	s_addc_u32 s99, s97, 0
	s_add_i32 s7, s71, s29
	s_mov_b32 m0, s7
	s_nop 0
	global_load_lds_dwordx4 v132, s[96:97]
	s_add_i32 m0, s7, 0x2000
	s_add_i32 s7, s72, s29
	global_load_lds_dwordx4 v136, s[96:97]
	s_mov_b32 m0, s7
	s_nop 0
	global_load_lds_dwordx4 v132, s[98:99]
	s_add_i32 m0, s7, 0x2000
	s_nop 0
	global_load_lds_dwordx4 v136, s[98:99]
	s_mov_b32 m0, s51
	s_nop 0
	global_load_lds_dwordx4 v130, s[94:95]
	s_mov_b32 m0, s60
	s_nop 0
	global_load_lds_dwordx4 v134, s[94:95]
	ds_read_b128 v[194:197], v163 offset:16384
	ds_read_b128 v[198:201], v163 offset:17408
	ds_read_b128 v[202:205], v163 offset:18432
	ds_read_b128 v[206:209], v163 offset:19456
	ds_read_b128 v[210:213], v163 offset:20480
	ds_read_b128 v[214:217], v163 offset:21504
	ds_read_b128 v[218:221], v163 offset:22528
	ds_read_b128 v[222:225], v163 offset:23552
	s_waitcnt vmcnt(8)
	s_waitcnt lgkmcnt(0)
	s_barrier
	s_setprio 1
	s_waitcnt lgkmcnt(0)
	v_mfma_f32_16x16x32_bf16 v[62:65], v[156:159], v[194:197], 0
	v_mfma_f32_16x16x32_bf16 v[54:57], v[170:173], v[194:197], 0
	v_mfma_f32_16x16x32_bf16 v[46:49], v[156:159], v[202:205], 0
	v_mfma_f32_16x16x32_bf16 v[38:41], v[170:173], v[202:205], 0
	v_mfma_f32_16x16x32_bf16 v[30:33], v[156:159], v[210:213], 0
	v_mfma_f32_16x16x32_bf16 v[22:25], v[170:173], v[210:213], 0
	v_mfma_f32_16x16x32_bf16 v[14:17], v[156:159], v[218:221], 0
	v_mfma_f32_16x16x32_bf16 v[6:9], v[170:173], v[218:221], 0
	v_mfma_f32_16x16x32_bf16 v[62:65], v[166:169], v[198:201], v[62:65]
	v_mfma_f32_16x16x32_bf16 v[54:57], v[174:177], v[198:201], v[54:57]
	v_mfma_f32_16x16x32_bf16 v[46:49], v[166:169], v[206:209], v[46:49]
	v_mfma_f32_16x16x32_bf16 v[38:41], v[174:177], v[206:209], v[38:41]
	v_mfma_f32_16x16x32_bf16 v[30:33], v[166:169], v[214:217], v[30:33]
	v_mfma_f32_16x16x32_bf16 v[22:25], v[174:177], v[214:217], v[22:25]
	v_mfma_f32_16x16x32_bf16 v[14:17], v[166:169], v[222:225], v[14:17]
	v_mfma_f32_16x16x32_bf16 v[6:9], v[174:177], v[222:225], v[6:9]
	s_setprio 0
	s_setprio 1
	v_mfma_f32_16x16x32_bf16 v[58:61], v[178:181], v[194:197], 0
	v_mfma_f32_16x16x32_bf16 v[50:53], v[186:189], v[194:197], 0
	v_mfma_f32_16x16x32_bf16 v[42:45], v[178:181], v[202:205], 0
	v_mfma_f32_16x16x32_bf16 v[34:37], v[186:189], v[202:205], 0
	v_mfma_f32_16x16x32_bf16 v[26:29], v[178:181], v[210:213], 0
	v_mfma_f32_16x16x32_bf16 v[18:21], v[186:189], v[210:213], 0
	v_mfma_f32_16x16x32_bf16 v[10:13], v[178:181], v[218:221], 0
	v_mfma_f32_16x16x32_bf16 v[2:5], v[186:189], v[218:221], 0
	v_mfma_f32_16x16x32_bf16 v[58:61], v[182:185], v[198:201], v[58:61]
	v_mfma_f32_16x16x32_bf16 v[50:53], v[190:193], v[198:201], v[50:53]
	v_mfma_f32_16x16x32_bf16 v[42:45], v[182:185], v[206:209], v[42:45]
	v_mfma_f32_16x16x32_bf16 v[34:37], v[190:193], v[206:209], v[34:37]
	v_mfma_f32_16x16x32_bf16 v[26:29], v[182:185], v[214:217], v[26:29]
	v_mfma_f32_16x16x32_bf16 v[18:21], v[190:193], v[214:217], v[18:21]
	v_mfma_f32_16x16x32_bf16 v[10:13], v[182:185], v[222:225], v[10:13]
	v_mfma_f32_16x16x32_bf16 v[2:5], v[190:193], v[222:225], v[2:5]
	s_setprio 0
	s_barrier
	s_add_u32 s98, s94, 0x40000
	s_addc_u32 s99, s95, 0
	s_add_i32 s7, 0, 0x18000
	s_add_i32 s49, 0, 0x1c000
	s_mov_b32 m0, s61
	s_nop 0
	global_load_lds_dwordx4 v130, s[98:99]
	s_mov_b32 m0, s62
	s_nop 0
	global_load_lds_dwordx4 v134, s[98:99]
	ds_read_b128 v[156:159], v232
	ds_read_b128 v[166:169], v232 offset:1024
	ds_read_b128 v[170:173], v232 offset:2048
	ds_read_b128 v[174:177], v232 offset:3072
	ds_read_b128 v[178:181], v233
	ds_read_b128 v[182:185], v233 offset:1024
	ds_read_b128 v[186:189], v233 offset:2048
	ds_read_b128 v[190:193], v233 offset:3072
	ds_read_b128 v[194:197], v163 offset:32768
	ds_read_b128 v[198:201], v163 offset:33792
	ds_read_b128 v[202:205], v163 offset:34816
	ds_read_b128 v[206:209], v163 offset:35840
	ds_read_b128 v[210:213], v163 offset:36864
	ds_read_b128 v[214:217], v163 offset:37888
	ds_read_b128 v[218:221], v163 offset:38912
	ds_read_b128 v[222:225], v163 offset:39936
	s_waitcnt vmcnt(8)
	s_waitcnt lgkmcnt(0)
	s_barrier
	s_setprio 1
	s_waitcnt lgkmcnt(0)
	v_mfma_f32_16x16x32_bf16 v[122:125], v[156:159], v[194:197], v[122:125]
	v_mfma_f32_16x16x32_bf16 v[118:121], v[170:173], v[194:197], v[118:121]
	v_mfma_f32_16x16x32_bf16 v[110:113], v[156:159], v[202:205], v[110:113]
	v_mfma_f32_16x16x32_bf16 v[102:105], v[170:173], v[202:205], v[102:105]
	v_mfma_f32_16x16x32_bf16 v[94:97], v[156:159], v[210:213], v[94:97]
	v_mfma_f32_16x16x32_bf16 v[86:89], v[170:173], v[210:213], v[86:89]
	v_mfma_f32_16x16x32_bf16 v[78:81], v[156:159], v[218:221], v[78:81]
	v_mfma_f32_16x16x32_bf16 v[70:73], v[170:173], v[218:221], v[70:73]
	v_mfma_f32_16x16x32_bf16 v[122:125], v[166:169], v[198:201], v[122:125]
	v_mfma_f32_16x16x32_bf16 v[118:121], v[174:177], v[198:201], v[118:121]
	v_mfma_f32_16x16x32_bf16 v[110:113], v[166:169], v[206:209], v[110:113]
	v_mfma_f32_16x16x32_bf16 v[102:105], v[174:177], v[206:209], v[102:105]
	v_mfma_f32_16x16x32_bf16 v[94:97], v[166:169], v[214:217], v[94:97]
	v_mfma_f32_16x16x32_bf16 v[86:89], v[174:177], v[214:217], v[86:89]
	v_mfma_f32_16x16x32_bf16 v[78:81], v[166:169], v[222:225], v[78:81]
	v_mfma_f32_16x16x32_bf16 v[70:73], v[174:177], v[222:225], v[70:73]
	s_setprio 0
	s_setprio 1
	v_mfma_f32_16x16x32_bf16 v[126:129], v[178:181], v[194:197], v[126:129]
	v_mfma_f32_16x16x32_bf16 v[114:117], v[186:189], v[194:197], v[114:117]
	v_mfma_f32_16x16x32_bf16 v[106:109], v[178:181], v[202:205], v[106:109]
	v_mfma_f32_16x16x32_bf16 v[98:101], v[186:189], v[202:205], v[98:101]
	v_mfma_f32_16x16x32_bf16 v[90:93], v[178:181], v[210:213], v[90:93]
	v_mfma_f32_16x16x32_bf16 v[82:85], v[186:189], v[210:213], v[82:85]
	v_mfma_f32_16x16x32_bf16 v[74:77], v[178:181], v[218:221], v[74:77]
	v_mfma_f32_16x16x32_bf16 v[66:69], v[186:189], v[218:221], v[66:69]
	v_mfma_f32_16x16x32_bf16 v[126:129], v[182:185], v[198:201], v[126:129]
	v_mfma_f32_16x16x32_bf16 v[114:117], v[190:193], v[198:201], v[114:117]
	v_mfma_f32_16x16x32_bf16 v[106:109], v[182:185], v[206:209], v[106:109]
	v_mfma_f32_16x16x32_bf16 v[98:101], v[190:193], v[206:209], v[98:101]
	v_mfma_f32_16x16x32_bf16 v[90:93], v[182:185], v[214:217], v[90:93]
	v_mfma_f32_16x16x32_bf16 v[82:85], v[190:193], v[214:217], v[82:85]
	v_mfma_f32_16x16x32_bf16 v[74:77], v[182:185], v[222:225], v[74:77]
	v_mfma_f32_16x16x32_bf16 v[66:69], v[190:193], v[222:225], v[66:69]
	s_setprio 0
	s_barrier
	s_add_u32 s96, s96, 0x80
	s_addc_u32 s97, s97, 0
	s_add_u32 s98, s96, 0x40000
	s_addc_u32 s99, s97, 0
	s_add_u32 s94, s94, 0x80
	s_addc_u32 s95, s95, 0
	s_add_i32 s7, s7, s29
	s_mov_b32 m0, s7
	s_nop 0
	global_load_lds_dwordx4 v132, s[96:97]
	s_add_i32 m0, s7, 0x2000
	s_add_i32 s7, s49, s29
	global_load_lds_dwordx4 v136, s[96:97]
	s_mov_b32 m0, s7
	s_nop 0
	global_load_lds_dwordx4 v132, s[98:99]
	s_add_i32 m0, s7, 0x2000
	s_nop 0
	global_load_lds_dwordx4 v136, s[98:99]
	s_mov_b32 m0, s63
	s_nop 0
	global_load_lds_dwordx4 v130, s[94:95]
	s_mov_b32 m0, s64
	s_nop 0
	global_load_lds_dwordx4 v134, s[94:95]
	ds_read_b128 v[194:197], v163 offset:49152
	ds_read_b128 v[198:201], v163 offset:50176
	ds_read_b128 v[202:205], v163 offset:51200
	ds_read_b128 v[206:209], v163 offset:52224
	ds_read_b128 v[210:213], v163 offset:53248
	ds_read_b128 v[214:217], v163 offset:54272
	ds_read_b128 v[218:221], v163 offset:55296
	ds_read_b128 v[222:225], v163 offset:56320
	s_waitcnt vmcnt(8)
	s_waitcnt lgkmcnt(0)
	s_barrier
	s_setprio 1
	s_waitcnt lgkmcnt(0)
	v_mfma_f32_16x16x32_bf16 v[62:65], v[156:159], v[194:197], v[62:65]
	v_mfma_f32_16x16x32_bf16 v[54:57], v[170:173], v[194:197], v[54:57]
	v_mfma_f32_16x16x32_bf16 v[46:49], v[156:159], v[202:205], v[46:49]
	v_mfma_f32_16x16x32_bf16 v[38:41], v[170:173], v[202:205], v[38:41]
	v_mfma_f32_16x16x32_bf16 v[30:33], v[156:159], v[210:213], v[30:33]
	v_mfma_f32_16x16x32_bf16 v[22:25], v[170:173], v[210:213], v[22:25]
	v_mfma_f32_16x16x32_bf16 v[14:17], v[156:159], v[218:221], v[14:17]
	v_mfma_f32_16x16x32_bf16 v[6:9], v[170:173], v[218:221], v[6:9]
	v_mfma_f32_16x16x32_bf16 v[62:65], v[166:169], v[198:201], v[62:65]
	v_mfma_f32_16x16x32_bf16 v[54:57], v[174:177], v[198:201], v[54:57]
	v_mfma_f32_16x16x32_bf16 v[46:49], v[166:169], v[206:209], v[46:49]
	v_mfma_f32_16x16x32_bf16 v[38:41], v[174:177], v[206:209], v[38:41]
	v_mfma_f32_16x16x32_bf16 v[30:33], v[166:169], v[214:217], v[30:33]
	v_mfma_f32_16x16x32_bf16 v[22:25], v[174:177], v[214:217], v[22:25]
	v_mfma_f32_16x16x32_bf16 v[14:17], v[166:169], v[222:225], v[14:17]
	v_mfma_f32_16x16x32_bf16 v[6:9], v[174:177], v[222:225], v[6:9]
	s_setprio 0
	s_setprio 1
	v_mfma_f32_16x16x32_bf16 v[58:61], v[178:181], v[194:197], v[58:61]
	v_mfma_f32_16x16x32_bf16 v[50:53], v[186:189], v[194:197], v[50:53]
	v_mfma_f32_16x16x32_bf16 v[42:45], v[178:181], v[202:205], v[42:45]
	v_mfma_f32_16x16x32_bf16 v[34:37], v[186:189], v[202:205], v[34:37]
	v_mfma_f32_16x16x32_bf16 v[26:29], v[178:181], v[210:213], v[26:29]
	v_mfma_f32_16x16x32_bf16 v[18:21], v[186:189], v[210:213], v[18:21]
	v_mfma_f32_16x16x32_bf16 v[10:13], v[178:181], v[218:221], v[10:13]
	v_mfma_f32_16x16x32_bf16 v[2:5], v[186:189], v[218:221], v[2:5]
	v_mfma_f32_16x16x32_bf16 v[58:61], v[182:185], v[198:201], v[58:61]
	v_mfma_f32_16x16x32_bf16 v[50:53], v[190:193], v[198:201], v[50:53]
	v_mfma_f32_16x16x32_bf16 v[42:45], v[182:185], v[206:209], v[42:45]
	v_mfma_f32_16x16x32_bf16 v[34:37], v[190:193], v[206:209], v[34:37]
	v_mfma_f32_16x16x32_bf16 v[26:29], v[182:185], v[214:217], v[26:29]
	v_mfma_f32_16x16x32_bf16 v[18:21], v[190:193], v[214:217], v[18:21]
	v_mfma_f32_16x16x32_bf16 v[10:13], v[182:185], v[222:225], v[10:13]
	v_mfma_f32_16x16x32_bf16 v[2:5], v[190:193], v[222:225], v[2:5]
	s_setprio 0
	s_barrier
	s_mov_b32 s7, s47
	s_add_u32 s88, s88, 0x100
	s_addc_u32 s89, s89, 0
	s_add_u32 s86, s86, 0x100
	s_addc_u32 s87, s87, 0
	s_cmp_ge_i32 s47, s101
	s_cbranch_scc1 .Lmy_kexit_8
.LBB0_1573:
	s_add_u32 s98, s86, 0xfffc0080
	s_addc_u32 s99, s87, -1
	s_cmp_eq_u32 s7, s100
	s_cselect_b64 s[94:95], s[90:91], s[98:99]
	s_cselect_b64 s[96:97], s[92:93], s[88:89]
	s_add_i32 s47, s7, 2
	s_nop 0
	s_mov_b32 m0, s74
	s_nop 0
	global_load_lds_dwordx4 v144, s[86:87]
	s_mov_b32 m0, s75
	s_nop 0
	global_load_lds_dwordx4 v142, s[86:87]
	ds_read_b128 v[156:159], v230
	ds_read_b128 v[166:169], v230 offset:1024
	ds_read_b128 v[170:173], v230 offset:2048
	ds_read_b128 v[174:177], v230 offset:3072
	ds_read_b128 v[178:181], v231
	ds_read_b128 v[182:185], v231 offset:1024
	ds_read_b128 v[186:189], v231 offset:2048
	ds_read_b128 v[190:193], v231 offset:3072
	ds_read_b128 v[194:197], v163
	ds_read_b128 v[198:201], v163 offset:1024
	ds_read_b128 v[202:205], v163 offset:2048
	ds_read_b128 v[206:209], v163 offset:3072
	ds_read_b128 v[210:213], v163 offset:4096
	ds_read_b128 v[214:217], v163 offset:5120
	ds_read_b128 v[218:221], v163 offset:6144
	ds_read_b128 v[222:225], v163 offset:7168
	s_waitcnt vmcnt(8)
	s_waitcnt lgkmcnt(0)
	s_barrier
	s_setprio 1
	s_waitcnt lgkmcnt(0)
	v_mfma_f32_16x16x32_bf16 v[122:125], v[156:159], v[194:197], v[122:125]
	v_mfma_f32_16x16x32_bf16 v[118:121], v[170:173], v[194:197], v[118:121]
	v_mfma_f32_16x16x32_bf16 v[110:113], v[156:159], v[202:205], v[110:113]
	v_mfma_f32_16x16x32_bf16 v[102:105], v[170:173], v[202:205], v[102:105]
	v_mfma_f32_16x16x32_bf16 v[94:97], v[156:159], v[210:213], v[94:97]
	v_mfma_f32_16x16x32_bf16 v[86:89], v[170:173], v[210:213], v[86:89]
	v_mfma_f32_16x16x32_bf16 v[78:81], v[156:159], v[218:221], v[78:81]
	v_mfma_f32_16x16x32_bf16 v[70:73], v[170:173], v[218:221], v[70:73]
	v_mfma_f32_16x16x32_bf16 v[122:125], v[166:169], v[198:201], v[122:125]
	v_mfma_f32_16x16x32_bf16 v[118:121], v[174:177], v[198:201], v[118:121]
	v_mfma_f32_16x16x32_bf16 v[110:113], v[166:169], v[206:209], v[110:113]
	v_mfma_f32_16x16x32_bf16 v[102:105], v[174:177], v[206:209], v[102:105]
	v_mfma_f32_16x16x32_bf16 v[94:97], v[166:169], v[214:217], v[94:97]
	v_mfma_f32_16x16x32_bf16 v[86:89], v[174:177], v[214:217], v[86:89]
	v_mfma_f32_16x16x32_bf16 v[78:81], v[166:169], v[222:225], v[78:81]
	v_mfma_f32_16x16x32_bf16 v[70:73], v[174:177], v[222:225], v[70:73]
	s_setprio 0
	s_setprio 1
	v_mfma_f32_16x16x32_bf16 v[126:129], v[178:181], v[194:197], v[126:129]
	v_mfma_f32_16x16x32_bf16 v[114:117], v[186:189], v[194:197], v[114:117]
	v_mfma_f32_16x16x32_bf16 v[106:109], v[178:181], v[202:205], v[106:109]
	v_mfma_f32_16x16x32_bf16 v[98:101], v[186:189], v[202:205], v[98:101]
	v_mfma_f32_16x16x32_bf16 v[90:93], v[178:181], v[210:213], v[90:93]
	v_mfma_f32_16x16x32_bf16 v[82:85], v[186:189], v[210:213], v[82:85]
	v_mfma_f32_16x16x32_bf16 v[74:77], v[178:181], v[218:221], v[74:77]
	v_mfma_f32_16x16x32_bf16 v[66:69], v[186:189], v[218:221], v[66:69]
	v_mfma_f32_16x16x32_bf16 v[126:129], v[182:185], v[198:201], v[126:129]
	v_mfma_f32_16x16x32_bf16 v[114:117], v[190:193], v[198:201], v[114:117]
	v_mfma_f32_16x16x32_bf16 v[106:109], v[182:185], v[206:209], v[106:109]
	v_mfma_f32_16x16x32_bf16 v[98:101], v[190:193], v[206:209], v[98:101]
	v_mfma_f32_16x16x32_bf16 v[90:93], v[182:185], v[214:217], v[90:93]
	v_mfma_f32_16x16x32_bf16 v[82:85], v[190:193], v[214:217], v[82:85]
	v_mfma_f32_16x16x32_bf16 v[74:77], v[182:185], v[222:225], v[74:77]
	v_mfma_f32_16x16x32_bf16 v[66:69], v[190:193], v[222:225], v[66:69]
	s_setprio 0
	s_barrier
	s_add_u32 s98, s96, 0x40000
	s_addc_u32 s99, s97, 0
	s_add_i32 s7, s71, s29
	s_mov_b32 m0, s7
	s_nop 0
	global_load_lds_dwordx4 v132, s[96:97]
	s_add_i32 m0, s7, 0x2000
	s_add_i32 s7, s72, s29
	global_load_lds_dwordx4 v136, s[96:97]
	s_mov_b32 m0, s7
	s_nop 0
	global_load_lds_dwordx4 v132, s[98:99]
	s_add_i32 m0, s7, 0x2000
	s_nop 0
	global_load_lds_dwordx4 v136, s[98:99]
	s_mov_b32 m0, s51
	s_nop 0
	global_load_lds_dwordx4 v130, s[94:95]
	s_mov_b32 m0, s60
	s_nop 0
	global_load_lds_dwordx4 v134, s[94:95]
	ds_read_b128 v[194:197], v163 offset:16384
	ds_read_b128 v[198:201], v163 offset:17408
	ds_read_b128 v[202:205], v163 offset:18432
	ds_read_b128 v[206:209], v163 offset:19456
	ds_read_b128 v[210:213], v163 offset:20480
	ds_read_b128 v[214:217], v163 offset:21504
	ds_read_b128 v[218:221], v163 offset:22528
	ds_read_b128 v[222:225], v163 offset:23552
	s_waitcnt vmcnt(8)
	s_waitcnt lgkmcnt(0)
	s_barrier
	s_setprio 1
	s_waitcnt lgkmcnt(0)
	v_mfma_f32_16x16x32_bf16 v[62:65], v[156:159], v[194:197], v[62:65]
	v_mfma_f32_16x16x32_bf16 v[54:57], v[170:173], v[194:197], v[54:57]
	v_mfma_f32_16x16x32_bf16 v[46:49], v[156:159], v[202:205], v[46:49]
	v_mfma_f32_16x16x32_bf16 v[38:41], v[170:173], v[202:205], v[38:41]
	v_mfma_f32_16x16x32_bf16 v[30:33], v[156:159], v[210:213], v[30:33]
	v_mfma_f32_16x16x32_bf16 v[22:25], v[170:173], v[210:213], v[22:25]
	v_mfma_f32_16x16x32_bf16 v[14:17], v[156:159], v[218:221], v[14:17]
	v_mfma_f32_16x16x32_bf16 v[6:9], v[170:173], v[218:221], v[6:9]
	v_mfma_f32_16x16x32_bf16 v[62:65], v[166:169], v[198:201], v[62:65]
	v_mfma_f32_16x16x32_bf16 v[54:57], v[174:177], v[198:201], v[54:57]
	v_mfma_f32_16x16x32_bf16 v[46:49], v[166:169], v[206:209], v[46:49]
	v_mfma_f32_16x16x32_bf16 v[38:41], v[174:177], v[206:209], v[38:41]
	v_mfma_f32_16x16x32_bf16 v[30:33], v[166:169], v[214:217], v[30:33]
	v_mfma_f32_16x16x32_bf16 v[22:25], v[174:177], v[214:217], v[22:25]
	v_mfma_f32_16x16x32_bf16 v[14:17], v[166:169], v[222:225], v[14:17]
	v_mfma_f32_16x16x32_bf16 v[6:9], v[174:177], v[222:225], v[6:9]
	s_setprio 0
	s_setprio 1
	v_mfma_f32_16x16x32_bf16 v[58:61], v[178:181], v[194:197], v[58:61]
	v_mfma_f32_16x16x32_bf16 v[50:53], v[186:189], v[194:197], v[50:53]
	v_mfma_f32_16x16x32_bf16 v[42:45], v[178:181], v[202:205], v[42:45]
	v_mfma_f32_16x16x32_bf16 v[34:37], v[186:189], v[202:205], v[34:37]
	v_mfma_f32_16x16x32_bf16 v[26:29], v[178:181], v[210:213], v[26:29]
	v_mfma_f32_16x16x32_bf16 v[18:21], v[186:189], v[210:213], v[18:21]
	v_mfma_f32_16x16x32_bf16 v[10:13], v[178:181], v[218:221], v[10:13]
	v_mfma_f32_16x16x32_bf16 v[2:5], v[186:189], v[218:221], v[2:5]
	v_mfma_f32_16x16x32_bf16 v[58:61], v[182:185], v[198:201], v[58:61]
	v_mfma_f32_16x16x32_bf16 v[50:53], v[190:193], v[198:201], v[50:53]
	v_mfma_f32_16x16x32_bf16 v[42:45], v[182:185], v[206:209], v[42:45]
	v_mfma_f32_16x16x32_bf16 v[34:37], v[190:193], v[206:209], v[34:37]
	v_mfma_f32_16x16x32_bf16 v[26:29], v[182:185], v[214:217], v[26:29]
	v_mfma_f32_16x16x32_bf16 v[18:21], v[190:193], v[214:217], v[18:21]
	v_mfma_f32_16x16x32_bf16 v[10:13], v[182:185], v[222:225], v[10:13]
	v_mfma_f32_16x16x32_bf16 v[2:5], v[190:193], v[222:225], v[2:5]
	s_setprio 0
	s_barrier
	s_add_u32 s98, s94, 0x40000
	s_addc_u32 s99, s95, 0
	s_add_i32 s7, 0, 0x18000
	s_add_i32 s49, 0, 0x1c000
	s_mov_b32 m0, s61
	s_nop 0
	global_load_lds_dwordx4 v130, s[98:99]
	s_mov_b32 m0, s62
	s_nop 0
	global_load_lds_dwordx4 v134, s[98:99]
	ds_read_b128 v[156:159], v232
	ds_read_b128 v[166:169], v232 offset:1024
	ds_read_b128 v[170:173], v232 offset:2048
	ds_read_b128 v[174:177], v232 offset:3072
	ds_read_b128 v[178:181], v233
	ds_read_b128 v[182:185], v233 offset:1024
	ds_read_b128 v[186:189], v233 offset:2048
	ds_read_b128 v[190:193], v233 offset:3072
	ds_read_b128 v[194:197], v163 offset:32768
	ds_read_b128 v[198:201], v163 offset:33792
	ds_read_b128 v[202:205], v163 offset:34816
	ds_read_b128 v[206:209], v163 offset:35840
	ds_read_b128 v[210:213], v163 offset:36864
	ds_read_b128 v[214:217], v163 offset:37888
	ds_read_b128 v[218:221], v163 offset:38912
	ds_read_b128 v[222:225], v163 offset:39936
	s_waitcnt vmcnt(8)
	s_waitcnt lgkmcnt(0)
	s_barrier
	s_setprio 1
	s_waitcnt lgkmcnt(0)
	v_mfma_f32_16x16x32_bf16 v[122:125], v[156:159], v[194:197], v[122:125]
	v_mfma_f32_16x16x32_bf16 v[118:121], v[170:173], v[194:197], v[118:121]
	v_mfma_f32_16x16x32_bf16 v[110:113], v[156:159], v[202:205], v[110:113]
	v_mfma_f32_16x16x32_bf16 v[102:105], v[170:173], v[202:205], v[102:105]
	v_mfma_f32_16x16x32_bf16 v[94:97], v[156:159], v[210:213], v[94:97]
	v_mfma_f32_16x16x32_bf16 v[86:89], v[170:173], v[210:213], v[86:89]
	v_mfma_f32_16x16x32_bf16 v[78:81], v[156:159], v[218:221], v[78:81]
	v_mfma_f32_16x16x32_bf16 v[70:73], v[170:173], v[218:221], v[70:73]
	v_mfma_f32_16x16x32_bf16 v[122:125], v[166:169], v[198:201], v[122:125]
	v_mfma_f32_16x16x32_bf16 v[118:121], v[174:177], v[198:201], v[118:121]
	v_mfma_f32_16x16x32_bf16 v[110:113], v[166:169], v[206:209], v[110:113]
	v_mfma_f32_16x16x32_bf16 v[102:105], v[174:177], v[206:209], v[102:105]
	v_mfma_f32_16x16x32_bf16 v[94:97], v[166:169], v[214:217], v[94:97]
	v_mfma_f32_16x16x32_bf16 v[86:89], v[174:177], v[214:217], v[86:89]
	v_mfma_f32_16x16x32_bf16 v[78:81], v[166:169], v[222:225], v[78:81]
	v_mfma_f32_16x16x32_bf16 v[70:73], v[174:177], v[222:225], v[70:73]
	s_setprio 0
	s_setprio 1
	v_mfma_f32_16x16x32_bf16 v[126:129], v[178:181], v[194:197], v[126:129]
	v_mfma_f32_16x16x32_bf16 v[114:117], v[186:189], v[194:197], v[114:117]
	v_mfma_f32_16x16x32_bf16 v[106:109], v[178:181], v[202:205], v[106:109]
	v_mfma_f32_16x16x32_bf16 v[98:101], v[186:189], v[202:205], v[98:101]
	v_mfma_f32_16x16x32_bf16 v[90:93], v[178:181], v[210:213], v[90:93]
	v_mfma_f32_16x16x32_bf16 v[82:85], v[186:189], v[210:213], v[82:85]
	v_mfma_f32_16x16x32_bf16 v[74:77], v[178:181], v[218:221], v[74:77]
	v_mfma_f32_16x16x32_bf16 v[66:69], v[186:189], v[218:221], v[66:69]
	v_mfma_f32_16x16x32_bf16 v[126:129], v[182:185], v[198:201], v[126:129]
	v_mfma_f32_16x16x32_bf16 v[114:117], v[190:193], v[198:201], v[114:117]
	v_mfma_f32_16x16x32_bf16 v[106:109], v[182:185], v[206:209], v[106:109]
	v_mfma_f32_16x16x32_bf16 v[98:101], v[190:193], v[206:209], v[98:101]
	v_mfma_f32_16x16x32_bf16 v[90:93], v[182:185], v[214:217], v[90:93]
	v_mfma_f32_16x16x32_bf16 v[82:85], v[190:193], v[214:217], v[82:85]
	v_mfma_f32_16x16x32_bf16 v[74:77], v[182:185], v[222:225], v[74:77]
	v_mfma_f32_16x16x32_bf16 v[66:69], v[190:193], v[222:225], v[66:69]
	s_setprio 0
	s_barrier
	s_add_u32 s96, s96, 0x80
	s_addc_u32 s97, s97, 0
	s_add_u32 s98, s96, 0x40000
	s_addc_u32 s99, s97, 0
	s_add_u32 s94, s94, 0x80
	s_addc_u32 s95, s95, 0
	s_add_i32 s7, s7, s29
	s_mov_b32 m0, s7
	s_nop 0
	global_load_lds_dwordx4 v132, s[96:97]
	s_add_i32 m0, s7, 0x2000
	s_add_i32 s7, s49, s29
	global_load_lds_dwordx4 v136, s[96:97]
	s_mov_b32 m0, s7
	s_nop 0
	global_load_lds_dwordx4 v132, s[98:99]
	s_add_i32 m0, s7, 0x2000
	s_nop 0
	global_load_lds_dwordx4 v136, s[98:99]
	s_mov_b32 m0, s63
	s_nop 0
	global_load_lds_dwordx4 v130, s[94:95]
	s_mov_b32 m0, s64
	s_nop 0
	global_load_lds_dwordx4 v134, s[94:95]
	ds_read_b128 v[194:197], v163 offset:49152
	ds_read_b128 v[198:201], v163 offset:50176
	ds_read_b128 v[202:205], v163 offset:51200
	ds_read_b128 v[206:209], v163 offset:52224
	ds_read_b128 v[210:213], v163 offset:53248
	ds_read_b128 v[214:217], v163 offset:54272
	ds_read_b128 v[218:221], v163 offset:55296
	ds_read_b128 v[222:225], v163 offset:56320
	s_waitcnt vmcnt(8)
	s_waitcnt lgkmcnt(0)
	s_barrier
	s_setprio 1
	s_waitcnt lgkmcnt(0)
	v_mfma_f32_16x16x32_bf16 v[62:65], v[156:159], v[194:197], v[62:65]
	v_mfma_f32_16x16x32_bf16 v[54:57], v[170:173], v[194:197], v[54:57]
	v_mfma_f32_16x16x32_bf16 v[46:49], v[156:159], v[202:205], v[46:49]
	v_mfma_f32_16x16x32_bf16 v[38:41], v[170:173], v[202:205], v[38:41]
	v_mfma_f32_16x16x32_bf16 v[30:33], v[156:159], v[210:213], v[30:33]
	v_mfma_f32_16x16x32_bf16 v[22:25], v[170:173], v[210:213], v[22:25]
	v_mfma_f32_16x16x32_bf16 v[14:17], v[156:159], v[218:221], v[14:17]
	v_mfma_f32_16x16x32_bf16 v[6:9], v[170:173], v[218:221], v[6:9]
	v_mfma_f32_16x16x32_bf16 v[62:65], v[166:169], v[198:201], v[62:65]
	v_mfma_f32_16x16x32_bf16 v[54:57], v[174:177], v[198:201], v[54:57]
	v_mfma_f32_16x16x32_bf16 v[46:49], v[166:169], v[206:209], v[46:49]
	v_mfma_f32_16x16x32_bf16 v[38:41], v[174:177], v[206:209], v[38:41]
	v_mfma_f32_16x16x32_bf16 v[30:33], v[166:169], v[214:217], v[30:33]
	v_mfma_f32_16x16x32_bf16 v[22:25], v[174:177], v[214:217], v[22:25]
	v_mfma_f32_16x16x32_bf16 v[14:17], v[166:169], v[222:225], v[14:17]
	v_mfma_f32_16x16x32_bf16 v[6:9], v[174:177], v[222:225], v[6:9]
	s_setprio 0
	s_setprio 1
	v_mfma_f32_16x16x32_bf16 v[58:61], v[178:181], v[194:197], v[58:61]
	v_mfma_f32_16x16x32_bf16 v[50:53], v[186:189], v[194:197], v[50:53]
	v_mfma_f32_16x16x32_bf16 v[42:45], v[178:181], v[202:205], v[42:45]
	v_mfma_f32_16x16x32_bf16 v[34:37], v[186:189], v[202:205], v[34:37]
	v_mfma_f32_16x16x32_bf16 v[26:29], v[178:181], v[210:213], v[26:29]
	v_mfma_f32_16x16x32_bf16 v[18:21], v[186:189], v[210:213], v[18:21]
	v_mfma_f32_16x16x32_bf16 v[10:13], v[178:181], v[218:221], v[10:13]
	v_mfma_f32_16x16x32_bf16 v[2:5], v[186:189], v[218:221], v[2:5]
	v_mfma_f32_16x16x32_bf16 v[58:61], v[182:185], v[198:201], v[58:61]
	v_mfma_f32_16x16x32_bf16 v[50:53], v[190:193], v[198:201], v[50:53]
	v_mfma_f32_16x16x32_bf16 v[42:45], v[182:185], v[206:209], v[42:45]
	v_mfma_f32_16x16x32_bf16 v[34:37], v[190:193], v[206:209], v[34:37]
	v_mfma_f32_16x16x32_bf16 v[26:29], v[182:185], v[214:217], v[26:29]
	v_mfma_f32_16x16x32_bf16 v[18:21], v[190:193], v[214:217], v[18:21]
	v_mfma_f32_16x16x32_bf16 v[10:13], v[182:185], v[222:225], v[10:13]
	v_mfma_f32_16x16x32_bf16 v[2:5], v[190:193], v[222:225], v[2:5]
	s_setprio 0
	s_barrier
	s_mov_b32 s7, s47
	s_add_u32 s88, s88, 0x100
	s_addc_u32 s89, s89, 0
	s_add_u32 s86, s86, 0x100
	s_addc_u32 s87, s87, 0
	s_cmp_ge_i32 s47, s101
	s_cbranch_scc0 .LBB0_1573

.LBB0_1761:
	v_cmp_gt_i32_e32 vcc, 1, v138
	s_cbranch_vccnz .LBB0_1823
	v_lshl_add_u64 v[152:153], v[2:3], 0, s[14:15]
	v_add_u32_e32 v154, -2, v138
	s_waitcnt lgkmcnt(0)
	v_lshl_add_u64 v[150:151], v[4:5], 0, s[18:19]
	s_mov_b32 s5, 0
	s_nop 0
	v_readfirstlane_b32 s86, v152
	v_readfirstlane_b32 s87, v153
	v_readfirstlane_b32 s88, v150
	v_readfirstlane_b32 s89, v151
	v_readfirstlane_b32 s90, v146
	v_readfirstlane_b32 s91, v147
	v_readfirstlane_b32 s92, v148
	v_readfirstlane_b32 s93, v149
	v_readfirstlane_b32 s100, v154
	v_readfirstlane_b32 s101, v138
	v_add_u32_e32 v230, s74, v141
	v_add_u32_e32 v231, s75, v141
	v_add_u32_e32 v232, 0x18000, v141
	v_add_u32_e32 v233, 0x1c000, v141
	s_add_u32 s98, s86, 0xfffc0080
	s_addc_u32 s99, s87, -1
	s_cmp_eq_u32 s5, s100
	s_cselect_b64 s[94:95], s[90:91], s[98:99]
	s_cselect_b64 s[96:97], s[92:93], s[88:89]
	s_add_i32 s29, s5, 2
	s_nop 0
	s_add_i32 m0, s47, 0xc000
	s_nop 0
	global_load_lds_dwordx4 v144, s[86:87]
	s_add_i32 m0, s47, 0xe000
	s_nop 0
	global_load_lds_dwordx4 v142, s[86:87]
	ds_read_b128 v[164:167], v230
	ds_read_b128 v[168:171], v230 offset:1024
	ds_read_b128 v[172:175], v230 offset:2048
	ds_read_b128 v[176:179], v230 offset:3072
	ds_read_b128 v[180:183], v231
	ds_read_b128 v[184:187], v231 offset:1024
	ds_read_b128 v[188:191], v231 offset:2048
	ds_read_b128 v[192:195], v231 offset:3072
	ds_read_b128 v[196:199], v160
	ds_read_b128 v[200:203], v160 offset:1024
	ds_read_b128 v[204:207], v160 offset:2048
	ds_read_b128 v[208:211], v160 offset:3072
	ds_read_b128 v[212:215], v160 offset:4096
	ds_read_b128 v[216:219], v160 offset:5120
	ds_read_b128 v[220:223], v160 offset:6144
	ds_read_b128 v[224:227], v160 offset:7168
	s_waitcnt vmcnt(8)
	s_waitcnt lgkmcnt(0)
	s_barrier
	s_setprio 1
	s_waitcnt lgkmcnt(0)
	v_mfma_f32_16x16x32_bf16 v[122:125], v[164:167], v[196:199], 0
	v_mfma_f32_16x16x32_bf16 v[118:121], v[172:175], v[196:199], 0
	v_mfma_f32_16x16x32_bf16 v[110:113], v[164:167], v[204:207], 0
	v_mfma_f32_16x16x32_bf16 v[102:105], v[172:175], v[204:207], 0
	v_mfma_f32_16x16x32_bf16 v[94:97], v[164:167], v[212:215], 0
	v_mfma_f32_16x16x32_bf16 v[86:89], v[172:175], v[212:215], 0
	v_mfma_f32_16x16x32_bf16 v[78:81], v[164:167], v[220:223], 0
	v_mfma_f32_16x16x32_bf16 v[70:73], v[172:175], v[220:223], 0
	v_mfma_f32_16x16x32_bf16 v[122:125], v[168:171], v[200:203], v[122:125]
	v_mfma_f32_16x16x32_bf16 v[118:121], v[176:179], v[200:203], v[118:121]
	v_mfma_f32_16x16x32_bf16 v[110:113], v[168:171], v[208:211], v[110:113]
	v_mfma_f32_16x16x32_bf16 v[102:105], v[176:179], v[208:211], v[102:105]
	v_mfma_f32_16x16x32_bf16 v[94:97], v[168:171], v[216:219], v[94:97]
	v_mfma_f32_16x16x32_bf16 v[86:89], v[176:179], v[216:219], v[86:89]
	v_mfma_f32_16x16x32_bf16 v[78:81], v[168:171], v[224:227], v[78:81]
	v_mfma_f32_16x16x32_bf16 v[70:73], v[176:179], v[224:227], v[70:73]
	s_setprio 0
	s_setprio 1
	v_mfma_f32_16x16x32_bf16 v[126:129], v[180:183], v[196:199], 0
	v_mfma_f32_16x16x32_bf16 v[114:117], v[188:191], v[196:199], 0
	v_mfma_f32_16x16x32_bf16 v[106:109], v[180:183], v[204:207], 0
	v_mfma_f32_16x16x32_bf16 v[98:101], v[188:191], v[204:207], 0
	v_mfma_f32_16x16x32_bf16 v[90:93], v[180:183], v[212:215], 0
	v_mfma_f32_16x16x32_bf16 v[82:85], v[188:191], v[212:215], 0
	v_mfma_f32_16x16x32_bf16 v[74:77], v[180:183], v[220:223], 0
	v_mfma_f32_16x16x32_bf16 v[66:69], v[188:191], v[220:223], 0
	v_mfma_f32_16x16x32_bf16 v[126:129], v[184:187], v[200:203], v[126:129]
	v_mfma_f32_16x16x32_bf16 v[114:117], v[192:195], v[200:203], v[114:117]
	v_mfma_f32_16x16x32_bf16 v[106:109], v[184:187], v[208:211], v[106:109]
	v_mfma_f32_16x16x32_bf16 v[98:101], v[192:195], v[208:211], v[98:101]
	v_mfma_f32_16x16x32_bf16 v[90:93], v[184:187], v[216:219], v[90:93]
	v_mfma_f32_16x16x32_bf16 v[82:85], v[192:195], v[216:219], v[82:85]
	v_mfma_f32_16x16x32_bf16 v[74:77], v[184:187], v[224:227], v[74:77]
	v_mfma_f32_16x16x32_bf16 v[66:69], v[192:195], v[224:227], v[66:69]
	s_setprio 0
	s_barrier
	s_add_u32 s98, s96, 0x40000
	s_addc_u32 s99, s97, 0
	s_add_i32 s5, s74, s23
	s_mov_b32 m0, s5
	s_nop 0
	global_load_lds_dwordx4 v132, s[96:97]
	s_add_i32 m0, s5, 0x2000
	s_add_i32 s5, s75, s23
	global_load_lds_dwordx4 v136, s[96:97]
	s_mov_b32 m0, s5
	s_nop 0
	global_load_lds_dwordx4 v132, s[98:99]
	s_add_i32 m0, s5, 0x2000
	s_nop 0
	global_load_lds_dwordx4 v136, s[98:99]
	s_mov_b32 m0, s47
	s_nop 0
	global_load_lds_dwordx4 v130, s[94:95]
	s_mov_b32 m0, s56
	s_nop 0
	global_load_lds_dwordx4 v134, s[94:95]
	ds_read_b128 v[196:199], v160 offset:16384
	ds_read_b128 v[200:203], v160 offset:17408
	ds_read_b128 v[204:207], v160 offset:18432
	ds_read_b128 v[208:211], v160 offset:19456
	ds_read_b128 v[212:215], v160 offset:20480
	ds_read_b128 v[216:219], v160 offset:21504
	ds_read_b128 v[220:223], v160 offset:22528
	ds_read_b128 v[224:227], v160 offset:23552
	s_waitcnt vmcnt(8)
	s_waitcnt lgkmcnt(0)
	s_barrier
	s_setprio 1
	s_waitcnt lgkmcnt(0)
	v_mfma_f32_16x16x32_bf16 v[62:65], v[164:167], v[196:199], 0
	v_mfma_f32_16x16x32_bf16 v[54:57], v[172:175], v[196:199], 0
	v_mfma_f32_16x16x32_bf16 v[46:49], v[164:167], v[204:207], 0
	v_mfma_f32_16x16x32_bf16 v[38:41], v[172:175], v[204:207], 0
	v_mfma_f32_16x16x32_bf16 v[30:33], v[164:167], v[212:215], 0
	v_mfma_f32_16x16x32_bf16 v[22:25], v[172:175], v[212:215], 0
	v_mfma_f32_16x16x32_bf16 v[14:17], v[164:167], v[220:223], 0
	v_mfma_f32_16x16x32_bf16 v[6:9], v[172:175], v[220:223], 0
	v_mfma_f32_16x16x32_bf16 v[62:65], v[168:171], v[200:203], v[62:65]
	v_mfma_f32_16x16x32_bf16 v[54:57], v[176:179], v[200:203], v[54:57]
	v_mfma_f32_16x16x32_bf16 v[46:49], v[168:171], v[208:211], v[46:49]
	v_mfma_f32_16x16x32_bf16 v[38:41], v[176:179], v[208:211], v[38:41]
	v_mfma_f32_16x16x32_bf16 v[30:33], v[168:171], v[216:219], v[30:33]
	v_mfma_f32_16x16x32_bf16 v[22:25], v[176:179], v[216:219], v[22:25]
	v_mfma_f32_16x16x32_bf16 v[14:17], v[168:171], v[224:227], v[14:17]
	v_mfma_f32_16x16x32_bf16 v[6:9], v[176:179], v[224:227], v[6:9]
	s_setprio 0
	s_setprio 1
	v_mfma_f32_16x16x32_bf16 v[58:61], v[180:183], v[196:199], 0
	v_mfma_f32_16x16x32_bf16 v[50:53], v[188:191], v[196:199], 0
	v_mfma_f32_16x16x32_bf16 v[42:45], v[180:183], v[204:207], 0
	v_mfma_f32_16x16x32_bf16 v[34:37], v[188:191], v[204:207], 0
	v_mfma_f32_16x16x32_bf16 v[26:29], v[180:183], v[212:215], 0
	v_mfma_f32_16x16x32_bf16 v[18:21], v[188:191], v[212:215], 0
	v_mfma_f32_16x16x32_bf16 v[10:13], v[180:183], v[220:223], 0
	v_mfma_f32_16x16x32_bf16 v[2:5], v[188:191], v[220:223], 0
	v_mfma_f32_16x16x32_bf16 v[58:61], v[184:187], v[200:203], v[58:61]
	v_mfma_f32_16x16x32_bf16 v[50:53], v[192:195], v[200:203], v[50:53]
	v_mfma_f32_16x16x32_bf16 v[42:45], v[184:187], v[208:211], v[42:45]
	v_mfma_f32_16x16x32_bf16 v[34:37], v[192:195], v[208:211], v[34:37]
	v_mfma_f32_16x16x32_bf16 v[26:29], v[184:187], v[216:219], v[26:29]
	v_mfma_f32_16x16x32_bf16 v[18:21], v[192:195], v[216:219], v[18:21]
	v_mfma_f32_16x16x32_bf16 v[10:13], v[184:187], v[224:227], v[10:13]
	v_mfma_f32_16x16x32_bf16 v[2:5], v[192:195], v[224:227], v[2:5]
	s_setprio 0
	s_barrier
	s_add_u32 s98, s94, 0x40000
	s_addc_u32 s99, s95, 0
	s_add_i32 s5, 0, 0x18000
	s_add_i32 s45, 0, 0x1c000
	s_mov_b32 m0, s57
	s_nop 0
	global_load_lds_dwordx4 v130, s[98:99]
	s_mov_b32 m0, s58
	s_nop 0
	global_load_lds_dwordx4 v134, s[98:99]
	ds_read_b128 v[164:167], v232
	ds_read_b128 v[168:171], v232 offset:1024
	ds_read_b128 v[172:175], v232 offset:2048
	ds_read_b128 v[176:179], v232 offset:3072
	ds_read_b128 v[180:183], v233
	ds_read_b128 v[184:187], v233 offset:1024
	ds_read_b128 v[188:191], v233 offset:2048
	ds_read_b128 v[192:195], v233 offset:3072
	ds_read_b128 v[196:199], v160 offset:32768
	ds_read_b128 v[200:203], v160 offset:33792
	ds_read_b128 v[204:207], v160 offset:34816
	ds_read_b128 v[208:211], v160 offset:35840
	ds_read_b128 v[212:215], v160 offset:36864
	ds_read_b128 v[216:219], v160 offset:37888
	ds_read_b128 v[220:223], v160 offset:38912
	ds_read_b128 v[224:227], v160 offset:39936
	s_waitcnt vmcnt(8)
	s_waitcnt lgkmcnt(0)
	s_barrier
	s_setprio 1
	s_waitcnt lgkmcnt(0)
	v_mfma_f32_16x16x32_bf16 v[122:125], v[164:167], v[196:199], v[122:125]
	v_mfma_f32_16x16x32_bf16 v[118:121], v[172:175], v[196:199], v[118:121]
	v_mfma_f32_16x16x32_bf16 v[110:113], v[164:167], v[204:207], v[110:113]
	v_mfma_f32_16x16x32_bf16 v[102:105], v[172:175], v[204:207], v[102:105]
	v_mfma_f32_16x16x32_bf16 v[94:97], v[164:167], v[212:215], v[94:97]
	v_mfma_f32_16x16x32_bf16 v[86:89], v[172:175], v[212:215], v[86:89]
	v_mfma_f32_16x16x32_bf16 v[78:81], v[164:167], v[220:223], v[78:81]
	v_mfma_f32_16x16x32_bf16 v[70:73], v[172:175], v[220:223], v[70:73]
	v_mfma_f32_16x16x32_bf16 v[122:125], v[168:171], v[200:203], v[122:125]
	v_mfma_f32_16x16x32_bf16 v[118:121], v[176:179], v[200:203], v[118:121]
	v_mfma_f32_16x16x32_bf16 v[110:113], v[168:171], v[208:211], v[110:113]
	v_mfma_f32_16x16x32_bf16 v[102:105], v[176:179], v[208:211], v[102:105]
	v_mfma_f32_16x16x32_bf16 v[94:97], v[168:171], v[216:219], v[94:97]
	v_mfma_f32_16x16x32_bf16 v[86:89], v[176:179], v[216:219], v[86:89]
	v_mfma_f32_16x16x32_bf16 v[78:81], v[168:171], v[224:227], v[78:81]
	v_mfma_f32_16x16x32_bf16 v[70:73], v[176:179], v[224:227], v[70:73]
	s_setprio 0
	s_setprio 1
	v_mfma_f32_16x16x32_bf16 v[126:129], v[180:183], v[196:199], v[126:129]
	v_mfma_f32_16x16x32_bf16 v[114:117], v[188:191], v[196:199], v[114:117]
	v_mfma_f32_16x16x32_bf16 v[106:109], v[180:183], v[204:207], v[106:109]
	v_mfma_f32_16x16x32_bf16 v[98:101], v[188:191], v[204:207], v[98:101]
	v_mfma_f32_16x16x32_bf16 v[90:93], v[180:183], v[212:215], v[90:93]
	v_mfma_f32_16x16x32_bf16 v[82:85], v[188:191], v[212:215], v[82:85]
	v_mfma_f32_16x16x32_bf16 v[74:77], v[180:183], v[220:223], v[74:77]
	v_mfma_f32_16x16x32_bf16 v[66:69], v[188:191], v[220:223], v[66:69]
	v_mfma_f32_16x16x32_bf16 v[126:129], v[184:187], v[200:203], v[126:129]
	v_mfma_f32_16x16x32_bf16 v[114:117], v[192:195], v[200:203], v[114:117]
	v_mfma_f32_16x16x32_bf16 v[106:109], v[184:187], v[208:211], v[106:109]
	v_mfma_f32_16x16x32_bf16 v[98:101], v[192:195], v[208:211], v[98:101]
	v_mfma_f32_16x16x32_bf16 v[90:93], v[184:187], v[216:219], v[90:93]
	v_mfma_f32_16x16x32_bf16 v[82:85], v[192:195], v[216:219], v[82:85]
	v_mfma_f32_16x16x32_bf16 v[74:77], v[184:187], v[224:227], v[74:77]
	v_mfma_f32_16x16x32_bf16 v[66:69], v[192:195], v[224:227], v[66:69]
	s_setprio 0
	s_barrier
	s_add_u32 s96, s96, 0x80
	s_addc_u32 s97, s97, 0
	s_add_u32 s98, s96, 0x40000
	s_addc_u32 s99, s97, 0
	s_add_u32 s94, s94, 0x80
	s_addc_u32 s95, s95, 0
	s_add_i32 s5, s5, s23
	s_mov_b32 m0, s5
	s_nop 0
	global_load_lds_dwordx4 v132, s[96:97]
	s_add_i32 m0, s5, 0x2000
	s_add_i32 s5, s45, s23
	global_load_lds_dwordx4 v136, s[96:97]
	s_mov_b32 m0, s5
	s_nop 0
	global_load_lds_dwordx4 v132, s[98:99]
	s_add_i32 m0, s5, 0x2000
	s_nop 0
	global_load_lds_dwordx4 v136, s[98:99]
	s_mov_b32 m0, s64
	s_nop 0
	global_load_lds_dwordx4 v130, s[94:95]
	s_mov_b32 m0, s65
	s_nop 0
	global_load_lds_dwordx4 v134, s[94:95]
	ds_read_b128 v[196:199], v160 offset:49152
	ds_read_b128 v[200:203], v160 offset:50176
	ds_read_b128 v[204:207], v160 offset:51200
	ds_read_b128 v[208:211], v160 offset:52224
	ds_read_b128 v[212:215], v160 offset:53248
	ds_read_b128 v[216:219], v160 offset:54272
	ds_read_b128 v[220:223], v160 offset:55296
	ds_read_b128 v[224:227], v160 offset:56320
	s_waitcnt vmcnt(8)
	s_waitcnt lgkmcnt(0)
	s_barrier
	s_setprio 1
	s_waitcnt lgkmcnt(0)
	v_mfma_f32_16x16x32_bf16 v[62:65], v[164:167], v[196:199], v[62:65]
	v_mfma_f32_16x16x32_bf16 v[54:57], v[172:175], v[196:199], v[54:57]
	v_mfma_f32_16x16x32_bf16 v[46:49], v[164:167], v[204:207], v[46:49]
	v_mfma_f32_16x16x32_bf16 v[38:41], v[172:175], v[204:207], v[38:41]
	v_mfma_f32_16x16x32_bf16 v[30:33], v[164:167], v[212:215], v[30:33]
	v_mfma_f32_16x16x32_bf16 v[22:25], v[172:175], v[212:215], v[22:25]
	v_mfma_f32_16x16x32_bf16 v[14:17], v[164:167], v[220:223], v[14:17]
	v_mfma_f32_16x16x32_bf16 v[6:9], v[172:175], v[220:223], v[6:9]
	v_mfma_f32_16x16x32_bf16 v[62:65], v[168:171], v[200:203], v[62:65]
	v_mfma_f32_16x16x32_bf16 v[54:57], v[176:179], v[200:203], v[54:57]
	v_mfma_f32_16x16x32_bf16 v[46:49], v[168:171], v[208:211], v[46:49]
	v_mfma_f32_16x16x32_bf16 v[38:41], v[176:179], v[208:211], v[38:41]
	v_mfma_f32_16x16x32_bf16 v[30:33], v[168:171], v[216:219], v[30:33]
	v_mfma_f32_16x16x32_bf16 v[22:25], v[176:179], v[216:219], v[22:25]
	v_mfma_f32_16x16x32_bf16 v[14:17], v[168:171], v[224:227], v[14:17]
	v_mfma_f32_16x16x32_bf16 v[6:9], v[176:179], v[224:227], v[6:9]
	s_setprio 0
	s_setprio 1
	v_mfma_f32_16x16x32_bf16 v[58:61], v[180:183], v[196:199], v[58:61]
	v_mfma_f32_16x16x32_bf16 v[50:53], v[188:191], v[196:199], v[50:53]
	v_mfma_f32_16x16x32_bf16 v[42:45], v[180:183], v[204:207], v[42:45]
	v_mfma_f32_16x16x32_bf16 v[34:37], v[188:191], v[204:207], v[34:37]
	v_mfma_f32_16x16x32_bf16 v[26:29], v[180:183], v[212:215], v[26:29]
	v_mfma_f32_16x16x32_bf16 v[18:21], v[188:191], v[212:215], v[18:21]
	v_mfma_f32_16x16x32_bf16 v[10:13], v[180:183], v[220:223], v[10:13]
	v_mfma_f32_16x16x32_bf16 v[2:5], v[188:191], v[220:223], v[2:5]
	v_mfma_f32_16x16x32_bf16 v[58:61], v[184:187], v[200:203], v[58:61]
	v_mfma_f32_16x16x32_bf16 v[50:53], v[192:195], v[200:203], v[50:53]
	v_mfma_f32_16x16x32_bf16 v[42:45], v[184:187], v[208:211], v[42:45]
	v_mfma_f32_16x16x32_bf16 v[34:37], v[192:195], v[208:211], v[34:37]
	v_mfma_f32_16x16x32_bf16 v[26:29], v[184:187], v[216:219], v[26:29]
	v_mfma_f32_16x16x32_bf16 v[18:21], v[192:195], v[216:219], v[18:21]
	v_mfma_f32_16x16x32_bf16 v[10:13], v[184:187], v[224:227], v[10:13]
	v_mfma_f32_16x16x32_bf16 v[2:5], v[192:195], v[224:227], v[2:5]
	s_setprio 0
	s_barrier
	s_mov_b32 s5, s29
	s_add_u32 s88, s88, 0x100
	s_addc_u32 s89, s89, 0
	s_add_u32 s86, s86, 0x100
	s_addc_u32 s87, s87, 0
	s_cmp_ge_i32 s29, s101
	s_cbranch_scc1 .Lmy_kexit_9
.LBB0_1763:
	s_add_u32 s98, s86, 0xfffc0080
	s_addc_u32 s99, s87, -1
	s_cmp_eq_u32 s5, s100
	s_cselect_b64 s[94:95], s[90:91], s[98:99]
	s_cselect_b64 s[96:97], s[92:93], s[88:89]
	s_add_i32 s29, s5, 2
	s_nop 0
	s_add_i32 m0, s47, 0xc000
	s_nop 0
	global_load_lds_dwordx4 v144, s[86:87]
	s_add_i32 m0, s47, 0xe000
	s_nop 0
	global_load_lds_dwordx4 v142, s[86:87]
	ds_read_b128 v[164:167], v230
	ds_read_b128 v[168:171], v230 offset:1024
	ds_read_b128 v[172:175], v230 offset:2048
	ds_read_b128 v[176:179], v230 offset:3072
	ds_read_b128 v[180:183], v231
	ds_read_b128 v[184:187], v231 offset:1024
	ds_read_b128 v[188:191], v231 offset:2048
	ds_read_b128 v[192:195], v231 offset:3072
	ds_read_b128 v[196:199], v160
	ds_read_b128 v[200:203], v160 offset:1024
	ds_read_b128 v[204:207], v160 offset:2048
	ds_read_b128 v[208:211], v160 offset:3072
	ds_read_b128 v[212:215], v160 offset:4096
	ds_read_b128 v[216:219], v160 offset:5120
	ds_read_b128 v[220:223], v160 offset:6144
	ds_read_b128 v[224:227], v160 offset:7168
	s_waitcnt vmcnt(8)
	s_waitcnt lgkmcnt(0)
	s_barrier
	s_setprio 1
	s_waitcnt lgkmcnt(0)
	v_mfma_f32_16x16x32_bf16 v[122:125], v[164:167], v[196:199], v[122:125]
	v_mfma_f32_16x16x32_bf16 v[118:121], v[172:175], v[196:199], v[118:121]
	v_mfma_f32_16x16x32_bf16 v[110:113], v[164:167], v[204:207], v[110:113]
	v_mfma_f32_16x16x32_bf16 v[102:105], v[172:175], v[204:207], v[102:105]
	v_mfma_f32_16x16x32_bf16 v[94:97], v[164:167], v[212:215], v[94:97]
	v_mfma_f32_16x16x32_bf16 v[86:89], v[172:175], v[212:215], v[86:89]
	v_mfma_f32_16x16x32_bf16 v[78:81], v[164:167], v[220:223], v[78:81]
	v_mfma_f32_16x16x32_bf16 v[70:73], v[172:175], v[220:223], v[70:73]
	v_mfma_f32_16x16x32_bf16 v[122:125], v[168:171], v[200:203], v[122:125]
	v_mfma_f32_16x16x32_bf16 v[118:121], v[176:179], v[200:203], v[118:121]
	v_mfma_f32_16x16x32_bf16 v[110:113], v[168:171], v[208:211], v[110:113]
	v_mfma_f32_16x16x32_bf16 v[102:105], v[176:179], v[208:211], v[102:105]
	v_mfma_f32_16x16x32_bf16 v[94:97], v[168:171], v[216:219], v[94:97]
	v_mfma_f32_16x16x32_bf16 v[86:89], v[176:179], v[216:219], v[86:89]
	v_mfma_f32_16x16x32_bf16 v[78:81], v[168:171], v[224:227], v[78:81]
	v_mfma_f32_16x16x32_bf16 v[70:73], v[176:179], v[224:227], v[70:73]
	s_setprio 0
	s_setprio 1
	v_mfma_f32_16x16x32_bf16 v[126:129], v[180:183], v[196:199], v[126:129]
	v_mfma_f32_16x16x32_bf16 v[114:117], v[188:191], v[196:199], v[114:117]
	v_mfma_f32_16x16x32_bf16 v[106:109], v[180:183], v[204:207], v[106:109]
	v_mfma_f32_16x16x32_bf16 v[98:101], v[188:191], v[204:207], v[98:101]
	v_mfma_f32_16x16x32_bf16 v[90:93], v[180:183], v[212:215], v[90:93]
	v_mfma_f32_16x16x32_bf16 v[82:85], v[188:191], v[212:215], v[82:85]
	v_mfma_f32_16x16x32_bf16 v[74:77], v[180:183], v[220:223], v[74:77]
	v_mfma_f32_16x16x32_bf16 v[66:69], v[188:191], v[220:223], v[66:69]
	v_mfma_f32_16x16x32_bf16 v[126:129], v[184:187], v[200:203], v[126:129]
	v_mfma_f32_16x16x32_bf16 v[114:117], v[192:195], v[200:203], v[114:117]
	v_mfma_f32_16x16x32_bf16 v[106:109], v[184:187], v[208:211], v[106:109]
	v_mfma_f32_16x16x32_bf16 v[98:101], v[192:195], v[208:211], v[98:101]
	v_mfma_f32_16x16x32_bf16 v[90:93], v[184:187], v[216:219], v[90:93]
	v_mfma_f32_16x16x32_bf16 v[82:85], v[192:195], v[216:219], v[82:85]
	v_mfma_f32_16x16x32_bf16 v[74:77], v[184:187], v[224:227], v[74:77]
	v_mfma_f32_16x16x32_bf16 v[66:69], v[192:195], v[224:227], v[66:69]
	s_setprio 0
	s_barrier
	s_add_u32 s98, s96, 0x40000
	s_addc_u32 s99, s97, 0
	s_add_i32 s5, s74, s23
	s_mov_b32 m0, s5
	s_nop 0
	global_load_lds_dwordx4 v132, s[96:97]
	s_add_i32 m0, s5, 0x2000
	s_add_i32 s5, s75, s23
	global_load_lds_dwordx4 v136, s[96:97]
	s_mov_b32 m0, s5
	s_nop 0
	global_load_lds_dwordx4 v132, s[98:99]
	s_add_i32 m0, s5, 0x2000
	s_nop 0
	global_load_lds_dwordx4 v136, s[98:99]
	s_mov_b32 m0, s47
	s_nop 0
	global_load_lds_dwordx4 v130, s[94:95]
	s_mov_b32 m0, s56
	s_nop 0
	global_load_lds_dwordx4 v134, s[94:95]
	ds_read_b128 v[196:199], v160 offset:16384
	ds_read_b128 v[200:203], v160 offset:17408
	ds_read_b128 v[204:207], v160 offset:18432
	ds_read_b128 v[208:211], v160 offset:19456
	ds_read_b128 v[212:215], v160 offset:20480
	ds_read_b128 v[216:219], v160 offset:21504
	ds_read_b128 v[220:223], v160 offset:22528
	ds_read_b128 v[224:227], v160 offset:23552
	s_waitcnt vmcnt(8)
	s_waitcnt lgkmcnt(0)
	s_barrier
	s_setprio 1
	s_waitcnt lgkmcnt(0)
	v_mfma_f32_16x16x32_bf16 v[62:65], v[164:167], v[196:199], v[62:65]
	v_mfma_f32_16x16x32_bf16 v[54:57], v[172:175], v[196:199], v[54:57]
	v_mfma_f32_16x16x32_bf16 v[46:49], v[164:167], v[204:207], v[46:49]
	v_mfma_f32_16x16x32_bf16 v[38:41], v[172:175], v[204:207], v[38:41]
	v_mfma_f32_16x16x32_bf16 v[30:33], v[164:167], v[212:215], v[30:33]
	v_mfma_f32_16x16x32_bf16 v[22:25], v[172:175], v[212:215], v[22:25]
	v_mfma_f32_16x16x32_bf16 v[14:17], v[164:167], v[220:223], v[14:17]
	v_mfma_f32_16x16x32_bf16 v[6:9], v[172:175], v[220:223], v[6:9]
	v_mfma_f32_16x16x32_bf16 v[62:65], v[168:171], v[200:203], v[62:65]
	v_mfma_f32_16x16x32_bf16 v[54:57], v[176:179], v[200:203], v[54:57]
	v_mfma_f32_16x16x32_bf16 v[46:49], v[168:171], v[208:211], v[46:49]
	v_mfma_f32_16x16x32_bf16 v[38:41], v[176:179], v[208:211], v[38:41]
	v_mfma_f32_16x16x32_bf16 v[30:33], v[168:171], v[216:219], v[30:33]
	v_mfma_f32_16x16x32_bf16 v[22:25], v[176:179], v[216:219], v[22:25]
	v_mfma_f32_16x16x32_bf16 v[14:17], v[168:171], v[224:227], v[14:17]
	v_mfma_f32_16x16x32_bf16 v[6:9], v[176:179], v[224:227], v[6:9]
	s_setprio 0
	s_setprio 1
	v_mfma_f32_16x16x32_bf16 v[58:61], v[180:183], v[196:199], v[58:61]
	v_mfma_f32_16x16x32_bf16 v[50:53], v[188:191], v[196:199], v[50:53]
	v_mfma_f32_16x16x32_bf16 v[42:45], v[180:183], v[204:207], v[42:45]
	v_mfma_f32_16x16x32_bf16 v[34:37], v[188:191], v[204:207], v[34:37]
	v_mfma_f32_16x16x32_bf16 v[26:29], v[180:183], v[212:215], v[26:29]
	v_mfma_f32_16x16x32_bf16 v[18:21], v[188:191], v[212:215], v[18:21]
	v_mfma_f32_16x16x32_bf16 v[10:13], v[180:183], v[220:223], v[10:13]
	v_mfma_f32_16x16x32_bf16 v[2:5], v[188:191], v[220:223], v[2:5]
	v_mfma_f32_16x16x32_bf16 v[58:61], v[184:187], v[200:203], v[58:61]
	v_mfma_f32_16x16x32_bf16 v[50:53], v[192:195], v[200:203], v[50:53]
	v_mfma_f32_16x16x32_bf16 v[42:45], v[184:187], v[208:211], v[42:45]
	v_mfma_f32_16x16x32_bf16 v[34:37], v[192:195], v[208:211], v[34:37]
	v_mfma_f32_16x16x32_bf16 v[26:29], v[184:187], v[216:219], v[26:29]
	v_mfma_f32_16x16x32_bf16 v[18:21], v[192:195], v[216:219], v[18:21]
	v_mfma_f32_16x16x32_bf16 v[10:13], v[184:187], v[224:227], v[10:13]
	v_mfma_f32_16x16x32_bf16 v[2:5], v[192:195], v[224:227], v[2:5]
	s_setprio 0
	s_barrier
	s_add_u32 s98, s94, 0x40000
	s_addc_u32 s99, s95, 0
	s_add_i32 s5, 0, 0x18000
	s_add_i32 s45, 0, 0x1c000
	s_mov_b32 m0, s57
	s_nop 0
	global_load_lds_dwordx4 v130, s[98:99]
	s_mov_b32 m0, s58
	s_nop 0
	global_load_lds_dwordx4 v134, s[98:99]
	ds_read_b128 v[164:167], v232
	ds_read_b128 v[168:171], v232 offset:1024
	ds_read_b128 v[172:175], v232 offset:2048
	ds_read_b128 v[176:179], v232 offset:3072
	ds_read_b128 v[180:183], v233
	ds_read_b128 v[184:187], v233 offset:1024
	ds_read_b128 v[188:191], v233 offset:2048
	ds_read_b128 v[192:195], v233 offset:3072
	ds_read_b128 v[196:199], v160 offset:32768
	ds_read_b128 v[200:203], v160 offset:33792
	ds_read_b128 v[204:207], v160 offset:34816
	ds_read_b128 v[208:211], v160 offset:35840
	ds_read_b128 v[212:215], v160 offset:36864
	ds_read_b128 v[216:219], v160 offset:37888
	ds_read_b128 v[220:223], v160 offset:38912
	ds_read_b128 v[224:227], v160 offset:39936
	s_waitcnt vmcnt(8)
	s_waitcnt lgkmcnt(0)
	s_barrier
	s_setprio 1
	s_waitcnt lgkmcnt(0)
	v_mfma_f32_16x16x32_bf16 v[122:125], v[164:167], v[196:199], v[122:125]
	v_mfma_f32_16x16x32_bf16 v[118:121], v[172:175], v[196:199], v[118:121]
	v_mfma_f32_16x16x32_bf16 v[110:113], v[164:167], v[204:207], v[110:113]
	v_mfma_f32_16x16x32_bf16 v[102:105], v[172:175], v[204:207], v[102:105]
	v_mfma_f32_16x16x32_bf16 v[94:97], v[164:167], v[212:215], v[94:97]
	v_mfma_f32_16x16x32_bf16 v[86:89], v[172:175], v[212:215], v[86:89]
	v_mfma_f32_16x16x32_bf16 v[78:81], v[164:167], v[220:223], v[78:81]
	v_mfma_f32_16x16x32_bf16 v[70:73], v[172:175], v[220:223], v[70:73]
	v_mfma_f32_16x16x32_bf16 v[122:125], v[168:171], v[200:203], v[122:125]
	v_mfma_f32_16x16x32_bf16 v[118:121], v[176:179], v[200:203], v[118:121]
	v_mfma_f32_16x16x32_bf16 v[110:113], v[168:171], v[208:211], v[110:113]
	v_mfma_f32_16x16x32_bf16 v[102:105], v[176:179], v[208:211], v[102:105]
	v_mfma_f32_16x16x32_bf16 v[94:97], v[168:171], v[216:219], v[94:97]
	v_mfma_f32_16x16x32_bf16 v[86:89], v[176:179], v[216:219], v[86:89]
	v_mfma_f32_16x16x32_bf16 v[78:81], v[168:171], v[224:227], v[78:81]
	v_mfma_f32_16x16x32_bf16 v[70:73], v[176:179], v[224:227], v[70:73]
	s_setprio 0
	s_setprio 1
	v_mfma_f32_16x16x32_bf16 v[126:129], v[180:183], v[196:199], v[126:129]
	v_mfma_f32_16x16x32_bf16 v[114:117], v[188:191], v[196:199], v[114:117]
	v_mfma_f32_16x16x32_bf16 v[106:109], v[180:183], v[204:207], v[106:109]
	v_mfma_f32_16x16x32_bf16 v[98:101], v[188:191], v[204:207], v[98:101]
	v_mfma_f32_16x16x32_bf16 v[90:93], v[180:183], v[212:215], v[90:93]
	v_mfma_f32_16x16x32_bf16 v[82:85], v[188:191], v[212:215], v[82:85]
	v_mfma_f32_16x16x32_bf16 v[74:77], v[180:183], v[220:223], v[74:77]
	v_mfma_f32_16x16x32_bf16 v[66:69], v[188:191], v[220:223], v[66:69]
	v_mfma_f32_16x16x32_bf16 v[126:129], v[184:187], v[200:203], v[126:129]
	v_mfma_f32_16x16x32_bf16 v[114:117], v[192:195], v[200:203], v[114:117]
	v_mfma_f32_16x16x32_bf16 v[106:109], v[184:187], v[208:211], v[106:109]
	v_mfma_f32_16x16x32_bf16 v[98:101], v[192:195], v[208:211], v[98:101]
	v_mfma_f32_16x16x32_bf16 v[90:93], v[184:187], v[216:219], v[90:93]
	v_mfma_f32_16x16x32_bf16 v[82:85], v[192:195], v[216:219], v[82:85]
	v_mfma_f32_16x16x32_bf16 v[74:77], v[184:187], v[224:227], v[74:77]
	v_mfma_f32_16x16x32_bf16 v[66:69], v[192:195], v[224:227], v[66:69]
	s_setprio 0
	s_barrier
	s_add_u32 s96, s96, 0x80
	s_addc_u32 s97, s97, 0
	s_add_u32 s98, s96, 0x40000
	s_addc_u32 s99, s97, 0
	s_add_u32 s94, s94, 0x80
	s_addc_u32 s95, s95, 0
	s_add_i32 s5, s5, s23
	s_mov_b32 m0, s5
	s_nop 0
	global_load_lds_dwordx4 v132, s[96:97]
	s_add_i32 m0, s5, 0x2000
	s_add_i32 s5, s45, s23
	global_load_lds_dwordx4 v136, s[96:97]
	s_mov_b32 m0, s5
	s_nop 0
	global_load_lds_dwordx4 v132, s[98:99]
	s_add_i32 m0, s5, 0x2000
	s_nop 0
	global_load_lds_dwordx4 v136, s[98:99]
	s_mov_b32 m0, s64
	s_nop 0
	global_load_lds_dwordx4 v130, s[94:95]
	s_mov_b32 m0, s65
	s_nop 0
	global_load_lds_dwordx4 v134, s[94:95]
	ds_read_b128 v[196:199], v160 offset:49152
	ds_read_b128 v[200:203], v160 offset:50176
	ds_read_b128 v[204:207], v160 offset:51200
	ds_read_b128 v[208:211], v160 offset:52224
	ds_read_b128 v[212:215], v160 offset:53248
	ds_read_b128 v[216:219], v160 offset:54272
	ds_read_b128 v[220:223], v160 offset:55296
	ds_read_b128 v[224:227], v160 offset:56320
	s_waitcnt vmcnt(8)
	s_waitcnt lgkmcnt(0)
	s_barrier
	s_setprio 1
	s_waitcnt lgkmcnt(0)
	v_mfma_f32_16x16x32_bf16 v[62:65], v[164:167], v[196:199], v[62:65]
	v_mfma_f32_16x16x32_bf16 v[54:57], v[172:175], v[196:199], v[54:57]
	v_mfma_f32_16x16x32_bf16 v[46:49], v[164:167], v[204:207], v[46:49]
	v_mfma_f32_16x16x32_bf16 v[38:41], v[172:175], v[204:207], v[38:41]
	v_mfma_f32_16x16x32_bf16 v[30:33], v[164:167], v[212:215], v[30:33]
	v_mfma_f32_16x16x32_bf16 v[22:25], v[172:175], v[212:215], v[22:25]
	v_mfma_f32_16x16x32_bf16 v[14:17], v[164:167], v[220:223], v[14:17]
	v_mfma_f32_16x16x32_bf16 v[6:9], v[172:175], v[220:223], v[6:9]
	v_mfma_f32_16x16x32_bf16 v[62:65], v[168:171], v[200:203], v[62:65]
	v_mfma_f32_16x16x32_bf16 v[54:57], v[176:179], v[200:203], v[54:57]
	v_mfma_f32_16x16x32_bf16 v[46:49], v[168:171], v[208:211], v[46:49]
	v_mfma_f32_16x16x32_bf16 v[38:41], v[176:179], v[208:211], v[38:41]
	v_mfma_f32_16x16x32_bf16 v[30:33], v[168:171], v[216:219], v[30:33]
	v_mfma_f32_16x16x32_bf16 v[22:25], v[176:179], v[216:219], v[22:25]
	v_mfma_f32_16x16x32_bf16 v[14:17], v[168:171], v[224:227], v[14:17]
	v_mfma_f32_16x16x32_bf16 v[6:9], v[176:179], v[224:227], v[6:9]
	s_setprio 0
	s_setprio 1
	v_mfma_f32_16x16x32_bf16 v[58:61], v[180:183], v[196:199], v[58:61]
	v_mfma_f32_16x16x32_bf16 v[50:53], v[188:191], v[196:199], v[50:53]
	v_mfma_f32_16x16x32_bf16 v[42:45], v[180:183], v[204:207], v[42:45]
	v_mfma_f32_16x16x32_bf16 v[34:37], v[188:191], v[204:207], v[34:37]
	v_mfma_f32_16x16x32_bf16 v[26:29], v[180:183], v[212:215], v[26:29]
	v_mfma_f32_16x16x32_bf16 v[18:21], v[188:191], v[212:215], v[18:21]
	v_mfma_f32_16x16x32_bf16 v[10:13], v[180:183], v[220:223], v[10:13]
	v_mfma_f32_16x16x32_bf16 v[2:5], v[188:191], v[220:223], v[2:5]
	v_mfma_f32_16x16x32_bf16 v[58:61], v[184:187], v[200:203], v[58:61]
	v_mfma_f32_16x16x32_bf16 v[50:53], v[192:195], v[200:203], v[50:53]
	v_mfma_f32_16x16x32_bf16 v[42:45], v[184:187], v[208:211], v[42:45]
	v_mfma_f32_16x16x32_bf16 v[34:37], v[192:195], v[208:211], v[34:37]
	v_mfma_f32_16x16x32_bf16 v[26:29], v[184:187], v[216:219], v[26:29]
	v_mfma_f32_16x16x32_bf16 v[18:21], v[192:195], v[216:219], v[18:21]
	v_mfma_f32_16x16x32_bf16 v[10:13], v[184:187], v[224:227], v[10:13]
	v_mfma_f32_16x16x32_bf16 v[2:5], v[192:195], v[224:227], v[2:5]
	s_setprio 0
	s_barrier
	s_mov_b32 s5, s29
	s_add_u32 s88, s88, 0x100
	s_addc_u32 s89, s89, 0
	s_add_u32 s86, s86, 0x100
	s_addc_u32 s87, s87, 0
	s_cmp_ge_i32 s29, s101
	s_cbranch_scc0 .LBB0_1763

.LBB0_1942:
	v_cmp_gt_i32_e32 vcc, 1, v138
	s_cbranch_vccnz .LBB0_2004
	v_lshl_add_u64 v[152:153], v[2:3], 0, s[16:17]
	v_add_u32_e32 v154, -2, v138
	s_waitcnt lgkmcnt(0)
	v_lshl_add_u64 v[150:151], v[4:5], 0, s[20:21]
	s_mov_b32 s5, 0
	s_nop 0
	v_readfirstlane_b32 s86, v152
	v_readfirstlane_b32 s87, v153
	v_readfirstlane_b32 s88, v150
	v_readfirstlane_b32 s89, v151
	v_readfirstlane_b32 s90, v146
	v_readfirstlane_b32 s91, v147
	v_readfirstlane_b32 s92, v148
	v_readfirstlane_b32 s93, v149
	v_readfirstlane_b32 s100, v154
	v_readfirstlane_b32 s101, v138
	v_add_u32_e32 v230, s72, v141
	v_add_u32_e32 v231, s73, v141
	v_add_u32_e32 v232, 0x18000, v141
	v_add_u32_e32 v233, 0x1c000, v141
	s_add_u32 s98, s86, 0xfffc0080
	s_addc_u32 s99, s87, -1
	s_cmp_eq_u32 s5, s100
	s_cselect_b64 s[94:95], s[90:91], s[98:99]
	s_cselect_b64 s[96:97], s[92:93], s[88:89]
	s_add_i32 s45, s5, 2
	s_nop 0
	s_mov_b32 m0, s74
	s_nop 0
	global_load_lds_dwordx4 v144, s[86:87]
	s_mov_b32 m0, s75
	s_nop 0
	global_load_lds_dwordx4 v142, s[86:87]
	ds_read_b128 v[164:167], v230
	ds_read_b128 v[168:171], v230 offset:1024
	ds_read_b128 v[172:175], v230 offset:2048
	ds_read_b128 v[176:179], v230 offset:3072
	ds_read_b128 v[180:183], v231
	ds_read_b128 v[184:187], v231 offset:1024
	ds_read_b128 v[188:191], v231 offset:2048
	ds_read_b128 v[192:195], v231 offset:3072
	ds_read_b128 v[196:199], v160
	ds_read_b128 v[200:203], v160 offset:1024
	ds_read_b128 v[204:207], v160 offset:2048
	ds_read_b128 v[208:211], v160 offset:3072
	ds_read_b128 v[212:215], v160 offset:4096
	ds_read_b128 v[216:219], v160 offset:5120
	ds_read_b128 v[220:223], v160 offset:6144
	ds_read_b128 v[224:227], v160 offset:7168
	s_waitcnt vmcnt(8)
	s_waitcnt lgkmcnt(0)
	s_barrier
	s_setprio 1
	s_waitcnt lgkmcnt(0)
	v_mfma_f32_16x16x32_bf16 v[122:125], v[164:167], v[196:199], 0
	v_mfma_f32_16x16x32_bf16 v[118:121], v[172:175], v[196:199], 0
	v_mfma_f32_16x16x32_bf16 v[110:113], v[164:167], v[204:207], 0
	v_mfma_f32_16x16x32_bf16 v[102:105], v[172:175], v[204:207], 0
	v_mfma_f32_16x16x32_bf16 v[94:97], v[164:167], v[212:215], 0
	v_mfma_f32_16x16x32_bf16 v[86:89], v[172:175], v[212:215], 0
	v_mfma_f32_16x16x32_bf16 v[78:81], v[164:167], v[220:223], 0
	v_mfma_f32_16x16x32_bf16 v[70:73], v[172:175], v[220:223], 0
	v_mfma_f32_16x16x32_bf16 v[122:125], v[168:171], v[200:203], v[122:125]
	v_mfma_f32_16x16x32_bf16 v[118:121], v[176:179], v[200:203], v[118:121]
	v_mfma_f32_16x16x32_bf16 v[110:113], v[168:171], v[208:211], v[110:113]
	v_mfma_f32_16x16x32_bf16 v[102:105], v[176:179], v[208:211], v[102:105]
	v_mfma_f32_16x16x32_bf16 v[94:97], v[168:171], v[216:219], v[94:97]
	v_mfma_f32_16x16x32_bf16 v[86:89], v[176:179], v[216:219], v[86:89]
	v_mfma_f32_16x16x32_bf16 v[78:81], v[168:171], v[224:227], v[78:81]
	v_mfma_f32_16x16x32_bf16 v[70:73], v[176:179], v[224:227], v[70:73]
	s_setprio 0
	s_setprio 1
	v_mfma_f32_16x16x32_bf16 v[126:129], v[180:183], v[196:199], 0
	v_mfma_f32_16x16x32_bf16 v[114:117], v[188:191], v[196:199], 0
	v_mfma_f32_16x16x32_bf16 v[106:109], v[180:183], v[204:207], 0
	v_mfma_f32_16x16x32_bf16 v[98:101], v[188:191], v[204:207], 0
	v_mfma_f32_16x16x32_bf16 v[90:93], v[180:183], v[212:215], 0
	v_mfma_f32_16x16x32_bf16 v[82:85], v[188:191], v[212:215], 0
	v_mfma_f32_16x16x32_bf16 v[74:77], v[180:183], v[220:223], 0
	v_mfma_f32_16x16x32_bf16 v[66:69], v[188:191], v[220:223], 0
	v_mfma_f32_16x16x32_bf16 v[126:129], v[184:187], v[200:203], v[126:129]
	v_mfma_f32_16x16x32_bf16 v[114:117], v[192:195], v[200:203], v[114:117]
	v_mfma_f32_16x16x32_bf16 v[106:109], v[184:187], v[208:211], v[106:109]
	v_mfma_f32_16x16x32_bf16 v[98:101], v[192:195], v[208:211], v[98:101]
	v_mfma_f32_16x16x32_bf16 v[90:93], v[184:187], v[216:219], v[90:93]
	v_mfma_f32_16x16x32_bf16 v[82:85], v[192:195], v[216:219], v[82:85]
	v_mfma_f32_16x16x32_bf16 v[74:77], v[184:187], v[224:227], v[74:77]
	v_mfma_f32_16x16x32_bf16 v[66:69], v[192:195], v[224:227], v[66:69]
	s_setprio 0
	s_barrier
	s_add_u32 s98, s96, 0x40000
	s_addc_u32 s99, s97, 0
	s_mov_b32 m0, s76
	s_nop 0
	global_load_lds_dwordx4 v132, s[96:97]
	s_mov_b32 m0, s77
	s_add_i32 s5, s73, s25
	global_load_lds_dwordx4 v136, s[96:97]
	s_mov_b32 m0, s5
	s_nop 0
	global_load_lds_dwordx4 v132, s[98:99]
	s_add_i32 m0, s5, 0x2000
	s_nop 0
	global_load_lds_dwordx4 v136, s[98:99]
	s_mov_b32 m0, s49
	s_nop 0
	global_load_lds_dwordx4 v130, s[94:95]
	s_mov_b32 m0, s58
	s_nop 0
	global_load_lds_dwordx4 v134, s[94:95]
	ds_read_b128 v[196:199], v160 offset:16384
	ds_read_b128 v[200:203], v160 offset:17408
	ds_read_b128 v[204:207], v160 offset:18432
	ds_read_b128 v[208:211], v160 offset:19456
	ds_read_b128 v[212:215], v160 offset:20480
	ds_read_b128 v[216:219], v160 offset:21504
	ds_read_b128 v[220:223], v160 offset:22528
	ds_read_b128 v[224:227], v160 offset:23552
	s_waitcnt vmcnt(8)
	s_waitcnt lgkmcnt(0)
	s_barrier
	s_setprio 1
	s_waitcnt lgkmcnt(0)
	v_mfma_f32_16x16x32_bf16 v[62:65], v[164:167], v[196:199], 0
	v_mfma_f32_16x16x32_bf16 v[54:57], v[172:175], v[196:199], 0
	v_mfma_f32_16x16x32_bf16 v[46:49], v[164:167], v[204:207], 0
	v_mfma_f32_16x16x32_bf16 v[38:41], v[172:175], v[204:207], 0
	v_mfma_f32_16x16x32_bf16 v[30:33], v[164:167], v[212:215], 0
	v_mfma_f32_16x16x32_bf16 v[22:25], v[172:175], v[212:215], 0
	v_mfma_f32_16x16x32_bf16 v[14:17], v[164:167], v[220:223], 0
	v_mfma_f32_16x16x32_bf16 v[6:9], v[172:175], v[220:223], 0
	v_mfma_f32_16x16x32_bf16 v[62:65], v[168:171], v[200:203], v[62:65]
	v_mfma_f32_16x16x32_bf16 v[54:57], v[176:179], v[200:203], v[54:57]
	v_mfma_f32_16x16x32_bf16 v[46:49], v[168:171], v[208:211], v[46:49]
	v_mfma_f32_16x16x32_bf16 v[38:41], v[176:179], v[208:211], v[38:41]
	v_mfma_f32_16x16x32_bf16 v[30:33], v[168:171], v[216:219], v[30:33]
	v_mfma_f32_16x16x32_bf16 v[22:25], v[176:179], v[216:219], v[22:25]
	v_mfma_f32_16x16x32_bf16 v[14:17], v[168:171], v[224:227], v[14:17]
	v_mfma_f32_16x16x32_bf16 v[6:9], v[176:179], v[224:227], v[6:9]
	s_setprio 0
	s_setprio 1
	v_mfma_f32_16x16x32_bf16 v[58:61], v[180:183], v[196:199], 0
	v_mfma_f32_16x16x32_bf16 v[50:53], v[188:191], v[196:199], 0
	v_mfma_f32_16x16x32_bf16 v[42:45], v[180:183], v[204:207], 0
	v_mfma_f32_16x16x32_bf16 v[34:37], v[188:191], v[204:207], 0
	v_mfma_f32_16x16x32_bf16 v[26:29], v[180:183], v[212:215], 0
	v_mfma_f32_16x16x32_bf16 v[18:21], v[188:191], v[212:215], 0
	v_mfma_f32_16x16x32_bf16 v[10:13], v[180:183], v[220:223], 0
	v_mfma_f32_16x16x32_bf16 v[2:5], v[188:191], v[220:223], 0
	v_mfma_f32_16x16x32_bf16 v[58:61], v[184:187], v[200:203], v[58:61]
	v_mfma_f32_16x16x32_bf16 v[50:53], v[192:195], v[200:203], v[50:53]
	v_mfma_f32_16x16x32_bf16 v[42:45], v[184:187], v[208:211], v[42:45]
	v_mfma_f32_16x16x32_bf16 v[34:37], v[192:195], v[208:211], v[34:37]
	v_mfma_f32_16x16x32_bf16 v[26:29], v[184:187], v[216:219], v[26:29]
	v_mfma_f32_16x16x32_bf16 v[18:21], v[192:195], v[216:219], v[18:21]
	v_mfma_f32_16x16x32_bf16 v[10:13], v[184:187], v[224:227], v[10:13]
	v_mfma_f32_16x16x32_bf16 v[2:5], v[192:195], v[224:227], v[2:5]
	s_setprio 0
	s_barrier
	s_add_u32 s98, s94, 0x40000
	s_addc_u32 s99, s95, 0
	s_add_i32 s5, 0, 0x18000
	s_add_i32 s47, 0, 0x1c000
	s_mov_b32 m0, s59
	s_nop 0
	global_load_lds_dwordx4 v130, s[98:99]
	s_mov_b32 m0, s60
	s_nop 0
	global_load_lds_dwordx4 v134, s[98:99]
	ds_read_b128 v[164:167], v232
	ds_read_b128 v[168:171], v232 offset:1024
	ds_read_b128 v[172:175], v232 offset:2048
	ds_read_b128 v[176:179], v232 offset:3072
	ds_read_b128 v[180:183], v233
	ds_read_b128 v[184:187], v233 offset:1024
	ds_read_b128 v[188:191], v233 offset:2048
	ds_read_b128 v[192:195], v233 offset:3072
	ds_read_b128 v[196:199], v160 offset:32768
	ds_read_b128 v[200:203], v160 offset:33792
	ds_read_b128 v[204:207], v160 offset:34816
	ds_read_b128 v[208:211], v160 offset:35840
	ds_read_b128 v[212:215], v160 offset:36864
	ds_read_b128 v[216:219], v160 offset:37888
	ds_read_b128 v[220:223], v160 offset:38912
	ds_read_b128 v[224:227], v160 offset:39936
	s_waitcnt vmcnt(8)
	s_waitcnt lgkmcnt(0)
	s_barrier
	s_setprio 1
	s_waitcnt lgkmcnt(0)
	v_mfma_f32_16x16x32_bf16 v[122:125], v[164:167], v[196:199], v[122:125]
	v_mfma_f32_16x16x32_bf16 v[118:121], v[172:175], v[196:199], v[118:121]
	v_mfma_f32_16x16x32_bf16 v[110:113], v[164:167], v[204:207], v[110:113]
	v_mfma_f32_16x16x32_bf16 v[102:105], v[172:175], v[204:207], v[102:105]
	v_mfma_f32_16x16x32_bf16 v[94:97], v[164:167], v[212:215], v[94:97]
	v_mfma_f32_16x16x32_bf16 v[86:89], v[172:175], v[212:215], v[86:89]
	v_mfma_f32_16x16x32_bf16 v[78:81], v[164:167], v[220:223], v[78:81]
	v_mfma_f32_16x16x32_bf16 v[70:73], v[172:175], v[220:223], v[70:73]
	v_mfma_f32_16x16x32_bf16 v[122:125], v[168:171], v[200:203], v[122:125]
	v_mfma_f32_16x16x32_bf16 v[118:121], v[176:179], v[200:203], v[118:121]
	v_mfma_f32_16x16x32_bf16 v[110:113], v[168:171], v[208:211], v[110:113]
	v_mfma_f32_16x16x32_bf16 v[102:105], v[176:179], v[208:211], v[102:105]
	v_mfma_f32_16x16x32_bf16 v[94:97], v[168:171], v[216:219], v[94:97]
	v_mfma_f32_16x16x32_bf16 v[86:89], v[176:179], v[216:219], v[86:89]
	v_mfma_f32_16x16x32_bf16 v[78:81], v[168:171], v[224:227], v[78:81]
	v_mfma_f32_16x16x32_bf16 v[70:73], v[176:179], v[224:227], v[70:73]
	s_setprio 0
	s_setprio 1
	v_mfma_f32_16x16x32_bf16 v[126:129], v[180:183], v[196:199], v[126:129]
	v_mfma_f32_16x16x32_bf16 v[114:117], v[188:191], v[196:199], v[114:117]
	v_mfma_f32_16x16x32_bf16 v[106:109], v[180:183], v[204:207], v[106:109]
	v_mfma_f32_16x16x32_bf16 v[98:101], v[188:191], v[204:207], v[98:101]
	v_mfma_f32_16x16x32_bf16 v[90:93], v[180:183], v[212:215], v[90:93]
	v_mfma_f32_16x16x32_bf16 v[82:85], v[188:191], v[212:215], v[82:85]
	v_mfma_f32_16x16x32_bf16 v[74:77], v[180:183], v[220:223], v[74:77]
	v_mfma_f32_16x16x32_bf16 v[66:69], v[188:191], v[220:223], v[66:69]
	v_mfma_f32_16x16x32_bf16 v[126:129], v[184:187], v[200:203], v[126:129]
	v_mfma_f32_16x16x32_bf16 v[114:117], v[192:195], v[200:203], v[114:117]
	v_mfma_f32_16x16x32_bf16 v[106:109], v[184:187], v[208:211], v[106:109]
	v_mfma_f32_16x16x32_bf16 v[98:101], v[192:195], v[208:211], v[98:101]
	v_mfma_f32_16x16x32_bf16 v[90:93], v[184:187], v[216:219], v[90:93]
	v_mfma_f32_16x16x32_bf16 v[82:85], v[192:195], v[216:219], v[82:85]
	v_mfma_f32_16x16x32_bf16 v[74:77], v[184:187], v[224:227], v[74:77]
	v_mfma_f32_16x16x32_bf16 v[66:69], v[192:195], v[224:227], v[66:69]
	s_setprio 0
	s_barrier
	s_add_u32 s96, s96, 0x80
	s_addc_u32 s97, s97, 0
	s_add_u32 s98, s96, 0x40000
	s_addc_u32 s99, s97, 0
	s_add_u32 s94, s94, 0x80
	s_addc_u32 s95, s95, 0
	s_add_i32 s5, s5, s25
	s_mov_b32 m0, s5
	s_nop 0
	global_load_lds_dwordx4 v132, s[96:97]
	s_add_i32 m0, s5, 0x2000
	s_add_i32 s5, s47, s25
	global_load_lds_dwordx4 v136, s[96:97]
	s_mov_b32 m0, s5
	s_nop 0
	global_load_lds_dwordx4 v132, s[98:99]
	s_add_i32 m0, s5, 0x2000
	s_nop 0
	global_load_lds_dwordx4 v136, s[98:99]
	s_mov_b32 m0, s61
	s_nop 0
	global_load_lds_dwordx4 v130, s[94:95]
	s_mov_b32 m0, s62
	s_nop 0
	global_load_lds_dwordx4 v134, s[94:95]
	ds_read_b128 v[196:199], v160 offset:49152
	ds_read_b128 v[200:203], v160 offset:50176
	ds_read_b128 v[204:207], v160 offset:51200
	ds_read_b128 v[208:211], v160 offset:52224
	ds_read_b128 v[212:215], v160 offset:53248
	ds_read_b128 v[216:219], v160 offset:54272
	ds_read_b128 v[220:223], v160 offset:55296
	ds_read_b128 v[224:227], v160 offset:56320
	s_waitcnt vmcnt(8)
	s_waitcnt lgkmcnt(0)
	s_barrier
	s_setprio 1
	s_waitcnt lgkmcnt(0)
	v_mfma_f32_16x16x32_bf16 v[62:65], v[164:167], v[196:199], v[62:65]
	v_mfma_f32_16x16x32_bf16 v[54:57], v[172:175], v[196:199], v[54:57]
	v_mfma_f32_16x16x32_bf16 v[46:49], v[164:167], v[204:207], v[46:49]
	v_mfma_f32_16x16x32_bf16 v[38:41], v[172:175], v[204:207], v[38:41]
	v_mfma_f32_16x16x32_bf16 v[30:33], v[164:167], v[212:215], v[30:33]
	v_mfma_f32_16x16x32_bf16 v[22:25], v[172:175], v[212:215], v[22:25]
	v_mfma_f32_16x16x32_bf16 v[14:17], v[164:167], v[220:223], v[14:17]
	v_mfma_f32_16x16x32_bf16 v[6:9], v[172:175], v[220:223], v[6:9]
	v_mfma_f32_16x16x32_bf16 v[62:65], v[168:171], v[200:203], v[62:65]
	v_mfma_f32_16x16x32_bf16 v[54:57], v[176:179], v[200:203], v[54:57]
	v_mfma_f32_16x16x32_bf16 v[46:49], v[168:171], v[208:211], v[46:49]
	v_mfma_f32_16x16x32_bf16 v[38:41], v[176:179], v[208:211], v[38:41]
	v_mfma_f32_16x16x32_bf16 v[30:33], v[168:171], v[216:219], v[30:33]
	v_mfma_f32_16x16x32_bf16 v[22:25], v[176:179], v[216:219], v[22:25]
	v_mfma_f32_16x16x32_bf16 v[14:17], v[168:171], v[224:227], v[14:17]
	v_mfma_f32_16x16x32_bf16 v[6:9], v[176:179], v[224:227], v[6:9]
	s_setprio 0
	s_setprio 1
	v_mfma_f32_16x16x32_bf16 v[58:61], v[180:183], v[196:199], v[58:61]
	v_mfma_f32_16x16x32_bf16 v[50:53], v[188:191], v[196:199], v[50:53]
	v_mfma_f32_16x16x32_bf16 v[42:45], v[180:183], v[204:207], v[42:45]
	v_mfma_f32_16x16x32_bf16 v[34:37], v[188:191], v[204:207], v[34:37]
	v_mfma_f32_16x16x32_bf16 v[26:29], v[180:183], v[212:215], v[26:29]
	v_mfma_f32_16x16x32_bf16 v[18:21], v[188:191], v[212:215], v[18:21]
	v_mfma_f32_16x16x32_bf16 v[10:13], v[180:183], v[220:223], v[10:13]
	v_mfma_f32_16x16x32_bf16 v[2:5], v[188:191], v[220:223], v[2:5]
	v_mfma_f32_16x16x32_bf16 v[58:61], v[184:187], v[200:203], v[58:61]
	v_mfma_f32_16x16x32_bf16 v[50:53], v[192:195], v[200:203], v[50:53]
	v_mfma_f32_16x16x32_bf16 v[42:45], v[184:187], v[208:211], v[42:45]
	v_mfma_f32_16x16x32_bf16 v[34:37], v[192:195], v[208:211], v[34:37]
	v_mfma_f32_16x16x32_bf16 v[26:29], v[184:187], v[216:219], v[26:29]
	v_mfma_f32_16x16x32_bf16 v[18:21], v[192:195], v[216:219], v[18:21]
	v_mfma_f32_16x16x32_bf16 v[10:13], v[184:187], v[224:227], v[10:13]
	v_mfma_f32_16x16x32_bf16 v[2:5], v[192:195], v[224:227], v[2:5]
	s_setprio 0
	s_barrier
	s_mov_b32 s5, s45
	s_add_u32 s88, s88, 0x100
	s_addc_u32 s89, s89, 0
	s_add_u32 s86, s86, 0x100
	s_addc_u32 s87, s87, 0
	s_cmp_ge_i32 s45, s101
	s_cbranch_scc1 .Lmy_kexit_10
.LBB0_1944:
	s_add_u32 s98, s86, 0xfffc0080
	s_addc_u32 s99, s87, -1
	s_cmp_eq_u32 s5, s100
	s_cselect_b64 s[94:95], s[90:91], s[98:99]
	s_cselect_b64 s[96:97], s[92:93], s[88:89]
	s_add_i32 s45, s5, 2
	s_nop 0
	s_mov_b32 m0, s74
	s_nop 0
	global_load_lds_dwordx4 v144, s[86:87]
	s_mov_b32 m0, s75
	s_nop 0
	global_load_lds_dwordx4 v142, s[86:87]
	ds_read_b128 v[164:167], v230
	ds_read_b128 v[168:171], v230 offset:1024
	ds_read_b128 v[172:175], v230 offset:2048
	ds_read_b128 v[176:179], v230 offset:3072
	ds_read_b128 v[180:183], v231
	ds_read_b128 v[184:187], v231 offset:1024
	ds_read_b128 v[188:191], v231 offset:2048
	ds_read_b128 v[192:195], v231 offset:3072
	ds_read_b128 v[196:199], v160
	ds_read_b128 v[200:203], v160 offset:1024
	ds_read_b128 v[204:207], v160 offset:2048
	ds_read_b128 v[208:211], v160 offset:3072
	ds_read_b128 v[212:215], v160 offset:4096
	ds_read_b128 v[216:219], v160 offset:5120
	ds_read_b128 v[220:223], v160 offset:6144
	ds_read_b128 v[224:227], v160 offset:7168
	s_waitcnt vmcnt(8)
	s_waitcnt lgkmcnt(0)
	s_barrier
	s_setprio 1
	s_waitcnt lgkmcnt(0)
	v_mfma_f32_16x16x32_bf16 v[122:125], v[164:167], v[196:199], v[122:125]
	v_mfma_f32_16x16x32_bf16 v[118:121], v[172:175], v[196:199], v[118:121]
	v_mfma_f32_16x16x32_bf16 v[110:113], v[164:167], v[204:207], v[110:113]
	v_mfma_f32_16x16x32_bf16 v[102:105], v[172:175], v[204:207], v[102:105]
	v_mfma_f32_16x16x32_bf16 v[94:97], v[164:167], v[212:215], v[94:97]
	v_mfma_f32_16x16x32_bf16 v[86:89], v[172:175], v[212:215], v[86:89]
	v_mfma_f32_16x16x32_bf16 v[78:81], v[164:167], v[220:223], v[78:81]
	v_mfma_f32_16x16x32_bf16 v[70:73], v[172:175], v[220:223], v[70:73]
	v_mfma_f32_16x16x32_bf16 v[122:125], v[168:171], v[200:203], v[122:125]
	v_mfma_f32_16x16x32_bf16 v[118:121], v[176:179], v[200:203], v[118:121]
	v_mfma_f32_16x16x32_bf16 v[110:113], v[168:171], v[208:211], v[110:113]
	v_mfma_f32_16x16x32_bf16 v[102:105], v[176:179], v[208:211], v[102:105]
	v_mfma_f32_16x16x32_bf16 v[94:97], v[168:171], v[216:219], v[94:97]
	v_mfma_f32_16x16x32_bf16 v[86:89], v[176:179], v[216:219], v[86:89]
	v_mfma_f32_16x16x32_bf16 v[78:81], v[168:171], v[224:227], v[78:81]
	v_mfma_f32_16x16x32_bf16 v[70:73], v[176:179], v[224:227], v[70:73]
	s_setprio 0
	s_setprio 1
	v_mfma_f32_16x16x32_bf16 v[126:129], v[180:183], v[196:199], v[126:129]
	v_mfma_f32_16x16x32_bf16 v[114:117], v[188:191], v[196:199], v[114:117]
	v_mfma_f32_16x16x32_bf16 v[106:109], v[180:183], v[204:207], v[106:109]
	v_mfma_f32_16x16x32_bf16 v[98:101], v[188:191], v[204:207], v[98:101]
	v_mfma_f32_16x16x32_bf16 v[90:93], v[180:183], v[212:215], v[90:93]
	v_mfma_f32_16x16x32_bf16 v[82:85], v[188:191], v[212:215], v[82:85]
	v_mfma_f32_16x16x32_bf16 v[74:77], v[180:183], v[220:223], v[74:77]
	v_mfma_f32_16x16x32_bf16 v[66:69], v[188:191], v[220:223], v[66:69]
	v_mfma_f32_16x16x32_bf16 v[126:129], v[184:187], v[200:203], v[126:129]
	v_mfma_f32_16x16x32_bf16 v[114:117], v[192:195], v[200:203], v[114:117]
	v_mfma_f32_16x16x32_bf16 v[106:109], v[184:187], v[208:211], v[106:109]
	v_mfma_f32_16x16x32_bf16 v[98:101], v[192:195], v[208:211], v[98:101]
	v_mfma_f32_16x16x32_bf16 v[90:93], v[184:187], v[216:219], v[90:93]
	v_mfma_f32_16x16x32_bf16 v[82:85], v[192:195], v[216:219], v[82:85]
	v_mfma_f32_16x16x32_bf16 v[74:77], v[184:187], v[224:227], v[74:77]
	v_mfma_f32_16x16x32_bf16 v[66:69], v[192:195], v[224:227], v[66:69]
	s_setprio 0
	s_barrier
	s_add_u32 s98, s96, 0x40000
	s_addc_u32 s99, s97, 0
	s_mov_b32 m0, s76
	s_nop 0
	global_load_lds_dwordx4 v132, s[96:97]
	s_mov_b32 m0, s77
	s_add_i32 s5, s73, s25
	global_load_lds_dwordx4 v136, s[96:97]
	s_mov_b32 m0, s5
	s_nop 0
	global_load_lds_dwordx4 v132, s[98:99]
	s_add_i32 m0, s5, 0x2000
	s_nop 0
	global_load_lds_dwordx4 v136, s[98:99]
	s_mov_b32 m0, s49
	s_nop 0
	global_load_lds_dwordx4 v130, s[94:95]
	s_mov_b32 m0, s58
	s_nop 0
	global_load_lds_dwordx4 v134, s[94:95]
	ds_read_b128 v[196:199], v160 offset:16384
	ds_read_b128 v[200:203], v160 offset:17408
	ds_read_b128 v[204:207], v160 offset:18432
	ds_read_b128 v[208:211], v160 offset:19456
	ds_read_b128 v[212:215], v160 offset:20480
	ds_read_b128 v[216:219], v160 offset:21504
	ds_read_b128 v[220:223], v160 offset:22528
	ds_read_b128 v[224:227], v160 offset:23552
	s_waitcnt vmcnt(8)
	s_waitcnt lgkmcnt(0)
	s_barrier
	s_setprio 1
	s_waitcnt lgkmcnt(0)
	v_mfma_f32_16x16x32_bf16 v[62:65], v[164:167], v[196:199], v[62:65]
	v_mfma_f32_16x16x32_bf16 v[54:57], v[172:175], v[196:199], v[54:57]
	v_mfma_f32_16x16x32_bf16 v[46:49], v[164:167], v[204:207], v[46:49]
	v_mfma_f32_16x16x32_bf16 v[38:41], v[172:175], v[204:207], v[38:41]
	v_mfma_f32_16x16x32_bf16 v[30:33], v[164:167], v[212:215], v[30:33]
	v_mfma_f32_16x16x32_bf16 v[22:25], v[172:175], v[212:215], v[22:25]
	v_mfma_f32_16x16x32_bf16 v[14:17], v[164:167], v[220:223], v[14:17]
	v_mfma_f32_16x16x32_bf16 v[6:9], v[172:175], v[220:223], v[6:9]
	v_mfma_f32_16x16x32_bf16 v[62:65], v[168:171], v[200:203], v[62:65]
	v_mfma_f32_16x16x32_bf16 v[54:57], v[176:179], v[200:203], v[54:57]
	v_mfma_f32_16x16x32_bf16 v[46:49], v[168:171], v[208:211], v[46:49]
	v_mfma_f32_16x16x32_bf16 v[38:41], v[176:179], v[208:211], v[38:41]
	v_mfma_f32_16x16x32_bf16 v[30:33], v[168:171], v[216:219], v[30:33]
	v_mfma_f32_16x16x32_bf16 v[22:25], v[176:179], v[216:219], v[22:25]
	v_mfma_f32_16x16x32_bf16 v[14:17], v[168:171], v[224:227], v[14:17]
	v_mfma_f32_16x16x32_bf16 v[6:9], v[176:179], v[224:227], v[6:9]
	s_setprio 0
	s_setprio 1
	v_mfma_f32_16x16x32_bf16 v[58:61], v[180:183], v[196:199], v[58:61]
	v_mfma_f32_16x16x32_bf16 v[50:53], v[188:191], v[196:199], v[50:53]
	v_mfma_f32_16x16x32_bf16 v[42:45], v[180:183], v[204:207], v[42:45]
	v_mfma_f32_16x16x32_bf16 v[34:37], v[188:191], v[204:207], v[34:37]
	v_mfma_f32_16x16x32_bf16 v[26:29], v[180:183], v[212:215], v[26:29]
	v_mfma_f32_16x16x32_bf16 v[18:21], v[188:191], v[212:215], v[18:21]
	v_mfma_f32_16x16x32_bf16 v[10:13], v[180:183], v[220:223], v[10:13]
	v_mfma_f32_16x16x32_bf16 v[2:5], v[188:191], v[220:223], v[2:5]
	v_mfma_f32_16x16x32_bf16 v[58:61], v[184:187], v[200:203], v[58:61]
	v_mfma_f32_16x16x32_bf16 v[50:53], v[192:195], v[200:203], v[50:53]
	v_mfma_f32_16x16x32_bf16 v[42:45], v[184:187], v[208:211], v[42:45]
	v_mfma_f32_16x16x32_bf16 v[34:37], v[192:195], v[208:211], v[34:37]
	v_mfma_f32_16x16x32_bf16 v[26:29], v[184:187], v[216:219], v[26:29]
	v_mfma_f32_16x16x32_bf16 v[18:21], v[192:195], v[216:219], v[18:21]
	v_mfma_f32_16x16x32_bf16 v[10:13], v[184:187], v[224:227], v[10:13]
	v_mfma_f32_16x16x32_bf16 v[2:5], v[192:195], v[224:227], v[2:5]
	s_setprio 0
	s_barrier
	s_add_u32 s98, s94, 0x40000
	s_addc_u32 s99, s95, 0
	s_add_i32 s5, 0, 0x18000
	s_add_i32 s47, 0, 0x1c000
	s_mov_b32 m0, s59
	s_nop 0
	global_load_lds_dwordx4 v130, s[98:99]
	s_mov_b32 m0, s60
	s_nop 0
	global_load_lds_dwordx4 v134, s[98:99]
	ds_read_b128 v[164:167], v232
	ds_read_b128 v[168:171], v232 offset:1024
	ds_read_b128 v[172:175], v232 offset:2048
	ds_read_b128 v[176:179], v232 offset:3072
	ds_read_b128 v[180:183], v233
	ds_read_b128 v[184:187], v233 offset:1024
	ds_read_b128 v[188:191], v233 offset:2048
	ds_read_b128 v[192:195], v233 offset:3072
	ds_read_b128 v[196:199], v160 offset:32768
	ds_read_b128 v[200:203], v160 offset:33792
	ds_read_b128 v[204:207], v160 offset:34816
	ds_read_b128 v[208:211], v160 offset:35840
	ds_read_b128 v[212:215], v160 offset:36864
	ds_read_b128 v[216:219], v160 offset:37888
	ds_read_b128 v[220:223], v160 offset:38912
	ds_read_b128 v[224:227], v160 offset:39936
	s_waitcnt vmcnt(8)
	s_waitcnt lgkmcnt(0)
	s_barrier
	s_setprio 1
	s_waitcnt lgkmcnt(0)
	v_mfma_f32_16x16x32_bf16 v[122:125], v[164:167], v[196:199], v[122:125]
	v_mfma_f32_16x16x32_bf16 v[118:121], v[172:175], v[196:199], v[118:121]
	v_mfma_f32_16x16x32_bf16 v[110:113], v[164:167], v[204:207], v[110:113]
	v_mfma_f32_16x16x32_bf16 v[102:105], v[172:175], v[204:207], v[102:105]
	v_mfma_f32_16x16x32_bf16 v[94:97], v[164:167], v[212:215], v[94:97]
	v_mfma_f32_16x16x32_bf16 v[86:89], v[172:175], v[212:215], v[86:89]
	v_mfma_f32_16x16x32_bf16 v[78:81], v[164:167], v[220:223], v[78:81]
	v_mfma_f32_16x16x32_bf16 v[70:73], v[172:175], v[220:223], v[70:73]
	v_mfma_f32_16x16x32_bf16 v[122:125], v[168:171], v[200:203], v[122:125]
	v_mfma_f32_16x16x32_bf16 v[118:121], v[176:179], v[200:203], v[118:121]
	v_mfma_f32_16x16x32_bf16 v[110:113], v[168:171], v[208:211], v[110:113]
	v_mfma_f32_16x16x32_bf16 v[102:105], v[176:179], v[208:211], v[102:105]
	v_mfma_f32_16x16x32_bf16 v[94:97], v[168:171], v[216:219], v[94:97]
	v_mfma_f32_16x16x32_bf16 v[86:89], v[176:179], v[216:219], v[86:89]
	v_mfma_f32_16x16x32_bf16 v[78:81], v[168:171], v[224:227], v[78:81]
	v_mfma_f32_16x16x32_bf16 v[70:73], v[176:179], v[224:227], v[70:73]
	s_setprio 0
	s_setprio 1
	v_mfma_f32_16x16x32_bf16 v[126:129], v[180:183], v[196:199], v[126:129]
	v_mfma_f32_16x16x32_bf16 v[114:117], v[188:191], v[196:199], v[114:117]
	v_mfma_f32_16x16x32_bf16 v[106:109], v[180:183], v[204:207], v[106:109]
	v_mfma_f32_16x16x32_bf16 v[98:101], v[188:191], v[204:207], v[98:101]
	v_mfma_f32_16x16x32_bf16 v[90:93], v[180:183], v[212:215], v[90:93]
	v_mfma_f32_16x16x32_bf16 v[82:85], v[188:191], v[212:215], v[82:85]
	v_mfma_f32_16x16x32_bf16 v[74:77], v[180:183], v[220:223], v[74:77]
	v_mfma_f32_16x16x32_bf16 v[66:69], v[188:191], v[220:223], v[66:69]
	v_mfma_f32_16x16x32_bf16 v[126:129], v[184:187], v[200:203], v[126:129]
	v_mfma_f32_16x16x32_bf16 v[114:117], v[192:195], v[200:203], v[114:117]
	v_mfma_f32_16x16x32_bf16 v[106:109], v[184:187], v[208:211], v[106:109]
	v_mfma_f32_16x16x32_bf16 v[98:101], v[192:195], v[208:211], v[98:101]
	v_mfma_f32_16x16x32_bf16 v[90:93], v[184:187], v[216:219], v[90:93]
	v_mfma_f32_16x16x32_bf16 v[82:85], v[192:195], v[216:219], v[82:85]
	v_mfma_f32_16x16x32_bf16 v[74:77], v[184:187], v[224:227], v[74:77]
	v_mfma_f32_16x16x32_bf16 v[66:69], v[192:195], v[224:227], v[66:69]
	s_setprio 0
	s_barrier
	s_add_u32 s96, s96, 0x80
	s_addc_u32 s97, s97, 0
	s_add_u32 s98, s96, 0x40000
	s_addc_u32 s99, s97, 0
	s_add_u32 s94, s94, 0x80
	s_addc_u32 s95, s95, 0
	s_add_i32 s5, s5, s25
	s_mov_b32 m0, s5
	s_nop 0
	global_load_lds_dwordx4 v132, s[96:97]
	s_add_i32 m0, s5, 0x2000
	s_add_i32 s5, s47, s25
	global_load_lds_dwordx4 v136, s[96:97]
	s_mov_b32 m0, s5
	s_nop 0
	global_load_lds_dwordx4 v132, s[98:99]
	s_add_i32 m0, s5, 0x2000
	s_nop 0
	global_load_lds_dwordx4 v136, s[98:99]
	s_mov_b32 m0, s61
	s_nop 0
	global_load_lds_dwordx4 v130, s[94:95]
	s_mov_b32 m0, s62
	s_nop 0
	global_load_lds_dwordx4 v134, s[94:95]
	ds_read_b128 v[196:199], v160 offset:49152
	ds_read_b128 v[200:203], v160 offset:50176
	ds_read_b128 v[204:207], v160 offset:51200
	ds_read_b128 v[208:211], v160 offset:52224
	ds_read_b128 v[212:215], v160 offset:53248
	ds_read_b128 v[216:219], v160 offset:54272
	ds_read_b128 v[220:223], v160 offset:55296
	ds_read_b128 v[224:227], v160 offset:56320
	s_waitcnt vmcnt(8)
	s_waitcnt lgkmcnt(0)
	s_barrier
	s_setprio 1
	s_waitcnt lgkmcnt(0)
	v_mfma_f32_16x16x32_bf16 v[62:65], v[164:167], v[196:199], v[62:65]
	v_mfma_f32_16x16x32_bf16 v[54:57], v[172:175], v[196:199], v[54:57]
	v_mfma_f32_16x16x32_bf16 v[46:49], v[164:167], v[204:207], v[46:49]
	v_mfma_f32_16x16x32_bf16 v[38:41], v[172:175], v[204:207], v[38:41]
	v_mfma_f32_16x16x32_bf16 v[30:33], v[164:167], v[212:215], v[30:33]
	v_mfma_f32_16x16x32_bf16 v[22:25], v[172:175], v[212:215], v[22:25]
	v_mfma_f32_16x16x32_bf16 v[14:17], v[164:167], v[220:223], v[14:17]
	v_mfma_f32_16x16x32_bf16 v[6:9], v[172:175], v[220:223], v[6:9]
	v_mfma_f32_16x16x32_bf16 v[62:65], v[168:171], v[200:203], v[62:65]
	v_mfma_f32_16x16x32_bf16 v[54:57], v[176:179], v[200:203], v[54:57]
	v_mfma_f32_16x16x32_bf16 v[46:49], v[168:171], v[208:211], v[46:49]
	v_mfma_f32_16x16x32_bf16 v[38:41], v[176:179], v[208:211], v[38:41]
	v_mfma_f32_16x16x32_bf16 v[30:33], v[168:171], v[216:219], v[30:33]
	v_mfma_f32_16x16x32_bf16 v[22:25], v[176:179], v[216:219], v[22:25]
	v_mfma_f32_16x16x32_bf16 v[14:17], v[168:171], v[224:227], v[14:17]
	v_mfma_f32_16x16x32_bf16 v[6:9], v[176:179], v[224:227], v[6:9]
	s_setprio 0
	s_setprio 1
	v_mfma_f32_16x16x32_bf16 v[58:61], v[180:183], v[196:199], v[58:61]
	v_mfma_f32_16x16x32_bf16 v[50:53], v[188:191], v[196:199], v[50:53]
	v_mfma_f32_16x16x32_bf16 v[42:45], v[180:183], v[204:207], v[42:45]
	v_mfma_f32_16x16x32_bf16 v[34:37], v[188:191], v[204:207], v[34:37]
	v_mfma_f32_16x16x32_bf16 v[26:29], v[180:183], v[212:215], v[26:29]
	v_mfma_f32_16x16x32_bf16 v[18:21], v[188:191], v[212:215], v[18:21]
	v_mfma_f32_16x16x32_bf16 v[10:13], v[180:183], v[220:223], v[10:13]
	v_mfma_f32_16x16x32_bf16 v[2:5], v[188:191], v[220:223], v[2:5]
	v_mfma_f32_16x16x32_bf16 v[58:61], v[184:187], v[200:203], v[58:61]
	v_mfma_f32_16x16x32_bf16 v[50:53], v[192:195], v[200:203], v[50:53]
	v_mfma_f32_16x16x32_bf16 v[42:45], v[184:187], v[208:211], v[42:45]
	v_mfma_f32_16x16x32_bf16 v[34:37], v[192:195], v[208:211], v[34:37]
	v_mfma_f32_16x16x32_bf16 v[26:29], v[184:187], v[216:219], v[26:29]
	v_mfma_f32_16x16x32_bf16 v[18:21], v[192:195], v[216:219], v[18:21]
	v_mfma_f32_16x16x32_bf16 v[10:13], v[184:187], v[224:227], v[10:13]
	v_mfma_f32_16x16x32_bf16 v[2:5], v[192:195], v[224:227], v[2:5]
	s_setprio 0
	s_barrier
	s_mov_b32 s5, s45
	s_add_u32 s88, s88, 0x100
	s_addc_u32 s89, s89, 0
	s_add_u32 s86, s86, 0x100
	s_addc_u32 s87, s87, 0
	s_cmp_ge_i32 s45, s101
	s_cbranch_scc0 .LBB0_1944

.LBB0_2073:
	v_cmp_gt_i32_e32 vcc, 1, v156
	s_cbranch_vccnz .LBB0_2135
	v_lshl_add_u64 v[152:153], v[2:3], 0, s[18:19]
	v_add_u32_e32 v138, -2, v156
	s_mov_b32 s4, 0
	s_nop 0
	v_readfirstlane_b32 s86, v150
	v_readfirstlane_b32 s87, v151
	v_readfirstlane_b32 s88, v152
	v_readfirstlane_b32 s89, v153
	v_readfirstlane_b32 s90, v146
	v_readfirstlane_b32 s91, v147
	v_readfirstlane_b32 s92, v148
	v_readfirstlane_b32 s93, v149
	v_readfirstlane_b32 s100, v138
	v_readfirstlane_b32 s101, v156
	v_add_u32_e32 v230, s65, v141
	v_add_u32_e32 v231, s66, v141
	v_add_u32_e32 v232, 0x18000, v141
	v_add_u32_e32 v233, 0x1c000, v141
	s_add_u32 s98, s86, 0x100
	s_addc_u32 s99, s87, 0
	s_cmp_eq_u32 s4, s100
	s_cselect_b64 s[94:95], s[90:91], s[98:99]
	s_cselect_b64 s[96:97], s[92:93], s[88:89]
	s_add_i32 s5, s4, 2
	s_nop 0
	s_add_i32 m0, s44, 0xc000
	s_nop 0
	global_load_lds_dwordx4 v144, s[86:87]
	s_add_i32 m0, s44, 0xe000
	s_nop 0
	global_load_lds_dwordx4 v142, s[86:87]
	ds_read_b128 v[164:167], v230
	ds_read_b128 v[168:171], v230 offset:1024
	ds_read_b128 v[172:175], v230 offset:2048
	ds_read_b128 v[176:179], v230 offset:3072
	ds_read_b128 v[180:183], v231
	ds_read_b128 v[184:187], v231 offset:1024
	ds_read_b128 v[188:191], v231 offset:2048
	ds_read_b128 v[192:195], v231 offset:3072
	ds_read_b128 v[196:199], v160
	ds_read_b128 v[200:203], v160 offset:1024
	ds_read_b128 v[204:207], v160 offset:2048
	ds_read_b128 v[208:211], v160 offset:3072
	ds_read_b128 v[212:215], v160 offset:4096
	ds_read_b128 v[216:219], v160 offset:5120
	ds_read_b128 v[220:223], v160 offset:6144
	ds_read_b128 v[224:227], v160 offset:7168
	s_waitcnt vmcnt(8)
	s_waitcnt lgkmcnt(0)
	s_barrier
	s_setprio 1
	s_waitcnt lgkmcnt(0)
	v_mfma_f32_16x16x32_bf16 v[122:125], v[164:167], v[196:199], 0
	v_mfma_f32_16x16x32_bf16 v[118:121], v[172:175], v[196:199], 0
	v_mfma_f32_16x16x32_bf16 v[110:113], v[164:167], v[204:207], 0
	v_mfma_f32_16x16x32_bf16 v[102:105], v[172:175], v[204:207], 0
	v_mfma_f32_16x16x32_bf16 v[94:97], v[164:167], v[212:215], 0
	v_mfma_f32_16x16x32_bf16 v[86:89], v[172:175], v[212:215], 0
	v_mfma_f32_16x16x32_bf16 v[78:81], v[164:167], v[220:223], 0
	v_mfma_f32_16x16x32_bf16 v[70:73], v[172:175], v[220:223], 0
	v_mfma_f32_16x16x32_bf16 v[122:125], v[168:171], v[200:203], v[122:125]
	v_mfma_f32_16x16x32_bf16 v[118:121], v[176:179], v[200:203], v[118:121]
	v_mfma_f32_16x16x32_bf16 v[110:113], v[168:171], v[208:211], v[110:113]
	v_mfma_f32_16x16x32_bf16 v[102:105], v[176:179], v[208:211], v[102:105]
	v_mfma_f32_16x16x32_bf16 v[94:97], v[168:171], v[216:219], v[94:97]
	v_mfma_f32_16x16x32_bf16 v[86:89], v[176:179], v[216:219], v[86:89]
	v_mfma_f32_16x16x32_bf16 v[78:81], v[168:171], v[224:227], v[78:81]
	v_mfma_f32_16x16x32_bf16 v[70:73], v[176:179], v[224:227], v[70:73]
	s_setprio 0
	s_setprio 1
	v_mfma_f32_16x16x32_bf16 v[126:129], v[180:183], v[196:199], 0
	v_mfma_f32_16x16x32_bf16 v[114:117], v[188:191], v[196:199], 0
	v_mfma_f32_16x16x32_bf16 v[106:109], v[180:183], v[204:207], 0
	v_mfma_f32_16x16x32_bf16 v[98:101], v[188:191], v[204:207], 0
	v_mfma_f32_16x16x32_bf16 v[90:93], v[180:183], v[212:215], 0
	v_mfma_f32_16x16x32_bf16 v[82:85], v[188:191], v[212:215], 0
	v_mfma_f32_16x16x32_bf16 v[74:77], v[180:183], v[220:223], 0
	v_mfma_f32_16x16x32_bf16 v[66:69], v[188:191], v[220:223], 0
	v_mfma_f32_16x16x32_bf16 v[126:129], v[184:187], v[200:203], v[126:129]
	v_mfma_f32_16x16x32_bf16 v[114:117], v[192:195], v[200:203], v[114:117]
	v_mfma_f32_16x16x32_bf16 v[106:109], v[184:187], v[208:211], v[106:109]
	v_mfma_f32_16x16x32_bf16 v[98:101], v[192:195], v[208:211], v[98:101]
	v_mfma_f32_16x16x32_bf16 v[90:93], v[184:187], v[216:219], v[90:93]
	v_mfma_f32_16x16x32_bf16 v[82:85], v[192:195], v[216:219], v[82:85]
	v_mfma_f32_16x16x32_bf16 v[74:77], v[184:187], v[224:227], v[74:77]
	v_mfma_f32_16x16x32_bf16 v[66:69], v[192:195], v[224:227], v[66:69]
	s_setprio 0
	s_barrier
	s_add_u32 s98, s96, 0xb0000
	s_addc_u32 s99, s97, 0
	s_add_i32 s4, s65, s21
	s_mov_b32 m0, s4
	s_nop 0
	global_load_lds_dwordx4 v132, s[96:97]
	s_add_i32 m0, s4, 0x2000
	s_add_i32 s4, s66, s21
	global_load_lds_dwordx4 v136, s[96:97]
	s_mov_b32 m0, s4
	s_nop 0
	global_load_lds_dwordx4 v132, s[98:99]
	s_add_i32 m0, s4, 0x2000
	s_nop 0
	global_load_lds_dwordx4 v136, s[98:99]
	s_mov_b32 m0, s44
	s_nop 0
	global_load_lds_dwordx4 v130, s[94:95]
	s_mov_b32 m0, s45
	s_nop 0
	global_load_lds_dwordx4 v134, s[94:95]
	ds_read_b128 v[196:199], v160 offset:16384
	ds_read_b128 v[200:203], v160 offset:17408
	ds_read_b128 v[204:207], v160 offset:18432
	ds_read_b128 v[208:211], v160 offset:19456
	ds_read_b128 v[212:215], v160 offset:20480
	ds_read_b128 v[216:219], v160 offset:21504
	ds_read_b128 v[220:223], v160 offset:22528
	ds_read_b128 v[224:227], v160 offset:23552
	s_waitcnt vmcnt(8)
	s_waitcnt lgkmcnt(0)
	s_barrier
	s_setprio 1
	s_waitcnt lgkmcnt(0)
	v_mfma_f32_16x16x32_bf16 v[62:65], v[164:167], v[196:199], 0
	v_mfma_f32_16x16x32_bf16 v[54:57], v[172:175], v[196:199], 0
	v_mfma_f32_16x16x32_bf16 v[46:49], v[164:167], v[204:207], 0
	v_mfma_f32_16x16x32_bf16 v[38:41], v[172:175], v[204:207], 0
	v_mfma_f32_16x16x32_bf16 v[30:33], v[164:167], v[212:215], 0
	v_mfma_f32_16x16x32_bf16 v[22:25], v[172:175], v[212:215], 0
	v_mfma_f32_16x16x32_bf16 v[14:17], v[164:167], v[220:223], 0
	v_mfma_f32_16x16x32_bf16 v[6:9], v[172:175], v[220:223], 0
	v_mfma_f32_16x16x32_bf16 v[62:65], v[168:171], v[200:203], v[62:65]
	v_mfma_f32_16x16x32_bf16 v[54:57], v[176:179], v[200:203], v[54:57]
	v_mfma_f32_16x16x32_bf16 v[46:49], v[168:171], v[208:211], v[46:49]
	v_mfma_f32_16x16x32_bf16 v[38:41], v[176:179], v[208:211], v[38:41]
	v_mfma_f32_16x16x32_bf16 v[30:33], v[168:171], v[216:219], v[30:33]
	v_mfma_f32_16x16x32_bf16 v[22:25], v[176:179], v[216:219], v[22:25]
	v_mfma_f32_16x16x32_bf16 v[14:17], v[168:171], v[224:227], v[14:17]
	v_mfma_f32_16x16x32_bf16 v[6:9], v[176:179], v[224:227], v[6:9]
	s_setprio 0
	s_setprio 1
	v_mfma_f32_16x16x32_bf16 v[58:61], v[180:183], v[196:199], 0
	v_mfma_f32_16x16x32_bf16 v[50:53], v[188:191], v[196:199], 0
	v_mfma_f32_16x16x32_bf16 v[42:45], v[180:183], v[204:207], 0
	v_mfma_f32_16x16x32_bf16 v[34:37], v[188:191], v[204:207], 0
	v_mfma_f32_16x16x32_bf16 v[26:29], v[180:183], v[212:215], 0
	v_mfma_f32_16x16x32_bf16 v[18:21], v[188:191], v[212:215], 0
	v_mfma_f32_16x16x32_bf16 v[10:13], v[180:183], v[220:223], 0
	v_mfma_f32_16x16x32_bf16 v[2:5], v[188:191], v[220:223], 0
	v_mfma_f32_16x16x32_bf16 v[58:61], v[184:187], v[200:203], v[58:61]
	v_mfma_f32_16x16x32_bf16 v[50:53], v[192:195], v[200:203], v[50:53]
	v_mfma_f32_16x16x32_bf16 v[42:45], v[184:187], v[208:211], v[42:45]
	v_mfma_f32_16x16x32_bf16 v[34:37], v[192:195], v[208:211], v[34:37]
	v_mfma_f32_16x16x32_bf16 v[26:29], v[184:187], v[216:219], v[26:29]
	v_mfma_f32_16x16x32_bf16 v[18:21], v[192:195], v[216:219], v[18:21]
	v_mfma_f32_16x16x32_bf16 v[10:13], v[184:187], v[224:227], v[10:13]
	v_mfma_f32_16x16x32_bf16 v[2:5], v[192:195], v[224:227], v[2:5]
	s_setprio 0
	s_barrier
	s_add_u32 s98, s94, 0xb0000
	s_addc_u32 s99, s95, 0
	s_add_i32 s4, 0, 0x18000
	s_add_i32 s25, 0, 0x1c000
	s_mov_b32 m0, s46
	s_nop 0
	global_load_lds_dwordx4 v130, s[98:99]
	s_mov_b32 m0, s47
	s_nop 0
	global_load_lds_dwordx4 v134, s[98:99]
	ds_read_b128 v[164:167], v232
	ds_read_b128 v[168:171], v232 offset:1024
	ds_read_b128 v[172:175], v232 offset:2048
	ds_read_b128 v[176:179], v232 offset:3072
	ds_read_b128 v[180:183], v233
	ds_read_b128 v[184:187], v233 offset:1024
	ds_read_b128 v[188:191], v233 offset:2048
	ds_read_b128 v[192:195], v233 offset:3072
	ds_read_b128 v[196:199], v160 offset:32768
	ds_read_b128 v[200:203], v160 offset:33792
	ds_read_b128 v[204:207], v160 offset:34816
	ds_read_b128 v[208:211], v160 offset:35840
	ds_read_b128 v[212:215], v160 offset:36864
	ds_read_b128 v[216:219], v160 offset:37888
	ds_read_b128 v[220:223], v160 offset:38912
	ds_read_b128 v[224:227], v160 offset:39936
	s_waitcnt vmcnt(8)
	s_waitcnt lgkmcnt(0)
	s_barrier
	s_setprio 1
	s_waitcnt lgkmcnt(0)
	v_mfma_f32_16x16x32_bf16 v[122:125], v[164:167], v[196:199], v[122:125]
	v_mfma_f32_16x16x32_bf16 v[118:121], v[172:175], v[196:199], v[118:121]
	v_mfma_f32_16x16x32_bf16 v[110:113], v[164:167], v[204:207], v[110:113]
	v_mfma_f32_16x16x32_bf16 v[102:105], v[172:175], v[204:207], v[102:105]
	v_mfma_f32_16x16x32_bf16 v[94:97], v[164:167], v[212:215], v[94:97]
	v_mfma_f32_16x16x32_bf16 v[86:89], v[172:175], v[212:215], v[86:89]
	v_mfma_f32_16x16x32_bf16 v[78:81], v[164:167], v[220:223], v[78:81]
	v_mfma_f32_16x16x32_bf16 v[70:73], v[172:175], v[220:223], v[70:73]
	v_mfma_f32_16x16x32_bf16 v[122:125], v[168:171], v[200:203], v[122:125]
	v_mfma_f32_16x16x32_bf16 v[118:121], v[176:179], v[200:203], v[118:121]
	v_mfma_f32_16x16x32_bf16 v[110:113], v[168:171], v[208:211], v[110:113]
	v_mfma_f32_16x16x32_bf16 v[102:105], v[176:179], v[208:211], v[102:105]
	v_mfma_f32_16x16x32_bf16 v[94:97], v[168:171], v[216:219], v[94:97]
	v_mfma_f32_16x16x32_bf16 v[86:89], v[176:179], v[216:219], v[86:89]
	v_mfma_f32_16x16x32_bf16 v[78:81], v[168:171], v[224:227], v[78:81]
	v_mfma_f32_16x16x32_bf16 v[70:73], v[176:179], v[224:227], v[70:73]
	s_setprio 0
	s_setprio 1
	v_mfma_f32_16x16x32_bf16 v[126:129], v[180:183], v[196:199], v[126:129]
	v_mfma_f32_16x16x32_bf16 v[114:117], v[188:191], v[196:199], v[114:117]
	v_mfma_f32_16x16x32_bf16 v[106:109], v[180:183], v[204:207], v[106:109]
	v_mfma_f32_16x16x32_bf16 v[98:101], v[188:191], v[204:207], v[98:101]
	v_mfma_f32_16x16x32_bf16 v[90:93], v[180:183], v[212:215], v[90:93]
	v_mfma_f32_16x16x32_bf16 v[82:85], v[188:191], v[212:215], v[82:85]
	v_mfma_f32_16x16x32_bf16 v[74:77], v[180:183], v[220:223], v[74:77]
	v_mfma_f32_16x16x32_bf16 v[66:69], v[188:191], v[220:223], v[66:69]
	v_mfma_f32_16x16x32_bf16 v[126:129], v[184:187], v[200:203], v[126:129]
	v_mfma_f32_16x16x32_bf16 v[114:117], v[192:195], v[200:203], v[114:117]
	v_mfma_f32_16x16x32_bf16 v[106:109], v[184:187], v[208:211], v[106:109]
	v_mfma_f32_16x16x32_bf16 v[98:101], v[192:195], v[208:211], v[98:101]
	v_mfma_f32_16x16x32_bf16 v[90:93], v[184:187], v[216:219], v[90:93]
	v_mfma_f32_16x16x32_bf16 v[82:85], v[192:195], v[216:219], v[82:85]
	v_mfma_f32_16x16x32_bf16 v[74:77], v[184:187], v[224:227], v[74:77]
	v_mfma_f32_16x16x32_bf16 v[66:69], v[192:195], v[224:227], v[66:69]
	s_setprio 0
	s_barrier
	s_add_u32 s96, s96, 0x80
	s_addc_u32 s97, s97, 0
	s_add_u32 s98, s96, 0xb0000
	s_addc_u32 s99, s97, 0
	s_add_u32 s94, s94, 0x80
	s_addc_u32 s95, s95, 0
	s_add_i32 s4, s4, s21
	s_mov_b32 m0, s4
	s_nop 0
	global_load_lds_dwordx4 v132, s[96:97]
	s_add_i32 m0, s4, 0x2000
	s_add_i32 s4, s25, s21
	global_load_lds_dwordx4 v136, s[96:97]
	s_mov_b32 m0, s4
	s_nop 0
	global_load_lds_dwordx4 v132, s[98:99]
	s_add_i32 m0, s4, 0x2000
	s_nop 0
	global_load_lds_dwordx4 v136, s[98:99]
	s_mov_b32 m0, s57
	s_nop 0
	global_load_lds_dwordx4 v130, s[94:95]
	s_mov_b32 m0, s58
	s_nop 0
	global_load_lds_dwordx4 v134, s[94:95]
	ds_read_b128 v[196:199], v160 offset:49152
	ds_read_b128 v[200:203], v160 offset:50176
	ds_read_b128 v[204:207], v160 offset:51200
	ds_read_b128 v[208:211], v160 offset:52224
	ds_read_b128 v[212:215], v160 offset:53248
	ds_read_b128 v[216:219], v160 offset:54272
	ds_read_b128 v[220:223], v160 offset:55296
	ds_read_b128 v[224:227], v160 offset:56320
	s_waitcnt vmcnt(8)
	s_waitcnt lgkmcnt(0)
	s_barrier
	s_setprio 1
	s_waitcnt lgkmcnt(0)
	v_mfma_f32_16x16x32_bf16 v[62:65], v[164:167], v[196:199], v[62:65]
	v_mfma_f32_16x16x32_bf16 v[54:57], v[172:175], v[196:199], v[54:57]
	v_mfma_f32_16x16x32_bf16 v[46:49], v[164:167], v[204:207], v[46:49]
	v_mfma_f32_16x16x32_bf16 v[38:41], v[172:175], v[204:207], v[38:41]
	v_mfma_f32_16x16x32_bf16 v[30:33], v[164:167], v[212:215], v[30:33]
	v_mfma_f32_16x16x32_bf16 v[22:25], v[172:175], v[212:215], v[22:25]
	v_mfma_f32_16x16x32_bf16 v[14:17], v[164:167], v[220:223], v[14:17]
	v_mfma_f32_16x16x32_bf16 v[6:9], v[172:175], v[220:223], v[6:9]
	v_mfma_f32_16x16x32_bf16 v[62:65], v[168:171], v[200:203], v[62:65]
	v_mfma_f32_16x16x32_bf16 v[54:57], v[176:179], v[200:203], v[54:57]
	v_mfma_f32_16x16x32_bf16 v[46:49], v[168:171], v[208:211], v[46:49]
	v_mfma_f32_16x16x32_bf16 v[38:41], v[176:179], v[208:211], v[38:41]
	v_mfma_f32_16x16x32_bf16 v[30:33], v[168:171], v[216:219], v[30:33]
	v_mfma_f32_16x16x32_bf16 v[22:25], v[176:179], v[216:219], v[22:25]
	v_mfma_f32_16x16x32_bf16 v[14:17], v[168:171], v[224:227], v[14:17]
	v_mfma_f32_16x16x32_bf16 v[6:9], v[176:179], v[224:227], v[6:9]
	s_setprio 0
	s_setprio 1
	v_mfma_f32_16x16x32_bf16 v[58:61], v[180:183], v[196:199], v[58:61]
	v_mfma_f32_16x16x32_bf16 v[50:53], v[188:191], v[196:199], v[50:53]
	v_mfma_f32_16x16x32_bf16 v[42:45], v[180:183], v[204:207], v[42:45]
	v_mfma_f32_16x16x32_bf16 v[34:37], v[188:191], v[204:207], v[34:37]
	v_mfma_f32_16x16x32_bf16 v[26:29], v[180:183], v[212:215], v[26:29]
	v_mfma_f32_16x16x32_bf16 v[18:21], v[188:191], v[212:215], v[18:21]
	v_mfma_f32_16x16x32_bf16 v[10:13], v[180:183], v[220:223], v[10:13]
	v_mfma_f32_16x16x32_bf16 v[2:5], v[188:191], v[220:223], v[2:5]
	v_mfma_f32_16x16x32_bf16 v[58:61], v[184:187], v[200:203], v[58:61]
	v_mfma_f32_16x16x32_bf16 v[50:53], v[192:195], v[200:203], v[50:53]
	v_mfma_f32_16x16x32_bf16 v[42:45], v[184:187], v[208:211], v[42:45]
	v_mfma_f32_16x16x32_bf16 v[34:37], v[192:195], v[208:211], v[34:37]
	v_mfma_f32_16x16x32_bf16 v[26:29], v[184:187], v[216:219], v[26:29]
	v_mfma_f32_16x16x32_bf16 v[18:21], v[192:195], v[216:219], v[18:21]
	v_mfma_f32_16x16x32_bf16 v[10:13], v[184:187], v[224:227], v[10:13]
	v_mfma_f32_16x16x32_bf16 v[2:5], v[192:195], v[224:227], v[2:5]
	s_setprio 0
	s_barrier
	s_mov_b32 s4, s5
	s_add_u32 s88, s88, 0x100
	s_addc_u32 s89, s89, 0
	s_add_u32 s86, s86, 0x100
	s_addc_u32 s87, s87, 0
	s_cmp_ge_i32 s5, s101
	s_cbranch_scc1 .Lmy_kexit_11
.LBB0_2075:
	s_add_u32 s98, s86, 0x100
	s_addc_u32 s99, s87, 0
	s_cmp_eq_u32 s4, s100
	s_cselect_b64 s[94:95], s[90:91], s[98:99]
	s_cselect_b64 s[96:97], s[92:93], s[88:89]
	s_add_i32 s5, s4, 2
	s_nop 0
	s_add_i32 m0, s44, 0xc000
	s_nop 0
	global_load_lds_dwordx4 v144, s[86:87]
	s_add_i32 m0, s44, 0xe000
	s_nop 0
	global_load_lds_dwordx4 v142, s[86:87]
	ds_read_b128 v[164:167], v230
	ds_read_b128 v[168:171], v230 offset:1024
	ds_read_b128 v[172:175], v230 offset:2048
	ds_read_b128 v[176:179], v230 offset:3072
	ds_read_b128 v[180:183], v231
	ds_read_b128 v[184:187], v231 offset:1024
	ds_read_b128 v[188:191], v231 offset:2048
	ds_read_b128 v[192:195], v231 offset:3072
	ds_read_b128 v[196:199], v160
	ds_read_b128 v[200:203], v160 offset:1024
	ds_read_b128 v[204:207], v160 offset:2048
	ds_read_b128 v[208:211], v160 offset:3072
	ds_read_b128 v[212:215], v160 offset:4096
	ds_read_b128 v[216:219], v160 offset:5120
	ds_read_b128 v[220:223], v160 offset:6144
	ds_read_b128 v[224:227], v160 offset:7168
	s_waitcnt vmcnt(8)
	s_waitcnt lgkmcnt(0)
	s_barrier
	s_setprio 1
	s_waitcnt lgkmcnt(0)
	v_mfma_f32_16x16x32_bf16 v[122:125], v[164:167], v[196:199], v[122:125]
	v_mfma_f32_16x16x32_bf16 v[118:121], v[172:175], v[196:199], v[118:121]
	v_mfma_f32_16x16x32_bf16 v[110:113], v[164:167], v[204:207], v[110:113]
	v_mfma_f32_16x16x32_bf16 v[102:105], v[172:175], v[204:207], v[102:105]
	v_mfma_f32_16x16x32_bf16 v[94:97], v[164:167], v[212:215], v[94:97]
	v_mfma_f32_16x16x32_bf16 v[86:89], v[172:175], v[212:215], v[86:89]
	v_mfma_f32_16x16x32_bf16 v[78:81], v[164:167], v[220:223], v[78:81]
	v_mfma_f32_16x16x32_bf16 v[70:73], v[172:175], v[220:223], v[70:73]
	v_mfma_f32_16x16x32_bf16 v[122:125], v[168:171], v[200:203], v[122:125]
	v_mfma_f32_16x16x32_bf16 v[118:121], v[176:179], v[200:203], v[118:121]
	v_mfma_f32_16x16x32_bf16 v[110:113], v[168:171], v[208:211], v[110:113]
	v_mfma_f32_16x16x32_bf16 v[102:105], v[176:179], v[208:211], v[102:105]
	v_mfma_f32_16x16x32_bf16 v[94:97], v[168:171], v[216:219], v[94:97]
	v_mfma_f32_16x16x32_bf16 v[86:89], v[176:179], v[216:219], v[86:89]
	v_mfma_f32_16x16x32_bf16 v[78:81], v[168:171], v[224:227], v[78:81]
	v_mfma_f32_16x16x32_bf16 v[70:73], v[176:179], v[224:227], v[70:73]
	s_setprio 0
	s_setprio 1
	v_mfma_f32_16x16x32_bf16 v[126:129], v[180:183], v[196:199], v[126:129]
	v_mfma_f32_16x16x32_bf16 v[114:117], v[188:191], v[196:199], v[114:117]
	v_mfma_f32_16x16x32_bf16 v[106:109], v[180:183], v[204:207], v[106:109]
	v_mfma_f32_16x16x32_bf16 v[98:101], v[188:191], v[204:207], v[98:101]
	v_mfma_f32_16x16x32_bf16 v[90:93], v[180:183], v[212:215], v[90:93]
	v_mfma_f32_16x16x32_bf16 v[82:85], v[188:191], v[212:215], v[82:85]
	v_mfma_f32_16x16x32_bf16 v[74:77], v[180:183], v[220:223], v[74:77]
	v_mfma_f32_16x16x32_bf16 v[66:69], v[188:191], v[220:223], v[66:69]
	v_mfma_f32_16x16x32_bf16 v[126:129], v[184:187], v[200:203], v[126:129]
	v_mfma_f32_16x16x32_bf16 v[114:117], v[192:195], v[200:203], v[114:117]
	v_mfma_f32_16x16x32_bf16 v[106:109], v[184:187], v[208:211], v[106:109]
	v_mfma_f32_16x16x32_bf16 v[98:101], v[192:195], v[208:211], v[98:101]
	v_mfma_f32_16x16x32_bf16 v[90:93], v[184:187], v[216:219], v[90:93]
	v_mfma_f32_16x16x32_bf16 v[82:85], v[192:195], v[216:219], v[82:85]
	v_mfma_f32_16x16x32_bf16 v[74:77], v[184:187], v[224:227], v[74:77]
	v_mfma_f32_16x16x32_bf16 v[66:69], v[192:195], v[224:227], v[66:69]
	s_setprio 0
	s_barrier
	s_add_u32 s98, s96, 0xb0000
	s_addc_u32 s99, s97, 0
	s_add_i32 s4, s65, s21
	s_mov_b32 m0, s4
	s_nop 0
	global_load_lds_dwordx4 v132, s[96:97]
	s_add_i32 m0, s4, 0x2000
	s_add_i32 s4, s66, s21
	global_load_lds_dwordx4 v136, s[96:97]
	s_mov_b32 m0, s4
	s_nop 0
	global_load_lds_dwordx4 v132, s[98:99]
	s_add_i32 m0, s4, 0x2000
	s_nop 0
	global_load_lds_dwordx4 v136, s[98:99]
	s_mov_b32 m0, s44
	s_nop 0
	global_load_lds_dwordx4 v130, s[94:95]
	s_mov_b32 m0, s45
	s_nop 0
	global_load_lds_dwordx4 v134, s[94:95]
	ds_read_b128 v[196:199], v160 offset:16384
	ds_read_b128 v[200:203], v160 offset:17408
	ds_read_b128 v[204:207], v160 offset:18432
	ds_read_b128 v[208:211], v160 offset:19456
	ds_read_b128 v[212:215], v160 offset:20480
	ds_read_b128 v[216:219], v160 offset:21504
	ds_read_b128 v[220:223], v160 offset:22528
	ds_read_b128 v[224:227], v160 offset:23552
	s_waitcnt vmcnt(8)
	s_waitcnt lgkmcnt(0)
	s_barrier
	s_setprio 1
	s_waitcnt lgkmcnt(0)
	v_mfma_f32_16x16x32_bf16 v[62:65], v[164:167], v[196:199], v[62:65]
	v_mfma_f32_16x16x32_bf16 v[54:57], v[172:175], v[196:199], v[54:57]
	v_mfma_f32_16x16x32_bf16 v[46:49], v[164:167], v[204:207], v[46:49]
	v_mfma_f32_16x16x32_bf16 v[38:41], v[172:175], v[204:207], v[38:41]
	v_mfma_f32_16x16x32_bf16 v[30:33], v[164:167], v[212:215], v[30:33]
	v_mfma_f32_16x16x32_bf16 v[22:25], v[172:175], v[212:215], v[22:25]
	v_mfma_f32_16x16x32_bf16 v[14:17], v[164:167], v[220:223], v[14:17]
	v_mfma_f32_16x16x32_bf16 v[6:9], v[172:175], v[220:223], v[6:9]
	v_mfma_f32_16x16x32_bf16 v[62:65], v[168:171], v[200:203], v[62:65]
	v_mfma_f32_16x16x32_bf16 v[54:57], v[176:179], v[200:203], v[54:57]
	v_mfma_f32_16x16x32_bf16 v[46:49], v[168:171], v[208:211], v[46:49]
	v_mfma_f32_16x16x32_bf16 v[38:41], v[176:179], v[208:211], v[38:41]
	v_mfma_f32_16x16x32_bf16 v[30:33], v[168:171], v[216:219], v[30:33]
	v_mfma_f32_16x16x32_bf16 v[22:25], v[176:179], v[216:219], v[22:25]
	v_mfma_f32_16x16x32_bf16 v[14:17], v[168:171], v[224:227], v[14:17]
	v_mfma_f32_16x16x32_bf16 v[6:9], v[176:179], v[224:227], v[6:9]
	s_setprio 0
	s_setprio 1
	v_mfma_f32_16x16x32_bf16 v[58:61], v[180:183], v[196:199], v[58:61]
	v_mfma_f32_16x16x32_bf16 v[50:53], v[188:191], v[196:199], v[50:53]
	v_mfma_f32_16x16x32_bf16 v[42:45], v[180:183], v[204:207], v[42:45]
	v_mfma_f32_16x16x32_bf16 v[34:37], v[188:191], v[204:207], v[34:37]
	v_mfma_f32_16x16x32_bf16 v[26:29], v[180:183], v[212:215], v[26:29]
	v_mfma_f32_16x16x32_bf16 v[18:21], v[188:191], v[212:215], v[18:21]
	v_mfma_f32_16x16x32_bf16 v[10:13], v[180:183], v[220:223], v[10:13]
	v_mfma_f32_16x16x32_bf16 v[2:5], v[188:191], v[220:223], v[2:5]
	v_mfma_f32_16x16x32_bf16 v[58:61], v[184:187], v[200:203], v[58:61]
	v_mfma_f32_16x16x32_bf16 v[50:53], v[192:195], v[200:203], v[50:53]
	v_mfma_f32_16x16x32_bf16 v[42:45], v[184:187], v[208:211], v[42:45]
	v_mfma_f32_16x16x32_bf16 v[34:37], v[192:195], v[208:211], v[34:37]
	v_mfma_f32_16x16x32_bf16 v[26:29], v[184:187], v[216:219], v[26:29]
	v_mfma_f32_16x16x32_bf16 v[18:21], v[192:195], v[216:219], v[18:21]
	v_mfma_f32_16x16x32_bf16 v[10:13], v[184:187], v[224:227], v[10:13]
	v_mfma_f32_16x16x32_bf16 v[2:5], v[192:195], v[224:227], v[2:5]
	s_setprio 0
	s_barrier
	s_add_u32 s98, s94, 0xb0000
	s_addc_u32 s99, s95, 0
	s_add_i32 s4, 0, 0x18000
	s_add_i32 s25, 0, 0x1c000
	s_mov_b32 m0, s46
	s_nop 0
	global_load_lds_dwordx4 v130, s[98:99]
	s_mov_b32 m0, s47
	s_nop 0
	global_load_lds_dwordx4 v134, s[98:99]
	ds_read_b128 v[164:167], v232
	ds_read_b128 v[168:171], v232 offset:1024
	ds_read_b128 v[172:175], v232 offset:2048
	ds_read_b128 v[176:179], v232 offset:3072
	ds_read_b128 v[180:183], v233
	ds_read_b128 v[184:187], v233 offset:1024
	ds_read_b128 v[188:191], v233 offset:2048
	ds_read_b128 v[192:195], v233 offset:3072
	ds_read_b128 v[196:199], v160 offset:32768
	ds_read_b128 v[200:203], v160 offset:33792
	ds_read_b128 v[204:207], v160 offset:34816
	ds_read_b128 v[208:211], v160 offset:35840
	ds_read_b128 v[212:215], v160 offset:36864
	ds_read_b128 v[216:219], v160 offset:37888
	ds_read_b128 v[220:223], v160 offset:38912
	ds_read_b128 v[224:227], v160 offset:39936
	s_waitcnt vmcnt(8)
	s_waitcnt lgkmcnt(0)
	s_barrier
	s_setprio 1
	s_waitcnt lgkmcnt(0)
	v_mfma_f32_16x16x32_bf16 v[122:125], v[164:167], v[196:199], v[122:125]
	v_mfma_f32_16x16x32_bf16 v[118:121], v[172:175], v[196:199], v[118:121]
	v_mfma_f32_16x16x32_bf16 v[110:113], v[164:167], v[204:207], v[110:113]
	v_mfma_f32_16x16x32_bf16 v[102:105], v[172:175], v[204:207], v[102:105]
	v_mfma_f32_16x16x32_bf16 v[94:97], v[164:167], v[212:215], v[94:97]
	v_mfma_f32_16x16x32_bf16 v[86:89], v[172:175], v[212:215], v[86:89]
	v_mfma_f32_16x16x32_bf16 v[78:81], v[164:167], v[220:223], v[78:81]
	v_mfma_f32_16x16x32_bf16 v[70:73], v[172:175], v[220:223], v[70:73]
	v_mfma_f32_16x16x32_bf16 v[122:125], v[168:171], v[200:203], v[122:125]
	v_mfma_f32_16x16x32_bf16 v[118:121], v[176:179], v[200:203], v[118:121]
	v_mfma_f32_16x16x32_bf16 v[110:113], v[168:171], v[208:211], v[110:113]
	v_mfma_f32_16x16x32_bf16 v[102:105], v[176:179], v[208:211], v[102:105]
	v_mfma_f32_16x16x32_bf16 v[94:97], v[168:171], v[216:219], v[94:97]
	v_mfma_f32_16x16x32_bf16 v[86:89], v[176:179], v[216:219], v[86:89]
	v_mfma_f32_16x16x32_bf16 v[78:81], v[168:171], v[224:227], v[78:81]
	v_mfma_f32_16x16x32_bf16 v[70:73], v[176:179], v[224:227], v[70:73]
	s_setprio 0
	s_setprio 1
	v_mfma_f32_16x16x32_bf16 v[126:129], v[180:183], v[196:199], v[126:129]
	v_mfma_f32_16x16x32_bf16 v[114:117], v[188:191], v[196:199], v[114:117]
	v_mfma_f32_16x16x32_bf16 v[106:109], v[180:183], v[204:207], v[106:109]
	v_mfma_f32_16x16x32_bf16 v[98:101], v[188:191], v[204:207], v[98:101]
	v_mfma_f32_16x16x32_bf16 v[90:93], v[180:183], v[212:215], v[90:93]
	v_mfma_f32_16x16x32_bf16 v[82:85], v[188:191], v[212:215], v[82:85]
	v_mfma_f32_16x16x32_bf16 v[74:77], v[180:183], v[220:223], v[74:77]
	v_mfma_f32_16x16x32_bf16 v[66:69], v[188:191], v[220:223], v[66:69]
	v_mfma_f32_16x16x32_bf16 v[126:129], v[184:187], v[200:203], v[126:129]
	v_mfma_f32_16x16x32_bf16 v[114:117], v[192:195], v[200:203], v[114:117]
	v_mfma_f32_16x16x32_bf16 v[106:109], v[184:187], v[208:211], v[106:109]
	v_mfma_f32_16x16x32_bf16 v[98:101], v[192:195], v[208:211], v[98:101]
	v_mfma_f32_16x16x32_bf16 v[90:93], v[184:187], v[216:219], v[90:93]
	v_mfma_f32_16x16x32_bf16 v[82:85], v[192:195], v[216:219], v[82:85]
	v_mfma_f32_16x16x32_bf16 v[74:77], v[184:187], v[224:227], v[74:77]
	v_mfma_f32_16x16x32_bf16 v[66:69], v[192:195], v[224:227], v[66:69]
	s_setprio 0
	s_barrier
	s_add_u32 s96, s96, 0x80
	s_addc_u32 s97, s97, 0
	s_add_u32 s98, s96, 0xb0000
	s_addc_u32 s99, s97, 0
	s_add_u32 s94, s94, 0x80
	s_addc_u32 s95, s95, 0
	s_add_i32 s4, s4, s21
	s_mov_b32 m0, s4
	s_nop 0
	global_load_lds_dwordx4 v132, s[96:97]
	s_add_i32 m0, s4, 0x2000
	s_add_i32 s4, s25, s21
	global_load_lds_dwordx4 v136, s[96:97]
	s_mov_b32 m0, s4
	s_nop 0
	global_load_lds_dwordx4 v132, s[98:99]
	s_add_i32 m0, s4, 0x2000
	s_nop 0
	global_load_lds_dwordx4 v136, s[98:99]
	s_mov_b32 m0, s57
	s_nop 0
	global_load_lds_dwordx4 v130, s[94:95]
	s_mov_b32 m0, s58
	s_nop 0
	global_load_lds_dwordx4 v134, s[94:95]
	ds_read_b128 v[196:199], v160 offset:49152
	ds_read_b128 v[200:203], v160 offset:50176
	ds_read_b128 v[204:207], v160 offset:51200
	ds_read_b128 v[208:211], v160 offset:52224
	ds_read_b128 v[212:215], v160 offset:53248
	ds_read_b128 v[216:219], v160 offset:54272
	ds_read_b128 v[220:223], v160 offset:55296
	ds_read_b128 v[224:227], v160 offset:56320
	s_waitcnt vmcnt(8)
	s_waitcnt lgkmcnt(0)
	s_barrier
	s_setprio 1
	s_waitcnt lgkmcnt(0)
	v_mfma_f32_16x16x32_bf16 v[62:65], v[164:167], v[196:199], v[62:65]
	v_mfma_f32_16x16x32_bf16 v[54:57], v[172:175], v[196:199], v[54:57]
	v_mfma_f32_16x16x32_bf16 v[46:49], v[164:167], v[204:207], v[46:49]
	v_mfma_f32_16x16x32_bf16 v[38:41], v[172:175], v[204:207], v[38:41]
	v_mfma_f32_16x16x32_bf16 v[30:33], v[164:167], v[212:215], v[30:33]
	v_mfma_f32_16x16x32_bf16 v[22:25], v[172:175], v[212:215], v[22:25]
	v_mfma_f32_16x16x32_bf16 v[14:17], v[164:167], v[220:223], v[14:17]
	v_mfma_f32_16x16x32_bf16 v[6:9], v[172:175], v[220:223], v[6:9]
	v_mfma_f32_16x16x32_bf16 v[62:65], v[168:171], v[200:203], v[62:65]
	v_mfma_f32_16x16x32_bf16 v[54:57], v[176:179], v[200:203], v[54:57]
	v_mfma_f32_16x16x32_bf16 v[46:49], v[168:171], v[208:211], v[46:49]
	v_mfma_f32_16x16x32_bf16 v[38:41], v[176:179], v[208:211], v[38:41]
	v_mfma_f32_16x16x32_bf16 v[30:33], v[168:171], v[216:219], v[30:33]
	v_mfma_f32_16x16x32_bf16 v[22:25], v[176:179], v[216:219], v[22:25]
	v_mfma_f32_16x16x32_bf16 v[14:17], v[168:171], v[224:227], v[14:17]
	v_mfma_f32_16x16x32_bf16 v[6:9], v[176:179], v[224:227], v[6:9]
	s_setprio 0
	s_setprio 1
	v_mfma_f32_16x16x32_bf16 v[58:61], v[180:183], v[196:199], v[58:61]
	v_mfma_f32_16x16x32_bf16 v[50:53], v[188:191], v[196:199], v[50:53]
	v_mfma_f32_16x16x32_bf16 v[42:45], v[180:183], v[204:207], v[42:45]
	v_mfma_f32_16x16x32_bf16 v[34:37], v[188:191], v[204:207], v[34:37]
	v_mfma_f32_16x16x32_bf16 v[26:29], v[180:183], v[212:215], v[26:29]
	v_mfma_f32_16x16x32_bf16 v[18:21], v[188:191], v[212:215], v[18:21]
	v_mfma_f32_16x16x32_bf16 v[10:13], v[180:183], v[220:223], v[10:13]
	v_mfma_f32_16x16x32_bf16 v[2:5], v[188:191], v[220:223], v[2:5]
	v_mfma_f32_16x16x32_bf16 v[58:61], v[184:187], v[200:203], v[58:61]
	v_mfma_f32_16x16x32_bf16 v[50:53], v[192:195], v[200:203], v[50:53]
	v_mfma_f32_16x16x32_bf16 v[42:45], v[184:187], v[208:211], v[42:45]
	v_mfma_f32_16x16x32_bf16 v[34:37], v[192:195], v[208:211], v[34:37]
	v_mfma_f32_16x16x32_bf16 v[26:29], v[184:187], v[216:219], v[26:29]
	v_mfma_f32_16x16x32_bf16 v[18:21], v[192:195], v[216:219], v[18:21]
	v_mfma_f32_16x16x32_bf16 v[10:13], v[184:187], v[224:227], v[10:13]
	v_mfma_f32_16x16x32_bf16 v[2:5], v[192:195], v[224:227], v[2:5]
	s_setprio 0
	s_barrier
	s_mov_b32 s4, s5
	s_add_u32 s88, s88, 0x100
	s_addc_u32 s89, s89, 0
	s_add_u32 s86, s86, 0x100
	s_addc_u32 s87, s87, 0
	s_cmp_ge_i32 s5, s101
	s_cbranch_scc0 .LBB0_2075
